# conv+gate now fused into all four up-GEMM epilogues; latent-half tiles write edge rows to a halo buffer and a small fix-up phase recomputes interior tile-edge rows; H2 operand moved into the dead up b
# speedup vs baseline: 1.0521x; 1.0342x over previous
.LBB0_727:
	s_add_u32 s63, s70, 0x22000
	s_addc_u32 s64, s71, 0
	s_add_u32 s65, s70, 0x24000
	s_addc_u32 s66, s71, 0
	s_add_u32 s67, s70, 0x3b00000
	s_addc_u32 s80, s71, 0
	s_lshl_b32 s1, s1, 5
	s_mov_b64 s[14:15], 0x80
	s_and_b32 s30, s1, 0x60
	s_add_i32 m0, s59, 0x18000
	v_lshl_add_u64 v[6:7], v[6:7], 0, s[14:15]
	s_lshl_b32 s20, s0, 13
	s_lshl_b32 s1, s30, 7
	s_waitcnt vmcnt(2)
	s_barrier
	global_load_lds_dwordx4 v[6:7], off
	v_lshl_add_u64 v[4:5], v[4:5], 0, s[14:15]
	s_add_i32 m0, s59, 0x1a000
	s_add_i32 s81, s59, 0x8000
	s_add_i32 s82, s59, 0xa000
	global_load_lds_dwordx4 v[4:5], off
	v_lshl_add_u64 v[0:1], v[0:1], 0, s[14:15]
	s_mov_b32 m0, s81
	s_add_u32 s4, s88, 0x40080
	global_load_lds_dwordx4 v[0:1], off
	v_lshl_add_u64 v[0:1], v[2:3], 0, s[14:15]
	s_mov_b32 m0, s82
	s_addc_u32 s5, s89, 0
	global_load_lds_dwordx4 v[0:1], off
	s_add_i32 m0, s59, 0x1c000
	v_lshl_add_u64 v[0:1], s[4:5], 0, v[128:129]
	global_load_lds_dwordx4 v[0:1], off
	v_lshl_add_u64 v[0:1], s[4:5], 0, v[130:131]
	s_add_i32 m0, s59, 0x1e000
	v_bfe_u32 v15, v8, 4, 2
	global_load_lds_dwordx4 v[0:1], off
	v_and_b32_e32 v1, 15, v8
	v_lshlrev_b32_e32 v2, 4, v15
	v_lshl_or_b32 v0, s0, 6, v1
	v_lshl_or_b32 v1, v1, 6, v2
	v_lshlrev_b32_e32 v2, 2, v8
	v_and_b32_e32 v2, 32, v2
	v_bitop3_b32 v8, v1, s20, v2 bitop3:0xde
	v_bitop3_b32 v178, v1, s1, v2 bitop3:0xde
	v_ashrrev_i32_e32 v1, 31, v0
	v_lshlrev_b64 v[132:133], 10, v[0:1]
	v_or_b32_e32 v2, 16, v0
	v_or_b32_e32 v4, 32, v0
	v_or_b32_e32 v6, 48, v0
	v_add_u32_e32 v16, 0x80, v0
	v_add_u32_e32 v18, 0x90, v0
	v_add_u32_e32 v20, 0xa0, v0
	v_add_u32_e32 v22, 0xb0, v0
	v_lshl_add_u64 v[148:149], v[0:1], 2, s[10:11]
	v_lshlrev_b32_e32 v0, 14, v9
	v_and_b32_e32 v0, 0xffff8000, v0
	v_lshl_add_u32 v0, v10, 11, v0
	v_and_b32_e32 v1, 1, v9
	v_lshl_or_b32 v0, v1, 6, v0
	v_lshl_add_u32 v164, v11, 1, v0
	v_lshlrev_b32_e32 v0, 14, v12
	v_and_b32_e32 v0, 0xffff8000, v0
	v_lshl_add_u32 v0, v13, 11, v0
	v_and_b32_e32 v1, 1, v12
	s_waitcnt vmcnt(6)
	v_lshl_or_b32 v0, v1, 6, v0
	s_cmpk_lt_u32 s8, 0x100
	v_ashrrev_i32_e32 v3, 31, v2
	v_ashrrev_i32_e32 v5, 31, v4
	v_ashrrev_i32_e32 v7, 31, v6
	v_ashrrev_i32_e32 v17, 31, v16
	v_ashrrev_i32_e32 v19, 31, v18
	v_ashrrev_i32_e32 v21, 31, v20
	v_ashrrev_i32_e32 v23, 31, v22
	v_readlane_b32 s4, v254, 47
	v_lshl_add_u32 v166, v14, 1, v0
	v_mbcnt_lo_u32_b32 v0, -1, 0
	s_cselect_b64 s[12:13], -1, 0
	v_cmp_eq_u32_e64 s[0:1], 0, v15
	v_lshlrev_b64 v[134:135], 10, v[2:3]
	v_lshlrev_b64 v[136:137], 10, v[4:5]
	v_lshlrev_b64 v[138:139], 10, v[6:7]
	v_lshlrev_b64 v[140:141], 10, v[16:17]
	v_lshlrev_b64 v[142:143], 10, v[18:19]
	v_lshlrev_b64 v[144:145], 10, v[20:21]
	v_lshlrev_b64 v[146:147], 10, v[22:23]
	s_ashr_i32 s83, s4, 31
	s_mov_b32 s93, s4
	s_ashr_i32 s94, s84, 31
	v_lshl_or_b32 v179, v15, 2, s30
	v_lshl_add_u64 v[150:151], v[2:3], 2, s[10:11]
	v_lshl_add_u64 v[152:153], v[4:5], 2, s[10:11]
	v_lshl_add_u64 v[154:155], v[6:7], 2, s[10:11]
	v_lshl_add_u64 v[156:157], v[16:17], 2, s[10:11]
	v_lshl_add_u64 v[158:159], v[18:19], 2, s[10:11]
	v_lshl_add_u64 v[160:161], v[20:21], 2, s[10:11]
	v_lshl_add_u64 v[162:163], v[22:23], 2, s[10:11]
	v_mov_b32_e32 v165, v129
	v_mov_b32_e32 v167, v129
	s_add_i32 s95, 0, 0x10000
	s_add_i32 s96, 0, 0x14000
	v_add_u32_e32 v180, 0, v8
	v_mbcnt_hi_u32_b32 v181, -1, v0
	v_mov_b64_e32 v[168:169], 0x100
	v_mov_b64_e32 v[170:171], 0xff
	s_mov_b32 s97, 0
	s_barrier
	v_readlane_b32 s5, v254, 48
	s_branch .LBB0_730

.LBB0_818:
	s_add_u32 s33, s70, 0xa00000
	s_mov_b64 s[2:3], s[82:83]
	s_addc_u32 s82, s71, 0
	s_cmpk_lt_i32 s84, 0x2c0
	s_cselect_b64 s[4:5], -1, 0
	s_ashr_i32 s85, s84, 31
	s_lshr_b32 s0, s85, 29
	s_add_i32 s0, s84, s0
	s_ashr_i32 s1, s0, 3
	s_and_b32 s0, s0, -8
	s_sub_i32 s0, s84, s0
	s_cmp_lt_i32 s0, 0
	v_writelane_b32 v254, s1, 61
	s_cselect_b64 s[6:7], -1, 0
	v_writelane_b32 v254, s6, 62
	s_cmp_gt_i32 s0, -1
	s_mov_b32 s18, s2
	v_writelane_b32 v254, s7, 63
	v_writelane_b32 v254, s0, 51
	s_cselect_b64 s[0:1], -1, 0
	s_ashr_i32 s19, s2, 31
	v_writelane_b32 v255, s0, 0
	s_cmpk_eq_i32 s2, 0x100
	v_cmp_eq_u32_e64 s[2:3], 0, v230
	v_writelane_b32 v255, s1, 1
	s_cselect_b64 s[0:1], -1, 0
	s_cmpk_gt_u32 s84, 0xbf
	s_cselect_b64 s[6:7], -1, 0
	s_and_b64 s[8:9], s[6:7], s[0:1]
	s_lshl_b32 s1, s84, 3
	s_add_i32 s83, s1, 0xfffffa00
	s_cmp_gt_i32 s72, 7
	v_writelane_b32 v254, s2, 59
	s_cselect_b64 s[6:7], -1, 0
	s_cmp_lt_i32 s73, 8
	v_cndmask_b32_e64 v0, 0, 1, s[4:5]
	v_writelane_b32 v254, s3, 60
	s_cselect_b64 s[12:13], -1, 0
	v_cmp_ne_u32_e64 s[2:3], 1, v0
	s_or_b64 s[6:7], s[6:7], s[12:13]
	s_and_b64 vcc, exec, s[6:7]
	v_writelane_b32 v255, s2, 2
	s_nop 1
	v_writelane_b32 v255, s3, 3
	s_cbranch_vccnz .LBB0_899
	v_readlane_b32 s2, v255, 2
	v_mov_b32_e32 v14, v230
	v_readlane_b32 s3, v255, 3
	s_and_b64 vcc, exec, s[2:3]
	v_readfirstlane_b32 s5, v14
	s_cbranch_vccnz .LBB0_834
	v_lshlrev_b32_e32 v0, 4, v14
	s_waitcnt lgkmcnt(0)
	v_add_u32_e32 v1, 0x2000, v0
	v_ashrrev_i32_e32 v2, 31, v1
	v_lshrrev_b32_e32 v2, 22, v2
	v_add_u32_e32 v2, v1, v2
	v_ashrrev_i32_e32 v8, 10, v2
	v_mul_i32_i24_e32 v2, 0x400, v8
	v_sub_u32_e32 v1, v1, v2
	v_lshrrev_b32_e32 v2, 4, v1
	v_bitop3_b32 v1, v2, v1, 32 bitop3:0x6c
	v_ashrrev_i32_e32 v2, 31, v1
	v_lshrrev_b32_e32 v2, 26, v2
	v_add_u32_e32 v2, v1, v2
	v_lshlrev_b32_e32 v3, 3, v8
	v_ashrrev_i32_e32 v9, 6, v2
	v_and_b32_e32 v3, -16, v3
	v_add_u32_e32 v3, v9, v3
	v_and_b32_e32 v4, 3, v9
	s_mov_b32 s4, 0x1fffe0
	v_lshrrev_b32_e32 v5, 2, v3
	v_lshlrev_b32_e32 v6, 1, v3
	v_and_b32_e32 v2, 0xc0, v2
	v_and_or_b32 v4, v3, s4, v4
	v_and_b32_e32 v5, 4, v5
	v_and_b32_e32 v6, 24, v6
	v_sub_u32_e32 v1, v1, v2
	v_mov_b32_e32 v2, 1
	v_or3_b32 v4, v4, v5, v6
	v_lshlrev_b32_e32 v5, 5, v8
	v_ashrrev_i16_sdwa v1, v2, sext(v1) dst_sel:DWORD dst_unused:UNUSED_PAD src0_sel:DWORD src1_sel:BYTE_0
	v_and_b32_e32 v5, 32, v5
	v_bfe_i32 v10, v1, 0, 16
	v_add_lshl_u32 v1, v5, v10, 1
	v_lshl_add_u32 v144, v4, 11, v1
	v_lshl_add_u32 v146, v3, 11, v1
	v_bfe_i32 v1, v14, 27, 1
	v_lshrrev_b32_e32 v1, 22, v1
	v_add_u32_e32 v1, v0, v1
	v_and_b32_e32 v1, 0xfffffc00, v1
	v_sub_u32_e32 v0, v0, v1
	v_lshrrev_b32_e32 v1, 4, v0
	v_ashrrev_i32_e32 v3, 31, v14
	v_bitop3_b32 v0, v1, v0, 32 bitop3:0x6c
	v_lshrrev_b32_e32 v3, 26, v3
	v_ashrrev_i32_e32 v1, 31, v0
	v_add_u32_e32 v3, v14, v3
	s_add_u32 s0, s70, 0x3b00000
	v_lshrrev_b32_e32 v1, 26, v1
	v_ashrrev_i32_e32 v12, 6, v3
	s_addc_u32 s20, s71, 0
	s_ashr_i32 s6, s5, 6
	v_add_u32_e32 v1, v0, v1
	v_lshlrev_b32_e32 v3, 3, v12
	v_readlane_b32 s2, v254, 62
	s_ashr_i32 s7, s5, 8
	s_lshl_b32 s21, s6, 10
	v_ashrrev_i32_e32 v11, 6, v1
	v_and_b32_e32 v3, -16, v3
	v_readlane_b32 s3, v254, 63
	v_add_u32_e32 v3, v11, v3
	v_and_b32_e32 v4, 3, v11
	s_movk_i32 s30, 0x59
	s_and_b64 s[12:13], s[2:3], exec
	v_and_or_b32 v4, v3, s4, v4
	s_cselect_b32 s4, s30, 0x58
	v_readlane_b32 s2, v254, 51
	s_mul_i32 s4, s4, s2
	v_readlane_b32 s2, v254, 61
	s_add_i32 s4, s4, s2
	s_mul_hi_i32 s12, s4, 0x2e8ba2e9
	s_lshr_b32 s13, s12, 31
	s_ashr_i32 s12, s12, 5
	s_add_i32 s12, s12, s13
	s_lshl_b32 s13, s12, 3
	s_mulk_i32 s12, 0xb0
	s_sub_i32 s12, s4, s12
	s_bfe_u32 s4, s12, 0x3001c
	s_add_i32 s14, s12, s4
	s_sext_i32_i16 s4, s14
	s_and_b32 s14, s14, 0xfff8
	s_sub_i32 s12, s12, s14
	s_sext_i32_i16 s12, s12
	v_lshrrev_b32_e32 v5, 2, v3
	v_lshlrev_b32_e32 v6, 1, v3
	v_and_b32_e32 v1, 0xc0, v1
	s_lshr_b32 s4, s4, 3
	s_add_i32 s88, s13, s12
	v_and_b32_e32 v5, 4, v5
	v_and_b32_e32 v6, 24, v6
	v_sub_u32_e32 v0, v0, v1
	s_ashr_i32 s89, s88, 31
	s_bfe_i64 s[14:15], s[4:5], 0x100000
	v_or3_b32 v4, v4, v5, v6
	v_lshlrev_b32_e32 v5, 5, v12
	v_ashrrev_i16_sdwa v0, v2, sext(v0) dst_sel:DWORD dst_unused:UNUSED_PAD src0_sel:DWORD src1_sel:BYTE_0
	s_lshl_b64 s[12:13], s[88:89], 19
	s_lshl_b64 s[14:15], s[14:15], 18
	v_and_b32_e32 v5, 32, v5
	v_bfe_i32 v13, v0, 0, 16
	s_add_u32 s92, s33, s14
	v_add_lshl_u32 v0, v5, v13, 1
	s_addc_u32 s93, s82, s15
	s_add_i32 s31, s21, 0
	v_lshl_add_u32 v148, v4, 11, v0
	s_add_i32 m0, s31, 0x10000
	v_lshl_add_u32 v150, v3, 11, v0
	global_load_lds_dwordx4 v148, s[92:93]
	s_add_i32 m0, s31, 0x12000
	s_add_u32 s14, s92, 0x580000
	global_load_lds_dwordx4 v144, s[92:93]
	s_addc_u32 s15, s93, 0
	s_add_i32 m0, s31, 0x14000
	v_mov_b32_e32 v149, 0
	global_load_lds_dwordx4 v148, s[14:15]
	s_add_i32 m0, s31, 0x16000
	s_add_u32 s90, s0, s12
	s_addc_u32 s91, s20, s13
	s_add_i32 s52, s31, 0x2000
	global_load_lds_dwordx4 v144, s[14:15]
	s_mov_b32 m0, s31
	s_add_u32 s12, s90, 0x40000
	global_load_lds_dwordx4 v150, s[90:91]
	s_mov_b32 m0, s52
	s_addc_u32 s13, s91, 0
	s_add_i32 s53, s31, 0x4000
	global_load_lds_dwordx4 v146, s[90:91]
	s_mov_b32 m0, s53
	s_add_i32 s58, s31, 0x6000
	global_load_lds_dwordx4 v150, s[12:13]
	s_mov_b32 m0, s58
	v_mov_b32_e32 v145, v149
	global_load_lds_dwordx4 v146, s[12:13]
	v_mov_b32_e32 v151, v149
	v_mov_b32_e32 v147, v149
	s_cmp_eq_u32 s7, 1
	s_mov_b32 s59, 0
	v_lshl_add_u64 v[6:7], s[92:93], 0, v[148:149]
	v_lshl_add_u64 v[4:5], s[92:93], 0, v[144:145]
	v_lshl_add_u64 v[0:1], s[90:91], 0, v[150:151]
	s_cselect_b64 s[12:13], -1, 0
	s_cmp_lg_u32 s7, 1
	v_lshl_add_u64 v[2:3], s[90:91], 0, v[146:147]
	s_cbranch_scc1 .LBB0_822
	s_barrier

.LBB0_831:
	s_and_b32 s32, s12, 1
	v_readlane_b32 s92, v254, 49
	v_readlane_b32 s93, v254, 50
	s_nop 0
	s_add_i32 s4, s88, -32
	s_ashr_i32 s4, s4, 2
	s_add_i32 s4, s4, 1
	s_cmp_gt_i32 s88, 31
	s_cselect_b32 s4, s4, 0
	s_mul_hi_i32 s5, s4, 0x5800
	s_mulk_i32 s4, 0x5800
	s_add_u32 s4, s92, s4
	s_addc_u32 s5, s93, s5
	v_lshl_add_u32 v236, s88, 8, v170
	v_lshlrev_b32_e32 v236, 2, v236
	v_lshl_or_b32 v177, s66, 7, v172
	v_lshlrev_b32_e32 v177, 2, v177
	global_load_dword v210, v236, s[10:11] offset:0
	global_load_dword v211, v236, s[10:11] offset:64
	global_load_dword v212, v236, s[10:11] offset:128
	global_load_dword v213, v236, s[10:11] offset:192
	global_load_dword v214, v236, s[10:11] offset:512
	global_load_dword v215, v236, s[10:11] offset:576
	global_load_dword v216, v236, s[10:11] offset:640
	global_load_dword v217, v236, s[10:11] offset:704
	global_load_dwordx4 v[202:205], v177, s[4:5]
	global_load_dwordx4 v[206:209], v177, s[4:5] offset:16
	v_add_u32_e32 v226, 0x2c00, v177
	global_load_dwordx4 v[218:221], v226, s[4:5]
	global_load_dwordx4 v[222:225], v226, s[4:5] offset:16
	v_readlane_b32 s2, v254, 5
	v_readlane_b32 s3, v254, 6
	v_readlane_b32 s28, v254, 7
	v_readlane_b32 s29, v254, 8
	s_mul_i32 s76, s88, 0x160000
	s_lshl_b32 s67, s66, 8
	s_add_i32 s76, s76, s67
	s_add_i32 s76, s76, 0x9300000
	s_add_u32 s76, s76, s70
	s_addc_u32 s77, s71, 0
	v_mul_u32_u24_e32 v168, 0x1600, v170
	v_lshl_add_u32 v168, v172, 1, v168
	s_mov_b32 s57, 0x20800
	v_lshl_add_u32 v169, v172, 2, s57
	v_and_b32_e32 v237, 15, v170
	v_cmp_eq_u32_e64 s[78:79], 0, v237
	v_cmp_eq_u32_e64 s[80:81], 15, v237
	v_and_b32_e32 v231, 8, v237
	v_lshlrev_b32_e32 v231, 9, v231
	s_lshl_b32 s67, s32, 10
	v_add3_u32 v231, v231, v169, s67
	s_waitcnt vmcnt(4)
	v_fmamk_f32 v210, v210, 0x3a800000, v176
	v_fmamk_f32 v211, v211, 0x3a800000, v176
	v_fmamk_f32 v212, v212, 0x3a800000, v176
	v_fmamk_f32 v213, v213, 0x3a800000, v176
	v_fmamk_f32 v214, v214, 0x3a800000, v176
	v_fmamk_f32 v215, v215, 0x3a800000, v176
	v_fmamk_f32 v216, v216, 0x3a800000, v176
	v_fmamk_f32 v217, v217, 0x3a800000, v176
	s_mov_b32 s67, 0x800000
	v_mul_f32_e32 v226, 0x4b800000, v210
	v_mul_f32_e32 v227, 0x4b800000, v211
	v_mul_f32_e32 v228, 0x4b800000, v212
	v_mul_f32_e32 v229, 0x4b800000, v213
	v_mul_f32_e32 v232, 0x4b800000, v214
	v_mul_f32_e32 v233, 0x4b800000, v215
	v_mul_f32_e32 v234, 0x4b800000, v216
	v_mul_f32_e32 v235, 0x4b800000, v217
	v_cmp_gt_f32_e32 vcc, s67, v210
	s_nop 1
	v_cndmask_b32_e32 v210, v210, v226, vcc
	v_rsq_f32_e32 v210, v210
	s_nop 0
	v_mul_f32_e32 v226, 0x45800000, v210
	v_cndmask_b32_e32 v210, v210, v226, vcc
	v_cmp_gt_f32_e32 vcc, s67, v211
	s_nop 1
	v_cndmask_b32_e32 v211, v211, v227, vcc
	v_rsq_f32_e32 v211, v211
	s_nop 0
	v_mul_f32_e32 v227, 0x45800000, v211
	v_cndmask_b32_e32 v211, v211, v227, vcc
	v_cmp_gt_f32_e32 vcc, s67, v212
	s_nop 1
	v_cndmask_b32_e32 v212, v212, v228, vcc
	v_rsq_f32_e32 v212, v212
	s_nop 0
	v_mul_f32_e32 v228, 0x45800000, v212
	v_cndmask_b32_e32 v212, v212, v228, vcc
	v_cmp_gt_f32_e32 vcc, s67, v213
	s_nop 1
	v_cndmask_b32_e32 v213, v213, v229, vcc
	v_rsq_f32_e32 v213, v213
	s_nop 0
	v_mul_f32_e32 v229, 0x45800000, v213
	v_cndmask_b32_e32 v213, v213, v229, vcc
	v_cmp_gt_f32_e32 vcc, s67, v214
	s_nop 1
	v_cndmask_b32_e32 v214, v214, v232, vcc
	v_rsq_f32_e32 v214, v214
	s_nop 0
	v_mul_f32_e32 v232, 0x45800000, v214
	v_cndmask_b32_e32 v214, v214, v232, vcc
	v_cmp_gt_f32_e32 vcc, s67, v215
	s_nop 1
	v_cndmask_b32_e32 v215, v215, v233, vcc
	v_rsq_f32_e32 v215, v215
	s_nop 0
	v_mul_f32_e32 v233, 0x45800000, v215
	v_cndmask_b32_e32 v215, v215, v233, vcc
	v_cmp_gt_f32_e32 vcc, s67, v216
	s_nop 1
	v_cndmask_b32_e32 v216, v216, v234, vcc
	v_rsq_f32_e32 v216, v216
	s_nop 0
	v_mul_f32_e32 v234, 0x45800000, v216
	v_cndmask_b32_e32 v216, v216, v234, vcc
	v_cmp_gt_f32_e32 vcc, s67, v217
	s_nop 1
	v_cndmask_b32_e32 v217, v217, v235, vcc
	v_rsq_f32_e32 v217, v217
	s_nop 0
	v_mul_f32_e32 v235, 0x45800000, v217
	v_cndmask_b32_e32 v217, v217, v235, vcc
	s_waitcnt vmcnt(0)
	v_fma_f32 v140, v140, v210, v202
	v_fma_f32 v141, v141, v210, v203
	v_fma_f32 v142, v142, v210, v204
	v_fma_f32 v143, v143, v210, v205
	v_fma_f32 v136, v136, v210, v206
	v_fma_f32 v137, v137, v210, v207
	v_fma_f32 v138, v138, v210, v208
	v_fma_f32 v139, v139, v210, v209
	v_fma_f32 v120, v120, v210, v218
	v_fma_f32 v121, v121, v210, v219
	v_fma_f32 v122, v122, v210, v220
	v_fma_f32 v123, v123, v210, v221
	v_fma_f32 v112, v112, v210, v222
	v_fma_f32 v113, v113, v210, v223
	v_fma_f32 v114, v114, v210, v224
	v_fma_f32 v115, v115, v210, v225
	v_fma_f32 v108, v108, v211, v202
	v_fma_f32 v109, v109, v211, v203
	v_fma_f32 v110, v110, v211, v204
	v_fma_f32 v111, v111, v211, v205
	v_fma_f32 v104, v104, v211, v206
	v_fma_f32 v105, v105, v211, v207
	v_fma_f32 v106, v106, v211, v208
	v_fma_f32 v107, v107, v211, v209
	v_fma_f32 v100, v100, v211, v218
	v_fma_f32 v101, v101, v211, v219
	v_fma_f32 v102, v102, v211, v220
	v_fma_f32 v103, v103, v211, v221
	v_fma_f32 v96, v96, v211, v222
	v_fma_f32 v97, v97, v211, v223
	v_fma_f32 v98, v98, v211, v224
	v_fma_f32 v99, v99, v211, v225
	v_fma_f32 v92, v92, v212, v202
	v_fma_f32 v93, v93, v212, v203
	v_fma_f32 v94, v94, v212, v204
	v_fma_f32 v95, v95, v212, v205
	v_fma_f32 v88, v88, v212, v206
	v_fma_f32 v89, v89, v212, v207
	v_fma_f32 v90, v90, v212, v208
	v_fma_f32 v91, v91, v212, v209
	v_fma_f32 v84, v84, v212, v218
	v_fma_f32 v85, v85, v212, v219
	v_fma_f32 v86, v86, v212, v220
	v_fma_f32 v87, v87, v212, v221
	v_fma_f32 v80, v80, v212, v222
	v_fma_f32 v81, v81, v212, v223
	v_fma_f32 v82, v82, v212, v224
	v_fma_f32 v83, v83, v212, v225
	v_fma_f32 v76, v76, v213, v202
	v_fma_f32 v77, v77, v213, v203
	v_fma_f32 v78, v78, v213, v204
	v_fma_f32 v79, v79, v213, v205
	v_fma_f32 v72, v72, v213, v206
	v_fma_f32 v73, v73, v213, v207
	v_fma_f32 v74, v74, v213, v208
	v_fma_f32 v75, v75, v213, v209
	v_fma_f32 v68, v68, v213, v218
	v_fma_f32 v69, v69, v213, v219
	v_fma_f32 v70, v70, v213, v220
	v_fma_f32 v71, v71, v213, v221
	v_fma_f32 v64, v64, v213, v222
	v_fma_f32 v65, v65, v213, v223
	v_fma_f32 v66, v66, v213, v224
	v_fma_f32 v67, v67, v213, v225
	v_fma_f32 v60, v60, v214, v202
	v_fma_f32 v61, v61, v214, v203
	v_fma_f32 v62, v62, v214, v204
	v_fma_f32 v63, v63, v214, v205
	v_fma_f32 v56, v56, v214, v206
	v_fma_f32 v57, v57, v214, v207
	v_fma_f32 v58, v58, v214, v208
	v_fma_f32 v59, v59, v214, v209
	v_fma_f32 v52, v52, v214, v218
	v_fma_f32 v53, v53, v214, v219
	v_fma_f32 v54, v54, v214, v220
	v_fma_f32 v55, v55, v214, v221
	v_fma_f32 v48, v48, v214, v222
	v_fma_f32 v49, v49, v214, v223
	v_fma_f32 v50, v50, v214, v224
	v_fma_f32 v51, v51, v214, v225
	v_fma_f32 v44, v44, v215, v202
	v_fma_f32 v45, v45, v215, v203
	v_fma_f32 v46, v46, v215, v204
	v_fma_f32 v47, v47, v215, v205
	v_fma_f32 v40, v40, v215, v206
	v_fma_f32 v41, v41, v215, v207
	v_fma_f32 v42, v42, v215, v208
	v_fma_f32 v43, v43, v215, v209
	v_fma_f32 v36, v36, v215, v218
	v_fma_f32 v37, v37, v215, v219
	v_fma_f32 v38, v38, v215, v220
	v_fma_f32 v39, v39, v215, v221
	v_fma_f32 v32, v32, v215, v222
	v_fma_f32 v33, v33, v215, v223
	v_fma_f32 v34, v34, v215, v224
	v_fma_f32 v35, v35, v215, v225
	v_fma_f32 v28, v28, v216, v202
	v_fma_f32 v29, v29, v216, v203
	v_fma_f32 v30, v30, v216, v204
	v_fma_f32 v31, v31, v216, v205
	v_fma_f32 v24, v24, v216, v206
	v_fma_f32 v25, v25, v216, v207
	v_fma_f32 v26, v26, v216, v208
	v_fma_f32 v27, v27, v216, v209
	v_fma_f32 v20, v20, v216, v218
	v_fma_f32 v21, v21, v216, v219
	v_fma_f32 v22, v22, v216, v220
	v_fma_f32 v23, v23, v216, v221
	v_fma_f32 v16, v16, v216, v222
	v_fma_f32 v17, v17, v216, v223
	v_fma_f32 v18, v18, v216, v224
	v_fma_f32 v19, v19, v216, v225
	v_fma_f32 v12, v12, v217, v202
	v_fma_f32 v13, v13, v217, v203
	v_fma_f32 v14, v14, v217, v204
	v_fma_f32 v15, v15, v217, v205
	v_fma_f32 v8, v8, v217, v206
	v_fma_f32 v9, v9, v217, v207
	v_fma_f32 v10, v10, v217, v208
	v_fma_f32 v11, v11, v217, v209
	v_fma_f32 v4, v4, v217, v218
	v_fma_f32 v5, v5, v217, v219
	v_fma_f32 v6, v6, v217, v220
	v_fma_f32 v7, v7, v217, v221
	v_fma_f32 v0, v0, v217, v222
	v_fma_f32 v1, v1, v217, v223
	v_fma_f32 v2, v2, v217, v224
	v_fma_f32 v3, v3, v217, v225
	global_load_dwordx4 v[116:119], v177, s[2:3]
	v_add_u32_e32 v213, 0x5800, v177
	global_load_dwordx4 v[124:127], v213, s[2:3]
	v_add_u32_e32 v212, 0xb000, v177
	global_load_dwordx4 v[128:131], v212, s[2:3]
	global_load_dwordx4 v[132:135], v177, s[28:29]
	v_add_u32_e32 v212, 0x2c00, v177
	global_load_dwordx4 v[160:163], v212, s[2:3]
	v_add_u32_e32 v213, 0x8400, v177
	global_load_dwordx4 v[164:167], v213, s[2:3]
	v_add_u32_e32 v212, 0xdc00, v177
	global_load_dwordx4 v[178:181], v212, s[2:3]
	v_add_u32_e32 v213, 0x2c00, v177
	global_load_dwordx4 v[182:185], v213, s[28:29]
	v_mov_b32_e32 v214, 0
	v_mov_b32_e32 v215, 0
	v_mov_b32_e32 v216, 0
	v_mov_b32_e32 v217, 0
	s_lshl_b32 s100, s32, 12
	s_sub_i32 s100, 0x2000, s100
	s_mul_i32 s101, s32, 0x1400
	s_add_i32 s101, s101, 0xc00
	s_lshl_b32 s67, s32, 10
	s_add_i32 s98, s67, 5120
	s_add_i32 s99, s67, 1024
	s_mov_b64 s[90:91], exec
	s_mov_b64 exec, s[78:79]
	v_add_u32_e32 v250, s100, v169
	ds_write_b128 v250, v[140:143] offset:0
	ds_write_b128 v250, v[136:139] offset:16
	ds_write_b128 v250, v[120:123] offset:512
	ds_write_b128 v250, v[112:115] offset:528
	v_add_u32_e32 v250, s98, v169
	ds_write_b128 v250, v[60:63] offset:0
	ds_write_b128 v250, v[56:59] offset:16
	ds_write_b128 v250, v[52:55] offset:512
	ds_write_b128 v250, v[48:51] offset:528
	ds_write_b128 v169, v[214:217] offset:0
	ds_write_b128 v169, v[214:217] offset:16
	ds_write_b128 v169, v[214:217] offset:512
	ds_write_b128 v169, v[214:217] offset:528
	s_mov_b64 exec, s[80:81]
	v_add_u32_e32 v251, s99, v169
	ds_write_b128 v251, v[76:79] offset:0
	ds_write_b128 v251, v[72:75] offset:16
	ds_write_b128 v251, v[68:71] offset:512
	ds_write_b128 v251, v[64:67] offset:528
	v_add_u32_e32 v251, s101, v169
	ds_write_b128 v251, v[12:15] offset:0
	ds_write_b128 v251, v[8:11] offset:16
	ds_write_b128 v251, v[4:7] offset:512
	ds_write_b128 v251, v[0:3] offset:528
	ds_write_b128 v169, v[214:217] offset:7168
	ds_write_b128 v169, v[214:217] offset:7184
	ds_write_b128 v169, v[214:217] offset:7680
	ds_write_b128 v169, v[214:217] offset:7696
	s_mov_b64 exec, s[90:91]
	s_waitcnt lgkmcnt(0)
	s_barrier
	ds_read_b128 v[186:189], v231 offset:0
	ds_read_b128 v[190:193], v231 offset:512
	ds_read_b128 v[194:197], v231 offset:2048
	ds_read_b128 v[198:201], v231 offset:2560
	s_waitcnt vmcnt(0)
	v_cndmask_b32_e64 v218, 0, v116, s[78:79]
	v_cndmask_b32_e64 v222, 0, v128, s[80:81]
	v_cndmask_b32_e64 v219, 0, v117, s[78:79]
	v_cndmask_b32_e64 v223, 0, v129, s[80:81]
	v_cndmask_b32_e64 v220, 0, v118, s[78:79]
	v_cndmask_b32_e64 v224, 0, v130, s[80:81]
	v_cndmask_b32_e64 v221, 0, v119, s[78:79]
	v_cndmask_b32_e64 v225, 0, v131, s[80:81]
	v_cndmask_b32_e64 v226, 0, v160, s[78:79]
	v_cndmask_b32_e64 v232, 0, v178, s[80:81]
	v_cndmask_b32_e64 v227, 0, v161, s[78:79]
	v_cndmask_b32_e64 v233, 0, v179, s[80:81]
	v_cndmask_b32_e64 v228, 0, v162, s[78:79]
	v_cndmask_b32_e64 v234, 0, v180, s[80:81]
	v_cndmask_b32_e64 v229, 0, v163, s[78:79]
	v_cndmask_b32_e64 v235, 0, v181, s[80:81]
	s_waitcnt lgkmcnt(0)
	s_nop 1
	v_fma_f32 v202, v124, v140, v132
	v_fma_f32 v203, v125, v141, v133
	v_fma_f32 v204, v126, v142, v134
	v_fma_f32 v205, v127, v143, v135
	v_fmac_f32_dpp v202, v140, v116 row_shr:1 row_mask:0xf bank_mask:0xf
	v_fmac_f32_dpp v203, v141, v117 row_shr:1 row_mask:0xf bank_mask:0xf
	v_fmac_f32_dpp v204, v142, v118 row_shr:1 row_mask:0xf bank_mask:0xf
	v_fmac_f32_dpp v205, v143, v119 row_shr:1 row_mask:0xf bank_mask:0xf
	v_fmac_f32_e32 v202, v186, v218
	v_fmac_f32_e32 v203, v187, v219
	v_fmac_f32_e32 v204, v188, v220
	v_fmac_f32_e32 v205, v189, v221
	v_fmac_f32_dpp v202, v140, v128 row_shl:1 row_mask:0xf bank_mask:0xf
	v_fmac_f32_dpp v203, v141, v129 row_shl:1 row_mask:0xf bank_mask:0xf
	v_fmac_f32_dpp v204, v142, v130 row_shl:1 row_mask:0xf bank_mask:0xf
	v_fmac_f32_dpp v205, v143, v131 row_shl:1 row_mask:0xf bank_mask:0xf
	v_fmac_f32_dpp v202, v108, v222 row_ror:15 row_mask:0xf bank_mask:0xf
	v_fmac_f32_dpp v203, v109, v223 row_ror:15 row_mask:0xf bank_mask:0xf
	v_fmac_f32_dpp v204, v110, v224 row_ror:15 row_mask:0xf bank_mask:0xf
	v_fmac_f32_dpp v205, v111, v225 row_ror:15 row_mask:0xf bank_mask:0xf
	v_fma_f32 v206, v164, v120, v182
	v_fma_f32 v207, v165, v121, v183
	v_fma_f32 v208, v166, v122, v184
	v_fma_f32 v209, v167, v123, v185
	v_fmac_f32_dpp v206, v120, v160 row_shr:1 row_mask:0xf bank_mask:0xf
	v_fmac_f32_dpp v207, v121, v161 row_shr:1 row_mask:0xf bank_mask:0xf
	v_fmac_f32_dpp v208, v122, v162 row_shr:1 row_mask:0xf bank_mask:0xf
	v_fmac_f32_dpp v209, v123, v163 row_shr:1 row_mask:0xf bank_mask:0xf
	v_fmac_f32_e32 v206, v190, v226
	v_fmac_f32_e32 v207, v191, v227
	v_fmac_f32_e32 v208, v192, v228
	v_fmac_f32_e32 v209, v193, v229
	v_fmac_f32_dpp v206, v120, v178 row_shl:1 row_mask:0xf bank_mask:0xf
	v_fmac_f32_dpp v207, v121, v179 row_shl:1 row_mask:0xf bank_mask:0xf
	v_fmac_f32_dpp v208, v122, v180 row_shl:1 row_mask:0xf bank_mask:0xf
	v_fmac_f32_dpp v209, v123, v181 row_shl:1 row_mask:0xf bank_mask:0xf
	v_fmac_f32_dpp v206, v100, v232 row_ror:15 row_mask:0xf bank_mask:0xf
	v_fmac_f32_dpp v207, v101, v233 row_ror:15 row_mask:0xf bank_mask:0xf
	v_fmac_f32_dpp v208, v102, v234 row_ror:15 row_mask:0xf bank_mask:0xf
	v_fmac_f32_dpp v209, v103, v235 row_ror:15 row_mask:0xf bank_mask:0xf
	v_mul_f32_e32 v210, 0xbfb8aa3b, v202
	v_mul_f32_e32 v211, 0xbfb8aa3b, v203
	v_mul_f32_e32 v212, 0xbfb8aa3b, v204
	v_mul_f32_e32 v213, 0xbfb8aa3b, v205
	v_exp_f32_e32 v210, v210
	v_exp_f32_e32 v211, v211
	v_exp_f32_e32 v212, v212
	v_exp_f32_e32 v213, v213
	v_add_f32_e32 v210, 1.0, v210
	v_add_f32_e32 v211, 1.0, v211
	v_add_f32_e32 v212, 1.0, v212
	v_add_f32_e32 v213, 1.0, v213
	v_rcp_f32_e32 v210, v210
	v_rcp_f32_e32 v211, v211
	v_rcp_f32_e32 v212, v212
	v_rcp_f32_e32 v213, v213
	v_mul_f32_e32 v202, v202, v210
	v_mul_f32_e32 v203, v203, v211
	v_mul_f32_e32 v204, v204, v212
	v_mul_f32_e32 v205, v205, v213
	v_mul_f32_e32 v202, v202, v206
	v_mul_f32_e32 v203, v203, v207
	v_mul_f32_e32 v204, v204, v208
	v_mul_f32_e32 v205, v205, v209
	v_cvt_pk_bf16_f32 v236, v202, v203
	v_cvt_pk_bf16_f32 v237, v204, v205
	v_fma_f32 v202, v124, v108, v132
	v_fma_f32 v203, v125, v109, v133
	v_fma_f32 v204, v126, v110, v134
	v_fma_f32 v205, v127, v111, v135
	v_fmac_f32_dpp v202, v108, v116 row_shr:1 row_mask:0xf bank_mask:0xf
	v_fmac_f32_dpp v203, v109, v117 row_shr:1 row_mask:0xf bank_mask:0xf
	v_fmac_f32_dpp v204, v110, v118 row_shr:1 row_mask:0xf bank_mask:0xf
	v_fmac_f32_dpp v205, v111, v119 row_shr:1 row_mask:0xf bank_mask:0xf
	v_fmac_f32_dpp v202, v140, v218 row_ror:1 row_mask:0xf bank_mask:0xf
	v_fmac_f32_dpp v203, v141, v219 row_ror:1 row_mask:0xf bank_mask:0xf
	v_fmac_f32_dpp v204, v142, v220 row_ror:1 row_mask:0xf bank_mask:0xf
	v_fmac_f32_dpp v205, v143, v221 row_ror:1 row_mask:0xf bank_mask:0xf
	v_fmac_f32_dpp v202, v108, v128 row_shl:1 row_mask:0xf bank_mask:0xf
	v_fmac_f32_dpp v203, v109, v129 row_shl:1 row_mask:0xf bank_mask:0xf
	v_fmac_f32_dpp v204, v110, v130 row_shl:1 row_mask:0xf bank_mask:0xf
	v_fmac_f32_dpp v205, v111, v131 row_shl:1 row_mask:0xf bank_mask:0xf
	v_fmac_f32_dpp v202, v92, v222 row_ror:15 row_mask:0xf bank_mask:0xf
	v_fmac_f32_dpp v203, v93, v223 row_ror:15 row_mask:0xf bank_mask:0xf
	v_fmac_f32_dpp v204, v94, v224 row_ror:15 row_mask:0xf bank_mask:0xf
	v_fmac_f32_dpp v205, v95, v225 row_ror:15 row_mask:0xf bank_mask:0xf
	v_fma_f32 v206, v164, v100, v182
	v_fma_f32 v207, v165, v101, v183
	v_fma_f32 v208, v166, v102, v184
	v_fma_f32 v209, v167, v103, v185
	v_fmac_f32_dpp v206, v100, v160 row_shr:1 row_mask:0xf bank_mask:0xf
	v_fmac_f32_dpp v207, v101, v161 row_shr:1 row_mask:0xf bank_mask:0xf
	v_fmac_f32_dpp v208, v102, v162 row_shr:1 row_mask:0xf bank_mask:0xf
	v_fmac_f32_dpp v209, v103, v163 row_shr:1 row_mask:0xf bank_mask:0xf
	v_fmac_f32_dpp v206, v120, v226 row_ror:1 row_mask:0xf bank_mask:0xf
	v_fmac_f32_dpp v207, v121, v227 row_ror:1 row_mask:0xf bank_mask:0xf
	v_fmac_f32_dpp v208, v122, v228 row_ror:1 row_mask:0xf bank_mask:0xf
	v_fmac_f32_dpp v209, v123, v229 row_ror:1 row_mask:0xf bank_mask:0xf
	v_fmac_f32_dpp v206, v100, v178 row_shl:1 row_mask:0xf bank_mask:0xf
	v_fmac_f32_dpp v207, v101, v179 row_shl:1 row_mask:0xf bank_mask:0xf
	v_fmac_f32_dpp v208, v102, v180 row_shl:1 row_mask:0xf bank_mask:0xf
	v_fmac_f32_dpp v209, v103, v181 row_shl:1 row_mask:0xf bank_mask:0xf
	v_fmac_f32_dpp v206, v84, v232 row_ror:15 row_mask:0xf bank_mask:0xf
	v_fmac_f32_dpp v207, v85, v233 row_ror:15 row_mask:0xf bank_mask:0xf
	v_fmac_f32_dpp v208, v86, v234 row_ror:15 row_mask:0xf bank_mask:0xf
	v_fmac_f32_dpp v209, v87, v235 row_ror:15 row_mask:0xf bank_mask:0xf
	v_mul_f32_e32 v210, 0xbfb8aa3b, v202
	v_mul_f32_e32 v211, 0xbfb8aa3b, v203
	v_mul_f32_e32 v212, 0xbfb8aa3b, v204
	v_mul_f32_e32 v213, 0xbfb8aa3b, v205
	v_exp_f32_e32 v210, v210
	v_exp_f32_e32 v211, v211
	v_exp_f32_e32 v212, v212
	v_exp_f32_e32 v213, v213
	v_add_f32_e32 v210, 1.0, v210
	v_add_f32_e32 v211, 1.0, v211
	v_add_f32_e32 v212, 1.0, v212
	v_add_f32_e32 v213, 1.0, v213
	v_rcp_f32_e32 v210, v210
	v_rcp_f32_e32 v211, v211
	v_rcp_f32_e32 v212, v212
	v_rcp_f32_e32 v213, v213
	v_mul_f32_e32 v202, v202, v210
	v_mul_f32_e32 v203, v203, v211
	v_mul_f32_e32 v204, v204, v212
	v_mul_f32_e32 v205, v205, v213
	v_mul_f32_e32 v202, v202, v206
	v_mul_f32_e32 v203, v203, v207
	v_mul_f32_e32 v204, v204, v208
	v_mul_f32_e32 v205, v205, v209
	v_cvt_pk_bf16_f32 v238, v202, v203
	v_cvt_pk_bf16_f32 v239, v204, v205
	v_fma_f32 v202, v124, v92, v132
	v_fma_f32 v203, v125, v93, v133
	v_fma_f32 v204, v126, v94, v134
	v_fma_f32 v205, v127, v95, v135
	v_fmac_f32_dpp v202, v92, v116 row_shr:1 row_mask:0xf bank_mask:0xf
	v_fmac_f32_dpp v203, v93, v117 row_shr:1 row_mask:0xf bank_mask:0xf
	v_fmac_f32_dpp v204, v94, v118 row_shr:1 row_mask:0xf bank_mask:0xf
	v_fmac_f32_dpp v205, v95, v119 row_shr:1 row_mask:0xf bank_mask:0xf
	v_fmac_f32_dpp v202, v108, v218 row_ror:1 row_mask:0xf bank_mask:0xf
	v_fmac_f32_dpp v203, v109, v219 row_ror:1 row_mask:0xf bank_mask:0xf
	v_fmac_f32_dpp v204, v110, v220 row_ror:1 row_mask:0xf bank_mask:0xf
	v_fmac_f32_dpp v205, v111, v221 row_ror:1 row_mask:0xf bank_mask:0xf
	v_fmac_f32_dpp v202, v92, v128 row_shl:1 row_mask:0xf bank_mask:0xf
	v_fmac_f32_dpp v203, v93, v129 row_shl:1 row_mask:0xf bank_mask:0xf
	v_fmac_f32_dpp v204, v94, v130 row_shl:1 row_mask:0xf bank_mask:0xf
	v_fmac_f32_dpp v205, v95, v131 row_shl:1 row_mask:0xf bank_mask:0xf
	v_fmac_f32_dpp v202, v76, v222 row_ror:15 row_mask:0xf bank_mask:0xf
	v_fmac_f32_dpp v203, v77, v223 row_ror:15 row_mask:0xf bank_mask:0xf
	v_fmac_f32_dpp v204, v78, v224 row_ror:15 row_mask:0xf bank_mask:0xf
	v_fmac_f32_dpp v205, v79, v225 row_ror:15 row_mask:0xf bank_mask:0xf
	v_fma_f32 v206, v164, v84, v182
	v_fma_f32 v207, v165, v85, v183
	v_fma_f32 v208, v166, v86, v184
	v_fma_f32 v209, v167, v87, v185
	v_fmac_f32_dpp v206, v84, v160 row_shr:1 row_mask:0xf bank_mask:0xf
	v_fmac_f32_dpp v207, v85, v161 row_shr:1 row_mask:0xf bank_mask:0xf
	v_fmac_f32_dpp v208, v86, v162 row_shr:1 row_mask:0xf bank_mask:0xf
	v_fmac_f32_dpp v209, v87, v163 row_shr:1 row_mask:0xf bank_mask:0xf
	v_fmac_f32_dpp v206, v100, v226 row_ror:1 row_mask:0xf bank_mask:0xf
	v_fmac_f32_dpp v207, v101, v227 row_ror:1 row_mask:0xf bank_mask:0xf
	v_fmac_f32_dpp v208, v102, v228 row_ror:1 row_mask:0xf bank_mask:0xf
	v_fmac_f32_dpp v209, v103, v229 row_ror:1 row_mask:0xf bank_mask:0xf
	v_fmac_f32_dpp v206, v84, v178 row_shl:1 row_mask:0xf bank_mask:0xf
	v_fmac_f32_dpp v207, v85, v179 row_shl:1 row_mask:0xf bank_mask:0xf
	v_fmac_f32_dpp v208, v86, v180 row_shl:1 row_mask:0xf bank_mask:0xf
	v_fmac_f32_dpp v209, v87, v181 row_shl:1 row_mask:0xf bank_mask:0xf
	v_fmac_f32_dpp v206, v68, v232 row_ror:15 row_mask:0xf bank_mask:0xf
	v_fmac_f32_dpp v207, v69, v233 row_ror:15 row_mask:0xf bank_mask:0xf
	v_fmac_f32_dpp v208, v70, v234 row_ror:15 row_mask:0xf bank_mask:0xf
	v_fmac_f32_dpp v209, v71, v235 row_ror:15 row_mask:0xf bank_mask:0xf
	v_mul_f32_e32 v210, 0xbfb8aa3b, v202
	v_mul_f32_e32 v211, 0xbfb8aa3b, v203
	v_mul_f32_e32 v212, 0xbfb8aa3b, v204
	v_mul_f32_e32 v213, 0xbfb8aa3b, v205
	v_exp_f32_e32 v210, v210
	v_exp_f32_e32 v211, v211
	v_exp_f32_e32 v212, v212
	v_exp_f32_e32 v213, v213
	v_add_f32_e32 v210, 1.0, v210
	v_add_f32_e32 v211, 1.0, v211
	v_add_f32_e32 v212, 1.0, v212
	v_add_f32_e32 v213, 1.0, v213
	v_rcp_f32_e32 v210, v210
	v_rcp_f32_e32 v211, v211
	v_rcp_f32_e32 v212, v212
	v_rcp_f32_e32 v213, v213
	v_mul_f32_e32 v202, v202, v210
	v_mul_f32_e32 v203, v203, v211
	v_mul_f32_e32 v204, v204, v212
	v_mul_f32_e32 v205, v205, v213
	v_mul_f32_e32 v202, v202, v206
	v_mul_f32_e32 v203, v203, v207
	v_mul_f32_e32 v204, v204, v208
	v_mul_f32_e32 v205, v205, v209
	v_cvt_pk_bf16_f32 v240, v202, v203
	v_cvt_pk_bf16_f32 v241, v204, v205
	v_fma_f32 v202, v124, v76, v132
	v_fma_f32 v203, v125, v77, v133
	v_fma_f32 v204, v126, v78, v134
	v_fma_f32 v205, v127, v79, v135
	v_fmac_f32_dpp v202, v76, v116 row_shr:1 row_mask:0xf bank_mask:0xf
	v_fmac_f32_dpp v203, v77, v117 row_shr:1 row_mask:0xf bank_mask:0xf
	v_fmac_f32_dpp v204, v78, v118 row_shr:1 row_mask:0xf bank_mask:0xf
	v_fmac_f32_dpp v205, v79, v119 row_shr:1 row_mask:0xf bank_mask:0xf
	v_fmac_f32_dpp v202, v92, v218 row_ror:1 row_mask:0xf bank_mask:0xf
	v_fmac_f32_dpp v203, v93, v219 row_ror:1 row_mask:0xf bank_mask:0xf
	v_fmac_f32_dpp v204, v94, v220 row_ror:1 row_mask:0xf bank_mask:0xf
	v_fmac_f32_dpp v205, v95, v221 row_ror:1 row_mask:0xf bank_mask:0xf
	v_fmac_f32_dpp v202, v76, v128 row_shl:1 row_mask:0xf bank_mask:0xf
	v_fmac_f32_dpp v203, v77, v129 row_shl:1 row_mask:0xf bank_mask:0xf
	v_fmac_f32_dpp v204, v78, v130 row_shl:1 row_mask:0xf bank_mask:0xf
	v_fmac_f32_dpp v205, v79, v131 row_shl:1 row_mask:0xf bank_mask:0xf
	v_fmac_f32_e32 v202, v186, v222
	v_fmac_f32_e32 v203, v187, v223
	v_fmac_f32_e32 v204, v188, v224
	v_fmac_f32_e32 v205, v189, v225
	v_fma_f32 v206, v164, v68, v182
	v_fma_f32 v207, v165, v69, v183
	v_fma_f32 v208, v166, v70, v184
	v_fma_f32 v209, v167, v71, v185
	v_fmac_f32_dpp v206, v68, v160 row_shr:1 row_mask:0xf bank_mask:0xf
	v_fmac_f32_dpp v207, v69, v161 row_shr:1 row_mask:0xf bank_mask:0xf
	v_fmac_f32_dpp v208, v70, v162 row_shr:1 row_mask:0xf bank_mask:0xf
	v_fmac_f32_dpp v209, v71, v163 row_shr:1 row_mask:0xf bank_mask:0xf
	v_fmac_f32_dpp v206, v84, v226 row_ror:1 row_mask:0xf bank_mask:0xf
	v_fmac_f32_dpp v207, v85, v227 row_ror:1 row_mask:0xf bank_mask:0xf
	v_fmac_f32_dpp v208, v86, v228 row_ror:1 row_mask:0xf bank_mask:0xf
	v_fmac_f32_dpp v209, v87, v229 row_ror:1 row_mask:0xf bank_mask:0xf
	v_fmac_f32_dpp v206, v68, v178 row_shl:1 row_mask:0xf bank_mask:0xf
	v_fmac_f32_dpp v207, v69, v179 row_shl:1 row_mask:0xf bank_mask:0xf
	v_fmac_f32_dpp v208, v70, v180 row_shl:1 row_mask:0xf bank_mask:0xf
	v_fmac_f32_dpp v209, v71, v181 row_shl:1 row_mask:0xf bank_mask:0xf
	v_fmac_f32_e32 v206, v190, v232
	v_fmac_f32_e32 v207, v191, v233
	v_fmac_f32_e32 v208, v192, v234
	v_fmac_f32_e32 v209, v193, v235
	v_mul_f32_e32 v210, 0xbfb8aa3b, v202
	v_mul_f32_e32 v211, 0xbfb8aa3b, v203
	v_mul_f32_e32 v212, 0xbfb8aa3b, v204
	v_mul_f32_e32 v213, 0xbfb8aa3b, v205
	v_exp_f32_e32 v210, v210
	v_exp_f32_e32 v211, v211
	v_exp_f32_e32 v212, v212
	v_exp_f32_e32 v213, v213
	v_add_f32_e32 v210, 1.0, v210
	v_add_f32_e32 v211, 1.0, v211
	v_add_f32_e32 v212, 1.0, v212
	v_add_f32_e32 v213, 1.0, v213
	v_rcp_f32_e32 v210, v210
	v_rcp_f32_e32 v211, v211
	v_rcp_f32_e32 v212, v212
	v_rcp_f32_e32 v213, v213
	v_mul_f32_e32 v202, v202, v210
	v_mul_f32_e32 v203, v203, v211
	v_mul_f32_e32 v204, v204, v212
	v_mul_f32_e32 v205, v205, v213
	v_mul_f32_e32 v202, v202, v206
	v_mul_f32_e32 v203, v203, v207
	v_mul_f32_e32 v204, v204, v208
	v_mul_f32_e32 v205, v205, v209
	v_cvt_pk_bf16_f32 v242, v202, v203
	v_cvt_pk_bf16_f32 v243, v204, v205
	v_fma_f32 v202, v124, v60, v132
	v_fma_f32 v203, v125, v61, v133
	v_fma_f32 v204, v126, v62, v134
	v_fma_f32 v205, v127, v63, v135
	v_fmac_f32_dpp v202, v60, v116 row_shr:1 row_mask:0xf bank_mask:0xf
	v_fmac_f32_dpp v203, v61, v117 row_shr:1 row_mask:0xf bank_mask:0xf
	v_fmac_f32_dpp v204, v62, v118 row_shr:1 row_mask:0xf bank_mask:0xf
	v_fmac_f32_dpp v205, v63, v119 row_shr:1 row_mask:0xf bank_mask:0xf
	v_fmac_f32_e32 v202, v194, v218
	v_fmac_f32_e32 v203, v195, v219
	v_fmac_f32_e32 v204, v196, v220
	v_fmac_f32_e32 v205, v197, v221
	v_fmac_f32_dpp v202, v60, v128 row_shl:1 row_mask:0xf bank_mask:0xf
	v_fmac_f32_dpp v203, v61, v129 row_shl:1 row_mask:0xf bank_mask:0xf
	v_fmac_f32_dpp v204, v62, v130 row_shl:1 row_mask:0xf bank_mask:0xf
	v_fmac_f32_dpp v205, v63, v131 row_shl:1 row_mask:0xf bank_mask:0xf
	v_fmac_f32_dpp v202, v44, v222 row_ror:15 row_mask:0xf bank_mask:0xf
	v_fmac_f32_dpp v203, v45, v223 row_ror:15 row_mask:0xf bank_mask:0xf
	v_fmac_f32_dpp v204, v46, v224 row_ror:15 row_mask:0xf bank_mask:0xf
	v_fmac_f32_dpp v205, v47, v225 row_ror:15 row_mask:0xf bank_mask:0xf
	v_fma_f32 v206, v164, v52, v182
	v_fma_f32 v207, v165, v53, v183
	v_fma_f32 v208, v166, v54, v184
	v_fma_f32 v209, v167, v55, v185
	v_fmac_f32_dpp v206, v52, v160 row_shr:1 row_mask:0xf bank_mask:0xf
	v_fmac_f32_dpp v207, v53, v161 row_shr:1 row_mask:0xf bank_mask:0xf
	v_fmac_f32_dpp v208, v54, v162 row_shr:1 row_mask:0xf bank_mask:0xf
	v_fmac_f32_dpp v209, v55, v163 row_shr:1 row_mask:0xf bank_mask:0xf
	v_fmac_f32_e32 v206, v198, v226
	v_fmac_f32_e32 v207, v199, v227
	v_fmac_f32_e32 v208, v200, v228
	v_fmac_f32_e32 v209, v201, v229
	v_fmac_f32_dpp v206, v52, v178 row_shl:1 row_mask:0xf bank_mask:0xf
	v_fmac_f32_dpp v207, v53, v179 row_shl:1 row_mask:0xf bank_mask:0xf
	v_fmac_f32_dpp v208, v54, v180 row_shl:1 row_mask:0xf bank_mask:0xf
	v_fmac_f32_dpp v209, v55, v181 row_shl:1 row_mask:0xf bank_mask:0xf
	v_fmac_f32_dpp v206, v36, v232 row_ror:15 row_mask:0xf bank_mask:0xf
	v_fmac_f32_dpp v207, v37, v233 row_ror:15 row_mask:0xf bank_mask:0xf
	v_fmac_f32_dpp v208, v38, v234 row_ror:15 row_mask:0xf bank_mask:0xf
	v_fmac_f32_dpp v209, v39, v235 row_ror:15 row_mask:0xf bank_mask:0xf
	v_mul_f32_e32 v210, 0xbfb8aa3b, v202
	v_mul_f32_e32 v211, 0xbfb8aa3b, v203
	v_mul_f32_e32 v212, 0xbfb8aa3b, v204
	v_mul_f32_e32 v213, 0xbfb8aa3b, v205
	v_exp_f32_e32 v210, v210
	v_exp_f32_e32 v211, v211
	v_exp_f32_e32 v212, v212
	v_exp_f32_e32 v213, v213
	v_add_f32_e32 v210, 1.0, v210
	v_add_f32_e32 v211, 1.0, v211
	v_add_f32_e32 v212, 1.0, v212
	v_add_f32_e32 v213, 1.0, v213
	v_rcp_f32_e32 v210, v210
	v_rcp_f32_e32 v211, v211
	v_rcp_f32_e32 v212, v212
	v_rcp_f32_e32 v213, v213
	v_mul_f32_e32 v202, v202, v210
	v_mul_f32_e32 v203, v203, v211
	v_mul_f32_e32 v204, v204, v212
	v_mul_f32_e32 v205, v205, v213
	v_mul_f32_e32 v202, v202, v206
	v_mul_f32_e32 v203, v203, v207
	v_mul_f32_e32 v204, v204, v208
	v_mul_f32_e32 v205, v205, v209
	v_cvt_pk_bf16_f32 v244, v202, v203
	v_cvt_pk_bf16_f32 v245, v204, v205
	v_fma_f32 v202, v124, v44, v132
	v_fma_f32 v203, v125, v45, v133
	v_fma_f32 v204, v126, v46, v134
	v_fma_f32 v205, v127, v47, v135
	v_fmac_f32_dpp v202, v44, v116 row_shr:1 row_mask:0xf bank_mask:0xf
	v_fmac_f32_dpp v203, v45, v117 row_shr:1 row_mask:0xf bank_mask:0xf
	v_fmac_f32_dpp v204, v46, v118 row_shr:1 row_mask:0xf bank_mask:0xf
	v_fmac_f32_dpp v205, v47, v119 row_shr:1 row_mask:0xf bank_mask:0xf
	v_fmac_f32_dpp v202, v60, v218 row_ror:1 row_mask:0xf bank_mask:0xf
	v_fmac_f32_dpp v203, v61, v219 row_ror:1 row_mask:0xf bank_mask:0xf
	v_fmac_f32_dpp v204, v62, v220 row_ror:1 row_mask:0xf bank_mask:0xf
	v_fmac_f32_dpp v205, v63, v221 row_ror:1 row_mask:0xf bank_mask:0xf
	v_fmac_f32_dpp v202, v44, v128 row_shl:1 row_mask:0xf bank_mask:0xf
	v_fmac_f32_dpp v203, v45, v129 row_shl:1 row_mask:0xf bank_mask:0xf
	v_fmac_f32_dpp v204, v46, v130 row_shl:1 row_mask:0xf bank_mask:0xf
	v_fmac_f32_dpp v205, v47, v131 row_shl:1 row_mask:0xf bank_mask:0xf
	v_fmac_f32_dpp v202, v28, v222 row_ror:15 row_mask:0xf bank_mask:0xf
	v_fmac_f32_dpp v203, v29, v223 row_ror:15 row_mask:0xf bank_mask:0xf
	v_fmac_f32_dpp v204, v30, v224 row_ror:15 row_mask:0xf bank_mask:0xf
	v_fmac_f32_dpp v205, v31, v225 row_ror:15 row_mask:0xf bank_mask:0xf
	v_fma_f32 v206, v164, v36, v182
	v_fma_f32 v207, v165, v37, v183
	v_fma_f32 v208, v166, v38, v184
	v_fma_f32 v209, v167, v39, v185
	v_fmac_f32_dpp v206, v36, v160 row_shr:1 row_mask:0xf bank_mask:0xf
	v_fmac_f32_dpp v207, v37, v161 row_shr:1 row_mask:0xf bank_mask:0xf
	v_fmac_f32_dpp v208, v38, v162 row_shr:1 row_mask:0xf bank_mask:0xf
	v_fmac_f32_dpp v209, v39, v163 row_shr:1 row_mask:0xf bank_mask:0xf
	v_fmac_f32_dpp v206, v52, v226 row_ror:1 row_mask:0xf bank_mask:0xf
	v_fmac_f32_dpp v207, v53, v227 row_ror:1 row_mask:0xf bank_mask:0xf
	v_fmac_f32_dpp v208, v54, v228 row_ror:1 row_mask:0xf bank_mask:0xf
	v_fmac_f32_dpp v209, v55, v229 row_ror:1 row_mask:0xf bank_mask:0xf
	v_fmac_f32_dpp v206, v36, v178 row_shl:1 row_mask:0xf bank_mask:0xf
	v_fmac_f32_dpp v207, v37, v179 row_shl:1 row_mask:0xf bank_mask:0xf
	v_fmac_f32_dpp v208, v38, v180 row_shl:1 row_mask:0xf bank_mask:0xf
	v_fmac_f32_dpp v209, v39, v181 row_shl:1 row_mask:0xf bank_mask:0xf
	v_fmac_f32_dpp v206, v20, v232 row_ror:15 row_mask:0xf bank_mask:0xf
	v_fmac_f32_dpp v207, v21, v233 row_ror:15 row_mask:0xf bank_mask:0xf
	v_fmac_f32_dpp v208, v22, v234 row_ror:15 row_mask:0xf bank_mask:0xf
	v_fmac_f32_dpp v209, v23, v235 row_ror:15 row_mask:0xf bank_mask:0xf
	v_mul_f32_e32 v210, 0xbfb8aa3b, v202
	v_mul_f32_e32 v211, 0xbfb8aa3b, v203
	v_mul_f32_e32 v212, 0xbfb8aa3b, v204
	v_mul_f32_e32 v213, 0xbfb8aa3b, v205
	v_exp_f32_e32 v210, v210
	v_exp_f32_e32 v211, v211
	v_exp_f32_e32 v212, v212
	v_exp_f32_e32 v213, v213
	v_add_f32_e32 v210, 1.0, v210
	v_add_f32_e32 v211, 1.0, v211
	v_add_f32_e32 v212, 1.0, v212
	v_add_f32_e32 v213, 1.0, v213
	v_rcp_f32_e32 v210, v210
	v_rcp_f32_e32 v211, v211
	v_rcp_f32_e32 v212, v212
	v_rcp_f32_e32 v213, v213
	v_mul_f32_e32 v202, v202, v210
	v_mul_f32_e32 v203, v203, v211
	v_mul_f32_e32 v204, v204, v212
	v_mul_f32_e32 v205, v205, v213
	v_mul_f32_e32 v202, v202, v206
	v_mul_f32_e32 v203, v203, v207
	v_mul_f32_e32 v204, v204, v208
	v_mul_f32_e32 v205, v205, v209
	v_cvt_pk_bf16_f32 v246, v202, v203
	v_cvt_pk_bf16_f32 v247, v204, v205
	v_fma_f32 v202, v124, v28, v132
	v_fma_f32 v203, v125, v29, v133
	v_fma_f32 v204, v126, v30, v134
	v_fma_f32 v205, v127, v31, v135
	v_fmac_f32_dpp v202, v28, v116 row_shr:1 row_mask:0xf bank_mask:0xf
	v_fmac_f32_dpp v203, v29, v117 row_shr:1 row_mask:0xf bank_mask:0xf
	v_fmac_f32_dpp v204, v30, v118 row_shr:1 row_mask:0xf bank_mask:0xf
	v_fmac_f32_dpp v205, v31, v119 row_shr:1 row_mask:0xf bank_mask:0xf
	v_fmac_f32_dpp v202, v44, v218 row_ror:1 row_mask:0xf bank_mask:0xf
	v_fmac_f32_dpp v203, v45, v219 row_ror:1 row_mask:0xf bank_mask:0xf
	v_fmac_f32_dpp v204, v46, v220 row_ror:1 row_mask:0xf bank_mask:0xf
	v_fmac_f32_dpp v205, v47, v221 row_ror:1 row_mask:0xf bank_mask:0xf
	v_fmac_f32_dpp v202, v28, v128 row_shl:1 row_mask:0xf bank_mask:0xf
	v_fmac_f32_dpp v203, v29, v129 row_shl:1 row_mask:0xf bank_mask:0xf
	v_fmac_f32_dpp v204, v30, v130 row_shl:1 row_mask:0xf bank_mask:0xf
	v_fmac_f32_dpp v205, v31, v131 row_shl:1 row_mask:0xf bank_mask:0xf
	v_fmac_f32_dpp v202, v12, v222 row_ror:15 row_mask:0xf bank_mask:0xf
	v_fmac_f32_dpp v203, v13, v223 row_ror:15 row_mask:0xf bank_mask:0xf
	v_fmac_f32_dpp v204, v14, v224 row_ror:15 row_mask:0xf bank_mask:0xf
	v_fmac_f32_dpp v205, v15, v225 row_ror:15 row_mask:0xf bank_mask:0xf
	v_fma_f32 v206, v164, v20, v182
	v_fma_f32 v207, v165, v21, v183
	v_fma_f32 v208, v166, v22, v184
	v_fma_f32 v209, v167, v23, v185
	v_fmac_f32_dpp v206, v20, v160 row_shr:1 row_mask:0xf bank_mask:0xf
	v_fmac_f32_dpp v207, v21, v161 row_shr:1 row_mask:0xf bank_mask:0xf
	v_fmac_f32_dpp v208, v22, v162 row_shr:1 row_mask:0xf bank_mask:0xf
	v_fmac_f32_dpp v209, v23, v163 row_shr:1 row_mask:0xf bank_mask:0xf
	v_fmac_f32_dpp v206, v36, v226 row_ror:1 row_mask:0xf bank_mask:0xf
	v_fmac_f32_dpp v207, v37, v227 row_ror:1 row_mask:0xf bank_mask:0xf
	v_fmac_f32_dpp v208, v38, v228 row_ror:1 row_mask:0xf bank_mask:0xf
	v_fmac_f32_dpp v209, v39, v229 row_ror:1 row_mask:0xf bank_mask:0xf
	v_fmac_f32_dpp v206, v20, v178 row_shl:1 row_mask:0xf bank_mask:0xf
	v_fmac_f32_dpp v207, v21, v179 row_shl:1 row_mask:0xf bank_mask:0xf
	v_fmac_f32_dpp v208, v22, v180 row_shl:1 row_mask:0xf bank_mask:0xf
	v_fmac_f32_dpp v209, v23, v181 row_shl:1 row_mask:0xf bank_mask:0xf
	v_fmac_f32_dpp v206, v4, v232 row_ror:15 row_mask:0xf bank_mask:0xf
	v_fmac_f32_dpp v207, v5, v233 row_ror:15 row_mask:0xf bank_mask:0xf
	v_fmac_f32_dpp v208, v6, v234 row_ror:15 row_mask:0xf bank_mask:0xf
	v_fmac_f32_dpp v209, v7, v235 row_ror:15 row_mask:0xf bank_mask:0xf
	v_mul_f32_e32 v210, 0xbfb8aa3b, v202
	v_mul_f32_e32 v211, 0xbfb8aa3b, v203
	v_mul_f32_e32 v212, 0xbfb8aa3b, v204
	v_mul_f32_e32 v213, 0xbfb8aa3b, v205
	v_exp_f32_e32 v210, v210
	v_exp_f32_e32 v211, v211
	v_exp_f32_e32 v212, v212
	v_exp_f32_e32 v213, v213
	v_add_f32_e32 v210, 1.0, v210
	v_add_f32_e32 v211, 1.0, v211
	v_add_f32_e32 v212, 1.0, v212
	v_add_f32_e32 v213, 1.0, v213
	v_rcp_f32_e32 v210, v210
	v_rcp_f32_e32 v211, v211
	v_rcp_f32_e32 v212, v212
	v_rcp_f32_e32 v213, v213
	v_mul_f32_e32 v202, v202, v210
	v_mul_f32_e32 v203, v203, v211
	v_mul_f32_e32 v204, v204, v212
	v_mul_f32_e32 v205, v205, v213
	v_mul_f32_e32 v202, v202, v206
	v_mul_f32_e32 v203, v203, v207
	v_mul_f32_e32 v204, v204, v208
	v_mul_f32_e32 v205, v205, v209
	v_cvt_pk_bf16_f32 v248, v202, v203
	v_cvt_pk_bf16_f32 v249, v204, v205
	v_fma_f32 v202, v124, v12, v132
	v_fma_f32 v203, v125, v13, v133
	v_fma_f32 v204, v126, v14, v134
	v_fma_f32 v205, v127, v15, v135
	v_fmac_f32_dpp v202, v12, v116 row_shr:1 row_mask:0xf bank_mask:0xf
	v_fmac_f32_dpp v203, v13, v117 row_shr:1 row_mask:0xf bank_mask:0xf
	v_fmac_f32_dpp v204, v14, v118 row_shr:1 row_mask:0xf bank_mask:0xf
	v_fmac_f32_dpp v205, v15, v119 row_shr:1 row_mask:0xf bank_mask:0xf
	v_fmac_f32_dpp v202, v28, v218 row_ror:1 row_mask:0xf bank_mask:0xf
	v_fmac_f32_dpp v203, v29, v219 row_ror:1 row_mask:0xf bank_mask:0xf
	v_fmac_f32_dpp v204, v30, v220 row_ror:1 row_mask:0xf bank_mask:0xf
	v_fmac_f32_dpp v205, v31, v221 row_ror:1 row_mask:0xf bank_mask:0xf
	v_fmac_f32_dpp v202, v12, v128 row_shl:1 row_mask:0xf bank_mask:0xf
	v_fmac_f32_dpp v203, v13, v129 row_shl:1 row_mask:0xf bank_mask:0xf
	v_fmac_f32_dpp v204, v14, v130 row_shl:1 row_mask:0xf bank_mask:0xf
	v_fmac_f32_dpp v205, v15, v131 row_shl:1 row_mask:0xf bank_mask:0xf
	v_fmac_f32_e32 v202, v194, v222
	v_fmac_f32_e32 v203, v195, v223
	v_fmac_f32_e32 v204, v196, v224
	v_fmac_f32_e32 v205, v197, v225
	v_fma_f32 v206, v164, v4, v182
	v_fma_f32 v207, v165, v5, v183
	v_fma_f32 v208, v166, v6, v184
	v_fma_f32 v209, v167, v7, v185
	v_fmac_f32_dpp v206, v4, v160 row_shr:1 row_mask:0xf bank_mask:0xf
	v_fmac_f32_dpp v207, v5, v161 row_shr:1 row_mask:0xf bank_mask:0xf
	v_fmac_f32_dpp v208, v6, v162 row_shr:1 row_mask:0xf bank_mask:0xf
	v_fmac_f32_dpp v209, v7, v163 row_shr:1 row_mask:0xf bank_mask:0xf
	v_fmac_f32_dpp v206, v20, v226 row_ror:1 row_mask:0xf bank_mask:0xf
	v_fmac_f32_dpp v207, v21, v227 row_ror:1 row_mask:0xf bank_mask:0xf
	v_fmac_f32_dpp v208, v22, v228 row_ror:1 row_mask:0xf bank_mask:0xf
	v_fmac_f32_dpp v209, v23, v229 row_ror:1 row_mask:0xf bank_mask:0xf
	v_fmac_f32_dpp v206, v4, v178 row_shl:1 row_mask:0xf bank_mask:0xf
	v_fmac_f32_dpp v207, v5, v179 row_shl:1 row_mask:0xf bank_mask:0xf
	v_fmac_f32_dpp v208, v6, v180 row_shl:1 row_mask:0xf bank_mask:0xf
	v_fmac_f32_dpp v209, v7, v181 row_shl:1 row_mask:0xf bank_mask:0xf
	v_fmac_f32_e32 v206, v198, v232
	v_fmac_f32_e32 v207, v199, v233
	v_fmac_f32_e32 v208, v200, v234
	v_fmac_f32_e32 v209, v201, v235
	v_mul_f32_e32 v210, 0xbfb8aa3b, v202
	v_mul_f32_e32 v211, 0xbfb8aa3b, v203
	v_mul_f32_e32 v212, 0xbfb8aa3b, v204
	v_mul_f32_e32 v213, 0xbfb8aa3b, v205
	v_exp_f32_e32 v210, v210
	v_exp_f32_e32 v211, v211
	v_exp_f32_e32 v212, v212
	v_exp_f32_e32 v213, v213
	v_add_f32_e32 v210, 1.0, v210
	v_add_f32_e32 v211, 1.0, v211
	v_add_f32_e32 v212, 1.0, v212
	v_add_f32_e32 v213, 1.0, v213
	v_rcp_f32_e32 v210, v210
	v_rcp_f32_e32 v211, v211
	v_rcp_f32_e32 v212, v212
	v_rcp_f32_e32 v213, v213
	v_mul_f32_e32 v202, v202, v210
	v_mul_f32_e32 v203, v203, v211
	v_mul_f32_e32 v204, v204, v212
	v_mul_f32_e32 v205, v205, v213
	v_mul_f32_e32 v202, v202, v206
	v_mul_f32_e32 v203, v203, v207
	v_mul_f32_e32 v204, v204, v208
	v_mul_f32_e32 v205, v205, v209
	v_cvt_pk_bf16_f32 v250, v202, v203
	v_cvt_pk_bf16_f32 v251, v204, v205
	global_load_dwordx4 v[116:119], v177, s[2:3] offset:16
	v_add_u32_e32 v213, 0x5800, v177
	global_load_dwordx4 v[124:127], v213, s[2:3] offset:16
	v_add_u32_e32 v212, 0xb000, v177
	global_load_dwordx4 v[128:131], v212, s[2:3] offset:16
	global_load_dwordx4 v[132:135], v177, s[28:29] offset:16
	v_add_u32_e32 v212, 0x2c00, v177
	global_load_dwordx4 v[160:163], v212, s[2:3] offset:16
	v_add_u32_e32 v213, 0x8400, v177
	global_load_dwordx4 v[164:167], v213, s[2:3] offset:16
	v_add_u32_e32 v212, 0xdc00, v177
	global_load_dwordx4 v[178:181], v212, s[2:3] offset:16
	v_add_u32_e32 v213, 0x2c00, v177
	global_load_dwordx4 v[182:185], v213, s[28:29] offset:16
	v_mov_b32_e32 v140, v236
	v_mov_b32_e32 v141, v237
	v_mov_b32_e32 v108, v238
	v_mov_b32_e32 v109, v239
	v_mov_b32_e32 v92, v240
	v_mov_b32_e32 v93, v241
	v_mov_b32_e32 v76, v242
	v_mov_b32_e32 v77, v243
	v_mov_b32_e32 v60, v244
	v_mov_b32_e32 v61, v245
	v_mov_b32_e32 v44, v246
	v_mov_b32_e32 v45, v247
	v_mov_b32_e32 v28, v248
	v_mov_b32_e32 v29, v249
	v_mov_b32_e32 v12, v250
	v_mov_b32_e32 v13, v251
	ds_read_b128 v[186:189], v231 offset:16
	ds_read_b128 v[190:193], v231 offset:528
	ds_read_b128 v[194:197], v231 offset:2064
	ds_read_b128 v[198:201], v231 offset:2576
	s_waitcnt vmcnt(0)
	v_cndmask_b32_e64 v218, 0, v116, s[78:79]
	v_cndmask_b32_e64 v222, 0, v128, s[80:81]
	v_cndmask_b32_e64 v219, 0, v117, s[78:79]
	v_cndmask_b32_e64 v223, 0, v129, s[80:81]
	v_cndmask_b32_e64 v220, 0, v118, s[78:79]
	v_cndmask_b32_e64 v224, 0, v130, s[80:81]
	v_cndmask_b32_e64 v221, 0, v119, s[78:79]
	v_cndmask_b32_e64 v225, 0, v131, s[80:81]
	v_cndmask_b32_e64 v226, 0, v160, s[78:79]
	v_cndmask_b32_e64 v232, 0, v178, s[80:81]
	v_cndmask_b32_e64 v227, 0, v161, s[78:79]
	v_cndmask_b32_e64 v233, 0, v179, s[80:81]
	v_cndmask_b32_e64 v228, 0, v162, s[78:79]
	v_cndmask_b32_e64 v234, 0, v180, s[80:81]
	v_cndmask_b32_e64 v229, 0, v163, s[78:79]
	v_cndmask_b32_e64 v235, 0, v181, s[80:81]
	s_waitcnt lgkmcnt(0)
	s_nop 1
	v_fma_f32 v202, v124, v136, v132
	v_fma_f32 v203, v125, v137, v133
	v_fma_f32 v204, v126, v138, v134
	v_fma_f32 v205, v127, v139, v135
	v_fmac_f32_dpp v202, v136, v116 row_shr:1 row_mask:0xf bank_mask:0xf
	v_fmac_f32_dpp v203, v137, v117 row_shr:1 row_mask:0xf bank_mask:0xf
	v_fmac_f32_dpp v204, v138, v118 row_shr:1 row_mask:0xf bank_mask:0xf
	v_fmac_f32_dpp v205, v139, v119 row_shr:1 row_mask:0xf bank_mask:0xf
	v_fmac_f32_e32 v202, v186, v218
	v_fmac_f32_e32 v203, v187, v219
	v_fmac_f32_e32 v204, v188, v220
	v_fmac_f32_e32 v205, v189, v221
	v_fmac_f32_dpp v202, v136, v128 row_shl:1 row_mask:0xf bank_mask:0xf
	v_fmac_f32_dpp v203, v137, v129 row_shl:1 row_mask:0xf bank_mask:0xf
	v_fmac_f32_dpp v204, v138, v130 row_shl:1 row_mask:0xf bank_mask:0xf
	v_fmac_f32_dpp v205, v139, v131 row_shl:1 row_mask:0xf bank_mask:0xf
	v_fmac_f32_dpp v202, v104, v222 row_ror:15 row_mask:0xf bank_mask:0xf
	v_fmac_f32_dpp v203, v105, v223 row_ror:15 row_mask:0xf bank_mask:0xf
	v_fmac_f32_dpp v204, v106, v224 row_ror:15 row_mask:0xf bank_mask:0xf
	v_fmac_f32_dpp v205, v107, v225 row_ror:15 row_mask:0xf bank_mask:0xf
	v_fma_f32 v206, v164, v112, v182
	v_fma_f32 v207, v165, v113, v183
	v_fma_f32 v208, v166, v114, v184
	v_fma_f32 v209, v167, v115, v185
	v_fmac_f32_dpp v206, v112, v160 row_shr:1 row_mask:0xf bank_mask:0xf
	v_fmac_f32_dpp v207, v113, v161 row_shr:1 row_mask:0xf bank_mask:0xf
	v_fmac_f32_dpp v208, v114, v162 row_shr:1 row_mask:0xf bank_mask:0xf
	v_fmac_f32_dpp v209, v115, v163 row_shr:1 row_mask:0xf bank_mask:0xf
	v_fmac_f32_e32 v206, v190, v226
	v_fmac_f32_e32 v207, v191, v227
	v_fmac_f32_e32 v208, v192, v228
	v_fmac_f32_e32 v209, v193, v229
	v_fmac_f32_dpp v206, v112, v178 row_shl:1 row_mask:0xf bank_mask:0xf
	v_fmac_f32_dpp v207, v113, v179 row_shl:1 row_mask:0xf bank_mask:0xf
	v_fmac_f32_dpp v208, v114, v180 row_shl:1 row_mask:0xf bank_mask:0xf
	v_fmac_f32_dpp v209, v115, v181 row_shl:1 row_mask:0xf bank_mask:0xf
	v_fmac_f32_dpp v206, v96, v232 row_ror:15 row_mask:0xf bank_mask:0xf
	v_fmac_f32_dpp v207, v97, v233 row_ror:15 row_mask:0xf bank_mask:0xf
	v_fmac_f32_dpp v208, v98, v234 row_ror:15 row_mask:0xf bank_mask:0xf
	v_fmac_f32_dpp v209, v99, v235 row_ror:15 row_mask:0xf bank_mask:0xf
	v_mul_f32_e32 v210, 0xbfb8aa3b, v202
	v_mul_f32_e32 v211, 0xbfb8aa3b, v203
	v_mul_f32_e32 v212, 0xbfb8aa3b, v204
	v_mul_f32_e32 v213, 0xbfb8aa3b, v205
	v_exp_f32_e32 v210, v210
	v_exp_f32_e32 v211, v211
	v_exp_f32_e32 v212, v212
	v_exp_f32_e32 v213, v213
	v_add_f32_e32 v210, 1.0, v210
	v_add_f32_e32 v211, 1.0, v211
	v_add_f32_e32 v212, 1.0, v212
	v_add_f32_e32 v213, 1.0, v213
	v_rcp_f32_e32 v210, v210
	v_rcp_f32_e32 v211, v211
	v_rcp_f32_e32 v212, v212
	v_rcp_f32_e32 v213, v213
	v_mul_f32_e32 v202, v202, v210
	v_mul_f32_e32 v203, v203, v211
	v_mul_f32_e32 v204, v204, v212
	v_mul_f32_e32 v205, v205, v213
	v_mul_f32_e32 v202, v202, v206
	v_mul_f32_e32 v203, v203, v207
	v_mul_f32_e32 v204, v204, v208
	v_mul_f32_e32 v205, v205, v209
	v_cvt_pk_bf16_f32 v142, v202, v203
	v_cvt_pk_bf16_f32 v143, v204, v205
	v_fma_f32 v202, v124, v104, v132
	v_fma_f32 v203, v125, v105, v133
	v_fma_f32 v204, v126, v106, v134
	v_fma_f32 v205, v127, v107, v135
	v_fmac_f32_dpp v202, v104, v116 row_shr:1 row_mask:0xf bank_mask:0xf
	v_fmac_f32_dpp v203, v105, v117 row_shr:1 row_mask:0xf bank_mask:0xf
	v_fmac_f32_dpp v204, v106, v118 row_shr:1 row_mask:0xf bank_mask:0xf
	v_fmac_f32_dpp v205, v107, v119 row_shr:1 row_mask:0xf bank_mask:0xf
	v_fmac_f32_dpp v202, v136, v218 row_ror:1 row_mask:0xf bank_mask:0xf
	v_fmac_f32_dpp v203, v137, v219 row_ror:1 row_mask:0xf bank_mask:0xf
	v_fmac_f32_dpp v204, v138, v220 row_ror:1 row_mask:0xf bank_mask:0xf
	v_fmac_f32_dpp v205, v139, v221 row_ror:1 row_mask:0xf bank_mask:0xf
	v_fmac_f32_dpp v202, v104, v128 row_shl:1 row_mask:0xf bank_mask:0xf
	v_fmac_f32_dpp v203, v105, v129 row_shl:1 row_mask:0xf bank_mask:0xf
	v_fmac_f32_dpp v204, v106, v130 row_shl:1 row_mask:0xf bank_mask:0xf
	v_fmac_f32_dpp v205, v107, v131 row_shl:1 row_mask:0xf bank_mask:0xf
	v_fmac_f32_dpp v202, v88, v222 row_ror:15 row_mask:0xf bank_mask:0xf
	v_fmac_f32_dpp v203, v89, v223 row_ror:15 row_mask:0xf bank_mask:0xf
	v_fmac_f32_dpp v204, v90, v224 row_ror:15 row_mask:0xf bank_mask:0xf
	v_fmac_f32_dpp v205, v91, v225 row_ror:15 row_mask:0xf bank_mask:0xf
	v_fma_f32 v206, v164, v96, v182
	v_fma_f32 v207, v165, v97, v183
	v_fma_f32 v208, v166, v98, v184
	v_fma_f32 v209, v167, v99, v185
	v_fmac_f32_dpp v206, v96, v160 row_shr:1 row_mask:0xf bank_mask:0xf
	v_fmac_f32_dpp v207, v97, v161 row_shr:1 row_mask:0xf bank_mask:0xf
	v_fmac_f32_dpp v208, v98, v162 row_shr:1 row_mask:0xf bank_mask:0xf
	v_fmac_f32_dpp v209, v99, v163 row_shr:1 row_mask:0xf bank_mask:0xf
	v_fmac_f32_dpp v206, v112, v226 row_ror:1 row_mask:0xf bank_mask:0xf
	v_fmac_f32_dpp v207, v113, v227 row_ror:1 row_mask:0xf bank_mask:0xf
	v_fmac_f32_dpp v208, v114, v228 row_ror:1 row_mask:0xf bank_mask:0xf
	v_fmac_f32_dpp v209, v115, v229 row_ror:1 row_mask:0xf bank_mask:0xf
	v_fmac_f32_dpp v206, v96, v178 row_shl:1 row_mask:0xf bank_mask:0xf
	v_fmac_f32_dpp v207, v97, v179 row_shl:1 row_mask:0xf bank_mask:0xf
	v_fmac_f32_dpp v208, v98, v180 row_shl:1 row_mask:0xf bank_mask:0xf
	v_fmac_f32_dpp v209, v99, v181 row_shl:1 row_mask:0xf bank_mask:0xf
	v_fmac_f32_dpp v206, v80, v232 row_ror:15 row_mask:0xf bank_mask:0xf
	v_fmac_f32_dpp v207, v81, v233 row_ror:15 row_mask:0xf bank_mask:0xf
	v_fmac_f32_dpp v208, v82, v234 row_ror:15 row_mask:0xf bank_mask:0xf
	v_fmac_f32_dpp v209, v83, v235 row_ror:15 row_mask:0xf bank_mask:0xf
	v_mul_f32_e32 v210, 0xbfb8aa3b, v202
	v_mul_f32_e32 v211, 0xbfb8aa3b, v203
	v_mul_f32_e32 v212, 0xbfb8aa3b, v204
	v_mul_f32_e32 v213, 0xbfb8aa3b, v205
	v_exp_f32_e32 v210, v210
	v_exp_f32_e32 v211, v211
	v_exp_f32_e32 v212, v212
	v_exp_f32_e32 v213, v213
	v_add_f32_e32 v210, 1.0, v210
	v_add_f32_e32 v211, 1.0, v211
	v_add_f32_e32 v212, 1.0, v212
	v_add_f32_e32 v213, 1.0, v213
	v_rcp_f32_e32 v210, v210
	v_rcp_f32_e32 v211, v211
	v_rcp_f32_e32 v212, v212
	v_rcp_f32_e32 v213, v213
	v_mul_f32_e32 v202, v202, v210
	v_mul_f32_e32 v203, v203, v211
	v_mul_f32_e32 v204, v204, v212
	v_mul_f32_e32 v205, v205, v213
	v_mul_f32_e32 v202, v202, v206
	v_mul_f32_e32 v203, v203, v207
	v_mul_f32_e32 v204, v204, v208
	v_mul_f32_e32 v205, v205, v209
	v_cvt_pk_bf16_f32 v110, v202, v203
	v_cvt_pk_bf16_f32 v111, v204, v205
	v_fma_f32 v202, v124, v88, v132
	v_fma_f32 v203, v125, v89, v133
	v_fma_f32 v204, v126, v90, v134
	v_fma_f32 v205, v127, v91, v135
	v_fmac_f32_dpp v202, v88, v116 row_shr:1 row_mask:0xf bank_mask:0xf
	v_fmac_f32_dpp v203, v89, v117 row_shr:1 row_mask:0xf bank_mask:0xf
	v_fmac_f32_dpp v204, v90, v118 row_shr:1 row_mask:0xf bank_mask:0xf
	v_fmac_f32_dpp v205, v91, v119 row_shr:1 row_mask:0xf bank_mask:0xf
	v_fmac_f32_dpp v202, v104, v218 row_ror:1 row_mask:0xf bank_mask:0xf
	v_fmac_f32_dpp v203, v105, v219 row_ror:1 row_mask:0xf bank_mask:0xf
	v_fmac_f32_dpp v204, v106, v220 row_ror:1 row_mask:0xf bank_mask:0xf
	v_fmac_f32_dpp v205, v107, v221 row_ror:1 row_mask:0xf bank_mask:0xf
	v_fmac_f32_dpp v202, v88, v128 row_shl:1 row_mask:0xf bank_mask:0xf
	v_fmac_f32_dpp v203, v89, v129 row_shl:1 row_mask:0xf bank_mask:0xf
	v_fmac_f32_dpp v204, v90, v130 row_shl:1 row_mask:0xf bank_mask:0xf
	v_fmac_f32_dpp v205, v91, v131 row_shl:1 row_mask:0xf bank_mask:0xf
	v_fmac_f32_dpp v202, v72, v222 row_ror:15 row_mask:0xf bank_mask:0xf
	v_fmac_f32_dpp v203, v73, v223 row_ror:15 row_mask:0xf bank_mask:0xf
	v_fmac_f32_dpp v204, v74, v224 row_ror:15 row_mask:0xf bank_mask:0xf
	v_fmac_f32_dpp v205, v75, v225 row_ror:15 row_mask:0xf bank_mask:0xf
	v_fma_f32 v206, v164, v80, v182
	v_fma_f32 v207, v165, v81, v183
	v_fma_f32 v208, v166, v82, v184
	v_fma_f32 v209, v167, v83, v185
	v_fmac_f32_dpp v206, v80, v160 row_shr:1 row_mask:0xf bank_mask:0xf
	v_fmac_f32_dpp v207, v81, v161 row_shr:1 row_mask:0xf bank_mask:0xf
	v_fmac_f32_dpp v208, v82, v162 row_shr:1 row_mask:0xf bank_mask:0xf
	v_fmac_f32_dpp v209, v83, v163 row_shr:1 row_mask:0xf bank_mask:0xf
	v_fmac_f32_dpp v206, v96, v226 row_ror:1 row_mask:0xf bank_mask:0xf
	v_fmac_f32_dpp v207, v97, v227 row_ror:1 row_mask:0xf bank_mask:0xf
	v_fmac_f32_dpp v208, v98, v228 row_ror:1 row_mask:0xf bank_mask:0xf
	v_fmac_f32_dpp v209, v99, v229 row_ror:1 row_mask:0xf bank_mask:0xf
	v_fmac_f32_dpp v206, v80, v178 row_shl:1 row_mask:0xf bank_mask:0xf
	v_fmac_f32_dpp v207, v81, v179 row_shl:1 row_mask:0xf bank_mask:0xf
	v_fmac_f32_dpp v208, v82, v180 row_shl:1 row_mask:0xf bank_mask:0xf
	v_fmac_f32_dpp v209, v83, v181 row_shl:1 row_mask:0xf bank_mask:0xf
	v_fmac_f32_dpp v206, v64, v232 row_ror:15 row_mask:0xf bank_mask:0xf
	v_fmac_f32_dpp v207, v65, v233 row_ror:15 row_mask:0xf bank_mask:0xf
	v_fmac_f32_dpp v208, v66, v234 row_ror:15 row_mask:0xf bank_mask:0xf
	v_fmac_f32_dpp v209, v67, v235 row_ror:15 row_mask:0xf bank_mask:0xf
	v_mul_f32_e32 v210, 0xbfb8aa3b, v202
	v_mul_f32_e32 v211, 0xbfb8aa3b, v203
	v_mul_f32_e32 v212, 0xbfb8aa3b, v204
	v_mul_f32_e32 v213, 0xbfb8aa3b, v205
	v_exp_f32_e32 v210, v210
	v_exp_f32_e32 v211, v211
	v_exp_f32_e32 v212, v212
	v_exp_f32_e32 v213, v213
	v_add_f32_e32 v210, 1.0, v210
	v_add_f32_e32 v211, 1.0, v211
	v_add_f32_e32 v212, 1.0, v212
	v_add_f32_e32 v213, 1.0, v213
	v_rcp_f32_e32 v210, v210
	v_rcp_f32_e32 v211, v211
	v_rcp_f32_e32 v212, v212
	v_rcp_f32_e32 v213, v213
	v_mul_f32_e32 v202, v202, v210
	v_mul_f32_e32 v203, v203, v211
	v_mul_f32_e32 v204, v204, v212
	v_mul_f32_e32 v205, v205, v213
	v_mul_f32_e32 v202, v202, v206
	v_mul_f32_e32 v203, v203, v207
	v_mul_f32_e32 v204, v204, v208
	v_mul_f32_e32 v205, v205, v209
	v_cvt_pk_bf16_f32 v94, v202, v203
	v_cvt_pk_bf16_f32 v95, v204, v205
	v_fma_f32 v202, v124, v72, v132
	v_fma_f32 v203, v125, v73, v133
	v_fma_f32 v204, v126, v74, v134
	v_fma_f32 v205, v127, v75, v135
	v_fmac_f32_dpp v202, v72, v116 row_shr:1 row_mask:0xf bank_mask:0xf
	v_fmac_f32_dpp v203, v73, v117 row_shr:1 row_mask:0xf bank_mask:0xf
	v_fmac_f32_dpp v204, v74, v118 row_shr:1 row_mask:0xf bank_mask:0xf
	v_fmac_f32_dpp v205, v75, v119 row_shr:1 row_mask:0xf bank_mask:0xf
	v_fmac_f32_dpp v202, v88, v218 row_ror:1 row_mask:0xf bank_mask:0xf
	v_fmac_f32_dpp v203, v89, v219 row_ror:1 row_mask:0xf bank_mask:0xf
	v_fmac_f32_dpp v204, v90, v220 row_ror:1 row_mask:0xf bank_mask:0xf
	v_fmac_f32_dpp v205, v91, v221 row_ror:1 row_mask:0xf bank_mask:0xf
	v_fmac_f32_dpp v202, v72, v128 row_shl:1 row_mask:0xf bank_mask:0xf
	v_fmac_f32_dpp v203, v73, v129 row_shl:1 row_mask:0xf bank_mask:0xf
	v_fmac_f32_dpp v204, v74, v130 row_shl:1 row_mask:0xf bank_mask:0xf
	v_fmac_f32_dpp v205, v75, v131 row_shl:1 row_mask:0xf bank_mask:0xf
	v_fmac_f32_e32 v202, v186, v222
	v_fmac_f32_e32 v203, v187, v223
	v_fmac_f32_e32 v204, v188, v224
	v_fmac_f32_e32 v205, v189, v225
	v_fma_f32 v206, v164, v64, v182
	v_fma_f32 v207, v165, v65, v183
	v_fma_f32 v208, v166, v66, v184
	v_fma_f32 v209, v167, v67, v185
	v_fmac_f32_dpp v206, v64, v160 row_shr:1 row_mask:0xf bank_mask:0xf
	v_fmac_f32_dpp v207, v65, v161 row_shr:1 row_mask:0xf bank_mask:0xf
	v_fmac_f32_dpp v208, v66, v162 row_shr:1 row_mask:0xf bank_mask:0xf
	v_fmac_f32_dpp v209, v67, v163 row_shr:1 row_mask:0xf bank_mask:0xf
	v_fmac_f32_dpp v206, v80, v226 row_ror:1 row_mask:0xf bank_mask:0xf
	v_fmac_f32_dpp v207, v81, v227 row_ror:1 row_mask:0xf bank_mask:0xf
	v_fmac_f32_dpp v208, v82, v228 row_ror:1 row_mask:0xf bank_mask:0xf
	v_fmac_f32_dpp v209, v83, v229 row_ror:1 row_mask:0xf bank_mask:0xf
	v_fmac_f32_dpp v206, v64, v178 row_shl:1 row_mask:0xf bank_mask:0xf
	v_fmac_f32_dpp v207, v65, v179 row_shl:1 row_mask:0xf bank_mask:0xf
	v_fmac_f32_dpp v208, v66, v180 row_shl:1 row_mask:0xf bank_mask:0xf
	v_fmac_f32_dpp v209, v67, v181 row_shl:1 row_mask:0xf bank_mask:0xf
	v_fmac_f32_e32 v206, v190, v232
	v_fmac_f32_e32 v207, v191, v233
	v_fmac_f32_e32 v208, v192, v234
	v_fmac_f32_e32 v209, v193, v235
	v_mul_f32_e32 v210, 0xbfb8aa3b, v202
	v_mul_f32_e32 v211, 0xbfb8aa3b, v203
	v_mul_f32_e32 v212, 0xbfb8aa3b, v204
	v_mul_f32_e32 v213, 0xbfb8aa3b, v205
	v_exp_f32_e32 v210, v210
	v_exp_f32_e32 v211, v211
	v_exp_f32_e32 v212, v212
	v_exp_f32_e32 v213, v213
	v_add_f32_e32 v210, 1.0, v210
	v_add_f32_e32 v211, 1.0, v211
	v_add_f32_e32 v212, 1.0, v212
	v_add_f32_e32 v213, 1.0, v213
	v_rcp_f32_e32 v210, v210
	v_rcp_f32_e32 v211, v211
	v_rcp_f32_e32 v212, v212
	v_rcp_f32_e32 v213, v213
	v_mul_f32_e32 v202, v202, v210
	v_mul_f32_e32 v203, v203, v211
	v_mul_f32_e32 v204, v204, v212
	v_mul_f32_e32 v205, v205, v213
	v_mul_f32_e32 v202, v202, v206
	v_mul_f32_e32 v203, v203, v207
	v_mul_f32_e32 v204, v204, v208
	v_mul_f32_e32 v205, v205, v209
	v_cvt_pk_bf16_f32 v78, v202, v203
	v_cvt_pk_bf16_f32 v79, v204, v205
	v_fma_f32 v202, v124, v56, v132
	v_fma_f32 v203, v125, v57, v133
	v_fma_f32 v204, v126, v58, v134
	v_fma_f32 v205, v127, v59, v135
	v_fmac_f32_dpp v202, v56, v116 row_shr:1 row_mask:0xf bank_mask:0xf
	v_fmac_f32_dpp v203, v57, v117 row_shr:1 row_mask:0xf bank_mask:0xf
	v_fmac_f32_dpp v204, v58, v118 row_shr:1 row_mask:0xf bank_mask:0xf
	v_fmac_f32_dpp v205, v59, v119 row_shr:1 row_mask:0xf bank_mask:0xf
	v_fmac_f32_e32 v202, v194, v218
	v_fmac_f32_e32 v203, v195, v219
	v_fmac_f32_e32 v204, v196, v220
	v_fmac_f32_e32 v205, v197, v221
	v_fmac_f32_dpp v202, v56, v128 row_shl:1 row_mask:0xf bank_mask:0xf
	v_fmac_f32_dpp v203, v57, v129 row_shl:1 row_mask:0xf bank_mask:0xf
	v_fmac_f32_dpp v204, v58, v130 row_shl:1 row_mask:0xf bank_mask:0xf
	v_fmac_f32_dpp v205, v59, v131 row_shl:1 row_mask:0xf bank_mask:0xf
	v_fmac_f32_dpp v202, v40, v222 row_ror:15 row_mask:0xf bank_mask:0xf
	v_fmac_f32_dpp v203, v41, v223 row_ror:15 row_mask:0xf bank_mask:0xf
	v_fmac_f32_dpp v204, v42, v224 row_ror:15 row_mask:0xf bank_mask:0xf
	v_fmac_f32_dpp v205, v43, v225 row_ror:15 row_mask:0xf bank_mask:0xf
	v_fma_f32 v206, v164, v48, v182
	v_fma_f32 v207, v165, v49, v183
	v_fma_f32 v208, v166, v50, v184
	v_fma_f32 v209, v167, v51, v185
	v_fmac_f32_dpp v206, v48, v160 row_shr:1 row_mask:0xf bank_mask:0xf
	v_fmac_f32_dpp v207, v49, v161 row_shr:1 row_mask:0xf bank_mask:0xf
	v_fmac_f32_dpp v208, v50, v162 row_shr:1 row_mask:0xf bank_mask:0xf
	v_fmac_f32_dpp v209, v51, v163 row_shr:1 row_mask:0xf bank_mask:0xf
	v_fmac_f32_e32 v206, v198, v226
	v_fmac_f32_e32 v207, v199, v227
	v_fmac_f32_e32 v208, v200, v228
	v_fmac_f32_e32 v209, v201, v229
	v_fmac_f32_dpp v206, v48, v178 row_shl:1 row_mask:0xf bank_mask:0xf
	v_fmac_f32_dpp v207, v49, v179 row_shl:1 row_mask:0xf bank_mask:0xf
	v_fmac_f32_dpp v208, v50, v180 row_shl:1 row_mask:0xf bank_mask:0xf
	v_fmac_f32_dpp v209, v51, v181 row_shl:1 row_mask:0xf bank_mask:0xf
	v_fmac_f32_dpp v206, v32, v232 row_ror:15 row_mask:0xf bank_mask:0xf
	v_fmac_f32_dpp v207, v33, v233 row_ror:15 row_mask:0xf bank_mask:0xf
	v_fmac_f32_dpp v208, v34, v234 row_ror:15 row_mask:0xf bank_mask:0xf
	v_fmac_f32_dpp v209, v35, v235 row_ror:15 row_mask:0xf bank_mask:0xf
	v_mul_f32_e32 v210, 0xbfb8aa3b, v202
	v_mul_f32_e32 v211, 0xbfb8aa3b, v203
	v_mul_f32_e32 v212, 0xbfb8aa3b, v204
	v_mul_f32_e32 v213, 0xbfb8aa3b, v205
	v_exp_f32_e32 v210, v210
	v_exp_f32_e32 v211, v211
	v_exp_f32_e32 v212, v212
	v_exp_f32_e32 v213, v213
	v_add_f32_e32 v210, 1.0, v210
	v_add_f32_e32 v211, 1.0, v211
	v_add_f32_e32 v212, 1.0, v212
	v_add_f32_e32 v213, 1.0, v213
	v_rcp_f32_e32 v210, v210
	v_rcp_f32_e32 v211, v211
	v_rcp_f32_e32 v212, v212
	v_rcp_f32_e32 v213, v213
	v_mul_f32_e32 v202, v202, v210
	v_mul_f32_e32 v203, v203, v211
	v_mul_f32_e32 v204, v204, v212
	v_mul_f32_e32 v205, v205, v213
	v_mul_f32_e32 v202, v202, v206
	v_mul_f32_e32 v203, v203, v207
	v_mul_f32_e32 v204, v204, v208
	v_mul_f32_e32 v205, v205, v209
	v_cvt_pk_bf16_f32 v62, v202, v203
	v_cvt_pk_bf16_f32 v63, v204, v205
	v_fma_f32 v202, v124, v40, v132
	v_fma_f32 v203, v125, v41, v133
	v_fma_f32 v204, v126, v42, v134
	v_fma_f32 v205, v127, v43, v135
	v_fmac_f32_dpp v202, v40, v116 row_shr:1 row_mask:0xf bank_mask:0xf
	v_fmac_f32_dpp v203, v41, v117 row_shr:1 row_mask:0xf bank_mask:0xf
	v_fmac_f32_dpp v204, v42, v118 row_shr:1 row_mask:0xf bank_mask:0xf
	v_fmac_f32_dpp v205, v43, v119 row_shr:1 row_mask:0xf bank_mask:0xf
	v_fmac_f32_dpp v202, v56, v218 row_ror:1 row_mask:0xf bank_mask:0xf
	v_fmac_f32_dpp v203, v57, v219 row_ror:1 row_mask:0xf bank_mask:0xf
	v_fmac_f32_dpp v204, v58, v220 row_ror:1 row_mask:0xf bank_mask:0xf
	v_fmac_f32_dpp v205, v59, v221 row_ror:1 row_mask:0xf bank_mask:0xf
	v_fmac_f32_dpp v202, v40, v128 row_shl:1 row_mask:0xf bank_mask:0xf
	v_fmac_f32_dpp v203, v41, v129 row_shl:1 row_mask:0xf bank_mask:0xf
	v_fmac_f32_dpp v204, v42, v130 row_shl:1 row_mask:0xf bank_mask:0xf
	v_fmac_f32_dpp v205, v43, v131 row_shl:1 row_mask:0xf bank_mask:0xf
	v_fmac_f32_dpp v202, v24, v222 row_ror:15 row_mask:0xf bank_mask:0xf
	v_fmac_f32_dpp v203, v25, v223 row_ror:15 row_mask:0xf bank_mask:0xf
	v_fmac_f32_dpp v204, v26, v224 row_ror:15 row_mask:0xf bank_mask:0xf
	v_fmac_f32_dpp v205, v27, v225 row_ror:15 row_mask:0xf bank_mask:0xf
	v_fma_f32 v206, v164, v32, v182
	v_fma_f32 v207, v165, v33, v183
	v_fma_f32 v208, v166, v34, v184
	v_fma_f32 v209, v167, v35, v185
	v_fmac_f32_dpp v206, v32, v160 row_shr:1 row_mask:0xf bank_mask:0xf
	v_fmac_f32_dpp v207, v33, v161 row_shr:1 row_mask:0xf bank_mask:0xf
	v_fmac_f32_dpp v208, v34, v162 row_shr:1 row_mask:0xf bank_mask:0xf
	v_fmac_f32_dpp v209, v35, v163 row_shr:1 row_mask:0xf bank_mask:0xf
	v_fmac_f32_dpp v206, v48, v226 row_ror:1 row_mask:0xf bank_mask:0xf
	v_fmac_f32_dpp v207, v49, v227 row_ror:1 row_mask:0xf bank_mask:0xf
	v_fmac_f32_dpp v208, v50, v228 row_ror:1 row_mask:0xf bank_mask:0xf
	v_fmac_f32_dpp v209, v51, v229 row_ror:1 row_mask:0xf bank_mask:0xf
	v_fmac_f32_dpp v206, v32, v178 row_shl:1 row_mask:0xf bank_mask:0xf
	v_fmac_f32_dpp v207, v33, v179 row_shl:1 row_mask:0xf bank_mask:0xf
	v_fmac_f32_dpp v208, v34, v180 row_shl:1 row_mask:0xf bank_mask:0xf
	v_fmac_f32_dpp v209, v35, v181 row_shl:1 row_mask:0xf bank_mask:0xf
	v_fmac_f32_dpp v206, v16, v232 row_ror:15 row_mask:0xf bank_mask:0xf
	v_fmac_f32_dpp v207, v17, v233 row_ror:15 row_mask:0xf bank_mask:0xf
	v_fmac_f32_dpp v208, v18, v234 row_ror:15 row_mask:0xf bank_mask:0xf
	v_fmac_f32_dpp v209, v19, v235 row_ror:15 row_mask:0xf bank_mask:0xf
	v_mul_f32_e32 v210, 0xbfb8aa3b, v202
	v_mul_f32_e32 v211, 0xbfb8aa3b, v203
	v_mul_f32_e32 v212, 0xbfb8aa3b, v204
	v_mul_f32_e32 v213, 0xbfb8aa3b, v205
	v_exp_f32_e32 v210, v210
	v_exp_f32_e32 v211, v211
	v_exp_f32_e32 v212, v212
	v_exp_f32_e32 v213, v213
	v_add_f32_e32 v210, 1.0, v210
	v_add_f32_e32 v211, 1.0, v211
	v_add_f32_e32 v212, 1.0, v212
	v_add_f32_e32 v213, 1.0, v213
	v_rcp_f32_e32 v210, v210
	v_rcp_f32_e32 v211, v211
	v_rcp_f32_e32 v212, v212
	v_rcp_f32_e32 v213, v213
	v_mul_f32_e32 v202, v202, v210
	v_mul_f32_e32 v203, v203, v211
	v_mul_f32_e32 v204, v204, v212
	v_mul_f32_e32 v205, v205, v213
	v_mul_f32_e32 v202, v202, v206
	v_mul_f32_e32 v203, v203, v207
	v_mul_f32_e32 v204, v204, v208
	v_mul_f32_e32 v205, v205, v209
	v_cvt_pk_bf16_f32 v46, v202, v203
	v_cvt_pk_bf16_f32 v47, v204, v205
	v_fma_f32 v202, v124, v24, v132
	v_fma_f32 v203, v125, v25, v133
	v_fma_f32 v204, v126, v26, v134
	v_fma_f32 v205, v127, v27, v135
	v_fmac_f32_dpp v202, v24, v116 row_shr:1 row_mask:0xf bank_mask:0xf
	v_fmac_f32_dpp v203, v25, v117 row_shr:1 row_mask:0xf bank_mask:0xf
	v_fmac_f32_dpp v204, v26, v118 row_shr:1 row_mask:0xf bank_mask:0xf
	v_fmac_f32_dpp v205, v27, v119 row_shr:1 row_mask:0xf bank_mask:0xf
	v_fmac_f32_dpp v202, v40, v218 row_ror:1 row_mask:0xf bank_mask:0xf
	v_fmac_f32_dpp v203, v41, v219 row_ror:1 row_mask:0xf bank_mask:0xf
	v_fmac_f32_dpp v204, v42, v220 row_ror:1 row_mask:0xf bank_mask:0xf
	v_fmac_f32_dpp v205, v43, v221 row_ror:1 row_mask:0xf bank_mask:0xf
	v_fmac_f32_dpp v202, v24, v128 row_shl:1 row_mask:0xf bank_mask:0xf
	v_fmac_f32_dpp v203, v25, v129 row_shl:1 row_mask:0xf bank_mask:0xf
	v_fmac_f32_dpp v204, v26, v130 row_shl:1 row_mask:0xf bank_mask:0xf
	v_fmac_f32_dpp v205, v27, v131 row_shl:1 row_mask:0xf bank_mask:0xf
	v_fmac_f32_dpp v202, v8, v222 row_ror:15 row_mask:0xf bank_mask:0xf
	v_fmac_f32_dpp v203, v9, v223 row_ror:15 row_mask:0xf bank_mask:0xf
	v_fmac_f32_dpp v204, v10, v224 row_ror:15 row_mask:0xf bank_mask:0xf
	v_fmac_f32_dpp v205, v11, v225 row_ror:15 row_mask:0xf bank_mask:0xf
	v_fma_f32 v206, v164, v16, v182
	v_fma_f32 v207, v165, v17, v183
	v_fma_f32 v208, v166, v18, v184
	v_fma_f32 v209, v167, v19, v185
	v_fmac_f32_dpp v206, v16, v160 row_shr:1 row_mask:0xf bank_mask:0xf
	v_fmac_f32_dpp v207, v17, v161 row_shr:1 row_mask:0xf bank_mask:0xf
	v_fmac_f32_dpp v208, v18, v162 row_shr:1 row_mask:0xf bank_mask:0xf
	v_fmac_f32_dpp v209, v19, v163 row_shr:1 row_mask:0xf bank_mask:0xf
	v_fmac_f32_dpp v206, v32, v226 row_ror:1 row_mask:0xf bank_mask:0xf
	v_fmac_f32_dpp v207, v33, v227 row_ror:1 row_mask:0xf bank_mask:0xf
	v_fmac_f32_dpp v208, v34, v228 row_ror:1 row_mask:0xf bank_mask:0xf
	v_fmac_f32_dpp v209, v35, v229 row_ror:1 row_mask:0xf bank_mask:0xf
	v_fmac_f32_dpp v206, v16, v178 row_shl:1 row_mask:0xf bank_mask:0xf
	v_fmac_f32_dpp v207, v17, v179 row_shl:1 row_mask:0xf bank_mask:0xf
	v_fmac_f32_dpp v208, v18, v180 row_shl:1 row_mask:0xf bank_mask:0xf
	v_fmac_f32_dpp v209, v19, v181 row_shl:1 row_mask:0xf bank_mask:0xf
	v_fmac_f32_dpp v206, v0, v232 row_ror:15 row_mask:0xf bank_mask:0xf
	v_fmac_f32_dpp v207, v1, v233 row_ror:15 row_mask:0xf bank_mask:0xf
	v_fmac_f32_dpp v208, v2, v234 row_ror:15 row_mask:0xf bank_mask:0xf
	v_fmac_f32_dpp v209, v3, v235 row_ror:15 row_mask:0xf bank_mask:0xf
	v_mul_f32_e32 v210, 0xbfb8aa3b, v202
	v_mul_f32_e32 v211, 0xbfb8aa3b, v203
	v_mul_f32_e32 v212, 0xbfb8aa3b, v204
	v_mul_f32_e32 v213, 0xbfb8aa3b, v205
	v_exp_f32_e32 v210, v210
	v_exp_f32_e32 v211, v211
	v_exp_f32_e32 v212, v212
	v_exp_f32_e32 v213, v213
	v_add_f32_e32 v210, 1.0, v210
	v_add_f32_e32 v211, 1.0, v211
	v_add_f32_e32 v212, 1.0, v212
	v_add_f32_e32 v213, 1.0, v213
	v_rcp_f32_e32 v210, v210
	v_rcp_f32_e32 v211, v211
	v_rcp_f32_e32 v212, v212
	v_rcp_f32_e32 v213, v213
	v_mul_f32_e32 v202, v202, v210
	v_mul_f32_e32 v203, v203, v211
	v_mul_f32_e32 v204, v204, v212
	v_mul_f32_e32 v205, v205, v213
	v_mul_f32_e32 v202, v202, v206
	v_mul_f32_e32 v203, v203, v207
	v_mul_f32_e32 v204, v204, v208
	v_mul_f32_e32 v205, v205, v209
	v_cvt_pk_bf16_f32 v30, v202, v203
	v_cvt_pk_bf16_f32 v31, v204, v205
	v_fma_f32 v202, v124, v8, v132
	v_fma_f32 v203, v125, v9, v133
	v_fma_f32 v204, v126, v10, v134
	v_fma_f32 v205, v127, v11, v135
	v_fmac_f32_dpp v202, v8, v116 row_shr:1 row_mask:0xf bank_mask:0xf
	v_fmac_f32_dpp v203, v9, v117 row_shr:1 row_mask:0xf bank_mask:0xf
	v_fmac_f32_dpp v204, v10, v118 row_shr:1 row_mask:0xf bank_mask:0xf
	v_fmac_f32_dpp v205, v11, v119 row_shr:1 row_mask:0xf bank_mask:0xf
	v_fmac_f32_dpp v202, v24, v218 row_ror:1 row_mask:0xf bank_mask:0xf
	v_fmac_f32_dpp v203, v25, v219 row_ror:1 row_mask:0xf bank_mask:0xf
	v_fmac_f32_dpp v204, v26, v220 row_ror:1 row_mask:0xf bank_mask:0xf
	v_fmac_f32_dpp v205, v27, v221 row_ror:1 row_mask:0xf bank_mask:0xf
	v_fmac_f32_dpp v202, v8, v128 row_shl:1 row_mask:0xf bank_mask:0xf
	v_fmac_f32_dpp v203, v9, v129 row_shl:1 row_mask:0xf bank_mask:0xf
	v_fmac_f32_dpp v204, v10, v130 row_shl:1 row_mask:0xf bank_mask:0xf
	v_fmac_f32_dpp v205, v11, v131 row_shl:1 row_mask:0xf bank_mask:0xf
	v_fmac_f32_e32 v202, v194, v222
	v_fmac_f32_e32 v203, v195, v223
	v_fmac_f32_e32 v204, v196, v224
	v_fmac_f32_e32 v205, v197, v225
	v_fma_f32 v206, v164, v0, v182
	v_fma_f32 v207, v165, v1, v183
	v_fma_f32 v208, v166, v2, v184
	v_fma_f32 v209, v167, v3, v185
	v_fmac_f32_dpp v206, v0, v160 row_shr:1 row_mask:0xf bank_mask:0xf
	v_fmac_f32_dpp v207, v1, v161 row_shr:1 row_mask:0xf bank_mask:0xf
	v_fmac_f32_dpp v208, v2, v162 row_shr:1 row_mask:0xf bank_mask:0xf
	v_fmac_f32_dpp v209, v3, v163 row_shr:1 row_mask:0xf bank_mask:0xf
	v_fmac_f32_dpp v206, v16, v226 row_ror:1 row_mask:0xf bank_mask:0xf
	v_fmac_f32_dpp v207, v17, v227 row_ror:1 row_mask:0xf bank_mask:0xf
	v_fmac_f32_dpp v208, v18, v228 row_ror:1 row_mask:0xf bank_mask:0xf
	v_fmac_f32_dpp v209, v19, v229 row_ror:1 row_mask:0xf bank_mask:0xf
	v_fmac_f32_dpp v206, v0, v178 row_shl:1 row_mask:0xf bank_mask:0xf
	v_fmac_f32_dpp v207, v1, v179 row_shl:1 row_mask:0xf bank_mask:0xf
	v_fmac_f32_dpp v208, v2, v180 row_shl:1 row_mask:0xf bank_mask:0xf
	v_fmac_f32_dpp v209, v3, v181 row_shl:1 row_mask:0xf bank_mask:0xf
	v_fmac_f32_e32 v206, v198, v232
	v_fmac_f32_e32 v207, v199, v233
	v_fmac_f32_e32 v208, v200, v234
	v_fmac_f32_e32 v209, v201, v235
	v_mul_f32_e32 v210, 0xbfb8aa3b, v202
	v_mul_f32_e32 v211, 0xbfb8aa3b, v203
	v_mul_f32_e32 v212, 0xbfb8aa3b, v204
	v_mul_f32_e32 v213, 0xbfb8aa3b, v205
	v_exp_f32_e32 v210, v210
	v_exp_f32_e32 v211, v211
	v_exp_f32_e32 v212, v212
	v_exp_f32_e32 v213, v213
	v_add_f32_e32 v210, 1.0, v210
	v_add_f32_e32 v211, 1.0, v211
	v_add_f32_e32 v212, 1.0, v212
	v_add_f32_e32 v213, 1.0, v213
	v_rcp_f32_e32 v210, v210
	v_rcp_f32_e32 v211, v211
	v_rcp_f32_e32 v212, v212
	v_rcp_f32_e32 v213, v213
	v_mul_f32_e32 v202, v202, v210
	v_mul_f32_e32 v203, v203, v211
	v_mul_f32_e32 v204, v204, v212
	v_mul_f32_e32 v205, v205, v213
	v_mul_f32_e32 v202, v202, v206
	v_mul_f32_e32 v203, v203, v207
	v_mul_f32_e32 v204, v204, v208
	v_mul_f32_e32 v205, v205, v209
	v_cvt_pk_bf16_f32 v14, v202, v203
	v_cvt_pk_bf16_f32 v15, v204, v205
	global_store_dwordx4 v168, v[140:143], s[76:77]
	v_add_u32_e32 v250, 0x16000, v168
	global_store_dwordx4 v250, v[108:111], s[76:77]
	s_nop 0
	v_add_u32_e32 v250, 0x2c000, v168
	global_store_dwordx4 v250, v[92:95], s[76:77]
	s_nop 0
	v_add_u32_e32 v250, 0x42000, v168
	global_store_dwordx4 v250, v[76:79], s[76:77]
	s_nop 0
	v_add_u32_e32 v250, 0xb0000, v168
	global_store_dwordx4 v250, v[60:63], s[76:77]
	s_nop 0
	v_add_u32_e32 v250, 0xc6000, v168
	global_store_dwordx4 v250, v[44:47], s[76:77]
	s_nop 0
	v_add_u32_e32 v250, 0xdc000, v168
	global_store_dwordx4 v250, v[28:31], s[76:77]
	s_nop 0
	v_add_u32_e32 v250, 0xf2000, v168
	global_store_dwordx4 v250, v[12:15], s[76:77]
	s_nop 0
	s_andn2_b64 vcc, exec, s[6:7]
	s_mov_b64 s[4:5], -1
	s_cbranch_vccnz .LBB0_824
	s_andn2_b64 vcc, exec, s[12:13]
	s_cbranch_vccnz .LBB0_823
	s_barrier
	s_branch .LBB0_823

.LBB0_957:
	s_cmp_gt_i32 s72, 9
	s_cselect_b64 s[4:5], -1, 0
	s_cmp_lt_i32 s73, 10
	s_cselect_b64 s[6:7], -1, 0
	s_or_b64 s[4:5], s[4:5], s[6:7]
	s_and_b64 vcc, exec, s[4:5]
	s_cbranch_vccnz .LBB0_1038
	v_readlane_b32 s2, v255, 2
	v_mov_b32_e32 v14, v230
	v_readlane_b32 s3, v255, 3
	s_and_b64 vcc, exec, s[2:3]
	v_readfirstlane_b32 s5, v14
	s_cbranch_vccnz .LBB0_973
	v_lshlrev_b32_e32 v0, 4, v14
	s_waitcnt lgkmcnt(0)
	v_add_u32_e32 v1, 0x2000, v0
	v_ashrrev_i32_e32 v2, 31, v1
	v_lshrrev_b32_e32 v2, 22, v2
	v_add_u32_e32 v2, v1, v2
	v_ashrrev_i32_e32 v8, 10, v2
	v_mul_i32_i24_e32 v2, 0x400, v8
	v_sub_u32_e32 v1, v1, v2
	v_lshrrev_b32_e32 v2, 4, v1
	v_bitop3_b32 v1, v2, v1, 32 bitop3:0x6c
	v_ashrrev_i32_e32 v2, 31, v1
	v_lshrrev_b32_e32 v2, 26, v2
	v_add_u32_e32 v2, v1, v2
	v_lshlrev_b32_e32 v3, 3, v8
	v_ashrrev_i32_e32 v9, 6, v2
	v_and_b32_e32 v3, -16, v3
	v_add_u32_e32 v3, v9, v3
	v_and_b32_e32 v4, 3, v9
	s_mov_b32 s4, 0x1fffe0
	v_lshrrev_b32_e32 v5, 2, v3
	v_lshlrev_b32_e32 v6, 1, v3
	v_and_b32_e32 v2, 0xc0, v2
	v_and_or_b32 v4, v3, s4, v4
	v_and_b32_e32 v5, 4, v5
	v_and_b32_e32 v6, 24, v6
	v_sub_u32_e32 v1, v1, v2
	v_mov_b32_e32 v2, 1
	v_or3_b32 v4, v4, v5, v6
	v_lshlrev_b32_e32 v5, 5, v8
	v_ashrrev_i16_sdwa v1, v2, sext(v1) dst_sel:DWORD dst_unused:UNUSED_PAD src0_sel:DWORD src1_sel:BYTE_0
	v_and_b32_e32 v5, 32, v5
	v_bfe_i32 v10, v1, 0, 16
	v_add_lshl_u32 v1, v5, v10, 1
	v_lshl_add_u32 v144, v4, 11, v1
	v_lshl_add_u32 v146, v3, 11, v1
	v_bfe_i32 v1, v14, 27, 1
	v_lshrrev_b32_e32 v1, 22, v1
	v_add_u32_e32 v1, v0, v1
	v_and_b32_e32 v1, 0xfffffc00, v1
	v_sub_u32_e32 v0, v0, v1
	v_lshrrev_b32_e32 v1, 4, v0
	v_ashrrev_i32_e32 v3, 31, v14
	v_bitop3_b32 v0, v1, v0, 32 bitop3:0x6c
	v_lshrrev_b32_e32 v3, 26, v3
	v_ashrrev_i32_e32 v1, 31, v0
	v_add_u32_e32 v3, v14, v3
	s_add_u32 s0, s70, 0x4b00000
	v_lshrrev_b32_e32 v1, 26, v1
	v_ashrrev_i32_e32 v12, 6, v3
	s_addc_u32 s20, s71, 0
	s_ashr_i32 s6, s5, 6
	v_add_u32_e32 v1, v0, v1
	v_lshlrev_b32_e32 v3, 3, v12
	v_readlane_b32 s2, v254, 62
	s_ashr_i32 s7, s5, 8
	s_lshl_b32 s21, s6, 10
	v_ashrrev_i32_e32 v11, 6, v1
	v_and_b32_e32 v3, -16, v3
	v_readlane_b32 s3, v254, 63
	v_add_u32_e32 v3, v11, v3
	v_and_b32_e32 v4, 3, v11
	s_movk_i32 s30, 0x59
	s_and_b64 s[10:11], s[2:3], exec
	v_and_or_b32 v4, v3, s4, v4
	s_cselect_b32 s4, s30, 0x58
	v_readlane_b32 s2, v254, 51
	s_mul_i32 s4, s4, s2
	v_readlane_b32 s2, v254, 61
	s_add_i32 s4, s4, s2
	s_mul_hi_i32 s10, s4, 0x2e8ba2e9
	s_lshr_b32 s11, s10, 31
	s_ashr_i32 s10, s10, 5
	s_add_i32 s10, s10, s11
	s_lshl_b32 s11, s10, 3
	s_mulk_i32 s10, 0xb0
	s_sub_i32 s10, s4, s10
	s_bfe_u32 s4, s10, 0x3001c
	s_add_i32 s12, s10, s4
	s_sext_i32_i16 s4, s12
	s_and_b32 s12, s12, 0xfff8
	s_sub_i32 s10, s10, s12
	s_sext_i32_i16 s10, s10
	v_lshrrev_b32_e32 v5, 2, v3
	v_lshlrev_b32_e32 v6, 1, v3
	v_and_b32_e32 v1, 0xc0, v1
	s_lshr_b32 s4, s4, 3
	s_add_i32 s88, s11, s10
	v_and_b32_e32 v5, 4, v5
	v_and_b32_e32 v6, 24, v6
	v_sub_u32_e32 v0, v0, v1
	s_ashr_i32 s89, s88, 31
	s_bfe_i64 s[12:13], s[4:5], 0x100000
	v_or3_b32 v4, v4, v5, v6
	v_lshlrev_b32_e32 v5, 5, v12
	v_ashrrev_i16_sdwa v0, v2, sext(v0) dst_sel:DWORD dst_unused:UNUSED_PAD src0_sel:DWORD src1_sel:BYTE_0
	s_lshl_b64 s[10:11], s[88:89], 19
	s_lshl_b64 s[12:13], s[12:13], 18
	v_and_b32_e32 v5, 32, v5
	v_bfe_i32 v13, v0, 0, 16
	s_add_u32 s92, s33, s12
	v_add_lshl_u32 v0, v5, v13, 1
	s_addc_u32 s93, s82, s13
	s_add_i32 s31, s21, 0
	v_lshl_add_u32 v148, v4, 11, v0
	s_add_i32 m0, s31, 0x10000
	v_lshl_add_u32 v150, v3, 11, v0
	global_load_lds_dwordx4 v148, s[92:93]
	s_add_i32 m0, s31, 0x12000
	s_add_u32 s12, s92, 0x580000
	global_load_lds_dwordx4 v144, s[92:93]
	s_addc_u32 s13, s93, 0
	s_add_i32 m0, s31, 0x14000
	v_mov_b32_e32 v149, 0
	global_load_lds_dwordx4 v148, s[12:13]
	s_add_i32 m0, s31, 0x16000
	s_add_u32 s90, s0, s10
	s_addc_u32 s91, s20, s11
	s_add_i32 s52, s31, 0x2000
	global_load_lds_dwordx4 v144, s[12:13]
	s_mov_b32 m0, s31
	s_add_u32 s10, s90, 0x40000
	global_load_lds_dwordx4 v150, s[90:91]
	s_mov_b32 m0, s52
	s_addc_u32 s11, s91, 0
	s_add_i32 s53, s31, 0x4000
	global_load_lds_dwordx4 v146, s[90:91]
	s_mov_b32 m0, s53
	s_add_i32 s58, s31, 0x6000
	global_load_lds_dwordx4 v150, s[10:11]
	s_mov_b32 m0, s58
	v_mov_b32_e32 v145, v149
	global_load_lds_dwordx4 v146, s[10:11]
	v_mov_b32_e32 v151, v149
	v_mov_b32_e32 v147, v149
	s_cmp_eq_u32 s7, 1
	s_mov_b32 s59, 0
	v_lshl_add_u64 v[6:7], s[92:93], 0, v[148:149]
	v_lshl_add_u64 v[4:5], s[92:93], 0, v[144:145]
	v_lshl_add_u64 v[0:1], s[90:91], 0, v[150:151]
	s_cselect_b64 s[10:11], -1, 0
	s_cmp_lg_u32 s7, 1
	v_lshl_add_u64 v[2:3], s[90:91], 0, v[146:147]
	s_cbranch_scc1 .LBB0_961
	s_barrier
.LBB0_961:
	s_add_u32 s12, s70, 0x108000
	v_lshrrev_b32_e32 v16, 1, v14
	s_addc_u32 s13, s71, 0
	v_and_b32_e32 v16, 24, v16
	s_add_u32 s14, s70, 0x3b00000
	v_and_b32_e32 v15, 15, v14
	v_lshlrev_b32_e32 v17, 1, v16
	v_lshlrev_b32_e32 v14, 2, v14
	s_sext_i32_i16 s66, s4
	s_addc_u32 s15, s71, 0
	v_lshl_or_b32 v170, s7, 6, v15
	v_lshl_or_b32 v15, v15, 6, v17
	s_lshl_b32 s4, s7, 13
	v_and_b32_e32 v14, 32, v14
	v_bitop3_b32 v17, v15, s4, v14 bitop3:0xde
	s_lshl_b32 s4, s6, 5
	s_mov_b64 s[16:17], 0x80
	s_and_b32 s4, s4, 0x60
	s_add_i32 m0, s31, 0x18000
	v_lshl_add_u64 v[6:7], v[6:7], 0, s[16:17]
	s_lshl_b32 s6, s4, 7
	s_waitcnt vmcnt(2)
	s_barrier
	global_load_lds_dwordx4 v[6:7], off
	v_lshl_add_u64 v[4:5], v[4:5], 0, s[16:17]
	s_add_i32 m0, s31, 0x1a000
	s_add_i32 s60, s31, 0x8000
	s_add_i32 s61, s31, 0xa000
	v_bitop3_b32 v171, v15, s6, v14 bitop3:0xde
	global_load_lds_dwordx4 v[4:5], off
	v_lshl_add_u64 v[0:1], v[0:1], 0, s[16:17]
	s_mov_b32 m0, s60
	s_add_u32 s6, s92, 0x580080
	global_load_lds_dwordx4 v[0:1], off
	v_lshl_add_u64 v[0:1], v[2:3], 0, s[16:17]
	s_mov_b32 m0, s61
	s_addc_u32 s7, s93, 0
	global_load_lds_dwordx4 v[0:1], off
	s_add_i32 m0, s31, 0x1c000
	v_lshl_add_u64 v[0:1], s[6:7], 0, v[148:149]
	global_load_lds_dwordx4 v[0:1], off
	v_lshl_add_u64 v[0:1], s[6:7], 0, v[144:145]
	s_add_i32 m0, s31, 0x1e000
	s_cmpk_lt_u32 s5, 0x100
	global_load_lds_dwordx4 v[0:1], off
	v_lshlrev_b32_e32 v0, 14, v12
	v_and_b32_e32 v0, 0xffff8000, v0
	v_lshl_add_u32 v0, v11, 11, v0
	v_and_b32_e32 v1, 1, v12
	v_lshl_or_b32 v0, v1, 6, v0
	v_lshl_add_u32 v152, v13, 1, v0
	v_lshlrev_b32_e32 v0, 14, v8
	v_and_b32_e32 v0, 0xffff8000, v0
	s_waitcnt vmcnt(6)
	v_lshl_add_u32 v0, v9, 11, v0
	v_and_b32_e32 v1, 1, v8
	s_cselect_b64 s[34:35], -1, 0
	v_lshl_or_b32 v0, v1, 6, v0
	s_add_i32 s62, 0, 0x10000
	s_add_i32 s63, 0, 0x14000
	v_or_b32_e32 v172, s4, v16
	v_mov_b32_e32 v153, v149
	v_lshl_add_u32 v154, v10, 1, v0
	v_mov_b32_e32 v155, v149
	v_mov_b64_e32 v[156:157], 0x2c0
	v_mov_b64_e32 v[158:159], 0x2bf
	v_add_u32_e32 v173, s62, v171
	v_add_u32_e32 v174, s63, v171
	v_add_u32_e32 v175, 0, v17
	v_mov_b32_e32 v176, 0x358637bd
	s_mov_b32 s64, 0x800000
	s_movk_i32 s65, 0x2c00
	s_barrier
	s_branch .LBB0_964

.LBB0_966:
	s_ashr_i32 s57, s56, 31
	v_cmp_lt_i64_e64 s[6:7], s[4:5], v[156:157]
	s_lshl_b64 s[4:5], s[56:57], 19
	s_add_u32 s74, s0, s4
	s_addc_u32 s75, s20, s5
	s_and_b64 s[4:5], s[6:7], exec
	s_cselect_b32 s4, s75, s91
	s_cselect_b32 s5, s74, s90
	s_ashr_i32 s55, s54, 31
	s_lshl_b64 s[76:77], s[54:55], 18
	s_add_u32 s86, s33, s76
	s_addc_u32 s87, s82, s77
	s_and_b64 s[76:77], s[6:7], exec
	s_cselect_b32 s55, s87, s93
	s_cselect_b32 s57, s86, s92
	s_add_u32 s90, s90, 0x40080
	s_addc_u32 s91, s91, 0
	s_add_u32 s67, s92, 0x100
	v_mov_b32_e32 v0, 0
	s_addc_u32 s76, s93, 0
	s_mov_b32 s77, -2
	v_mov_b32_e32 v1, v0
	v_mov_b32_e32 v2, v0
	v_mov_b32_e32 v3, v0
	v_mov_b32_e32 v4, v0
	v_mov_b32_e32 v5, v0
	v_mov_b32_e32 v6, v0
	v_mov_b32_e32 v7, v0
	v_mov_b32_e32 v16, v0
	v_mov_b32_e32 v17, v0
	v_mov_b32_e32 v18, v0
	v_mov_b32_e32 v19, v0
	v_mov_b32_e32 v20, v0
	v_mov_b32_e32 v21, v0
	v_mov_b32_e32 v22, v0
	v_mov_b32_e32 v23, v0
	v_mov_b32_e32 v32, v0
	v_mov_b32_e32 v33, v0
	v_mov_b32_e32 v34, v0
	v_mov_b32_e32 v35, v0
	v_mov_b32_e32 v36, v0
	v_mov_b32_e32 v37, v0
	v_mov_b32_e32 v38, v0
	v_mov_b32_e32 v39, v0
	v_mov_b32_e32 v48, v0
	v_mov_b32_e32 v49, v0
	v_mov_b32_e32 v50, v0
	v_mov_b32_e32 v51, v0
	v_mov_b32_e32 v52, v0
	v_mov_b32_e32 v53, v0
	v_mov_b32_e32 v54, v0
	v_mov_b32_e32 v55, v0
	v_mov_b32_e32 v8, v0
	v_mov_b32_e32 v9, v0
	v_mov_b32_e32 v10, v0
	v_mov_b32_e32 v11, v0
	v_mov_b32_e32 v12, v0
	v_mov_b32_e32 v13, v0
	v_mov_b32_e32 v14, v0
	v_mov_b32_e32 v15, v0
	v_mov_b32_e32 v24, v0
	v_mov_b32_e32 v25, v0
	v_mov_b32_e32 v26, v0
	v_mov_b32_e32 v27, v0
	v_mov_b32_e32 v28, v0
	v_mov_b32_e32 v29, v0
	v_mov_b32_e32 v30, v0
	v_mov_b32_e32 v31, v0
	v_mov_b32_e32 v40, v0
	v_mov_b32_e32 v41, v0
	v_mov_b32_e32 v42, v0
	v_mov_b32_e32 v43, v0
	v_mov_b32_e32 v44, v0
	v_mov_b32_e32 v45, v0
	v_mov_b32_e32 v46, v0
	v_mov_b32_e32 v47, v0
	v_mov_b32_e32 v56, v0
	v_mov_b32_e32 v57, v0
	v_mov_b32_e32 v58, v0
	v_mov_b32_e32 v59, v0
	v_mov_b32_e32 v60, v0
	v_mov_b32_e32 v61, v0
	v_mov_b32_e32 v62, v0
	v_mov_b32_e32 v63, v0
	v_mov_b32_e32 v64, v0
	v_mov_b32_e32 v65, v0
	v_mov_b32_e32 v66, v0
	v_mov_b32_e32 v67, v0
	v_mov_b32_e32 v68, v0
	v_mov_b32_e32 v69, v0
	v_mov_b32_e32 v70, v0
	v_mov_b32_e32 v71, v0
	v_mov_b32_e32 v80, v0
	v_mov_b32_e32 v81, v0
	v_mov_b32_e32 v82, v0
	v_mov_b32_e32 v83, v0
	v_mov_b32_e32 v84, v0
	v_mov_b32_e32 v85, v0
	v_mov_b32_e32 v86, v0
	v_mov_b32_e32 v87, v0
	v_mov_b32_e32 v96, v0
	v_mov_b32_e32 v97, v0
	v_mov_b32_e32 v98, v0
	v_mov_b32_e32 v99, v0
	v_mov_b32_e32 v100, v0
	v_mov_b32_e32 v101, v0
	v_mov_b32_e32 v102, v0
	v_mov_b32_e32 v103, v0
	v_mov_b32_e32 v112, v0
	v_mov_b32_e32 v113, v0
	v_mov_b32_e32 v114, v0
	v_mov_b32_e32 v115, v0
	v_mov_b32_e32 v120, v0
	v_mov_b32_e32 v121, v0
	v_mov_b32_e32 v122, v0
	v_mov_b32_e32 v123, v0
	v_mov_b32_e32 v72, v0
	v_mov_b32_e32 v73, v0
	v_mov_b32_e32 v74, v0
	v_mov_b32_e32 v75, v0
	v_mov_b32_e32 v76, v0
	v_mov_b32_e32 v77, v0
	v_mov_b32_e32 v78, v0
	v_mov_b32_e32 v79, v0
	v_mov_b32_e32 v88, v0
	v_mov_b32_e32 v89, v0
	v_mov_b32_e32 v90, v0
	v_mov_b32_e32 v91, v0
	v_mov_b32_e32 v92, v0
	v_mov_b32_e32 v93, v0
	v_mov_b32_e32 v94, v0
	v_mov_b32_e32 v95, v0
	v_mov_b32_e32 v104, v0
	v_mov_b32_e32 v105, v0
	v_mov_b32_e32 v106, v0
	v_mov_b32_e32 v107, v0
	v_mov_b32_e32 v108, v0
	v_mov_b32_e32 v109, v0
	v_mov_b32_e32 v110, v0
	v_mov_b32_e32 v111, v0
	v_mov_b32_e32 v136, v0
	v_mov_b32_e32 v137, v0
	v_mov_b32_e32 v138, v0
	v_mov_b32_e32 v139, v0
	v_mov_b32_e32 v140, v0
	v_mov_b32_e32 v141, v0
	v_mov_b32_e32 v142, v0
	v_mov_b32_e32 v143, v0
.LBB0_967:
	ds_read_b128 v[116:119], v173
	ds_read_b128 v[124:127], v173 offset:1024
	ds_read_b128 v[128:131], v173 offset:2048
	ds_read_b128 v[132:135], v173 offset:3072
	ds_read_b128 v[160:163], v174
	ds_read_b128 v[164:167], v174 offset:1024
	ds_read_b128 v[178:181], v174 offset:2048
	ds_read_b128 v[182:185], v174 offset:3072
	s_add_u32 s78, s90, 0xfffc0080
	s_addc_u32 s79, s91, -1
	s_cmp_eq_u32 s77, 12
	s_cselect_b32 s95, s4, s79
	s_cselect_b32 s94, s5, s78
	s_cselect_b32 s93, s55, s76
	s_cselect_b32 s92, s57, s67
	v_lshl_add_u64 v[168:169], s[90:91], 0, v[152:153]
	s_add_i32 m0, s31, 0xc000
	ds_read_b128 v[186:189], v175
	ds_read_b128 v[190:193], v175 offset:1024
	ds_read_b128 v[194:197], v175 offset:2048
	ds_read_b128 v[198:201], v175 offset:3072
	ds_read_b128 v[202:205], v175 offset:4096
	ds_read_b128 v[206:209], v175 offset:5120
	ds_read_b128 v[210:213], v175 offset:6144
	ds_read_b128 v[214:217], v175 offset:7168
	global_load_lds_dwordx4 v[168:169], off
	v_lshl_add_u64 v[168:169], s[90:91], 0, v[154:155]
	s_add_i32 m0, s31, 0xe000
	s_nop 0
	global_load_lds_dwordx4 v[168:169], off
	s_waitcnt vmcnt(8)
	s_waitcnt lgkmcnt(0)
	s_barrier
	s_setprio 1
	s_waitcnt lgkmcnt(0)
	v_mfma_f32_16x16x32_bf16 v[140:143], v[116:119], v[186:189], v[140:143]
	v_mfma_f32_16x16x32_bf16 v[136:139], v[128:131], v[186:189], v[136:139]
	v_mfma_f32_16x16x32_bf16 v[108:111], v[116:119], v[194:197], v[108:111]
	v_mfma_f32_16x16x32_bf16 v[104:107], v[128:131], v[194:197], v[104:107]
	v_mfma_f32_16x16x32_bf16 v[92:95], v[116:119], v[202:205], v[92:95]
	v_mfma_f32_16x16x32_bf16 v[88:91], v[128:131], v[202:205], v[88:91]
	v_mfma_f32_16x16x32_bf16 v[76:79], v[116:119], v[210:213], v[76:79]
	v_mfma_f32_16x16x32_bf16 v[72:75], v[128:131], v[210:213], v[72:75]
	v_mfma_f32_16x16x32_bf16 v[140:143], v[124:127], v[190:193], v[140:143]
	v_mfma_f32_16x16x32_bf16 v[136:139], v[132:135], v[190:193], v[136:139]
	v_mfma_f32_16x16x32_bf16 v[108:111], v[124:127], v[198:201], v[108:111]
	v_mfma_f32_16x16x32_bf16 v[104:107], v[132:135], v[198:201], v[104:107]
	v_mfma_f32_16x16x32_bf16 v[92:95], v[124:127], v[206:209], v[92:95]
	v_mfma_f32_16x16x32_bf16 v[88:91], v[132:135], v[206:209], v[88:91]
	v_mfma_f32_16x16x32_bf16 v[76:79], v[124:127], v[214:217], v[76:79]
	v_mfma_f32_16x16x32_bf16 v[72:75], v[132:135], v[214:217], v[72:75]
	s_setprio 0
	s_setprio 1
	v_mfma_f32_16x16x32_bf16 v[120:123], v[160:163], v[186:189], v[120:123]
	v_mfma_f32_16x16x32_bf16 v[112:115], v[178:181], v[186:189], v[112:115]
	v_mfma_f32_16x16x32_bf16 v[100:103], v[160:163], v[194:197], v[100:103]
	v_mfma_f32_16x16x32_bf16 v[96:99], v[178:181], v[194:197], v[96:99]
	v_mfma_f32_16x16x32_bf16 v[84:87], v[160:163], v[202:205], v[84:87]
	v_mfma_f32_16x16x32_bf16 v[80:83], v[178:181], v[202:205], v[80:83]
	v_mfma_f32_16x16x32_bf16 v[68:71], v[160:163], v[210:213], v[68:71]
	v_mfma_f32_16x16x32_bf16 v[64:67], v[178:181], v[210:213], v[64:67]
	v_mfma_f32_16x16x32_bf16 v[120:123], v[164:167], v[190:193], v[120:123]
	v_mfma_f32_16x16x32_bf16 v[112:115], v[182:185], v[190:193], v[112:115]
	v_mfma_f32_16x16x32_bf16 v[100:103], v[164:167], v[198:201], v[100:103]
	v_mfma_f32_16x16x32_bf16 v[96:99], v[182:185], v[198:201], v[96:99]
	v_mfma_f32_16x16x32_bf16 v[84:87], v[164:167], v[206:209], v[84:87]
	v_mfma_f32_16x16x32_bf16 v[80:83], v[182:185], v[206:209], v[80:83]
	v_mfma_f32_16x16x32_bf16 v[68:71], v[164:167], v[214:217], v[68:71]
	v_mfma_f32_16x16x32_bf16 v[64:67], v[182:185], v[214:217], v[64:67]
	s_setprio 0
	s_barrier
	s_add_i32 s78, s62, s21
	v_lshl_add_u64 v[168:169], s[92:93], 0, v[148:149]
	s_mov_b32 m0, s78
	ds_read_b128 v[186:189], v175 offset:16384
	ds_read_b128 v[190:193], v175 offset:17408
	ds_read_b128 v[194:197], v175 offset:18432
	ds_read_b128 v[198:201], v175 offset:19456
	ds_read_b128 v[202:205], v175 offset:20480
	ds_read_b128 v[206:209], v175 offset:21504
	ds_read_b128 v[210:213], v175 offset:22528
	ds_read_b128 v[214:217], v175 offset:23552
	global_load_lds_dwordx4 v[168:169], off
	s_add_i32 m0, s78, 0x2000
	s_add_u32 s78, s92, 0x580000
	v_lshl_add_u64 v[218:219], s[92:93], 0, v[144:145]
	s_addc_u32 s79, s93, 0
	s_add_i32 s80, s63, s21
	global_load_lds_dwordx4 v[218:219], off
	v_lshl_add_u64 v[220:221], s[78:79], 0, v[148:149]
	s_mov_b32 m0, s80
	v_lshl_add_u64 v[222:223], s[94:95], 0, v[146:147]
	global_load_lds_dwordx4 v[220:221], off
	v_lshl_add_u64 v[220:221], s[78:79], 0, v[144:145]
	s_add_i32 m0, s80, 0x2000
	s_nop 0
	global_load_lds_dwordx4 v[220:221], off
	v_lshl_add_u64 v[220:221], s[94:95], 0, v[150:151]
	s_mov_b32 m0, s31
	s_nop 0
	global_load_lds_dwordx4 v[220:221], off
	s_mov_b32 m0, s52
	s_nop 0
	global_load_lds_dwordx4 v[222:223], off
	s_waitcnt vmcnt(8)
	s_waitcnt lgkmcnt(0)
	s_barrier
	s_setprio 1
	s_waitcnt lgkmcnt(0)
	v_mfma_f32_16x16x32_bf16 v[60:63], v[116:119], v[186:189], v[60:63]
	v_mfma_f32_16x16x32_bf16 v[56:59], v[128:131], v[186:189], v[56:59]
	v_mfma_f32_16x16x32_bf16 v[44:47], v[116:119], v[194:197], v[44:47]
	v_mfma_f32_16x16x32_bf16 v[40:43], v[128:131], v[194:197], v[40:43]
	v_mfma_f32_16x16x32_bf16 v[28:31], v[116:119], v[202:205], v[28:31]
	v_mfma_f32_16x16x32_bf16 v[24:27], v[128:131], v[202:205], v[24:27]
	v_mfma_f32_16x16x32_bf16 v[12:15], v[116:119], v[210:213], v[12:15]
	v_mfma_f32_16x16x32_bf16 v[8:11], v[128:131], v[210:213], v[8:11]
	v_mfma_f32_16x16x32_bf16 v[60:63], v[124:127], v[190:193], v[60:63]
	v_mfma_f32_16x16x32_bf16 v[56:59], v[132:135], v[190:193], v[56:59]
	v_mfma_f32_16x16x32_bf16 v[44:47], v[124:127], v[198:201], v[44:47]
	v_mfma_f32_16x16x32_bf16 v[40:43], v[132:135], v[198:201], v[40:43]
	v_mfma_f32_16x16x32_bf16 v[28:31], v[124:127], v[206:209], v[28:31]
	v_mfma_f32_16x16x32_bf16 v[24:27], v[132:135], v[206:209], v[24:27]
	v_mfma_f32_16x16x32_bf16 v[12:15], v[124:127], v[214:217], v[12:15]
	v_mfma_f32_16x16x32_bf16 v[8:11], v[132:135], v[214:217], v[8:11]
	s_setprio 0
	s_setprio 1
	v_mfma_f32_16x16x32_bf16 v[52:55], v[160:163], v[186:189], v[52:55]
	v_mfma_f32_16x16x32_bf16 v[48:51], v[178:181], v[186:189], v[48:51]
	v_mfma_f32_16x16x32_bf16 v[36:39], v[160:163], v[194:197], v[36:39]
	v_mfma_f32_16x16x32_bf16 v[32:35], v[178:181], v[194:197], v[32:35]
	v_mfma_f32_16x16x32_bf16 v[20:23], v[160:163], v[202:205], v[20:23]
	v_mfma_f32_16x16x32_bf16 v[16:19], v[178:181], v[202:205], v[16:19]
	v_mfma_f32_16x16x32_bf16 v[4:7], v[160:163], v[210:213], v[4:7]
	v_mfma_f32_16x16x32_bf16 v[0:3], v[178:181], v[210:213], v[0:3]
	v_mfma_f32_16x16x32_bf16 v[52:55], v[164:167], v[190:193], v[52:55]
	v_mfma_f32_16x16x32_bf16 v[48:51], v[182:185], v[190:193], v[48:51]
	v_mfma_f32_16x16x32_bf16 v[36:39], v[164:167], v[198:201], v[36:39]
	v_mfma_f32_16x16x32_bf16 v[32:35], v[182:185], v[198:201], v[32:35]
	v_mfma_f32_16x16x32_bf16 v[20:23], v[164:167], v[206:209], v[20:23]
	v_mfma_f32_16x16x32_bf16 v[16:19], v[182:185], v[206:209], v[16:19]
	v_mfma_f32_16x16x32_bf16 v[4:7], v[164:167], v[214:217], v[4:7]
	v_mfma_f32_16x16x32_bf16 v[0:3], v[182:185], v[214:217], v[0:3]
	s_setprio 0
	s_barrier
	s_add_i32 s80, 0, 0x18000
	s_add_i32 s81, 0, 0x1c000
	v_add_u32_e32 v132, s80, v171
	v_add_u32_e32 v177, s81, v171
	ds_read_b128 v[116:119], v132
	ds_read_b128 v[124:127], v132 offset:1024
	ds_read_b128 v[128:131], v132 offset:2048
	ds_read_b128 v[132:135], v132 offset:3072
	ds_read_b128 v[160:163], v177
	ds_read_b128 v[164:167], v177 offset:1024
	ds_read_b128 v[178:181], v177 offset:2048
	ds_read_b128 v[182:185], v177 offset:3072
	s_add_u32 s78, s94, 0x40000
	s_addc_u32 s79, s95, 0
	s_mov_b32 m0, s53
	v_lshl_add_u64 v[224:225], s[78:79], 0, v[150:151]
	ds_read_b128 v[186:189], v175 offset:32768
	ds_read_b128 v[190:193], v175 offset:33792
	ds_read_b128 v[194:197], v175 offset:34816
	ds_read_b128 v[198:201], v175 offset:35840
	ds_read_b128 v[202:205], v175 offset:36864
	ds_read_b128 v[206:209], v175 offset:37888
	ds_read_b128 v[210:213], v175 offset:38912
	ds_read_b128 v[214:217], v175 offset:39936
	global_load_lds_dwordx4 v[224:225], off
	v_lshl_add_u64 v[224:225], s[78:79], 0, v[146:147]
	s_mov_b32 m0, s58
	s_nop 0
	global_load_lds_dwordx4 v[224:225], off
	s_waitcnt vmcnt(8)
	s_waitcnt lgkmcnt(0)
	s_barrier
	s_setprio 1
	s_waitcnt lgkmcnt(0)
	v_mfma_f32_16x16x32_bf16 v[140:143], v[116:119], v[186:189], v[140:143]
	v_mfma_f32_16x16x32_bf16 v[136:139], v[128:131], v[186:189], v[136:139]
	v_mfma_f32_16x16x32_bf16 v[108:111], v[116:119], v[194:197], v[108:111]
	v_mfma_f32_16x16x32_bf16 v[104:107], v[128:131], v[194:197], v[104:107]
	v_mfma_f32_16x16x32_bf16 v[92:95], v[116:119], v[202:205], v[92:95]
	v_mfma_f32_16x16x32_bf16 v[88:91], v[128:131], v[202:205], v[88:91]
	v_mfma_f32_16x16x32_bf16 v[76:79], v[116:119], v[210:213], v[76:79]
	v_mfma_f32_16x16x32_bf16 v[72:75], v[128:131], v[210:213], v[72:75]
	v_mfma_f32_16x16x32_bf16 v[140:143], v[124:127], v[190:193], v[140:143]
	v_mfma_f32_16x16x32_bf16 v[136:139], v[132:135], v[190:193], v[136:139]
	v_mfma_f32_16x16x32_bf16 v[108:111], v[124:127], v[198:201], v[108:111]
	v_mfma_f32_16x16x32_bf16 v[104:107], v[132:135], v[198:201], v[104:107]
	v_mfma_f32_16x16x32_bf16 v[92:95], v[124:127], v[206:209], v[92:95]
	v_mfma_f32_16x16x32_bf16 v[88:91], v[132:135], v[206:209], v[88:91]
	v_mfma_f32_16x16x32_bf16 v[76:79], v[124:127], v[214:217], v[76:79]
	v_mfma_f32_16x16x32_bf16 v[72:75], v[132:135], v[214:217], v[72:75]
	s_setprio 0
	s_setprio 1
	v_mfma_f32_16x16x32_bf16 v[120:123], v[160:163], v[186:189], v[120:123]
	v_mfma_f32_16x16x32_bf16 v[112:115], v[178:181], v[186:189], v[112:115]
	v_mfma_f32_16x16x32_bf16 v[100:103], v[160:163], v[194:197], v[100:103]
	v_mfma_f32_16x16x32_bf16 v[96:99], v[178:181], v[194:197], v[96:99]
	v_mfma_f32_16x16x32_bf16 v[84:87], v[160:163], v[202:205], v[84:87]
	v_mfma_f32_16x16x32_bf16 v[80:83], v[178:181], v[202:205], v[80:83]
	v_mfma_f32_16x16x32_bf16 v[68:71], v[160:163], v[210:213], v[68:71]
	v_mfma_f32_16x16x32_bf16 v[64:67], v[178:181], v[210:213], v[64:67]
	v_mfma_f32_16x16x32_bf16 v[120:123], v[164:167], v[190:193], v[120:123]
	v_mfma_f32_16x16x32_bf16 v[112:115], v[182:185], v[190:193], v[112:115]
	v_mfma_f32_16x16x32_bf16 v[100:103], v[164:167], v[198:201], v[100:103]
	v_mfma_f32_16x16x32_bf16 v[96:99], v[182:185], v[198:201], v[96:99]
	v_mfma_f32_16x16x32_bf16 v[84:87], v[164:167], v[206:209], v[84:87]
	v_mfma_f32_16x16x32_bf16 v[80:83], v[182:185], v[206:209], v[80:83]
	v_mfma_f32_16x16x32_bf16 v[68:71], v[164:167], v[214:217], v[68:71]
	v_mfma_f32_16x16x32_bf16 v[64:67], v[182:185], v[214:217], v[64:67]
	s_setprio 0
	s_barrier
	s_add_i32 s78, s80, s21
	v_lshl_add_u64 v[168:169], v[168:169], 0, s[16:17]
	s_mov_b32 m0, s78
	ds_read_b128 v[186:189], v175 offset:49152
	ds_read_b128 v[190:193], v175 offset:50176
	ds_read_b128 v[194:197], v175 offset:51200
	ds_read_b128 v[198:201], v175 offset:52224
	ds_read_b128 v[202:205], v175 offset:53248
	ds_read_b128 v[206:209], v175 offset:54272
	ds_read_b128 v[210:213], v175 offset:55296
	ds_read_b128 v[214:217], v175 offset:56320
	global_load_lds_dwordx4 v[168:169], off
	s_add_i32 m0, s78, 0x2000
	s_add_u32 s78, s92, 0x580080
	v_lshl_add_u64 v[168:169], v[218:219], 0, s[16:17]
	s_addc_u32 s79, s93, 0
	s_add_i32 s80, s81, s21
	global_load_lds_dwordx4 v[168:169], off
	v_lshl_add_u64 v[168:169], s[78:79], 0, v[148:149]
	s_mov_b32 m0, s80
	s_nop 0
	global_load_lds_dwordx4 v[168:169], off
	v_lshl_add_u64 v[168:169], s[78:79], 0, v[144:145]
	s_add_i32 m0, s80, 0x2000
	s_nop 0
	global_load_lds_dwordx4 v[168:169], off
	v_lshl_add_u64 v[168:169], v[220:221], 0, s[16:17]
	s_mov_b32 m0, s60
	s_nop 0
	global_load_lds_dwordx4 v[168:169], off
	v_lshl_add_u64 v[168:169], v[222:223], 0, s[16:17]
	s_mov_b32 m0, s61
	s_nop 0
	global_load_lds_dwordx4 v[168:169], off
	s_waitcnt vmcnt(8)
	s_waitcnt lgkmcnt(0)
	s_barrier
	s_setprio 1
	s_waitcnt lgkmcnt(0)
	v_mfma_f32_16x16x32_bf16 v[60:63], v[116:119], v[186:189], v[60:63]
	v_mfma_f32_16x16x32_bf16 v[56:59], v[128:131], v[186:189], v[56:59]
	v_mfma_f32_16x16x32_bf16 v[44:47], v[116:119], v[194:197], v[44:47]
	v_mfma_f32_16x16x32_bf16 v[40:43], v[128:131], v[194:197], v[40:43]
	v_mfma_f32_16x16x32_bf16 v[28:31], v[116:119], v[202:205], v[28:31]
	v_mfma_f32_16x16x32_bf16 v[24:27], v[128:131], v[202:205], v[24:27]
	v_mfma_f32_16x16x32_bf16 v[12:15], v[116:119], v[210:213], v[12:15]
	v_mfma_f32_16x16x32_bf16 v[8:11], v[128:131], v[210:213], v[8:11]
	v_mfma_f32_16x16x32_bf16 v[60:63], v[124:127], v[190:193], v[60:63]
	v_mfma_f32_16x16x32_bf16 v[56:59], v[132:135], v[190:193], v[56:59]
	v_mfma_f32_16x16x32_bf16 v[44:47], v[124:127], v[198:201], v[44:47]
	v_mfma_f32_16x16x32_bf16 v[40:43], v[132:135], v[198:201], v[40:43]
	v_mfma_f32_16x16x32_bf16 v[28:31], v[124:127], v[206:209], v[28:31]
	v_mfma_f32_16x16x32_bf16 v[24:27], v[132:135], v[206:209], v[24:27]
	v_mfma_f32_16x16x32_bf16 v[12:15], v[124:127], v[214:217], v[12:15]
	v_mfma_f32_16x16x32_bf16 v[8:11], v[132:135], v[214:217], v[8:11]
	s_setprio 0
	s_setprio 1
	v_mfma_f32_16x16x32_bf16 v[52:55], v[160:163], v[186:189], v[52:55]
	v_mfma_f32_16x16x32_bf16 v[48:51], v[178:181], v[186:189], v[48:51]
	v_mfma_f32_16x16x32_bf16 v[36:39], v[160:163], v[194:197], v[36:39]
	v_mfma_f32_16x16x32_bf16 v[32:35], v[178:181], v[194:197], v[32:35]
	v_mfma_f32_16x16x32_bf16 v[20:23], v[160:163], v[202:205], v[20:23]
	v_mfma_f32_16x16x32_bf16 v[16:19], v[178:181], v[202:205], v[16:19]
	v_mfma_f32_16x16x32_bf16 v[4:7], v[160:163], v[210:213], v[4:7]
	v_mfma_f32_16x16x32_bf16 v[0:3], v[178:181], v[210:213], v[0:3]
	v_mfma_f32_16x16x32_bf16 v[52:55], v[164:167], v[190:193], v[52:55]
	v_mfma_f32_16x16x32_bf16 v[48:51], v[182:185], v[190:193], v[48:51]
	v_mfma_f32_16x16x32_bf16 v[36:39], v[164:167], v[198:201], v[36:39]
	v_mfma_f32_16x16x32_bf16 v[32:35], v[182:185], v[198:201], v[32:35]
	v_mfma_f32_16x16x32_bf16 v[20:23], v[164:167], v[206:209], v[20:23]
	v_mfma_f32_16x16x32_bf16 v[16:19], v[182:185], v[206:209], v[16:19]
	v_mfma_f32_16x16x32_bf16 v[4:7], v[164:167], v[214:217], v[4:7]
	v_mfma_f32_16x16x32_bf16 v[0:3], v[182:185], v[214:217], v[0:3]
	s_setprio 0
	s_barrier
	s_add_i32 s77, s77, 2
	s_add_u32 s90, s90, 0x100
	s_addc_u32 s91, s91, 0
	s_add_u32 s67, s67, 0x100
	s_addc_u32 s76, s76, 0
	s_cmp_lt_u32 s77, 14
	s_cbranch_scc1 .LBB0_967
	s_andn2_b64 vcc, exec, s[34:35]
	s_cbranch_vccnz .LBB0_970
	s_barrier
.LBB0_970:
	s_and_b32 s32, s10, 1
	v_readlane_b32 s98, v254, 49
	v_readlane_b32 s99, v254, 50
	s_nop 0
	s_add_i32 s4, s88, 0
	s_ashr_i32 s4, s4, 2
	s_add_i32 s4, s4, 1
	s_cmp_gt_i32 s88, -1
	s_cselect_b32 s4, s4, 0
	s_mul_hi_i32 s5, s4, 0x5800
	s_mulk_i32 s4, 0x5800
	s_add_u32 s4, s98, s4
	s_addc_u32 s5, s99, s5
	v_lshl_add_u32 v236, s88, 8, v170
	v_lshlrev_b32_e32 v236, 2, v236
	v_lshl_or_b32 v177, s66, 7, v172
	v_lshlrev_b32_e32 v177, 2, v177
	global_load_dword v210, v236, s[12:13] offset:0
	global_load_dword v211, v236, s[12:13] offset:64
	global_load_dword v212, v236, s[12:13] offset:128
	global_load_dword v213, v236, s[12:13] offset:192
	global_load_dword v214, v236, s[12:13] offset:512
	global_load_dword v215, v236, s[12:13] offset:576
	global_load_dword v216, v236, s[12:13] offset:640
	global_load_dword v217, v236, s[12:13] offset:704
	global_load_dwordx4 v[202:205], v177, s[4:5]
	global_load_dwordx4 v[206:209], v177, s[4:5] offset:16
	v_add_u32_e32 v226, 0x2c00, v177
	global_load_dwordx4 v[218:221], v226, s[4:5]
	global_load_dwordx4 v[222:225], v226, s[4:5] offset:16
	v_readlane_b32 s2, v254, 5
	v_readlane_b32 s3, v254, 6
	v_readlane_b32 s28, v254, 7
	v_readlane_b32 s29, v254, 8
	s_mul_i32 s76, s88, 0x160000
	s_lshl_b32 s57, s66, 8
	s_add_i32 s76, s76, s57
	s_add_i32 s76, s76, 0xbf00000
	s_add_u32 s76, s76, s70
	s_addc_u32 s77, s71, 0
	v_mul_u32_u24_e32 v168, 0x1600, v170
	v_lshl_add_u32 v168, v172, 1, v168
	s_mov_b32 s55, 0x20800
	v_lshl_add_u32 v169, v172, 2, s55
	v_and_b32_e32 v237, 15, v170
	v_cmp_eq_u32_e64 s[78:79], 0, v237
	v_cmp_eq_u32_e64 s[80:81], 15, v237
	v_and_b32_e32 v231, 8, v237
	v_lshlrev_b32_e32 v231, 9, v231
	s_lshl_b32 s57, s32, 10
	v_add3_u32 v231, v231, v169, s57
	s_waitcnt vmcnt(4)
	v_fmamk_f32 v210, v210, 0x3a800000, v176
	v_fmamk_f32 v211, v211, 0x3a800000, v176
	v_fmamk_f32 v212, v212, 0x3a800000, v176
	v_fmamk_f32 v213, v213, 0x3a800000, v176
	v_fmamk_f32 v214, v214, 0x3a800000, v176
	v_fmamk_f32 v215, v215, 0x3a800000, v176
	v_fmamk_f32 v216, v216, 0x3a800000, v176
	v_fmamk_f32 v217, v217, 0x3a800000, v176
	s_mov_b32 s57, 0x800000
	v_mul_f32_e32 v226, 0x4b800000, v210
	v_mul_f32_e32 v227, 0x4b800000, v211
	v_mul_f32_e32 v228, 0x4b800000, v212
	v_mul_f32_e32 v229, 0x4b800000, v213
	v_mul_f32_e32 v232, 0x4b800000, v214
	v_mul_f32_e32 v233, 0x4b800000, v215
	v_mul_f32_e32 v234, 0x4b800000, v216
	v_mul_f32_e32 v235, 0x4b800000, v217
	v_cmp_gt_f32_e32 vcc, s57, v210
	s_nop 1
	v_cndmask_b32_e32 v210, v210, v226, vcc
	v_rsq_f32_e32 v210, v210
	s_nop 0
	v_mul_f32_e32 v226, 0x45800000, v210
	v_cndmask_b32_e32 v210, v210, v226, vcc
	v_cmp_gt_f32_e32 vcc, s57, v211
	s_nop 1
	v_cndmask_b32_e32 v211, v211, v227, vcc
	v_rsq_f32_e32 v211, v211
	s_nop 0
	v_mul_f32_e32 v227, 0x45800000, v211
	v_cndmask_b32_e32 v211, v211, v227, vcc
	v_cmp_gt_f32_e32 vcc, s57, v212
	s_nop 1
	v_cndmask_b32_e32 v212, v212, v228, vcc
	v_rsq_f32_e32 v212, v212
	s_nop 0
	v_mul_f32_e32 v228, 0x45800000, v212
	v_cndmask_b32_e32 v212, v212, v228, vcc
	v_cmp_gt_f32_e32 vcc, s57, v213
	s_nop 1
	v_cndmask_b32_e32 v213, v213, v229, vcc
	v_rsq_f32_e32 v213, v213
	s_nop 0
	v_mul_f32_e32 v229, 0x45800000, v213
	v_cndmask_b32_e32 v213, v213, v229, vcc
	v_cmp_gt_f32_e32 vcc, s57, v214
	s_nop 1
	v_cndmask_b32_e32 v214, v214, v232, vcc
	v_rsq_f32_e32 v214, v214
	s_nop 0
	v_mul_f32_e32 v232, 0x45800000, v214
	v_cndmask_b32_e32 v214, v214, v232, vcc
	v_cmp_gt_f32_e32 vcc, s57, v215
	s_nop 1
	v_cndmask_b32_e32 v215, v215, v233, vcc
	v_rsq_f32_e32 v215, v215
	s_nop 0
	v_mul_f32_e32 v233, 0x45800000, v215
	v_cndmask_b32_e32 v215, v215, v233, vcc
	v_cmp_gt_f32_e32 vcc, s57, v216
	s_nop 1
	v_cndmask_b32_e32 v216, v216, v234, vcc
	v_rsq_f32_e32 v216, v216
	s_nop 0
	v_mul_f32_e32 v234, 0x45800000, v216
	v_cndmask_b32_e32 v216, v216, v234, vcc
	v_cmp_gt_f32_e32 vcc, s57, v217
	s_nop 1
	v_cndmask_b32_e32 v217, v217, v235, vcc
	v_rsq_f32_e32 v217, v217
	s_nop 0
	v_mul_f32_e32 v235, 0x45800000, v217
	v_cndmask_b32_e32 v217, v217, v235, vcc
	s_waitcnt vmcnt(0)
	v_fma_f32 v140, v140, v210, v202
	v_fma_f32 v141, v141, v210, v203
	v_fma_f32 v142, v142, v210, v204
	v_fma_f32 v143, v143, v210, v205
	v_fma_f32 v136, v136, v210, v206
	v_fma_f32 v137, v137, v210, v207
	v_fma_f32 v138, v138, v210, v208
	v_fma_f32 v139, v139, v210, v209
	v_fma_f32 v120, v120, v210, v218
	v_fma_f32 v121, v121, v210, v219
	v_fma_f32 v122, v122, v210, v220
	v_fma_f32 v123, v123, v210, v221
	v_fma_f32 v112, v112, v210, v222
	v_fma_f32 v113, v113, v210, v223
	v_fma_f32 v114, v114, v210, v224
	v_fma_f32 v115, v115, v210, v225
	v_fma_f32 v108, v108, v211, v202
	v_fma_f32 v109, v109, v211, v203
	v_fma_f32 v110, v110, v211, v204
	v_fma_f32 v111, v111, v211, v205
	v_fma_f32 v104, v104, v211, v206
	v_fma_f32 v105, v105, v211, v207
	v_fma_f32 v106, v106, v211, v208
	v_fma_f32 v107, v107, v211, v209
	v_fma_f32 v100, v100, v211, v218
	v_fma_f32 v101, v101, v211, v219
	v_fma_f32 v102, v102, v211, v220
	v_fma_f32 v103, v103, v211, v221
	v_fma_f32 v96, v96, v211, v222
	v_fma_f32 v97, v97, v211, v223
	v_fma_f32 v98, v98, v211, v224
	v_fma_f32 v99, v99, v211, v225
	v_fma_f32 v92, v92, v212, v202
	v_fma_f32 v93, v93, v212, v203
	v_fma_f32 v94, v94, v212, v204
	v_fma_f32 v95, v95, v212, v205
	v_fma_f32 v88, v88, v212, v206
	v_fma_f32 v89, v89, v212, v207
	v_fma_f32 v90, v90, v212, v208
	v_fma_f32 v91, v91, v212, v209
	v_fma_f32 v84, v84, v212, v218
	v_fma_f32 v85, v85, v212, v219
	v_fma_f32 v86, v86, v212, v220
	v_fma_f32 v87, v87, v212, v221
	v_fma_f32 v80, v80, v212, v222
	v_fma_f32 v81, v81, v212, v223
	v_fma_f32 v82, v82, v212, v224
	v_fma_f32 v83, v83, v212, v225
	v_fma_f32 v76, v76, v213, v202
	v_fma_f32 v77, v77, v213, v203
	v_fma_f32 v78, v78, v213, v204
	v_fma_f32 v79, v79, v213, v205
	v_fma_f32 v72, v72, v213, v206
	v_fma_f32 v73, v73, v213, v207
	v_fma_f32 v74, v74, v213, v208
	v_fma_f32 v75, v75, v213, v209
	v_fma_f32 v68, v68, v213, v218
	v_fma_f32 v69, v69, v213, v219
	v_fma_f32 v70, v70, v213, v220
	v_fma_f32 v71, v71, v213, v221
	v_fma_f32 v64, v64, v213, v222
	v_fma_f32 v65, v65, v213, v223
	v_fma_f32 v66, v66, v213, v224
	v_fma_f32 v67, v67, v213, v225
	v_fma_f32 v60, v60, v214, v202
	v_fma_f32 v61, v61, v214, v203
	v_fma_f32 v62, v62, v214, v204
	v_fma_f32 v63, v63, v214, v205
	v_fma_f32 v56, v56, v214, v206
	v_fma_f32 v57, v57, v214, v207
	v_fma_f32 v58, v58, v214, v208
	v_fma_f32 v59, v59, v214, v209
	v_fma_f32 v52, v52, v214, v218
	v_fma_f32 v53, v53, v214, v219
	v_fma_f32 v54, v54, v214, v220
	v_fma_f32 v55, v55, v214, v221
	v_fma_f32 v48, v48, v214, v222
	v_fma_f32 v49, v49, v214, v223
	v_fma_f32 v50, v50, v214, v224
	v_fma_f32 v51, v51, v214, v225
	v_fma_f32 v44, v44, v215, v202
	v_fma_f32 v45, v45, v215, v203
	v_fma_f32 v46, v46, v215, v204
	v_fma_f32 v47, v47, v215, v205
	v_fma_f32 v40, v40, v215, v206
	v_fma_f32 v41, v41, v215, v207
	v_fma_f32 v42, v42, v215, v208
	v_fma_f32 v43, v43, v215, v209
	v_fma_f32 v36, v36, v215, v218
	v_fma_f32 v37, v37, v215, v219
	v_fma_f32 v38, v38, v215, v220
	v_fma_f32 v39, v39, v215, v221
	v_fma_f32 v32, v32, v215, v222
	v_fma_f32 v33, v33, v215, v223
	v_fma_f32 v34, v34, v215, v224
	v_fma_f32 v35, v35, v215, v225
	v_fma_f32 v28, v28, v216, v202
	v_fma_f32 v29, v29, v216, v203
	v_fma_f32 v30, v30, v216, v204
	v_fma_f32 v31, v31, v216, v205
	v_fma_f32 v24, v24, v216, v206
	v_fma_f32 v25, v25, v216, v207
	v_fma_f32 v26, v26, v216, v208
	v_fma_f32 v27, v27, v216, v209
	v_fma_f32 v20, v20, v216, v218
	v_fma_f32 v21, v21, v216, v219
	v_fma_f32 v22, v22, v216, v220
	v_fma_f32 v23, v23, v216, v221
	v_fma_f32 v16, v16, v216, v222
	v_fma_f32 v17, v17, v216, v223
	v_fma_f32 v18, v18, v216, v224
	v_fma_f32 v19, v19, v216, v225
	v_fma_f32 v12, v12, v217, v202
	v_fma_f32 v13, v13, v217, v203
	v_fma_f32 v14, v14, v217, v204
	v_fma_f32 v15, v15, v217, v205
	v_fma_f32 v8, v8, v217, v206
	v_fma_f32 v9, v9, v217, v207
	v_fma_f32 v10, v10, v217, v208
	v_fma_f32 v11, v11, v217, v209
	v_fma_f32 v4, v4, v217, v218
	v_fma_f32 v5, v5, v217, v219
	v_fma_f32 v6, v6, v217, v220
	v_fma_f32 v7, v7, v217, v221
	v_fma_f32 v0, v0, v217, v222
	v_fma_f32 v1, v1, v217, v223
	v_fma_f32 v2, v2, v217, v224
	v_fma_f32 v3, v3, v217, v225
	global_load_dwordx4 v[116:119], v177, s[2:3]
	v_add_u32_e32 v213, 0x5800, v177
	global_load_dwordx4 v[124:127], v213, s[2:3]
	v_add_u32_e32 v212, 0xb000, v177
	global_load_dwordx4 v[128:131], v212, s[2:3]
	global_load_dwordx4 v[132:135], v177, s[28:29]
	v_add_u32_e32 v212, 0x2c00, v177
	global_load_dwordx4 v[160:163], v212, s[2:3]
	v_add_u32_e32 v213, 0x8400, v177
	global_load_dwordx4 v[164:167], v213, s[2:3]
	v_add_u32_e32 v212, 0xdc00, v177
	global_load_dwordx4 v[178:181], v212, s[2:3]
	v_add_u32_e32 v213, 0x2c00, v177
	global_load_dwordx4 v[182:185], v213, s[28:29]
	v_mov_b32_e32 v214, 0
	v_mov_b32_e32 v215, 0
	v_mov_b32_e32 v216, 0
	v_mov_b32_e32 v217, 0
	s_lshl_b32 s67, s32, 12
	s_sub_i32 s67, 0x2000, s67
	s_mul_i32 s89, s32, 0x1400
	s_add_i32 s89, s89, 0xc00
	s_lshl_b32 s57, s32, 10
	s_add_i32 s100, s57, 5120
	s_add_i32 s101, s57, 1024
	s_mov_b64 s[90:91], exec
	s_mov_b64 exec, s[78:79]
	v_add_u32_e32 v250, s67, v169
	ds_write_b128 v250, v[140:143] offset:0
	ds_write_b128 v250, v[136:139] offset:16
	ds_write_b128 v250, v[120:123] offset:512
	ds_write_b128 v250, v[112:115] offset:528
	v_add_u32_e32 v250, s100, v169
	ds_write_b128 v250, v[60:63] offset:0
	ds_write_b128 v250, v[56:59] offset:16
	ds_write_b128 v250, v[52:55] offset:512
	ds_write_b128 v250, v[48:51] offset:528
	ds_write_b128 v169, v[214:217] offset:0
	ds_write_b128 v169, v[214:217] offset:16
	ds_write_b128 v169, v[214:217] offset:512
	ds_write_b128 v169, v[214:217] offset:528
	s_mov_b64 exec, s[80:81]
	v_add_u32_e32 v251, s101, v169
	ds_write_b128 v251, v[76:79] offset:0
	ds_write_b128 v251, v[72:75] offset:16
	ds_write_b128 v251, v[68:71] offset:512
	ds_write_b128 v251, v[64:67] offset:528
	v_add_u32_e32 v251, s89, v169
	ds_write_b128 v251, v[12:15] offset:0
	ds_write_b128 v251, v[8:11] offset:16
	ds_write_b128 v251, v[4:7] offset:512
	ds_write_b128 v251, v[0:3] offset:528
	ds_write_b128 v169, v[214:217] offset:7168
	ds_write_b128 v169, v[214:217] offset:7184
	ds_write_b128 v169, v[214:217] offset:7680
	ds_write_b128 v169, v[214:217] offset:7696
	s_mov_b64 exec, s[90:91]
	s_cmp_eq_u32 s32, 0
	s_cselect_b64 s[92:93], s[78:79], 0
	s_cselect_b64 s[94:95], 0, s[80:81]
	s_mul_i32 s98, s88, 0x16000
	s_add_u32 s98, s98, 0x5b00000
	s_add_u32 s98, s98, s70
	s_addc_u32 s99, s71, 0
	s_mov_b64 exec, s[92:93]
	global_store_dwordx4 v177, v[140:143], s[98:99]
	global_store_dwordx4 v177, v[136:139], s[98:99] offset:16
	v_add_u32_e32 v250, 0x2c00, v177
	global_store_dwordx4 v250, v[120:123], s[98:99]
	global_store_dwordx4 v250, v[112:115], s[98:99] offset:16
	s_mov_b64 exec, s[94:95]
	v_add_u32_e32 v250, 0xb000, v177
	global_store_dwordx4 v250, v[12:15], s[98:99]
	global_store_dwordx4 v250, v[8:11], s[98:99] offset:16
	v_add_u32_e32 v250, 0xdc00, v177
	global_store_dwordx4 v250, v[4:7], s[98:99]
	global_store_dwordx4 v250, v[0:3], s[98:99] offset:16
	s_mov_b64 exec, s[90:91]
	s_waitcnt lgkmcnt(0)
	s_barrier
	ds_read_b128 v[186:189], v231 offset:0
	ds_read_b128 v[190:193], v231 offset:512
	ds_read_b128 v[194:197], v231 offset:2048
	ds_read_b128 v[198:201], v231 offset:2560
	s_waitcnt vmcnt(0)
	v_cndmask_b32_e64 v218, 0, v116, s[78:79]
	v_cndmask_b32_e64 v222, 0, v128, s[80:81]
	v_cndmask_b32_e64 v219, 0, v117, s[78:79]
	v_cndmask_b32_e64 v223, 0, v129, s[80:81]
	v_cndmask_b32_e64 v220, 0, v118, s[78:79]
	v_cndmask_b32_e64 v224, 0, v130, s[80:81]
	v_cndmask_b32_e64 v221, 0, v119, s[78:79]
	v_cndmask_b32_e64 v225, 0, v131, s[80:81]
	v_cndmask_b32_e64 v226, 0, v160, s[78:79]
	v_cndmask_b32_e64 v232, 0, v178, s[80:81]
	v_cndmask_b32_e64 v227, 0, v161, s[78:79]
	v_cndmask_b32_e64 v233, 0, v179, s[80:81]
	v_cndmask_b32_e64 v228, 0, v162, s[78:79]
	v_cndmask_b32_e64 v234, 0, v180, s[80:81]
	v_cndmask_b32_e64 v229, 0, v163, s[78:79]
	v_cndmask_b32_e64 v235, 0, v181, s[80:81]
	s_waitcnt lgkmcnt(0)
	s_nop 1
	v_fma_f32 v202, v124, v140, v132
	v_fma_f32 v203, v125, v141, v133
	v_fma_f32 v204, v126, v142, v134
	v_fma_f32 v205, v127, v143, v135
	v_fmac_f32_dpp v202, v140, v116 row_shr:1 row_mask:0xf bank_mask:0xf
	v_fmac_f32_dpp v203, v141, v117 row_shr:1 row_mask:0xf bank_mask:0xf
	v_fmac_f32_dpp v204, v142, v118 row_shr:1 row_mask:0xf bank_mask:0xf
	v_fmac_f32_dpp v205, v143, v119 row_shr:1 row_mask:0xf bank_mask:0xf
	v_fmac_f32_e32 v202, v186, v218
	v_fmac_f32_e32 v203, v187, v219
	v_fmac_f32_e32 v204, v188, v220
	v_fmac_f32_e32 v205, v189, v221
	v_fmac_f32_dpp v202, v140, v128 row_shl:1 row_mask:0xf bank_mask:0xf
	v_fmac_f32_dpp v203, v141, v129 row_shl:1 row_mask:0xf bank_mask:0xf
	v_fmac_f32_dpp v204, v142, v130 row_shl:1 row_mask:0xf bank_mask:0xf
	v_fmac_f32_dpp v205, v143, v131 row_shl:1 row_mask:0xf bank_mask:0xf
	v_fmac_f32_dpp v202, v108, v222 row_ror:15 row_mask:0xf bank_mask:0xf
	v_fmac_f32_dpp v203, v109, v223 row_ror:15 row_mask:0xf bank_mask:0xf
	v_fmac_f32_dpp v204, v110, v224 row_ror:15 row_mask:0xf bank_mask:0xf
	v_fmac_f32_dpp v205, v111, v225 row_ror:15 row_mask:0xf bank_mask:0xf
	v_fma_f32 v206, v164, v120, v182
	v_fma_f32 v207, v165, v121, v183
	v_fma_f32 v208, v166, v122, v184
	v_fma_f32 v209, v167, v123, v185
	v_fmac_f32_dpp v206, v120, v160 row_shr:1 row_mask:0xf bank_mask:0xf
	v_fmac_f32_dpp v207, v121, v161 row_shr:1 row_mask:0xf bank_mask:0xf
	v_fmac_f32_dpp v208, v122, v162 row_shr:1 row_mask:0xf bank_mask:0xf
	v_fmac_f32_dpp v209, v123, v163 row_shr:1 row_mask:0xf bank_mask:0xf
	v_fmac_f32_e32 v206, v190, v226
	v_fmac_f32_e32 v207, v191, v227
	v_fmac_f32_e32 v208, v192, v228
	v_fmac_f32_e32 v209, v193, v229
	v_fmac_f32_dpp v206, v120, v178 row_shl:1 row_mask:0xf bank_mask:0xf
	v_fmac_f32_dpp v207, v121, v179 row_shl:1 row_mask:0xf bank_mask:0xf
	v_fmac_f32_dpp v208, v122, v180 row_shl:1 row_mask:0xf bank_mask:0xf
	v_fmac_f32_dpp v209, v123, v181 row_shl:1 row_mask:0xf bank_mask:0xf
	v_fmac_f32_dpp v206, v100, v232 row_ror:15 row_mask:0xf bank_mask:0xf
	v_fmac_f32_dpp v207, v101, v233 row_ror:15 row_mask:0xf bank_mask:0xf
	v_fmac_f32_dpp v208, v102, v234 row_ror:15 row_mask:0xf bank_mask:0xf
	v_fmac_f32_dpp v209, v103, v235 row_ror:15 row_mask:0xf bank_mask:0xf
	s_mov_b64 exec, s[92:93]
	v_add_u32_e32 v250, 0x5800, v177
	global_store_dwordx4 v250, v[202:205], s[98:99]
	v_add_u32_e32 v250, 0x8400, v177
	global_store_dwordx4 v250, v[206:209], s[98:99]
	s_mov_b64 exec, s[90:91]
	s_nop 4
	v_mul_f32_e32 v210, 0xbfb8aa3b, v202
	v_mul_f32_e32 v211, 0xbfb8aa3b, v203
	v_mul_f32_e32 v212, 0xbfb8aa3b, v204
	v_mul_f32_e32 v213, 0xbfb8aa3b, v205
	v_exp_f32_e32 v210, v210
	v_exp_f32_e32 v211, v211
	v_exp_f32_e32 v212, v212
	v_exp_f32_e32 v213, v213
	v_add_f32_e32 v210, 1.0, v210
	v_add_f32_e32 v211, 1.0, v211
	v_add_f32_e32 v212, 1.0, v212
	v_add_f32_e32 v213, 1.0, v213
	v_rcp_f32_e32 v210, v210
	v_rcp_f32_e32 v211, v211
	v_rcp_f32_e32 v212, v212
	v_rcp_f32_e32 v213, v213
	v_mul_f32_e32 v202, v202, v210
	v_mul_f32_e32 v203, v203, v211
	v_mul_f32_e32 v204, v204, v212
	v_mul_f32_e32 v205, v205, v213
	v_mul_f32_e32 v202, v202, v206
	v_mul_f32_e32 v203, v203, v207
	v_mul_f32_e32 v204, v204, v208
	v_mul_f32_e32 v205, v205, v209
	v_cvt_pk_bf16_f32 v236, v202, v203
	v_cvt_pk_bf16_f32 v237, v204, v205
	v_fma_f32 v202, v124, v108, v132
	v_fma_f32 v203, v125, v109, v133
	v_fma_f32 v204, v126, v110, v134
	v_fma_f32 v205, v127, v111, v135
	v_fmac_f32_dpp v202, v108, v116 row_shr:1 row_mask:0xf bank_mask:0xf
	v_fmac_f32_dpp v203, v109, v117 row_shr:1 row_mask:0xf bank_mask:0xf
	v_fmac_f32_dpp v204, v110, v118 row_shr:1 row_mask:0xf bank_mask:0xf
	v_fmac_f32_dpp v205, v111, v119 row_shr:1 row_mask:0xf bank_mask:0xf
	v_fmac_f32_dpp v202, v140, v218 row_ror:1 row_mask:0xf bank_mask:0xf
	v_fmac_f32_dpp v203, v141, v219 row_ror:1 row_mask:0xf bank_mask:0xf
	v_fmac_f32_dpp v204, v142, v220 row_ror:1 row_mask:0xf bank_mask:0xf
	v_fmac_f32_dpp v205, v143, v221 row_ror:1 row_mask:0xf bank_mask:0xf
	v_fmac_f32_dpp v202, v108, v128 row_shl:1 row_mask:0xf bank_mask:0xf
	v_fmac_f32_dpp v203, v109, v129 row_shl:1 row_mask:0xf bank_mask:0xf
	v_fmac_f32_dpp v204, v110, v130 row_shl:1 row_mask:0xf bank_mask:0xf
	v_fmac_f32_dpp v205, v111, v131 row_shl:1 row_mask:0xf bank_mask:0xf
	v_fmac_f32_dpp v202, v92, v222 row_ror:15 row_mask:0xf bank_mask:0xf
	v_fmac_f32_dpp v203, v93, v223 row_ror:15 row_mask:0xf bank_mask:0xf
	v_fmac_f32_dpp v204, v94, v224 row_ror:15 row_mask:0xf bank_mask:0xf
	v_fmac_f32_dpp v205, v95, v225 row_ror:15 row_mask:0xf bank_mask:0xf
	v_fma_f32 v206, v164, v100, v182
	v_fma_f32 v207, v165, v101, v183
	v_fma_f32 v208, v166, v102, v184
	v_fma_f32 v209, v167, v103, v185
	v_fmac_f32_dpp v206, v100, v160 row_shr:1 row_mask:0xf bank_mask:0xf
	v_fmac_f32_dpp v207, v101, v161 row_shr:1 row_mask:0xf bank_mask:0xf
	v_fmac_f32_dpp v208, v102, v162 row_shr:1 row_mask:0xf bank_mask:0xf
	v_fmac_f32_dpp v209, v103, v163 row_shr:1 row_mask:0xf bank_mask:0xf
	v_fmac_f32_dpp v206, v120, v226 row_ror:1 row_mask:0xf bank_mask:0xf
	v_fmac_f32_dpp v207, v121, v227 row_ror:1 row_mask:0xf bank_mask:0xf
	v_fmac_f32_dpp v208, v122, v228 row_ror:1 row_mask:0xf bank_mask:0xf
	v_fmac_f32_dpp v209, v123, v229 row_ror:1 row_mask:0xf bank_mask:0xf
	v_fmac_f32_dpp v206, v100, v178 row_shl:1 row_mask:0xf bank_mask:0xf
	v_fmac_f32_dpp v207, v101, v179 row_shl:1 row_mask:0xf bank_mask:0xf
	v_fmac_f32_dpp v208, v102, v180 row_shl:1 row_mask:0xf bank_mask:0xf
	v_fmac_f32_dpp v209, v103, v181 row_shl:1 row_mask:0xf bank_mask:0xf
	v_fmac_f32_dpp v206, v84, v232 row_ror:15 row_mask:0xf bank_mask:0xf
	v_fmac_f32_dpp v207, v85, v233 row_ror:15 row_mask:0xf bank_mask:0xf
	v_fmac_f32_dpp v208, v86, v234 row_ror:15 row_mask:0xf bank_mask:0xf
	v_fmac_f32_dpp v209, v87, v235 row_ror:15 row_mask:0xf bank_mask:0xf
	v_mul_f32_e32 v210, 0xbfb8aa3b, v202
	v_mul_f32_e32 v211, 0xbfb8aa3b, v203
	v_mul_f32_e32 v212, 0xbfb8aa3b, v204
	v_mul_f32_e32 v213, 0xbfb8aa3b, v205
	v_exp_f32_e32 v210, v210
	v_exp_f32_e32 v211, v211
	v_exp_f32_e32 v212, v212
	v_exp_f32_e32 v213, v213
	v_add_f32_e32 v210, 1.0, v210
	v_add_f32_e32 v211, 1.0, v211
	v_add_f32_e32 v212, 1.0, v212
	v_add_f32_e32 v213, 1.0, v213
	v_rcp_f32_e32 v210, v210
	v_rcp_f32_e32 v211, v211
	v_rcp_f32_e32 v212, v212
	v_rcp_f32_e32 v213, v213
	v_mul_f32_e32 v202, v202, v210
	v_mul_f32_e32 v203, v203, v211
	v_mul_f32_e32 v204, v204, v212
	v_mul_f32_e32 v205, v205, v213
	v_mul_f32_e32 v202, v202, v206
	v_mul_f32_e32 v203, v203, v207
	v_mul_f32_e32 v204, v204, v208
	v_mul_f32_e32 v205, v205, v209
	v_cvt_pk_bf16_f32 v238, v202, v203
	v_cvt_pk_bf16_f32 v239, v204, v205
	v_fma_f32 v202, v124, v92, v132
	v_fma_f32 v203, v125, v93, v133
	v_fma_f32 v204, v126, v94, v134
	v_fma_f32 v205, v127, v95, v135
	v_fmac_f32_dpp v202, v92, v116 row_shr:1 row_mask:0xf bank_mask:0xf
	v_fmac_f32_dpp v203, v93, v117 row_shr:1 row_mask:0xf bank_mask:0xf
	v_fmac_f32_dpp v204, v94, v118 row_shr:1 row_mask:0xf bank_mask:0xf
	v_fmac_f32_dpp v205, v95, v119 row_shr:1 row_mask:0xf bank_mask:0xf
	v_fmac_f32_dpp v202, v108, v218 row_ror:1 row_mask:0xf bank_mask:0xf
	v_fmac_f32_dpp v203, v109, v219 row_ror:1 row_mask:0xf bank_mask:0xf
	v_fmac_f32_dpp v204, v110, v220 row_ror:1 row_mask:0xf bank_mask:0xf
	v_fmac_f32_dpp v205, v111, v221 row_ror:1 row_mask:0xf bank_mask:0xf
	v_fmac_f32_dpp v202, v92, v128 row_shl:1 row_mask:0xf bank_mask:0xf
	v_fmac_f32_dpp v203, v93, v129 row_shl:1 row_mask:0xf bank_mask:0xf
	v_fmac_f32_dpp v204, v94, v130 row_shl:1 row_mask:0xf bank_mask:0xf
	v_fmac_f32_dpp v205, v95, v131 row_shl:1 row_mask:0xf bank_mask:0xf
	v_fmac_f32_dpp v202, v76, v222 row_ror:15 row_mask:0xf bank_mask:0xf
	v_fmac_f32_dpp v203, v77, v223 row_ror:15 row_mask:0xf bank_mask:0xf
	v_fmac_f32_dpp v204, v78, v224 row_ror:15 row_mask:0xf bank_mask:0xf
	v_fmac_f32_dpp v205, v79, v225 row_ror:15 row_mask:0xf bank_mask:0xf
	v_fma_f32 v206, v164, v84, v182
	v_fma_f32 v207, v165, v85, v183
	v_fma_f32 v208, v166, v86, v184
	v_fma_f32 v209, v167, v87, v185
	v_fmac_f32_dpp v206, v84, v160 row_shr:1 row_mask:0xf bank_mask:0xf
	v_fmac_f32_dpp v207, v85, v161 row_shr:1 row_mask:0xf bank_mask:0xf
	v_fmac_f32_dpp v208, v86, v162 row_shr:1 row_mask:0xf bank_mask:0xf
	v_fmac_f32_dpp v209, v87, v163 row_shr:1 row_mask:0xf bank_mask:0xf
	v_fmac_f32_dpp v206, v100, v226 row_ror:1 row_mask:0xf bank_mask:0xf
	v_fmac_f32_dpp v207, v101, v227 row_ror:1 row_mask:0xf bank_mask:0xf
	v_fmac_f32_dpp v208, v102, v228 row_ror:1 row_mask:0xf bank_mask:0xf
	v_fmac_f32_dpp v209, v103, v229 row_ror:1 row_mask:0xf bank_mask:0xf
	v_fmac_f32_dpp v206, v84, v178 row_shl:1 row_mask:0xf bank_mask:0xf
	v_fmac_f32_dpp v207, v85, v179 row_shl:1 row_mask:0xf bank_mask:0xf
	v_fmac_f32_dpp v208, v86, v180 row_shl:1 row_mask:0xf bank_mask:0xf
	v_fmac_f32_dpp v209, v87, v181 row_shl:1 row_mask:0xf bank_mask:0xf
	v_fmac_f32_dpp v206, v68, v232 row_ror:15 row_mask:0xf bank_mask:0xf
	v_fmac_f32_dpp v207, v69, v233 row_ror:15 row_mask:0xf bank_mask:0xf
	v_fmac_f32_dpp v208, v70, v234 row_ror:15 row_mask:0xf bank_mask:0xf
	v_fmac_f32_dpp v209, v71, v235 row_ror:15 row_mask:0xf bank_mask:0xf
	v_mul_f32_e32 v210, 0xbfb8aa3b, v202
	v_mul_f32_e32 v211, 0xbfb8aa3b, v203
	v_mul_f32_e32 v212, 0xbfb8aa3b, v204
	v_mul_f32_e32 v213, 0xbfb8aa3b, v205
	v_exp_f32_e32 v210, v210
	v_exp_f32_e32 v211, v211
	v_exp_f32_e32 v212, v212
	v_exp_f32_e32 v213, v213
	v_add_f32_e32 v210, 1.0, v210
	v_add_f32_e32 v211, 1.0, v211
	v_add_f32_e32 v212, 1.0, v212
	v_add_f32_e32 v213, 1.0, v213
	v_rcp_f32_e32 v210, v210
	v_rcp_f32_e32 v211, v211
	v_rcp_f32_e32 v212, v212
	v_rcp_f32_e32 v213, v213
	v_mul_f32_e32 v202, v202, v210
	v_mul_f32_e32 v203, v203, v211
	v_mul_f32_e32 v204, v204, v212
	v_mul_f32_e32 v205, v205, v213
	v_mul_f32_e32 v202, v202, v206
	v_mul_f32_e32 v203, v203, v207
	v_mul_f32_e32 v204, v204, v208
	v_mul_f32_e32 v205, v205, v209
	v_cvt_pk_bf16_f32 v240, v202, v203
	v_cvt_pk_bf16_f32 v241, v204, v205
	v_fma_f32 v202, v124, v76, v132
	v_fma_f32 v203, v125, v77, v133
	v_fma_f32 v204, v126, v78, v134
	v_fma_f32 v205, v127, v79, v135
	v_fmac_f32_dpp v202, v76, v116 row_shr:1 row_mask:0xf bank_mask:0xf
	v_fmac_f32_dpp v203, v77, v117 row_shr:1 row_mask:0xf bank_mask:0xf
	v_fmac_f32_dpp v204, v78, v118 row_shr:1 row_mask:0xf bank_mask:0xf
	v_fmac_f32_dpp v205, v79, v119 row_shr:1 row_mask:0xf bank_mask:0xf
	v_fmac_f32_dpp v202, v92, v218 row_ror:1 row_mask:0xf bank_mask:0xf
	v_fmac_f32_dpp v203, v93, v219 row_ror:1 row_mask:0xf bank_mask:0xf
	v_fmac_f32_dpp v204, v94, v220 row_ror:1 row_mask:0xf bank_mask:0xf
	v_fmac_f32_dpp v205, v95, v221 row_ror:1 row_mask:0xf bank_mask:0xf
	v_fmac_f32_dpp v202, v76, v128 row_shl:1 row_mask:0xf bank_mask:0xf
	v_fmac_f32_dpp v203, v77, v129 row_shl:1 row_mask:0xf bank_mask:0xf
	v_fmac_f32_dpp v204, v78, v130 row_shl:1 row_mask:0xf bank_mask:0xf
	v_fmac_f32_dpp v205, v79, v131 row_shl:1 row_mask:0xf bank_mask:0xf
	v_fmac_f32_e32 v202, v186, v222
	v_fmac_f32_e32 v203, v187, v223
	v_fmac_f32_e32 v204, v188, v224
	v_fmac_f32_e32 v205, v189, v225
	v_fma_f32 v206, v164, v68, v182
	v_fma_f32 v207, v165, v69, v183
	v_fma_f32 v208, v166, v70, v184
	v_fma_f32 v209, v167, v71, v185
	v_fmac_f32_dpp v206, v68, v160 row_shr:1 row_mask:0xf bank_mask:0xf
	v_fmac_f32_dpp v207, v69, v161 row_shr:1 row_mask:0xf bank_mask:0xf
	v_fmac_f32_dpp v208, v70, v162 row_shr:1 row_mask:0xf bank_mask:0xf
	v_fmac_f32_dpp v209, v71, v163 row_shr:1 row_mask:0xf bank_mask:0xf
	v_fmac_f32_dpp v206, v84, v226 row_ror:1 row_mask:0xf bank_mask:0xf
	v_fmac_f32_dpp v207, v85, v227 row_ror:1 row_mask:0xf bank_mask:0xf
	v_fmac_f32_dpp v208, v86, v228 row_ror:1 row_mask:0xf bank_mask:0xf
	v_fmac_f32_dpp v209, v87, v229 row_ror:1 row_mask:0xf bank_mask:0xf
	v_fmac_f32_dpp v206, v68, v178 row_shl:1 row_mask:0xf bank_mask:0xf
	v_fmac_f32_dpp v207, v69, v179 row_shl:1 row_mask:0xf bank_mask:0xf
	v_fmac_f32_dpp v208, v70, v180 row_shl:1 row_mask:0xf bank_mask:0xf
	v_fmac_f32_dpp v209, v71, v181 row_shl:1 row_mask:0xf bank_mask:0xf
	v_fmac_f32_e32 v206, v190, v232
	v_fmac_f32_e32 v207, v191, v233
	v_fmac_f32_e32 v208, v192, v234
	v_fmac_f32_e32 v209, v193, v235
	v_mul_f32_e32 v210, 0xbfb8aa3b, v202
	v_mul_f32_e32 v211, 0xbfb8aa3b, v203
	v_mul_f32_e32 v212, 0xbfb8aa3b, v204
	v_mul_f32_e32 v213, 0xbfb8aa3b, v205
	v_exp_f32_e32 v210, v210
	v_exp_f32_e32 v211, v211
	v_exp_f32_e32 v212, v212
	v_exp_f32_e32 v213, v213
	v_add_f32_e32 v210, 1.0, v210
	v_add_f32_e32 v211, 1.0, v211
	v_add_f32_e32 v212, 1.0, v212
	v_add_f32_e32 v213, 1.0, v213
	v_rcp_f32_e32 v210, v210
	v_rcp_f32_e32 v211, v211
	v_rcp_f32_e32 v212, v212
	v_rcp_f32_e32 v213, v213
	v_mul_f32_e32 v202, v202, v210
	v_mul_f32_e32 v203, v203, v211
	v_mul_f32_e32 v204, v204, v212
	v_mul_f32_e32 v205, v205, v213
	v_mul_f32_e32 v202, v202, v206
	v_mul_f32_e32 v203, v203, v207
	v_mul_f32_e32 v204, v204, v208
	v_mul_f32_e32 v205, v205, v209
	v_cvt_pk_bf16_f32 v242, v202, v203
	v_cvt_pk_bf16_f32 v243, v204, v205
	v_fma_f32 v202, v124, v60, v132
	v_fma_f32 v203, v125, v61, v133
	v_fma_f32 v204, v126, v62, v134
	v_fma_f32 v205, v127, v63, v135
	v_fmac_f32_dpp v202, v60, v116 row_shr:1 row_mask:0xf bank_mask:0xf
	v_fmac_f32_dpp v203, v61, v117 row_shr:1 row_mask:0xf bank_mask:0xf
	v_fmac_f32_dpp v204, v62, v118 row_shr:1 row_mask:0xf bank_mask:0xf
	v_fmac_f32_dpp v205, v63, v119 row_shr:1 row_mask:0xf bank_mask:0xf
	v_fmac_f32_e32 v202, v194, v218
	v_fmac_f32_e32 v203, v195, v219
	v_fmac_f32_e32 v204, v196, v220
	v_fmac_f32_e32 v205, v197, v221
	v_fmac_f32_dpp v202, v60, v128 row_shl:1 row_mask:0xf bank_mask:0xf
	v_fmac_f32_dpp v203, v61, v129 row_shl:1 row_mask:0xf bank_mask:0xf
	v_fmac_f32_dpp v204, v62, v130 row_shl:1 row_mask:0xf bank_mask:0xf
	v_fmac_f32_dpp v205, v63, v131 row_shl:1 row_mask:0xf bank_mask:0xf
	v_fmac_f32_dpp v202, v44, v222 row_ror:15 row_mask:0xf bank_mask:0xf
	v_fmac_f32_dpp v203, v45, v223 row_ror:15 row_mask:0xf bank_mask:0xf
	v_fmac_f32_dpp v204, v46, v224 row_ror:15 row_mask:0xf bank_mask:0xf
	v_fmac_f32_dpp v205, v47, v225 row_ror:15 row_mask:0xf bank_mask:0xf
	v_fma_f32 v206, v164, v52, v182
	v_fma_f32 v207, v165, v53, v183
	v_fma_f32 v208, v166, v54, v184
	v_fma_f32 v209, v167, v55, v185
	v_fmac_f32_dpp v206, v52, v160 row_shr:1 row_mask:0xf bank_mask:0xf
	v_fmac_f32_dpp v207, v53, v161 row_shr:1 row_mask:0xf bank_mask:0xf
	v_fmac_f32_dpp v208, v54, v162 row_shr:1 row_mask:0xf bank_mask:0xf
	v_fmac_f32_dpp v209, v55, v163 row_shr:1 row_mask:0xf bank_mask:0xf
	v_fmac_f32_e32 v206, v198, v226
	v_fmac_f32_e32 v207, v199, v227
	v_fmac_f32_e32 v208, v200, v228
	v_fmac_f32_e32 v209, v201, v229
	v_fmac_f32_dpp v206, v52, v178 row_shl:1 row_mask:0xf bank_mask:0xf
	v_fmac_f32_dpp v207, v53, v179 row_shl:1 row_mask:0xf bank_mask:0xf
	v_fmac_f32_dpp v208, v54, v180 row_shl:1 row_mask:0xf bank_mask:0xf
	v_fmac_f32_dpp v209, v55, v181 row_shl:1 row_mask:0xf bank_mask:0xf
	v_fmac_f32_dpp v206, v36, v232 row_ror:15 row_mask:0xf bank_mask:0xf
	v_fmac_f32_dpp v207, v37, v233 row_ror:15 row_mask:0xf bank_mask:0xf
	v_fmac_f32_dpp v208, v38, v234 row_ror:15 row_mask:0xf bank_mask:0xf
	v_fmac_f32_dpp v209, v39, v235 row_ror:15 row_mask:0xf bank_mask:0xf
	v_mul_f32_e32 v210, 0xbfb8aa3b, v202
	v_mul_f32_e32 v211, 0xbfb8aa3b, v203
	v_mul_f32_e32 v212, 0xbfb8aa3b, v204
	v_mul_f32_e32 v213, 0xbfb8aa3b, v205
	v_exp_f32_e32 v210, v210
	v_exp_f32_e32 v211, v211
	v_exp_f32_e32 v212, v212
	v_exp_f32_e32 v213, v213
	v_add_f32_e32 v210, 1.0, v210
	v_add_f32_e32 v211, 1.0, v211
	v_add_f32_e32 v212, 1.0, v212
	v_add_f32_e32 v213, 1.0, v213
	v_rcp_f32_e32 v210, v210
	v_rcp_f32_e32 v211, v211
	v_rcp_f32_e32 v212, v212
	v_rcp_f32_e32 v213, v213
	v_mul_f32_e32 v202, v202, v210
	v_mul_f32_e32 v203, v203, v211
	v_mul_f32_e32 v204, v204, v212
	v_mul_f32_e32 v205, v205, v213
	v_mul_f32_e32 v202, v202, v206
	v_mul_f32_e32 v203, v203, v207
	v_mul_f32_e32 v204, v204, v208
	v_mul_f32_e32 v205, v205, v209
	v_cvt_pk_bf16_f32 v244, v202, v203
	v_cvt_pk_bf16_f32 v245, v204, v205
	v_fma_f32 v202, v124, v44, v132
	v_fma_f32 v203, v125, v45, v133
	v_fma_f32 v204, v126, v46, v134
	v_fma_f32 v205, v127, v47, v135
	v_fmac_f32_dpp v202, v44, v116 row_shr:1 row_mask:0xf bank_mask:0xf
	v_fmac_f32_dpp v203, v45, v117 row_shr:1 row_mask:0xf bank_mask:0xf
	v_fmac_f32_dpp v204, v46, v118 row_shr:1 row_mask:0xf bank_mask:0xf
	v_fmac_f32_dpp v205, v47, v119 row_shr:1 row_mask:0xf bank_mask:0xf
	v_fmac_f32_dpp v202, v60, v218 row_ror:1 row_mask:0xf bank_mask:0xf
	v_fmac_f32_dpp v203, v61, v219 row_ror:1 row_mask:0xf bank_mask:0xf
	v_fmac_f32_dpp v204, v62, v220 row_ror:1 row_mask:0xf bank_mask:0xf
	v_fmac_f32_dpp v205, v63, v221 row_ror:1 row_mask:0xf bank_mask:0xf
	v_fmac_f32_dpp v202, v44, v128 row_shl:1 row_mask:0xf bank_mask:0xf
	v_fmac_f32_dpp v203, v45, v129 row_shl:1 row_mask:0xf bank_mask:0xf
	v_fmac_f32_dpp v204, v46, v130 row_shl:1 row_mask:0xf bank_mask:0xf
	v_fmac_f32_dpp v205, v47, v131 row_shl:1 row_mask:0xf bank_mask:0xf
	v_fmac_f32_dpp v202, v28, v222 row_ror:15 row_mask:0xf bank_mask:0xf
	v_fmac_f32_dpp v203, v29, v223 row_ror:15 row_mask:0xf bank_mask:0xf
	v_fmac_f32_dpp v204, v30, v224 row_ror:15 row_mask:0xf bank_mask:0xf
	v_fmac_f32_dpp v205, v31, v225 row_ror:15 row_mask:0xf bank_mask:0xf
	v_fma_f32 v206, v164, v36, v182
	v_fma_f32 v207, v165, v37, v183
	v_fma_f32 v208, v166, v38, v184
	v_fma_f32 v209, v167, v39, v185
	v_fmac_f32_dpp v206, v36, v160 row_shr:1 row_mask:0xf bank_mask:0xf
	v_fmac_f32_dpp v207, v37, v161 row_shr:1 row_mask:0xf bank_mask:0xf
	v_fmac_f32_dpp v208, v38, v162 row_shr:1 row_mask:0xf bank_mask:0xf
	v_fmac_f32_dpp v209, v39, v163 row_shr:1 row_mask:0xf bank_mask:0xf
	v_fmac_f32_dpp v206, v52, v226 row_ror:1 row_mask:0xf bank_mask:0xf
	v_fmac_f32_dpp v207, v53, v227 row_ror:1 row_mask:0xf bank_mask:0xf
	v_fmac_f32_dpp v208, v54, v228 row_ror:1 row_mask:0xf bank_mask:0xf
	v_fmac_f32_dpp v209, v55, v229 row_ror:1 row_mask:0xf bank_mask:0xf
	v_fmac_f32_dpp v206, v36, v178 row_shl:1 row_mask:0xf bank_mask:0xf
	v_fmac_f32_dpp v207, v37, v179 row_shl:1 row_mask:0xf bank_mask:0xf
	v_fmac_f32_dpp v208, v38, v180 row_shl:1 row_mask:0xf bank_mask:0xf
	v_fmac_f32_dpp v209, v39, v181 row_shl:1 row_mask:0xf bank_mask:0xf
	v_fmac_f32_dpp v206, v20, v232 row_ror:15 row_mask:0xf bank_mask:0xf
	v_fmac_f32_dpp v207, v21, v233 row_ror:15 row_mask:0xf bank_mask:0xf
	v_fmac_f32_dpp v208, v22, v234 row_ror:15 row_mask:0xf bank_mask:0xf
	v_fmac_f32_dpp v209, v23, v235 row_ror:15 row_mask:0xf bank_mask:0xf
	v_mul_f32_e32 v210, 0xbfb8aa3b, v202
	v_mul_f32_e32 v211, 0xbfb8aa3b, v203
	v_mul_f32_e32 v212, 0xbfb8aa3b, v204
	v_mul_f32_e32 v213, 0xbfb8aa3b, v205
	v_exp_f32_e32 v210, v210
	v_exp_f32_e32 v211, v211
	v_exp_f32_e32 v212, v212
	v_exp_f32_e32 v213, v213
	v_add_f32_e32 v210, 1.0, v210
	v_add_f32_e32 v211, 1.0, v211
	v_add_f32_e32 v212, 1.0, v212
	v_add_f32_e32 v213, 1.0, v213
	v_rcp_f32_e32 v210, v210
	v_rcp_f32_e32 v211, v211
	v_rcp_f32_e32 v212, v212
	v_rcp_f32_e32 v213, v213
	v_mul_f32_e32 v202, v202, v210
	v_mul_f32_e32 v203, v203, v211
	v_mul_f32_e32 v204, v204, v212
	v_mul_f32_e32 v205, v205, v213
	v_mul_f32_e32 v202, v202, v206
	v_mul_f32_e32 v203, v203, v207
	v_mul_f32_e32 v204, v204, v208
	v_mul_f32_e32 v205, v205, v209
	v_cvt_pk_bf16_f32 v246, v202, v203
	v_cvt_pk_bf16_f32 v247, v204, v205
	v_fma_f32 v202, v124, v28, v132
	v_fma_f32 v203, v125, v29, v133
	v_fma_f32 v204, v126, v30, v134
	v_fma_f32 v205, v127, v31, v135
	v_fmac_f32_dpp v202, v28, v116 row_shr:1 row_mask:0xf bank_mask:0xf
	v_fmac_f32_dpp v203, v29, v117 row_shr:1 row_mask:0xf bank_mask:0xf
	v_fmac_f32_dpp v204, v30, v118 row_shr:1 row_mask:0xf bank_mask:0xf
	v_fmac_f32_dpp v205, v31, v119 row_shr:1 row_mask:0xf bank_mask:0xf
	v_fmac_f32_dpp v202, v44, v218 row_ror:1 row_mask:0xf bank_mask:0xf
	v_fmac_f32_dpp v203, v45, v219 row_ror:1 row_mask:0xf bank_mask:0xf
	v_fmac_f32_dpp v204, v46, v220 row_ror:1 row_mask:0xf bank_mask:0xf
	v_fmac_f32_dpp v205, v47, v221 row_ror:1 row_mask:0xf bank_mask:0xf
	v_fmac_f32_dpp v202, v28, v128 row_shl:1 row_mask:0xf bank_mask:0xf
	v_fmac_f32_dpp v203, v29, v129 row_shl:1 row_mask:0xf bank_mask:0xf
	v_fmac_f32_dpp v204, v30, v130 row_shl:1 row_mask:0xf bank_mask:0xf
	v_fmac_f32_dpp v205, v31, v131 row_shl:1 row_mask:0xf bank_mask:0xf
	v_fmac_f32_dpp v202, v12, v222 row_ror:15 row_mask:0xf bank_mask:0xf
	v_fmac_f32_dpp v203, v13, v223 row_ror:15 row_mask:0xf bank_mask:0xf
	v_fmac_f32_dpp v204, v14, v224 row_ror:15 row_mask:0xf bank_mask:0xf
	v_fmac_f32_dpp v205, v15, v225 row_ror:15 row_mask:0xf bank_mask:0xf
	v_fma_f32 v206, v164, v20, v182
	v_fma_f32 v207, v165, v21, v183
	v_fma_f32 v208, v166, v22, v184
	v_fma_f32 v209, v167, v23, v185
	v_fmac_f32_dpp v206, v20, v160 row_shr:1 row_mask:0xf bank_mask:0xf
	v_fmac_f32_dpp v207, v21, v161 row_shr:1 row_mask:0xf bank_mask:0xf
	v_fmac_f32_dpp v208, v22, v162 row_shr:1 row_mask:0xf bank_mask:0xf
	v_fmac_f32_dpp v209, v23, v163 row_shr:1 row_mask:0xf bank_mask:0xf
	v_fmac_f32_dpp v206, v36, v226 row_ror:1 row_mask:0xf bank_mask:0xf
	v_fmac_f32_dpp v207, v37, v227 row_ror:1 row_mask:0xf bank_mask:0xf
	v_fmac_f32_dpp v208, v38, v228 row_ror:1 row_mask:0xf bank_mask:0xf
	v_fmac_f32_dpp v209, v39, v229 row_ror:1 row_mask:0xf bank_mask:0xf
	v_fmac_f32_dpp v206, v20, v178 row_shl:1 row_mask:0xf bank_mask:0xf
	v_fmac_f32_dpp v207, v21, v179 row_shl:1 row_mask:0xf bank_mask:0xf
	v_fmac_f32_dpp v208, v22, v180 row_shl:1 row_mask:0xf bank_mask:0xf
	v_fmac_f32_dpp v209, v23, v181 row_shl:1 row_mask:0xf bank_mask:0xf
	v_fmac_f32_dpp v206, v4, v232 row_ror:15 row_mask:0xf bank_mask:0xf
	v_fmac_f32_dpp v207, v5, v233 row_ror:15 row_mask:0xf bank_mask:0xf
	v_fmac_f32_dpp v208, v6, v234 row_ror:15 row_mask:0xf bank_mask:0xf
	v_fmac_f32_dpp v209, v7, v235 row_ror:15 row_mask:0xf bank_mask:0xf
	v_mul_f32_e32 v210, 0xbfb8aa3b, v202
	v_mul_f32_e32 v211, 0xbfb8aa3b, v203
	v_mul_f32_e32 v212, 0xbfb8aa3b, v204
	v_mul_f32_e32 v213, 0xbfb8aa3b, v205
	v_exp_f32_e32 v210, v210
	v_exp_f32_e32 v211, v211
	v_exp_f32_e32 v212, v212
	v_exp_f32_e32 v213, v213
	v_add_f32_e32 v210, 1.0, v210
	v_add_f32_e32 v211, 1.0, v211
	v_add_f32_e32 v212, 1.0, v212
	v_add_f32_e32 v213, 1.0, v213
	v_rcp_f32_e32 v210, v210
	v_rcp_f32_e32 v211, v211
	v_rcp_f32_e32 v212, v212
	v_rcp_f32_e32 v213, v213
	v_mul_f32_e32 v202, v202, v210
	v_mul_f32_e32 v203, v203, v211
	v_mul_f32_e32 v204, v204, v212
	v_mul_f32_e32 v205, v205, v213
	v_mul_f32_e32 v202, v202, v206
	v_mul_f32_e32 v203, v203, v207
	v_mul_f32_e32 v204, v204, v208
	v_mul_f32_e32 v205, v205, v209
	v_cvt_pk_bf16_f32 v248, v202, v203
	v_cvt_pk_bf16_f32 v249, v204, v205
	v_fma_f32 v202, v124, v12, v132
	v_fma_f32 v203, v125, v13, v133
	v_fma_f32 v204, v126, v14, v134
	v_fma_f32 v205, v127, v15, v135
	v_fmac_f32_dpp v202, v12, v116 row_shr:1 row_mask:0xf bank_mask:0xf
	v_fmac_f32_dpp v203, v13, v117 row_shr:1 row_mask:0xf bank_mask:0xf
	v_fmac_f32_dpp v204, v14, v118 row_shr:1 row_mask:0xf bank_mask:0xf
	v_fmac_f32_dpp v205, v15, v119 row_shr:1 row_mask:0xf bank_mask:0xf
	v_fmac_f32_dpp v202, v28, v218 row_ror:1 row_mask:0xf bank_mask:0xf
	v_fmac_f32_dpp v203, v29, v219 row_ror:1 row_mask:0xf bank_mask:0xf
	v_fmac_f32_dpp v204, v30, v220 row_ror:1 row_mask:0xf bank_mask:0xf
	v_fmac_f32_dpp v205, v31, v221 row_ror:1 row_mask:0xf bank_mask:0xf
	v_fmac_f32_dpp v202, v12, v128 row_shl:1 row_mask:0xf bank_mask:0xf
	v_fmac_f32_dpp v203, v13, v129 row_shl:1 row_mask:0xf bank_mask:0xf
	v_fmac_f32_dpp v204, v14, v130 row_shl:1 row_mask:0xf bank_mask:0xf
	v_fmac_f32_dpp v205, v15, v131 row_shl:1 row_mask:0xf bank_mask:0xf
	v_fmac_f32_e32 v202, v194, v222
	v_fmac_f32_e32 v203, v195, v223
	v_fmac_f32_e32 v204, v196, v224
	v_fmac_f32_e32 v205, v197, v225
	v_fma_f32 v206, v164, v4, v182
	v_fma_f32 v207, v165, v5, v183
	v_fma_f32 v208, v166, v6, v184
	v_fma_f32 v209, v167, v7, v185
	v_fmac_f32_dpp v206, v4, v160 row_shr:1 row_mask:0xf bank_mask:0xf
	v_fmac_f32_dpp v207, v5, v161 row_shr:1 row_mask:0xf bank_mask:0xf
	v_fmac_f32_dpp v208, v6, v162 row_shr:1 row_mask:0xf bank_mask:0xf
	v_fmac_f32_dpp v209, v7, v163 row_shr:1 row_mask:0xf bank_mask:0xf
	v_fmac_f32_dpp v206, v20, v226 row_ror:1 row_mask:0xf bank_mask:0xf
	v_fmac_f32_dpp v207, v21, v227 row_ror:1 row_mask:0xf bank_mask:0xf
	v_fmac_f32_dpp v208, v22, v228 row_ror:1 row_mask:0xf bank_mask:0xf
	v_fmac_f32_dpp v209, v23, v229 row_ror:1 row_mask:0xf bank_mask:0xf
	v_fmac_f32_dpp v206, v4, v178 row_shl:1 row_mask:0xf bank_mask:0xf
	v_fmac_f32_dpp v207, v5, v179 row_shl:1 row_mask:0xf bank_mask:0xf
	v_fmac_f32_dpp v208, v6, v180 row_shl:1 row_mask:0xf bank_mask:0xf
	v_fmac_f32_dpp v209, v7, v181 row_shl:1 row_mask:0xf bank_mask:0xf
	v_fmac_f32_e32 v206, v198, v232
	v_fmac_f32_e32 v207, v199, v233
	v_fmac_f32_e32 v208, v200, v234
	v_fmac_f32_e32 v209, v201, v235
	s_mov_b64 exec, s[94:95]
	v_add_u32_e32 v250, 0x10800, v177
	global_store_dwordx4 v250, v[202:205], s[98:99]
	v_add_u32_e32 v250, 0x13400, v177
	global_store_dwordx4 v250, v[206:209], s[98:99]
	s_mov_b64 exec, s[90:91]
	s_nop 4
	v_mul_f32_e32 v210, 0xbfb8aa3b, v202
	v_mul_f32_e32 v211, 0xbfb8aa3b, v203
	v_mul_f32_e32 v212, 0xbfb8aa3b, v204
	v_mul_f32_e32 v213, 0xbfb8aa3b, v205
	v_exp_f32_e32 v210, v210
	v_exp_f32_e32 v211, v211
	v_exp_f32_e32 v212, v212
	v_exp_f32_e32 v213, v213
	v_add_f32_e32 v210, 1.0, v210
	v_add_f32_e32 v211, 1.0, v211
	v_add_f32_e32 v212, 1.0, v212
	v_add_f32_e32 v213, 1.0, v213
	v_rcp_f32_e32 v210, v210
	v_rcp_f32_e32 v211, v211
	v_rcp_f32_e32 v212, v212
	v_rcp_f32_e32 v213, v213
	v_mul_f32_e32 v202, v202, v210
	v_mul_f32_e32 v203, v203, v211
	v_mul_f32_e32 v204, v204, v212
	v_mul_f32_e32 v205, v205, v213
	v_mul_f32_e32 v202, v202, v206
	v_mul_f32_e32 v203, v203, v207
	v_mul_f32_e32 v204, v204, v208
	v_mul_f32_e32 v205, v205, v209
	v_cvt_pk_bf16_f32 v250, v202, v203
	v_cvt_pk_bf16_f32 v251, v204, v205
	global_load_dwordx4 v[116:119], v177, s[2:3] offset:16
	v_add_u32_e32 v213, 0x5800, v177
	global_load_dwordx4 v[124:127], v213, s[2:3] offset:16
	v_add_u32_e32 v212, 0xb000, v177
	global_load_dwordx4 v[128:131], v212, s[2:3] offset:16
	global_load_dwordx4 v[132:135], v177, s[28:29] offset:16
	v_add_u32_e32 v212, 0x2c00, v177
	global_load_dwordx4 v[160:163], v212, s[2:3] offset:16
	v_add_u32_e32 v213, 0x8400, v177
	global_load_dwordx4 v[164:167], v213, s[2:3] offset:16
	v_add_u32_e32 v212, 0xdc00, v177
	global_load_dwordx4 v[178:181], v212, s[2:3] offset:16
	v_add_u32_e32 v213, 0x2c00, v177
	global_load_dwordx4 v[182:185], v213, s[28:29] offset:16
	v_mov_b32_e32 v140, v236
	v_mov_b32_e32 v141, v237
	v_mov_b32_e32 v108, v238
	v_mov_b32_e32 v109, v239
	v_mov_b32_e32 v92, v240
	v_mov_b32_e32 v93, v241
	v_mov_b32_e32 v76, v242
	v_mov_b32_e32 v77, v243
	v_mov_b32_e32 v60, v244
	v_mov_b32_e32 v61, v245
	v_mov_b32_e32 v44, v246
	v_mov_b32_e32 v45, v247
	v_mov_b32_e32 v28, v248
	v_mov_b32_e32 v29, v249
	v_mov_b32_e32 v12, v250
	v_mov_b32_e32 v13, v251
	ds_read_b128 v[186:189], v231 offset:16
	ds_read_b128 v[190:193], v231 offset:528
	ds_read_b128 v[194:197], v231 offset:2064
	ds_read_b128 v[198:201], v231 offset:2576
	s_waitcnt vmcnt(0)
	v_cndmask_b32_e64 v218, 0, v116, s[78:79]
	v_cndmask_b32_e64 v222, 0, v128, s[80:81]
	v_cndmask_b32_e64 v219, 0, v117, s[78:79]
	v_cndmask_b32_e64 v223, 0, v129, s[80:81]
	v_cndmask_b32_e64 v220, 0, v118, s[78:79]
	v_cndmask_b32_e64 v224, 0, v130, s[80:81]
	v_cndmask_b32_e64 v221, 0, v119, s[78:79]
	v_cndmask_b32_e64 v225, 0, v131, s[80:81]
	v_cndmask_b32_e64 v226, 0, v160, s[78:79]
	v_cndmask_b32_e64 v232, 0, v178, s[80:81]
	v_cndmask_b32_e64 v227, 0, v161, s[78:79]
	v_cndmask_b32_e64 v233, 0, v179, s[80:81]
	v_cndmask_b32_e64 v228, 0, v162, s[78:79]
	v_cndmask_b32_e64 v234, 0, v180, s[80:81]
	v_cndmask_b32_e64 v229, 0, v163, s[78:79]
	v_cndmask_b32_e64 v235, 0, v181, s[80:81]
	s_waitcnt lgkmcnt(0)
	s_nop 1
	v_fma_f32 v202, v124, v136, v132
	v_fma_f32 v203, v125, v137, v133
	v_fma_f32 v204, v126, v138, v134
	v_fma_f32 v205, v127, v139, v135
	v_fmac_f32_dpp v202, v136, v116 row_shr:1 row_mask:0xf bank_mask:0xf
	v_fmac_f32_dpp v203, v137, v117 row_shr:1 row_mask:0xf bank_mask:0xf
	v_fmac_f32_dpp v204, v138, v118 row_shr:1 row_mask:0xf bank_mask:0xf
	v_fmac_f32_dpp v205, v139, v119 row_shr:1 row_mask:0xf bank_mask:0xf
	v_fmac_f32_e32 v202, v186, v218
	v_fmac_f32_e32 v203, v187, v219
	v_fmac_f32_e32 v204, v188, v220
	v_fmac_f32_e32 v205, v189, v221
	v_fmac_f32_dpp v202, v136, v128 row_shl:1 row_mask:0xf bank_mask:0xf
	v_fmac_f32_dpp v203, v137, v129 row_shl:1 row_mask:0xf bank_mask:0xf
	v_fmac_f32_dpp v204, v138, v130 row_shl:1 row_mask:0xf bank_mask:0xf
	v_fmac_f32_dpp v205, v139, v131 row_shl:1 row_mask:0xf bank_mask:0xf
	v_fmac_f32_dpp v202, v104, v222 row_ror:15 row_mask:0xf bank_mask:0xf
	v_fmac_f32_dpp v203, v105, v223 row_ror:15 row_mask:0xf bank_mask:0xf
	v_fmac_f32_dpp v204, v106, v224 row_ror:15 row_mask:0xf bank_mask:0xf
	v_fmac_f32_dpp v205, v107, v225 row_ror:15 row_mask:0xf bank_mask:0xf
	v_fma_f32 v206, v164, v112, v182
	v_fma_f32 v207, v165, v113, v183
	v_fma_f32 v208, v166, v114, v184
	v_fma_f32 v209, v167, v115, v185
	v_fmac_f32_dpp v206, v112, v160 row_shr:1 row_mask:0xf bank_mask:0xf
	v_fmac_f32_dpp v207, v113, v161 row_shr:1 row_mask:0xf bank_mask:0xf
	v_fmac_f32_dpp v208, v114, v162 row_shr:1 row_mask:0xf bank_mask:0xf
	v_fmac_f32_dpp v209, v115, v163 row_shr:1 row_mask:0xf bank_mask:0xf
	v_fmac_f32_e32 v206, v190, v226
	v_fmac_f32_e32 v207, v191, v227
	v_fmac_f32_e32 v208, v192, v228
	v_fmac_f32_e32 v209, v193, v229
	v_fmac_f32_dpp v206, v112, v178 row_shl:1 row_mask:0xf bank_mask:0xf
	v_fmac_f32_dpp v207, v113, v179 row_shl:1 row_mask:0xf bank_mask:0xf
	v_fmac_f32_dpp v208, v114, v180 row_shl:1 row_mask:0xf bank_mask:0xf
	v_fmac_f32_dpp v209, v115, v181 row_shl:1 row_mask:0xf bank_mask:0xf
	v_fmac_f32_dpp v206, v96, v232 row_ror:15 row_mask:0xf bank_mask:0xf
	v_fmac_f32_dpp v207, v97, v233 row_ror:15 row_mask:0xf bank_mask:0xf
	v_fmac_f32_dpp v208, v98, v234 row_ror:15 row_mask:0xf bank_mask:0xf
	v_fmac_f32_dpp v209, v99, v235 row_ror:15 row_mask:0xf bank_mask:0xf
	s_mov_b64 exec, s[92:93]
	v_add_u32_e32 v250, 0x5800, v177
	global_store_dwordx4 v250, v[202:205], s[98:99] offset:16
	v_add_u32_e32 v250, 0x8400, v177
	global_store_dwordx4 v250, v[206:209], s[98:99] offset:16
	s_mov_b64 exec, s[90:91]
	s_nop 4
	v_mul_f32_e32 v210, 0xbfb8aa3b, v202
	v_mul_f32_e32 v211, 0xbfb8aa3b, v203
	v_mul_f32_e32 v212, 0xbfb8aa3b, v204
	v_mul_f32_e32 v213, 0xbfb8aa3b, v205
	v_exp_f32_e32 v210, v210
	v_exp_f32_e32 v211, v211
	v_exp_f32_e32 v212, v212
	v_exp_f32_e32 v213, v213
	v_add_f32_e32 v210, 1.0, v210
	v_add_f32_e32 v211, 1.0, v211
	v_add_f32_e32 v212, 1.0, v212
	v_add_f32_e32 v213, 1.0, v213
	v_rcp_f32_e32 v210, v210
	v_rcp_f32_e32 v211, v211
	v_rcp_f32_e32 v212, v212
	v_rcp_f32_e32 v213, v213
	v_mul_f32_e32 v202, v202, v210
	v_mul_f32_e32 v203, v203, v211
	v_mul_f32_e32 v204, v204, v212
	v_mul_f32_e32 v205, v205, v213
	v_mul_f32_e32 v202, v202, v206
	v_mul_f32_e32 v203, v203, v207
	v_mul_f32_e32 v204, v204, v208
	v_mul_f32_e32 v205, v205, v209
	v_cvt_pk_bf16_f32 v142, v202, v203
	v_cvt_pk_bf16_f32 v143, v204, v205
	v_fma_f32 v202, v124, v104, v132
	v_fma_f32 v203, v125, v105, v133
	v_fma_f32 v204, v126, v106, v134
	v_fma_f32 v205, v127, v107, v135
	v_fmac_f32_dpp v202, v104, v116 row_shr:1 row_mask:0xf bank_mask:0xf
	v_fmac_f32_dpp v203, v105, v117 row_shr:1 row_mask:0xf bank_mask:0xf
	v_fmac_f32_dpp v204, v106, v118 row_shr:1 row_mask:0xf bank_mask:0xf
	v_fmac_f32_dpp v205, v107, v119 row_shr:1 row_mask:0xf bank_mask:0xf
	v_fmac_f32_dpp v202, v136, v218 row_ror:1 row_mask:0xf bank_mask:0xf
	v_fmac_f32_dpp v203, v137, v219 row_ror:1 row_mask:0xf bank_mask:0xf
	v_fmac_f32_dpp v204, v138, v220 row_ror:1 row_mask:0xf bank_mask:0xf
	v_fmac_f32_dpp v205, v139, v221 row_ror:1 row_mask:0xf bank_mask:0xf
	v_fmac_f32_dpp v202, v104, v128 row_shl:1 row_mask:0xf bank_mask:0xf
	v_fmac_f32_dpp v203, v105, v129 row_shl:1 row_mask:0xf bank_mask:0xf
	v_fmac_f32_dpp v204, v106, v130 row_shl:1 row_mask:0xf bank_mask:0xf
	v_fmac_f32_dpp v205, v107, v131 row_shl:1 row_mask:0xf bank_mask:0xf
	v_fmac_f32_dpp v202, v88, v222 row_ror:15 row_mask:0xf bank_mask:0xf
	v_fmac_f32_dpp v203, v89, v223 row_ror:15 row_mask:0xf bank_mask:0xf
	v_fmac_f32_dpp v204, v90, v224 row_ror:15 row_mask:0xf bank_mask:0xf
	v_fmac_f32_dpp v205, v91, v225 row_ror:15 row_mask:0xf bank_mask:0xf
	v_fma_f32 v206, v164, v96, v182
	v_fma_f32 v207, v165, v97, v183
	v_fma_f32 v208, v166, v98, v184
	v_fma_f32 v209, v167, v99, v185
	v_fmac_f32_dpp v206, v96, v160 row_shr:1 row_mask:0xf bank_mask:0xf
	v_fmac_f32_dpp v207, v97, v161 row_shr:1 row_mask:0xf bank_mask:0xf
	v_fmac_f32_dpp v208, v98, v162 row_shr:1 row_mask:0xf bank_mask:0xf
	v_fmac_f32_dpp v209, v99, v163 row_shr:1 row_mask:0xf bank_mask:0xf
	v_fmac_f32_dpp v206, v112, v226 row_ror:1 row_mask:0xf bank_mask:0xf
	v_fmac_f32_dpp v207, v113, v227 row_ror:1 row_mask:0xf bank_mask:0xf
	v_fmac_f32_dpp v208, v114, v228 row_ror:1 row_mask:0xf bank_mask:0xf
	v_fmac_f32_dpp v209, v115, v229 row_ror:1 row_mask:0xf bank_mask:0xf
	v_fmac_f32_dpp v206, v96, v178 row_shl:1 row_mask:0xf bank_mask:0xf
	v_fmac_f32_dpp v207, v97, v179 row_shl:1 row_mask:0xf bank_mask:0xf
	v_fmac_f32_dpp v208, v98, v180 row_shl:1 row_mask:0xf bank_mask:0xf
	v_fmac_f32_dpp v209, v99, v181 row_shl:1 row_mask:0xf bank_mask:0xf
	v_fmac_f32_dpp v206, v80, v232 row_ror:15 row_mask:0xf bank_mask:0xf
	v_fmac_f32_dpp v207, v81, v233 row_ror:15 row_mask:0xf bank_mask:0xf
	v_fmac_f32_dpp v208, v82, v234 row_ror:15 row_mask:0xf bank_mask:0xf
	v_fmac_f32_dpp v209, v83, v235 row_ror:15 row_mask:0xf bank_mask:0xf
	v_mul_f32_e32 v210, 0xbfb8aa3b, v202
	v_mul_f32_e32 v211, 0xbfb8aa3b, v203
	v_mul_f32_e32 v212, 0xbfb8aa3b, v204
	v_mul_f32_e32 v213, 0xbfb8aa3b, v205
	v_exp_f32_e32 v210, v210
	v_exp_f32_e32 v211, v211
	v_exp_f32_e32 v212, v212
	v_exp_f32_e32 v213, v213
	v_add_f32_e32 v210, 1.0, v210
	v_add_f32_e32 v211, 1.0, v211
	v_add_f32_e32 v212, 1.0, v212
	v_add_f32_e32 v213, 1.0, v213
	v_rcp_f32_e32 v210, v210
	v_rcp_f32_e32 v211, v211
	v_rcp_f32_e32 v212, v212
	v_rcp_f32_e32 v213, v213
	v_mul_f32_e32 v202, v202, v210
	v_mul_f32_e32 v203, v203, v211
	v_mul_f32_e32 v204, v204, v212
	v_mul_f32_e32 v205, v205, v213
	v_mul_f32_e32 v202, v202, v206
	v_mul_f32_e32 v203, v203, v207
	v_mul_f32_e32 v204, v204, v208
	v_mul_f32_e32 v205, v205, v209
	v_cvt_pk_bf16_f32 v110, v202, v203
	v_cvt_pk_bf16_f32 v111, v204, v205
	v_fma_f32 v202, v124, v88, v132
	v_fma_f32 v203, v125, v89, v133
	v_fma_f32 v204, v126, v90, v134
	v_fma_f32 v205, v127, v91, v135
	v_fmac_f32_dpp v202, v88, v116 row_shr:1 row_mask:0xf bank_mask:0xf
	v_fmac_f32_dpp v203, v89, v117 row_shr:1 row_mask:0xf bank_mask:0xf
	v_fmac_f32_dpp v204, v90, v118 row_shr:1 row_mask:0xf bank_mask:0xf
	v_fmac_f32_dpp v205, v91, v119 row_shr:1 row_mask:0xf bank_mask:0xf
	v_fmac_f32_dpp v202, v104, v218 row_ror:1 row_mask:0xf bank_mask:0xf
	v_fmac_f32_dpp v203, v105, v219 row_ror:1 row_mask:0xf bank_mask:0xf
	v_fmac_f32_dpp v204, v106, v220 row_ror:1 row_mask:0xf bank_mask:0xf
	v_fmac_f32_dpp v205, v107, v221 row_ror:1 row_mask:0xf bank_mask:0xf
	v_fmac_f32_dpp v202, v88, v128 row_shl:1 row_mask:0xf bank_mask:0xf
	v_fmac_f32_dpp v203, v89, v129 row_shl:1 row_mask:0xf bank_mask:0xf
	v_fmac_f32_dpp v204, v90, v130 row_shl:1 row_mask:0xf bank_mask:0xf
	v_fmac_f32_dpp v205, v91, v131 row_shl:1 row_mask:0xf bank_mask:0xf
	v_fmac_f32_dpp v202, v72, v222 row_ror:15 row_mask:0xf bank_mask:0xf
	v_fmac_f32_dpp v203, v73, v223 row_ror:15 row_mask:0xf bank_mask:0xf
	v_fmac_f32_dpp v204, v74, v224 row_ror:15 row_mask:0xf bank_mask:0xf
	v_fmac_f32_dpp v205, v75, v225 row_ror:15 row_mask:0xf bank_mask:0xf
	v_fma_f32 v206, v164, v80, v182
	v_fma_f32 v207, v165, v81, v183
	v_fma_f32 v208, v166, v82, v184
	v_fma_f32 v209, v167, v83, v185
	v_fmac_f32_dpp v206, v80, v160 row_shr:1 row_mask:0xf bank_mask:0xf
	v_fmac_f32_dpp v207, v81, v161 row_shr:1 row_mask:0xf bank_mask:0xf
	v_fmac_f32_dpp v208, v82, v162 row_shr:1 row_mask:0xf bank_mask:0xf
	v_fmac_f32_dpp v209, v83, v163 row_shr:1 row_mask:0xf bank_mask:0xf
	v_fmac_f32_dpp v206, v96, v226 row_ror:1 row_mask:0xf bank_mask:0xf
	v_fmac_f32_dpp v207, v97, v227 row_ror:1 row_mask:0xf bank_mask:0xf
	v_fmac_f32_dpp v208, v98, v228 row_ror:1 row_mask:0xf bank_mask:0xf
	v_fmac_f32_dpp v209, v99, v229 row_ror:1 row_mask:0xf bank_mask:0xf
	v_fmac_f32_dpp v206, v80, v178 row_shl:1 row_mask:0xf bank_mask:0xf
	v_fmac_f32_dpp v207, v81, v179 row_shl:1 row_mask:0xf bank_mask:0xf
	v_fmac_f32_dpp v208, v82, v180 row_shl:1 row_mask:0xf bank_mask:0xf
	v_fmac_f32_dpp v209, v83, v181 row_shl:1 row_mask:0xf bank_mask:0xf
	v_fmac_f32_dpp v206, v64, v232 row_ror:15 row_mask:0xf bank_mask:0xf
	v_fmac_f32_dpp v207, v65, v233 row_ror:15 row_mask:0xf bank_mask:0xf
	v_fmac_f32_dpp v208, v66, v234 row_ror:15 row_mask:0xf bank_mask:0xf
	v_fmac_f32_dpp v209, v67, v235 row_ror:15 row_mask:0xf bank_mask:0xf
	v_mul_f32_e32 v210, 0xbfb8aa3b, v202
	v_mul_f32_e32 v211, 0xbfb8aa3b, v203
	v_mul_f32_e32 v212, 0xbfb8aa3b, v204
	v_mul_f32_e32 v213, 0xbfb8aa3b, v205
	v_exp_f32_e32 v210, v210
	v_exp_f32_e32 v211, v211
	v_exp_f32_e32 v212, v212
	v_exp_f32_e32 v213, v213
	v_add_f32_e32 v210, 1.0, v210
	v_add_f32_e32 v211, 1.0, v211
	v_add_f32_e32 v212, 1.0, v212
	v_add_f32_e32 v213, 1.0, v213
	v_rcp_f32_e32 v210, v210
	v_rcp_f32_e32 v211, v211
	v_rcp_f32_e32 v212, v212
	v_rcp_f32_e32 v213, v213
	v_mul_f32_e32 v202, v202, v210
	v_mul_f32_e32 v203, v203, v211
	v_mul_f32_e32 v204, v204, v212
	v_mul_f32_e32 v205, v205, v213
	v_mul_f32_e32 v202, v202, v206
	v_mul_f32_e32 v203, v203, v207
	v_mul_f32_e32 v204, v204, v208
	v_mul_f32_e32 v205, v205, v209
	v_cvt_pk_bf16_f32 v94, v202, v203
	v_cvt_pk_bf16_f32 v95, v204, v205
	v_fma_f32 v202, v124, v72, v132
	v_fma_f32 v203, v125, v73, v133
	v_fma_f32 v204, v126, v74, v134
	v_fma_f32 v205, v127, v75, v135
	v_fmac_f32_dpp v202, v72, v116 row_shr:1 row_mask:0xf bank_mask:0xf
	v_fmac_f32_dpp v203, v73, v117 row_shr:1 row_mask:0xf bank_mask:0xf
	v_fmac_f32_dpp v204, v74, v118 row_shr:1 row_mask:0xf bank_mask:0xf
	v_fmac_f32_dpp v205, v75, v119 row_shr:1 row_mask:0xf bank_mask:0xf
	v_fmac_f32_dpp v202, v88, v218 row_ror:1 row_mask:0xf bank_mask:0xf
	v_fmac_f32_dpp v203, v89, v219 row_ror:1 row_mask:0xf bank_mask:0xf
	v_fmac_f32_dpp v204, v90, v220 row_ror:1 row_mask:0xf bank_mask:0xf
	v_fmac_f32_dpp v205, v91, v221 row_ror:1 row_mask:0xf bank_mask:0xf
	v_fmac_f32_dpp v202, v72, v128 row_shl:1 row_mask:0xf bank_mask:0xf
	v_fmac_f32_dpp v203, v73, v129 row_shl:1 row_mask:0xf bank_mask:0xf
	v_fmac_f32_dpp v204, v74, v130 row_shl:1 row_mask:0xf bank_mask:0xf
	v_fmac_f32_dpp v205, v75, v131 row_shl:1 row_mask:0xf bank_mask:0xf
	v_fmac_f32_e32 v202, v186, v222
	v_fmac_f32_e32 v203, v187, v223
	v_fmac_f32_e32 v204, v188, v224
	v_fmac_f32_e32 v205, v189, v225
	v_fma_f32 v206, v164, v64, v182
	v_fma_f32 v207, v165, v65, v183
	v_fma_f32 v208, v166, v66, v184
	v_fma_f32 v209, v167, v67, v185
	v_fmac_f32_dpp v206, v64, v160 row_shr:1 row_mask:0xf bank_mask:0xf
	v_fmac_f32_dpp v207, v65, v161 row_shr:1 row_mask:0xf bank_mask:0xf
	v_fmac_f32_dpp v208, v66, v162 row_shr:1 row_mask:0xf bank_mask:0xf
	v_fmac_f32_dpp v209, v67, v163 row_shr:1 row_mask:0xf bank_mask:0xf
	v_fmac_f32_dpp v206, v80, v226 row_ror:1 row_mask:0xf bank_mask:0xf
	v_fmac_f32_dpp v207, v81, v227 row_ror:1 row_mask:0xf bank_mask:0xf
	v_fmac_f32_dpp v208, v82, v228 row_ror:1 row_mask:0xf bank_mask:0xf
	v_fmac_f32_dpp v209, v83, v229 row_ror:1 row_mask:0xf bank_mask:0xf
	v_fmac_f32_dpp v206, v64, v178 row_shl:1 row_mask:0xf bank_mask:0xf
	v_fmac_f32_dpp v207, v65, v179 row_shl:1 row_mask:0xf bank_mask:0xf
	v_fmac_f32_dpp v208, v66, v180 row_shl:1 row_mask:0xf bank_mask:0xf
	v_fmac_f32_dpp v209, v67, v181 row_shl:1 row_mask:0xf bank_mask:0xf
	v_fmac_f32_e32 v206, v190, v232
	v_fmac_f32_e32 v207, v191, v233
	v_fmac_f32_e32 v208, v192, v234
	v_fmac_f32_e32 v209, v193, v235
	v_mul_f32_e32 v210, 0xbfb8aa3b, v202
	v_mul_f32_e32 v211, 0xbfb8aa3b, v203
	v_mul_f32_e32 v212, 0xbfb8aa3b, v204
	v_mul_f32_e32 v213, 0xbfb8aa3b, v205
	v_exp_f32_e32 v210, v210
	v_exp_f32_e32 v211, v211
	v_exp_f32_e32 v212, v212
	v_exp_f32_e32 v213, v213
	v_add_f32_e32 v210, 1.0, v210
	v_add_f32_e32 v211, 1.0, v211
	v_add_f32_e32 v212, 1.0, v212
	v_add_f32_e32 v213, 1.0, v213
	v_rcp_f32_e32 v210, v210
	v_rcp_f32_e32 v211, v211
	v_rcp_f32_e32 v212, v212
	v_rcp_f32_e32 v213, v213
	v_mul_f32_e32 v202, v202, v210
	v_mul_f32_e32 v203, v203, v211
	v_mul_f32_e32 v204, v204, v212
	v_mul_f32_e32 v205, v205, v213
	v_mul_f32_e32 v202, v202, v206
	v_mul_f32_e32 v203, v203, v207
	v_mul_f32_e32 v204, v204, v208
	v_mul_f32_e32 v205, v205, v209
	v_cvt_pk_bf16_f32 v78, v202, v203
	v_cvt_pk_bf16_f32 v79, v204, v205
	v_fma_f32 v202, v124, v56, v132
	v_fma_f32 v203, v125, v57, v133
	v_fma_f32 v204, v126, v58, v134
	v_fma_f32 v205, v127, v59, v135
	v_fmac_f32_dpp v202, v56, v116 row_shr:1 row_mask:0xf bank_mask:0xf
	v_fmac_f32_dpp v203, v57, v117 row_shr:1 row_mask:0xf bank_mask:0xf
	v_fmac_f32_dpp v204, v58, v118 row_shr:1 row_mask:0xf bank_mask:0xf
	v_fmac_f32_dpp v205, v59, v119 row_shr:1 row_mask:0xf bank_mask:0xf
	v_fmac_f32_e32 v202, v194, v218
	v_fmac_f32_e32 v203, v195, v219
	v_fmac_f32_e32 v204, v196, v220
	v_fmac_f32_e32 v205, v197, v221
	v_fmac_f32_dpp v202, v56, v128 row_shl:1 row_mask:0xf bank_mask:0xf
	v_fmac_f32_dpp v203, v57, v129 row_shl:1 row_mask:0xf bank_mask:0xf
	v_fmac_f32_dpp v204, v58, v130 row_shl:1 row_mask:0xf bank_mask:0xf
	v_fmac_f32_dpp v205, v59, v131 row_shl:1 row_mask:0xf bank_mask:0xf
	v_fmac_f32_dpp v202, v40, v222 row_ror:15 row_mask:0xf bank_mask:0xf
	v_fmac_f32_dpp v203, v41, v223 row_ror:15 row_mask:0xf bank_mask:0xf
	v_fmac_f32_dpp v204, v42, v224 row_ror:15 row_mask:0xf bank_mask:0xf
	v_fmac_f32_dpp v205, v43, v225 row_ror:15 row_mask:0xf bank_mask:0xf
	v_fma_f32 v206, v164, v48, v182
	v_fma_f32 v207, v165, v49, v183
	v_fma_f32 v208, v166, v50, v184
	v_fma_f32 v209, v167, v51, v185
	v_fmac_f32_dpp v206, v48, v160 row_shr:1 row_mask:0xf bank_mask:0xf
	v_fmac_f32_dpp v207, v49, v161 row_shr:1 row_mask:0xf bank_mask:0xf
	v_fmac_f32_dpp v208, v50, v162 row_shr:1 row_mask:0xf bank_mask:0xf
	v_fmac_f32_dpp v209, v51, v163 row_shr:1 row_mask:0xf bank_mask:0xf
	v_fmac_f32_e32 v206, v198, v226
	v_fmac_f32_e32 v207, v199, v227
	v_fmac_f32_e32 v208, v200, v228
	v_fmac_f32_e32 v209, v201, v229
	v_fmac_f32_dpp v206, v48, v178 row_shl:1 row_mask:0xf bank_mask:0xf
	v_fmac_f32_dpp v207, v49, v179 row_shl:1 row_mask:0xf bank_mask:0xf
	v_fmac_f32_dpp v208, v50, v180 row_shl:1 row_mask:0xf bank_mask:0xf
	v_fmac_f32_dpp v209, v51, v181 row_shl:1 row_mask:0xf bank_mask:0xf
	v_fmac_f32_dpp v206, v32, v232 row_ror:15 row_mask:0xf bank_mask:0xf
	v_fmac_f32_dpp v207, v33, v233 row_ror:15 row_mask:0xf bank_mask:0xf
	v_fmac_f32_dpp v208, v34, v234 row_ror:15 row_mask:0xf bank_mask:0xf
	v_fmac_f32_dpp v209, v35, v235 row_ror:15 row_mask:0xf bank_mask:0xf
	v_mul_f32_e32 v210, 0xbfb8aa3b, v202
	v_mul_f32_e32 v211, 0xbfb8aa3b, v203
	v_mul_f32_e32 v212, 0xbfb8aa3b, v204
	v_mul_f32_e32 v213, 0xbfb8aa3b, v205
	v_exp_f32_e32 v210, v210
	v_exp_f32_e32 v211, v211
	v_exp_f32_e32 v212, v212
	v_exp_f32_e32 v213, v213
	v_add_f32_e32 v210, 1.0, v210
	v_add_f32_e32 v211, 1.0, v211
	v_add_f32_e32 v212, 1.0, v212
	v_add_f32_e32 v213, 1.0, v213
	v_rcp_f32_e32 v210, v210
	v_rcp_f32_e32 v211, v211
	v_rcp_f32_e32 v212, v212
	v_rcp_f32_e32 v213, v213
	v_mul_f32_e32 v202, v202, v210
	v_mul_f32_e32 v203, v203, v211
	v_mul_f32_e32 v204, v204, v212
	v_mul_f32_e32 v205, v205, v213
	v_mul_f32_e32 v202, v202, v206
	v_mul_f32_e32 v203, v203, v207
	v_mul_f32_e32 v204, v204, v208
	v_mul_f32_e32 v205, v205, v209
	v_cvt_pk_bf16_f32 v62, v202, v203
	v_cvt_pk_bf16_f32 v63, v204, v205
	v_fma_f32 v202, v124, v40, v132
	v_fma_f32 v203, v125, v41, v133
	v_fma_f32 v204, v126, v42, v134
	v_fma_f32 v205, v127, v43, v135
	v_fmac_f32_dpp v202, v40, v116 row_shr:1 row_mask:0xf bank_mask:0xf
	v_fmac_f32_dpp v203, v41, v117 row_shr:1 row_mask:0xf bank_mask:0xf
	v_fmac_f32_dpp v204, v42, v118 row_shr:1 row_mask:0xf bank_mask:0xf
	v_fmac_f32_dpp v205, v43, v119 row_shr:1 row_mask:0xf bank_mask:0xf
	v_fmac_f32_dpp v202, v56, v218 row_ror:1 row_mask:0xf bank_mask:0xf
	v_fmac_f32_dpp v203, v57, v219 row_ror:1 row_mask:0xf bank_mask:0xf
	v_fmac_f32_dpp v204, v58, v220 row_ror:1 row_mask:0xf bank_mask:0xf
	v_fmac_f32_dpp v205, v59, v221 row_ror:1 row_mask:0xf bank_mask:0xf
	v_fmac_f32_dpp v202, v40, v128 row_shl:1 row_mask:0xf bank_mask:0xf
	v_fmac_f32_dpp v203, v41, v129 row_shl:1 row_mask:0xf bank_mask:0xf
	v_fmac_f32_dpp v204, v42, v130 row_shl:1 row_mask:0xf bank_mask:0xf
	v_fmac_f32_dpp v205, v43, v131 row_shl:1 row_mask:0xf bank_mask:0xf
	v_fmac_f32_dpp v202, v24, v222 row_ror:15 row_mask:0xf bank_mask:0xf
	v_fmac_f32_dpp v203, v25, v223 row_ror:15 row_mask:0xf bank_mask:0xf
	v_fmac_f32_dpp v204, v26, v224 row_ror:15 row_mask:0xf bank_mask:0xf
	v_fmac_f32_dpp v205, v27, v225 row_ror:15 row_mask:0xf bank_mask:0xf
	v_fma_f32 v206, v164, v32, v182
	v_fma_f32 v207, v165, v33, v183
	v_fma_f32 v208, v166, v34, v184
	v_fma_f32 v209, v167, v35, v185
	v_fmac_f32_dpp v206, v32, v160 row_shr:1 row_mask:0xf bank_mask:0xf
	v_fmac_f32_dpp v207, v33, v161 row_shr:1 row_mask:0xf bank_mask:0xf
	v_fmac_f32_dpp v208, v34, v162 row_shr:1 row_mask:0xf bank_mask:0xf
	v_fmac_f32_dpp v209, v35, v163 row_shr:1 row_mask:0xf bank_mask:0xf
	v_fmac_f32_dpp v206, v48, v226 row_ror:1 row_mask:0xf bank_mask:0xf
	v_fmac_f32_dpp v207, v49, v227 row_ror:1 row_mask:0xf bank_mask:0xf
	v_fmac_f32_dpp v208, v50, v228 row_ror:1 row_mask:0xf bank_mask:0xf
	v_fmac_f32_dpp v209, v51, v229 row_ror:1 row_mask:0xf bank_mask:0xf
	v_fmac_f32_dpp v206, v32, v178 row_shl:1 row_mask:0xf bank_mask:0xf
	v_fmac_f32_dpp v207, v33, v179 row_shl:1 row_mask:0xf bank_mask:0xf
	v_fmac_f32_dpp v208, v34, v180 row_shl:1 row_mask:0xf bank_mask:0xf
	v_fmac_f32_dpp v209, v35, v181 row_shl:1 row_mask:0xf bank_mask:0xf
	v_fmac_f32_dpp v206, v16, v232 row_ror:15 row_mask:0xf bank_mask:0xf
	v_fmac_f32_dpp v207, v17, v233 row_ror:15 row_mask:0xf bank_mask:0xf
	v_fmac_f32_dpp v208, v18, v234 row_ror:15 row_mask:0xf bank_mask:0xf
	v_fmac_f32_dpp v209, v19, v235 row_ror:15 row_mask:0xf bank_mask:0xf
	v_mul_f32_e32 v210, 0xbfb8aa3b, v202
	v_mul_f32_e32 v211, 0xbfb8aa3b, v203
	v_mul_f32_e32 v212, 0xbfb8aa3b, v204
	v_mul_f32_e32 v213, 0xbfb8aa3b, v205
	v_exp_f32_e32 v210, v210
	v_exp_f32_e32 v211, v211
	v_exp_f32_e32 v212, v212
	v_exp_f32_e32 v213, v213
	v_add_f32_e32 v210, 1.0, v210
	v_add_f32_e32 v211, 1.0, v211
	v_add_f32_e32 v212, 1.0, v212
	v_add_f32_e32 v213, 1.0, v213
	v_rcp_f32_e32 v210, v210
	v_rcp_f32_e32 v211, v211
	v_rcp_f32_e32 v212, v212
	v_rcp_f32_e32 v213, v213
	v_mul_f32_e32 v202, v202, v210
	v_mul_f32_e32 v203, v203, v211
	v_mul_f32_e32 v204, v204, v212
	v_mul_f32_e32 v205, v205, v213
	v_mul_f32_e32 v202, v202, v206
	v_mul_f32_e32 v203, v203, v207
	v_mul_f32_e32 v204, v204, v208
	v_mul_f32_e32 v205, v205, v209
	v_cvt_pk_bf16_f32 v46, v202, v203
	v_cvt_pk_bf16_f32 v47, v204, v205
	v_fma_f32 v202, v124, v24, v132
	v_fma_f32 v203, v125, v25, v133
	v_fma_f32 v204, v126, v26, v134
	v_fma_f32 v205, v127, v27, v135
	v_fmac_f32_dpp v202, v24, v116 row_shr:1 row_mask:0xf bank_mask:0xf
	v_fmac_f32_dpp v203, v25, v117 row_shr:1 row_mask:0xf bank_mask:0xf
	v_fmac_f32_dpp v204, v26, v118 row_shr:1 row_mask:0xf bank_mask:0xf
	v_fmac_f32_dpp v205, v27, v119 row_shr:1 row_mask:0xf bank_mask:0xf
	v_fmac_f32_dpp v202, v40, v218 row_ror:1 row_mask:0xf bank_mask:0xf
	v_fmac_f32_dpp v203, v41, v219 row_ror:1 row_mask:0xf bank_mask:0xf
	v_fmac_f32_dpp v204, v42, v220 row_ror:1 row_mask:0xf bank_mask:0xf
	v_fmac_f32_dpp v205, v43, v221 row_ror:1 row_mask:0xf bank_mask:0xf
	v_fmac_f32_dpp v202, v24, v128 row_shl:1 row_mask:0xf bank_mask:0xf
	v_fmac_f32_dpp v203, v25, v129 row_shl:1 row_mask:0xf bank_mask:0xf
	v_fmac_f32_dpp v204, v26, v130 row_shl:1 row_mask:0xf bank_mask:0xf
	v_fmac_f32_dpp v205, v27, v131 row_shl:1 row_mask:0xf bank_mask:0xf
	v_fmac_f32_dpp v202, v8, v222 row_ror:15 row_mask:0xf bank_mask:0xf
	v_fmac_f32_dpp v203, v9, v223 row_ror:15 row_mask:0xf bank_mask:0xf
	v_fmac_f32_dpp v204, v10, v224 row_ror:15 row_mask:0xf bank_mask:0xf
	v_fmac_f32_dpp v205, v11, v225 row_ror:15 row_mask:0xf bank_mask:0xf
	v_fma_f32 v206, v164, v16, v182
	v_fma_f32 v207, v165, v17, v183
	v_fma_f32 v208, v166, v18, v184
	v_fma_f32 v209, v167, v19, v185
	v_fmac_f32_dpp v206, v16, v160 row_shr:1 row_mask:0xf bank_mask:0xf
	v_fmac_f32_dpp v207, v17, v161 row_shr:1 row_mask:0xf bank_mask:0xf
	v_fmac_f32_dpp v208, v18, v162 row_shr:1 row_mask:0xf bank_mask:0xf
	v_fmac_f32_dpp v209, v19, v163 row_shr:1 row_mask:0xf bank_mask:0xf
	v_fmac_f32_dpp v206, v32, v226 row_ror:1 row_mask:0xf bank_mask:0xf
	v_fmac_f32_dpp v207, v33, v227 row_ror:1 row_mask:0xf bank_mask:0xf
	v_fmac_f32_dpp v208, v34, v228 row_ror:1 row_mask:0xf bank_mask:0xf
	v_fmac_f32_dpp v209, v35, v229 row_ror:1 row_mask:0xf bank_mask:0xf
	v_fmac_f32_dpp v206, v16, v178 row_shl:1 row_mask:0xf bank_mask:0xf
	v_fmac_f32_dpp v207, v17, v179 row_shl:1 row_mask:0xf bank_mask:0xf
	v_fmac_f32_dpp v208, v18, v180 row_shl:1 row_mask:0xf bank_mask:0xf
	v_fmac_f32_dpp v209, v19, v181 row_shl:1 row_mask:0xf bank_mask:0xf
	v_fmac_f32_dpp v206, v0, v232 row_ror:15 row_mask:0xf bank_mask:0xf
	v_fmac_f32_dpp v207, v1, v233 row_ror:15 row_mask:0xf bank_mask:0xf
	v_fmac_f32_dpp v208, v2, v234 row_ror:15 row_mask:0xf bank_mask:0xf
	v_fmac_f32_dpp v209, v3, v235 row_ror:15 row_mask:0xf bank_mask:0xf
	v_mul_f32_e32 v210, 0xbfb8aa3b, v202
	v_mul_f32_e32 v211, 0xbfb8aa3b, v203
	v_mul_f32_e32 v212, 0xbfb8aa3b, v204
	v_mul_f32_e32 v213, 0xbfb8aa3b, v205
	v_exp_f32_e32 v210, v210
	v_exp_f32_e32 v211, v211
	v_exp_f32_e32 v212, v212
	v_exp_f32_e32 v213, v213
	v_add_f32_e32 v210, 1.0, v210
	v_add_f32_e32 v211, 1.0, v211
	v_add_f32_e32 v212, 1.0, v212
	v_add_f32_e32 v213, 1.0, v213
	v_rcp_f32_e32 v210, v210
	v_rcp_f32_e32 v211, v211
	v_rcp_f32_e32 v212, v212
	v_rcp_f32_e32 v213, v213
	v_mul_f32_e32 v202, v202, v210
	v_mul_f32_e32 v203, v203, v211
	v_mul_f32_e32 v204, v204, v212
	v_mul_f32_e32 v205, v205, v213
	v_mul_f32_e32 v202, v202, v206
	v_mul_f32_e32 v203, v203, v207
	v_mul_f32_e32 v204, v204, v208
	v_mul_f32_e32 v205, v205, v209
	v_cvt_pk_bf16_f32 v30, v202, v203
	v_cvt_pk_bf16_f32 v31, v204, v205
	v_fma_f32 v202, v124, v8, v132
	v_fma_f32 v203, v125, v9, v133
	v_fma_f32 v204, v126, v10, v134
	v_fma_f32 v205, v127, v11, v135
	v_fmac_f32_dpp v202, v8, v116 row_shr:1 row_mask:0xf bank_mask:0xf
	v_fmac_f32_dpp v203, v9, v117 row_shr:1 row_mask:0xf bank_mask:0xf
	v_fmac_f32_dpp v204, v10, v118 row_shr:1 row_mask:0xf bank_mask:0xf
	v_fmac_f32_dpp v205, v11, v119 row_shr:1 row_mask:0xf bank_mask:0xf
	v_fmac_f32_dpp v202, v24, v218 row_ror:1 row_mask:0xf bank_mask:0xf
	v_fmac_f32_dpp v203, v25, v219 row_ror:1 row_mask:0xf bank_mask:0xf
	v_fmac_f32_dpp v204, v26, v220 row_ror:1 row_mask:0xf bank_mask:0xf
	v_fmac_f32_dpp v205, v27, v221 row_ror:1 row_mask:0xf bank_mask:0xf
	v_fmac_f32_dpp v202, v8, v128 row_shl:1 row_mask:0xf bank_mask:0xf
	v_fmac_f32_dpp v203, v9, v129 row_shl:1 row_mask:0xf bank_mask:0xf
	v_fmac_f32_dpp v204, v10, v130 row_shl:1 row_mask:0xf bank_mask:0xf
	v_fmac_f32_dpp v205, v11, v131 row_shl:1 row_mask:0xf bank_mask:0xf
	v_fmac_f32_e32 v202, v194, v222
	v_fmac_f32_e32 v203, v195, v223
	v_fmac_f32_e32 v204, v196, v224
	v_fmac_f32_e32 v205, v197, v225
	v_fma_f32 v206, v164, v0, v182
	v_fma_f32 v207, v165, v1, v183
	v_fma_f32 v208, v166, v2, v184
	v_fma_f32 v209, v167, v3, v185
	v_fmac_f32_dpp v206, v0, v160 row_shr:1 row_mask:0xf bank_mask:0xf
	v_fmac_f32_dpp v207, v1, v161 row_shr:1 row_mask:0xf bank_mask:0xf
	v_fmac_f32_dpp v208, v2, v162 row_shr:1 row_mask:0xf bank_mask:0xf
	v_fmac_f32_dpp v209, v3, v163 row_shr:1 row_mask:0xf bank_mask:0xf
	v_fmac_f32_dpp v206, v16, v226 row_ror:1 row_mask:0xf bank_mask:0xf
	v_fmac_f32_dpp v207, v17, v227 row_ror:1 row_mask:0xf bank_mask:0xf
	v_fmac_f32_dpp v208, v18, v228 row_ror:1 row_mask:0xf bank_mask:0xf
	v_fmac_f32_dpp v209, v19, v229 row_ror:1 row_mask:0xf bank_mask:0xf
	v_fmac_f32_dpp v206, v0, v178 row_shl:1 row_mask:0xf bank_mask:0xf
	v_fmac_f32_dpp v207, v1, v179 row_shl:1 row_mask:0xf bank_mask:0xf
	v_fmac_f32_dpp v208, v2, v180 row_shl:1 row_mask:0xf bank_mask:0xf
	v_fmac_f32_dpp v209, v3, v181 row_shl:1 row_mask:0xf bank_mask:0xf
	v_fmac_f32_e32 v206, v198, v232
	v_fmac_f32_e32 v207, v199, v233
	v_fmac_f32_e32 v208, v200, v234
	v_fmac_f32_e32 v209, v201, v235
	s_mov_b64 exec, s[94:95]
	v_add_u32_e32 v250, 0x10800, v177
	global_store_dwordx4 v250, v[202:205], s[98:99] offset:16
	v_add_u32_e32 v250, 0x13400, v177
	global_store_dwordx4 v250, v[206:209], s[98:99] offset:16
	s_mov_b64 exec, s[90:91]
	s_nop 4
	v_mul_f32_e32 v210, 0xbfb8aa3b, v202
	v_mul_f32_e32 v211, 0xbfb8aa3b, v203
	v_mul_f32_e32 v212, 0xbfb8aa3b, v204
	v_mul_f32_e32 v213, 0xbfb8aa3b, v205
	v_exp_f32_e32 v210, v210
	v_exp_f32_e32 v211, v211
	v_exp_f32_e32 v212, v212
	v_exp_f32_e32 v213, v213
	v_add_f32_e32 v210, 1.0, v210
	v_add_f32_e32 v211, 1.0, v211
	v_add_f32_e32 v212, 1.0, v212
	v_add_f32_e32 v213, 1.0, v213
	v_rcp_f32_e32 v210, v210
	v_rcp_f32_e32 v211, v211
	v_rcp_f32_e32 v212, v212
	v_rcp_f32_e32 v213, v213
	v_mul_f32_e32 v202, v202, v210
	v_mul_f32_e32 v203, v203, v211
	v_mul_f32_e32 v204, v204, v212
	v_mul_f32_e32 v205, v205, v213
	v_mul_f32_e32 v202, v202, v206
	v_mul_f32_e32 v203, v203, v207
	v_mul_f32_e32 v204, v204, v208
	v_mul_f32_e32 v205, v205, v209
	v_cvt_pk_bf16_f32 v14, v202, v203
	v_cvt_pk_bf16_f32 v15, v204, v205
	global_store_dwordx4 v168, v[140:143], s[76:77]
	v_add_u32_e32 v250, 0x16000, v168
	global_store_dwordx4 v250, v[108:111], s[76:77]
	s_nop 0
	v_add_u32_e32 v250, 0x2c000, v168
	global_store_dwordx4 v250, v[92:95], s[76:77]
	s_nop 0
	v_add_u32_e32 v250, 0x42000, v168
	global_store_dwordx4 v250, v[76:79], s[76:77]
	s_nop 0
	v_add_u32_e32 v250, 0xb0000, v168
	global_store_dwordx4 v250, v[60:63], s[76:77]
	s_nop 0
	v_add_u32_e32 v250, 0xc6000, v168
	global_store_dwordx4 v250, v[44:47], s[76:77]
	s_nop 0
	v_add_u32_e32 v250, 0xdc000, v168
	global_store_dwordx4 v250, v[28:31], s[76:77]
	s_nop 0
	v_add_u32_e32 v250, 0xf2000, v168
	global_store_dwordx4 v250, v[12:15], s[76:77]
	s_nop 0
	s_mov_b64 s[4:5], -1
	s_and_b64 vcc, exec, s[6:7]
	s_cbranch_vccz .LBB0_963
	s_andn2_b64 vcc, exec, s[10:11]
	s_cbranch_vccnz .LBB0_962
	s_barrier
	s_branch .LBB0_962

.LBB0_1038:
	s_cmp_gt_i32 s72, 10
	s_cselect_b64 s[4:5], -1, 0
	s_cmp_lt_i32 s73, 11
	s_cselect_b64 s[6:7], -1, 0
	s_or_b64 s[4:5], s[4:5], s[6:7]
	v_readlane_b32 s2, v254, 47
	s_and_b64 vcc, exec, s[4:5]
	v_readlane_b32 s3, v254, 48
	s_cbranch_vccnz .LBB0_1097
	s_mov_b64 s[6:7], exec
	s_cmpk_gt_i32 s84, 63
	s_cbranch_scc1 .LfixA_done
	s_lshr_b32 s8, s84, 1
	s_and_b32 s9, s84, 1
	s_and_b32 s10, s8, 3
	s_mul_i32 s11, s9, 3
	s_cmp_eq_u32 s10, s11
	s_cbranch_scc1 .LfixA_done
	s_add_u32 s12, s70, 0x5b00000
	s_addc_u32 s13, s71, 0
	s_mul_i32 s14, s8, 0x16000
	s_mul_i32 s15, s9, 0xb000
	s_add_i32 s14, s14, s15
	s_add_i32 s14, s14, 0x5800
	s_add_u32 s60, s12, s14
	s_addc_u32 s61, s13, 0
	s_lshl_b32 s14, s9, 1
	s_add_i32 s14, s14, s8
	s_add_i32 s14, s14, -1
	s_mul_i32 s14, s14, 0x16000
	s_sub_i32 s15, 1, s9
	s_mul_i32 s15, s15, 0xb000
	s_add_i32 s14, s14, s15
	s_add_u32 s62, s12, s14
	s_addc_u32 s63, s13, 0
	v_readlane_b32 s64, v254, 5
	v_readlane_b32 s65, v254, 6
	s_mul_i32 s15, s9, 0xb000
	s_add_i32 s15, s15, 0x0
	s_add_u32 s64, s64, s15
	s_addc_u32 s65, s65, 0
	s_lshl_b32 s14, s8, 8
	s_mul_i32 s15, s9, 255
	s_add_i32 s14, s14, s15
	s_mul_i32 s14, s14, 0x1600
	s_add_u32 s14, s14, 0xbf00000
	s_add_u32 s66, s70, s14
	s_addc_u32 s67, s71, 0
	s_nop 4
	v_mov_b32_e32 v0, v230
	v_cmp_gt_u32_e32 vcc, 0x580, v0
	s_and_saveexec_b64 s[74:75], vcc
	v_lshlrev_b32_e32 v1, 3, v0
	v_add_u32_e32 v2, 0x2c00, v1
	global_load_dwordx2 v[4:5], v1, s[60:61]
	global_load_dwordx2 v[6:7], v2, s[60:61]
	global_load_dwordx2 v[8:9], v1, s[62:63]
	global_load_dwordx2 v[10:11], v2, s[62:63]
	global_load_dwordx2 v[12:13], v1, s[64:65]
	global_load_dwordx2 v[14:15], v2, s[64:65]
	v_lshlrev_b32_e32 v3, 2, v0
	s_waitcnt vmcnt(0)
	v_fmac_f32_e32 v4, v12, v8
	v_fmac_f32_e32 v5, v13, v9
	v_fmac_f32_e32 v6, v14, v10
	v_fmac_f32_e32 v7, v15, v11
	v_mul_f32_e32 v16, 0xbfb8aa3b, v4
	v_mul_f32_e32 v17, 0xbfb8aa3b, v5
	v_exp_f32_e32 v16, v16
	v_exp_f32_e32 v17, v17
	s_nop 0
	v_add_f32_e32 v16, 1.0, v16
	v_add_f32_e32 v17, 1.0, v17
	v_rcp_f32_e32 v16, v16
	v_rcp_f32_e32 v17, v17
	s_nop 0
	v_mul_f32_e32 v4, v4, v16
	v_mul_f32_e32 v5, v5, v17
	v_mul_f32_e32 v4, v4, v6
	v_mul_f32_e32 v5, v5, v7
	v_cvt_pk_bf16_f32 v4, v4, v5
	global_store_dword v3, v4, s[66:67]
	s_or_b64 exec, exec, s[74:75]
	v_add_u32_e32 v0, 512, v230
	v_cmp_gt_u32_e32 vcc, 0x580, v0
	s_and_saveexec_b64 s[74:75], vcc
	v_lshlrev_b32_e32 v1, 3, v0
	v_add_u32_e32 v2, 0x2c00, v1
	global_load_dwordx2 v[4:5], v1, s[60:61]
	global_load_dwordx2 v[6:7], v2, s[60:61]
	global_load_dwordx2 v[8:9], v1, s[62:63]
	global_load_dwordx2 v[10:11], v2, s[62:63]
	global_load_dwordx2 v[12:13], v1, s[64:65]
	global_load_dwordx2 v[14:15], v2, s[64:65]
	v_lshlrev_b32_e32 v3, 2, v0
	s_waitcnt vmcnt(0)
	v_fmac_f32_e32 v4, v12, v8
	v_fmac_f32_e32 v5, v13, v9
	v_fmac_f32_e32 v6, v14, v10
	v_fmac_f32_e32 v7, v15, v11
	v_mul_f32_e32 v16, 0xbfb8aa3b, v4
	v_mul_f32_e32 v17, 0xbfb8aa3b, v5
	v_exp_f32_e32 v16, v16
	v_exp_f32_e32 v17, v17
	s_nop 0
	v_add_f32_e32 v16, 1.0, v16
	v_add_f32_e32 v17, 1.0, v17
	v_rcp_f32_e32 v16, v16
	v_rcp_f32_e32 v17, v17
	s_nop 0
	v_mul_f32_e32 v4, v4, v16
	v_mul_f32_e32 v5, v5, v17
	v_mul_f32_e32 v4, v4, v6
	v_mul_f32_e32 v5, v5, v7
	v_cvt_pk_bf16_f32 v4, v4, v5
	global_store_dword v3, v4, s[66:67]
	s_or_b64 exec, exec, s[74:75]
	v_add_u32_e32 v0, 1024, v230
	v_cmp_gt_u32_e32 vcc, 0x580, v0
	s_and_saveexec_b64 s[74:75], vcc
	v_lshlrev_b32_e32 v1, 3, v0
	v_add_u32_e32 v2, 0x2c00, v1
	global_load_dwordx2 v[4:5], v1, s[60:61]
	global_load_dwordx2 v[6:7], v2, s[60:61]
	global_load_dwordx2 v[8:9], v1, s[62:63]
	global_load_dwordx2 v[10:11], v2, s[62:63]
	global_load_dwordx2 v[12:13], v1, s[64:65]
	global_load_dwordx2 v[14:15], v2, s[64:65]
	v_lshlrev_b32_e32 v3, 2, v0
	s_waitcnt vmcnt(0)
	v_fmac_f32_e32 v4, v12, v8
	v_fmac_f32_e32 v5, v13, v9
	v_fmac_f32_e32 v6, v14, v10
	v_fmac_f32_e32 v7, v15, v11
	v_mul_f32_e32 v16, 0xbfb8aa3b, v4
	v_mul_f32_e32 v17, 0xbfb8aa3b, v5
	v_exp_f32_e32 v16, v16
	v_exp_f32_e32 v17, v17
	s_nop 0
	v_add_f32_e32 v16, 1.0, v16
	v_add_f32_e32 v17, 1.0, v17
	v_rcp_f32_e32 v16, v16
	v_rcp_f32_e32 v17, v17
	s_nop 0
	v_mul_f32_e32 v4, v4, v16
	v_mul_f32_e32 v5, v5, v17
	v_mul_f32_e32 v4, v4, v6
	v_mul_f32_e32 v5, v5, v7
	v_cvt_pk_bf16_f32 v4, v4, v5
	global_store_dword v3, v4, s[66:67]
	s_or_b64 exec, exec, s[74:75]
.LfixA_done:
	s_waitcnt vmcnt(0)
	s_branch .LBB0_1046
	v_mov_b32_e32 v0, v230
	v_readlane_b32 s0, v254, 55
	s_nop 1
	v_add_u32_e32 v160, s0, v0
	s_mov_b32 s0, 0x58000
	v_cmp_gt_i32_e32 vcc, s0, v160
	s_and_saveexec_b64 s[6:7], vcc
	s_cbranch_execz .LBB0_1046
	s_add_u32 s8, s70, 0x3b00000
	s_addc_u32 s9, s71, 0
	s_add_u32 s10, s70, 0xbf00000
	v_readlane_b32 s52, v254, 3
	s_addc_u32 s11, s71, 0
	v_readlane_b32 s56, v254, 7
	v_readlane_b32 s57, v254, 8
	s_add_u32 s12, s56, 0x2c00
	v_readlane_b32 s54, v254, 5
	s_addc_u32 s13, s57, 0
	v_readlane_b32 s55, v254, 6
	s_add_u32 s14, s54, 0x2c00
	s_addc_u32 s15, s55, 0
	s_add_u32 s16, s54, 0x5800
	s_addc_u32 s17, s55, 0
	s_add_u32 s34, s54, 0x8400
	s_addc_u32 s35, s55, 0
	s_add_u32 s48, s54, 0xb000
	s_addc_u32 s49, s55, 0
	v_readlane_b32 s58, v254, 9
	s_add_u32 s54, s54, 0xdc00
	v_lshlrev_b32_e32 v0, 3, v0
	s_addc_u32 s55, s55, 0
	v_lshl_add_u32 v161, s84, 12, v0
	s_lshl_b32 s0, s97, 3
	s_mov_b64 s[56:57], 0
	s_movk_i32 s20, 0x2c00
	s_movk_i32 s21, 0x3f8
	v_mov_b64_e32 v[136:137], s[8:9]
	s_mov_b32 s58, 0xbfb8aa3b
	s_movk_i32 s30, 0x1600
	s_mov_b32 s31, 0x57fff
	v_readlane_b32 s53, v254, 4
	v_readlane_b32 s59, v254, 10
	s_branch .LBB0_1042

.LBB0_1655:
	s_add_u32 s55, s68, 0x2000000
	s_addc_u32 s56, s69, 0
	s_add_u32 s57, s70, 0x58000
	s_addc_u32 s58, s71, 0
	s_add_u32 s22, s50, 0x1000
	s_addc_u32 s23, s51, 0
	s_add_u32 s50, s70, 0x5a000
	s_addc_u32 s51, s71, 0
	s_add_u32 s59, s70, 0x3b00000
	s_addc_u32 s60, s71, 0
	s_lshl_b32 s5, s5, 5
	s_mov_b64 s[24:25], 0x80
	s_and_b32 s5, s5, 0x60
	s_add_i32 m0, s49, 0x18000
	v_lshl_add_u64 v[6:7], v[6:7], 0, s[24:25]
	s_lshl_b32 s9, s4, 13
	s_lshl_b32 s14, s5, 7
	s_waitcnt vmcnt(2)
	s_barrier
	global_load_lds_dwordx4 v[6:7], off
	v_lshl_add_u64 v[4:5], v[4:5], 0, s[24:25]
	s_add_i32 m0, s49, 0x1a000
	s_add_i32 s61, s49, 0x8000
	s_add_i32 s62, s49, 0xa000
	global_load_lds_dwordx4 v[4:5], off
	v_lshl_add_u64 v[0:1], v[0:1], 0, s[24:25]
	s_mov_b32 m0, s61
	s_add_u32 s6, s44, 0x40080
	global_load_lds_dwordx4 v[0:1], off
	v_lshl_add_u64 v[0:1], v[2:3], 0, s[24:25]
	s_mov_b32 m0, s62
	s_addc_u32 s7, s45, 0
	global_load_lds_dwordx4 v[0:1], off
	s_add_i32 m0, s49, 0x1c000
	v_lshl_add_u64 v[0:1], s[6:7], 0, v[128:129]
	global_load_lds_dwordx4 v[0:1], off
	v_lshl_add_u64 v[0:1], s[6:7], 0, v[130:131]
	s_add_i32 m0, s49, 0x1e000
	v_bfe_u32 v15, v8, 4, 2
	global_load_lds_dwordx4 v[0:1], off
	v_and_b32_e32 v1, 15, v8
	v_lshlrev_b32_e32 v2, 4, v15
	v_lshl_or_b32 v0, s4, 6, v1
	v_lshl_or_b32 v1, v1, 6, v2
	v_lshlrev_b32_e32 v2, 2, v8
	v_and_b32_e32 v2, 32, v2
	v_bitop3_b32 v8, v1, s9, v2 bitop3:0xde
	v_bitop3_b32 v178, v1, s14, v2 bitop3:0xde
	v_ashrrev_i32_e32 v1, 31, v0
	v_lshlrev_b64 v[132:133], 10, v[0:1]
	v_or_b32_e32 v2, 16, v0
	v_or_b32_e32 v4, 32, v0
	v_or_b32_e32 v6, 48, v0
	v_add_u32_e32 v16, 0x80, v0
	v_add_u32_e32 v18, 0x90, v0
	v_add_u32_e32 v20, 0xa0, v0
	v_add_u32_e32 v22, 0xb0, v0
	v_lshl_add_u64 v[148:149], v[0:1], 2, s[10:11]
	v_lshlrev_b32_e32 v0, 14, v9
	v_and_b32_e32 v0, 0xffff8000, v0
	v_lshl_add_u32 v0, v10, 11, v0
	v_and_b32_e32 v1, 1, v9
	v_lshl_or_b32 v0, v1, 6, v0
	v_lshl_add_u32 v164, v11, 1, v0
	v_lshlrev_b32_e32 v0, 14, v12
	v_and_b32_e32 v0, 0xffff8000, v0
	v_lshl_add_u32 v0, v13, 11, v0
	v_and_b32_e32 v1, 1, v12
	s_waitcnt vmcnt(6)
	v_lshl_or_b32 v0, v1, 6, v0
	s_cmpk_lt_u32 s8, 0x100
	v_ashrrev_i32_e32 v3, 31, v2
	v_ashrrev_i32_e32 v5, 31, v4
	v_ashrrev_i32_e32 v7, 31, v6
	v_ashrrev_i32_e32 v17, 31, v16
	v_ashrrev_i32_e32 v19, 31, v18
	v_ashrrev_i32_e32 v21, 31, v20
	v_ashrrev_i32_e32 v23, 31, v22
	v_lshl_add_u32 v166, v14, 1, v0
	v_mbcnt_lo_u32_b32 v0, -1, 0
	s_cselect_b64 s[26:27], -1, 0
	v_cmp_eq_u32_e64 s[6:7], 0, v15
	v_lshlrev_b64 v[134:135], 10, v[2:3]
	v_lshlrev_b64 v[136:137], 10, v[4:5]
	v_lshlrev_b64 v[138:139], 10, v[6:7]
	v_lshlrev_b64 v[140:141], 10, v[16:17]
	v_lshlrev_b64 v[142:143], 10, v[18:19]
	v_lshlrev_b64 v[144:145], 10, v[20:21]
	v_lshlrev_b64 v[146:147], 10, v[22:23]
	v_lshl_or_b32 v179, v15, 2, s5
	v_lshl_add_u64 v[150:151], v[2:3], 2, s[10:11]
	v_lshl_add_u64 v[152:153], v[4:5], 2, s[10:11]
	v_lshl_add_u64 v[154:155], v[6:7], 2, s[10:11]
	v_lshl_add_u64 v[156:157], v[16:17], 2, s[10:11]
	v_lshl_add_u64 v[158:159], v[18:19], 2, s[10:11]
	v_lshl_add_u64 v[160:161], v[20:21], 2, s[10:11]
	v_lshl_add_u64 v[162:163], v[22:23], 2, s[10:11]
	v_mov_b32_e32 v165, v129
	v_mov_b32_e32 v167, v129
	s_add_i32 s63, 0, 0x10000
	s_add_i32 s64, 0, 0x14000
	v_add_u32_e32 v180, 0, v8
	v_mbcnt_hi_u32_b32 v181, -1, v0
	v_mov_b64_e32 v[168:169], 0x100
	v_mov_b64_e32 v[170:171], 0xff
	s_mov_b32 s65, 0
	s_barrier
	s_branch .LBB0_1658

.LBB0_1742:
	s_add_u32 s0, s70, 0xf500000
	s_addc_u32 s1, s71, 0
	s_add_u32 s33, s70, 0xec63000
	s_addc_u32 s50, s71, 0
	s_cmp_gt_i32 s72, 18
	s_cselect_b64 s[4:5], -1, 0
	s_cmp_lt_i32 s73, 19
	s_cselect_b64 s[6:7], -1, 0
	s_or_b64 s[4:5], s[4:5], s[6:7]
	s_and_b64 vcc, exec, s[4:5]
	s_cbranch_vccnz .LBB0_1809
	v_readlane_b32 s4, v255, 2
	v_mov_b32_e32 v9, v230
	v_readlane_b32 s5, v255, 3
	s_and_b64 vcc, exec, s[4:5]
	v_readfirstlane_b32 s4, v9
	s_cbranch_vccnz .LBB0_1759
	v_lshlrev_b32_e32 v0, 4, v9
	s_waitcnt lgkmcnt(0)
	v_add_u32_e32 v1, 0x2000, v0
	v_ashrrev_i32_e32 v2, 31, v1
	v_lshrrev_b32_e32 v2, 22, v2
	v_add_u32_e32 v2, v1, v2
	v_ashrrev_i32_e32 v8, 10, v2
	v_mul_i32_i24_e32 v2, 0x400, v8
	v_sub_u32_e32 v1, v1, v2
	v_lshrrev_b32_e32 v2, 4, v1
	v_bitop3_b32 v1, v2, v1, 32 bitop3:0x6c
	v_ashrrev_i32_e32 v2, 31, v1
	v_lshrrev_b32_e32 v2, 26, v2
	v_add_u32_e32 v2, v1, v2
	v_lshlrev_b32_e32 v3, 3, v8
	v_ashrrev_i32_e32 v10, 6, v2
	v_and_b32_e32 v3, -16, v3
	v_add_u32_e32 v3, v10, v3
	v_and_b32_e32 v4, 3, v10
	s_mov_b32 s6, 0x1fffe0
	v_lshrrev_b32_e32 v5, 2, v3
	v_lshlrev_b32_e32 v6, 1, v3
	v_and_b32_e32 v2, 0xc0, v2
	v_and_or_b32 v4, v3, s6, v4
	v_and_b32_e32 v5, 4, v5
	v_and_b32_e32 v6, 24, v6
	v_sub_u32_e32 v1, v1, v2
	v_mov_b32_e32 v2, 1
	v_or3_b32 v4, v4, v5, v6
	v_lshlrev_b32_e32 v5, 5, v8
	v_ashrrev_i16_sdwa v1, v2, sext(v1) dst_sel:DWORD dst_unused:UNUSED_PAD src0_sel:DWORD src1_sel:BYTE_0
	v_and_b32_e32 v5, 32, v5
	v_bfe_i32 v11, v1, 0, 16
	v_add_lshl_u32 v1, v5, v11, 1
	v_lshl_add_u32 v144, v4, 11, v1
	v_lshl_add_u32 v146, v3, 11, v1
	v_bfe_i32 v1, v9, 27, 1
	v_lshrrev_b32_e32 v1, 22, v1
	v_add_u32_e32 v1, v0, v1
	v_and_b32_e32 v1, 0xfffffc00, v1
	v_sub_u32_e32 v0, v0, v1
	v_lshrrev_b32_e32 v1, 4, v0
	v_ashrrev_i32_e32 v3, 31, v9
	v_bitop3_b32 v0, v1, v0, 32 bitop3:0x6c
	v_lshrrev_b32_e32 v3, 26, v3
	v_ashrrev_i32_e32 v1, 31, v0
	v_add_u32_e32 v3, v9, v3
	s_add_u32 s20, s70, 0x3b00000
	v_lshrrev_b32_e32 v1, 26, v1
	v_ashrrev_i32_e32 v13, 6, v3
	s_addc_u32 s21, s71, 0
	s_ashr_i32 s7, s4, 6
	v_add_u32_e32 v1, v0, v1
	v_lshlrev_b32_e32 v3, 3, v13
	v_readlane_b32 s8, v254, 62
	s_ashr_i32 s5, s4, 8
	s_lshl_b32 s30, s7, 10
	v_ashrrev_i32_e32 v12, 6, v1
	v_and_b32_e32 v3, -16, v3
	v_readlane_b32 s9, v254, 63
	v_add_u32_e32 v3, v12, v3
	v_and_b32_e32 v4, 3, v12
	s_movk_i32 s31, 0x59
	s_and_b64 s[8:9], s[8:9], exec
	v_and_or_b32 v4, v3, s6, v4
	s_cselect_b32 s6, s31, 0x58
	v_readlane_b32 s8, v254, 51
	s_mul_i32 s6, s6, s8
	v_readlane_b32 s8, v254, 61
	s_add_i32 s6, s6, s8
	s_mul_hi_i32 s8, s6, 0x2e8ba2e9
	s_lshr_b32 s9, s8, 31
	s_ashr_i32 s8, s8, 5
	s_add_i32 s8, s8, s9
	s_lshl_b32 s9, s8, 3
	s_mulk_i32 s8, 0xb0
	s_sub_i32 s8, s6, s8
	s_bfe_u32 s6, s8, 0x3001c
	s_add_i32 s12, s8, s6
	s_sext_i32_i16 s6, s12
	s_and_b32 s12, s12, 0xfff8
	s_sub_i32 s8, s8, s12
	s_sext_i32_i16 s8, s8
	v_lshrrev_b32_e32 v5, 2, v3
	v_lshlrev_b32_e32 v6, 1, v3
	v_and_b32_e32 v1, 0xc0, v1
	s_lshr_b32 s6, s6, 3
	s_add_i32 s8, s9, s8
	v_and_b32_e32 v5, 4, v5
	v_and_b32_e32 v6, 24, v6
	v_sub_u32_e32 v0, v0, v1
	s_ashr_i32 s9, s8, 31
	s_bfe_i64 s[14:15], s[6:7], 0x100000
	v_or3_b32 v4, v4, v5, v6
	v_lshlrev_b32_e32 v5, 5, v13
	v_ashrrev_i16_sdwa v0, v2, sext(v0) dst_sel:DWORD dst_unused:UNUSED_PAD src0_sel:DWORD src1_sel:BYTE_0
	s_lshl_b64 s[12:13], s[8:9], 19
	s_lshl_b64 s[14:15], s[14:15], 18
	v_and_b32_e32 v5, 32, v5
	v_bfe_i32 v14, v0, 0, 16
	s_add_u32 s38, s0, s14
	v_add_lshl_u32 v0, v5, v14, 1
	s_addc_u32 s39, s1, s15
	s_add_i32 s42, s30, 0
	v_lshl_add_u32 v148, v4, 11, v0
	s_add_i32 m0, s42, 0x10000
	v_lshl_add_u32 v150, v3, 11, v0
	global_load_lds_dwordx4 v148, s[38:39]
	s_add_i32 m0, s42, 0x12000
	s_add_u32 s14, s38, 0x580000
	global_load_lds_dwordx4 v144, s[38:39]
	s_addc_u32 s15, s39, 0
	s_add_i32 m0, s42, 0x14000
	v_mov_b32_e32 v149, 0
	global_load_lds_dwordx4 v148, s[14:15]
	s_add_i32 m0, s42, 0x16000
	s_add_u32 s36, s20, s12
	s_addc_u32 s37, s21, s13
	s_add_i32 s43, s42, 0x2000
	global_load_lds_dwordx4 v144, s[14:15]
	s_mov_b32 m0, s42
	s_add_u32 s12, s36, 0x40000
	global_load_lds_dwordx4 v150, s[36:37]
	s_mov_b32 m0, s43
	s_addc_u32 s13, s37, 0
	s_add_i32 s44, s42, 0x4000
	global_load_lds_dwordx4 v146, s[36:37]
	s_mov_b32 m0, s44
	s_add_i32 s45, s42, 0x6000
	global_load_lds_dwordx4 v150, s[12:13]
	s_mov_b32 m0, s45
	v_mov_b32_e32 v145, v149
	global_load_lds_dwordx4 v146, s[12:13]
	v_mov_b32_e32 v151, v149
	v_mov_b32_e32 v147, v149
	s_cmp_eq_u32 s5, 1
	s_mov_b32 s46, 0
	v_lshl_add_u64 v[6:7], s[38:39], 0, v[148:149]
	v_lshl_add_u64 v[4:5], s[38:39], 0, v[144:145]
	v_lshl_add_u64 v[0:1], s[36:37], 0, v[150:151]
	s_cselect_b64 s[12:13], -1, 0
	s_cmp_lg_u32 s5, 1
	v_lshl_add_u64 v[2:3], s[36:37], 0, v[146:147]
	s_cbranch_scc1 .LBB0_1746
	s_barrier

.LBB0_1755:
	s_and_b32 s27, s12, 1
	s_add_i32 s4, s8, -32
	s_ashr_i32 s4, s4, 2
	s_add_i32 s4, s4, 1
	s_cmp_gt_i32 s8, 31
	s_cselect_b32 s4, s4, 0
	s_mul_hi_i32 s5, s4, 0x5800
	s_mulk_i32 s4, 0x5800
	s_add_u32 s4, s33, s4
	s_addc_u32 s5, s50, s5
	v_lshl_add_u32 v236, s8, 8, v164
	v_lshlrev_b32_e32 v236, 2, v236
	v_lshl_or_b32 v229, s9, 7, v166
	v_lshlrev_b32_e32 v229, 2, v229
	global_load_dword v208, v236, s[10:11] offset:0
	global_load_dword v209, v236, s[10:11] offset:64
	global_load_dword v210, v236, s[10:11] offset:128
	global_load_dword v211, v236, s[10:11] offset:192
	global_load_dword v212, v236, s[10:11] offset:512
	global_load_dword v213, v236, s[10:11] offset:576
	global_load_dword v214, v236, s[10:11] offset:640
	global_load_dword v215, v236, s[10:11] offset:704
	global_load_dwordx4 v[200:203], v229, s[4:5]
	global_load_dwordx4 v[204:207], v229, s[4:5] offset:16
	v_add_u32_e32 v224, 0x2c00, v229
	global_load_dwordx4 v[216:219], v224, s[4:5]
	global_load_dwordx4 v[220:223], v224, s[4:5] offset:16
	v_readlane_b32 s36, v254, 5
	v_readlane_b32 s37, v254, 6
	v_readlane_b32 s38, v254, 7
	v_readlane_b32 s39, v254, 8
	s_add_u32 s36, s36, 0x10800
	s_addc_u32 s37, s37, 0
	s_add_u32 s38, s38, 0x5800
	s_addc_u32 s39, s39, 0
	s_mul_i32 s40, s8, 0x160000
	s_lshl_b32 s79, s9, 8
	s_add_i32 s40, s40, s79
	s_add_i32 s40, s40, 0x9300000
	s_add_u32 s40, s40, s70
	s_addc_u32 s41, s71, 0
	v_mul_u32_u24_e32 v171, 0x1600, v164
	v_lshl_add_u32 v171, v166, 1, v171
	s_mov_b32 s32, 0x20800
	v_lshl_add_u32 v228, v166, 2, s32
	v_and_b32_e32 v237, 15, v164
	v_cmp_eq_u32_e64 s[54:55], 0, v237
	v_cmp_eq_u32_e64 s[56:57], 15, v237
	v_and_b32_e32 v231, 8, v237
	v_lshlrev_b32_e32 v231, 9, v231
	s_lshl_b32 s79, s27, 10
	v_add3_u32 v231, v231, v228, s79
	s_waitcnt vmcnt(4)
	v_fmamk_f32 v208, v208, 0x3a800000, v170
	v_fmamk_f32 v209, v209, 0x3a800000, v170
	v_fmamk_f32 v210, v210, 0x3a800000, v170
	v_fmamk_f32 v211, v211, 0x3a800000, v170
	v_fmamk_f32 v212, v212, 0x3a800000, v170
	v_fmamk_f32 v213, v213, 0x3a800000, v170
	v_fmamk_f32 v214, v214, 0x3a800000, v170
	v_fmamk_f32 v215, v215, 0x3a800000, v170
	s_mov_b32 s79, 0x800000
	v_mul_f32_e32 v224, 0x4b800000, v208
	v_mul_f32_e32 v225, 0x4b800000, v209
	v_mul_f32_e32 v226, 0x4b800000, v210
	v_mul_f32_e32 v227, 0x4b800000, v211
	v_mul_f32_e32 v232, 0x4b800000, v212
	v_mul_f32_e32 v233, 0x4b800000, v213
	v_mul_f32_e32 v234, 0x4b800000, v214
	v_mul_f32_e32 v235, 0x4b800000, v215
	v_cmp_gt_f32_e32 vcc, s79, v208
	s_nop 1
	v_cndmask_b32_e32 v208, v208, v224, vcc
	v_rsq_f32_e32 v208, v208
	s_nop 0
	v_mul_f32_e32 v224, 0x45800000, v208
	v_cndmask_b32_e32 v208, v208, v224, vcc
	v_cmp_gt_f32_e32 vcc, s79, v209
	s_nop 1
	v_cndmask_b32_e32 v209, v209, v225, vcc
	v_rsq_f32_e32 v209, v209
	s_nop 0
	v_mul_f32_e32 v225, 0x45800000, v209
	v_cndmask_b32_e32 v209, v209, v225, vcc
	v_cmp_gt_f32_e32 vcc, s79, v210
	s_nop 1
	v_cndmask_b32_e32 v210, v210, v226, vcc
	v_rsq_f32_e32 v210, v210
	s_nop 0
	v_mul_f32_e32 v226, 0x45800000, v210
	v_cndmask_b32_e32 v210, v210, v226, vcc
	v_cmp_gt_f32_e32 vcc, s79, v211
	s_nop 1
	v_cndmask_b32_e32 v211, v211, v227, vcc
	v_rsq_f32_e32 v211, v211
	s_nop 0
	v_mul_f32_e32 v227, 0x45800000, v211
	v_cndmask_b32_e32 v211, v211, v227, vcc
	v_cmp_gt_f32_e32 vcc, s79, v212
	s_nop 1
	v_cndmask_b32_e32 v212, v212, v232, vcc
	v_rsq_f32_e32 v212, v212
	s_nop 0
	v_mul_f32_e32 v232, 0x45800000, v212
	v_cndmask_b32_e32 v212, v212, v232, vcc
	v_cmp_gt_f32_e32 vcc, s79, v213
	s_nop 1
	v_cndmask_b32_e32 v213, v213, v233, vcc
	v_rsq_f32_e32 v213, v213
	s_nop 0
	v_mul_f32_e32 v233, 0x45800000, v213
	v_cndmask_b32_e32 v213, v213, v233, vcc
	v_cmp_gt_f32_e32 vcc, s79, v214
	s_nop 1
	v_cndmask_b32_e32 v214, v214, v234, vcc
	v_rsq_f32_e32 v214, v214
	s_nop 0
	v_mul_f32_e32 v234, 0x45800000, v214
	v_cndmask_b32_e32 v214, v214, v234, vcc
	v_cmp_gt_f32_e32 vcc, s79, v215
	s_nop 1
	v_cndmask_b32_e32 v215, v215, v235, vcc
	v_rsq_f32_e32 v215, v215
	s_nop 0
	v_mul_f32_e32 v235, 0x45800000, v215
	v_cndmask_b32_e32 v215, v215, v235, vcc
	s_waitcnt vmcnt(0)
	v_fma_f32 v124, v124, v208, v200
	v_fma_f32 v125, v125, v208, v201
	v_fma_f32 v126, v126, v208, v202
	v_fma_f32 v127, v127, v208, v203
	v_fma_f32 v120, v120, v208, v204
	v_fma_f32 v121, v121, v208, v205
	v_fma_f32 v122, v122, v208, v206
	v_fma_f32 v123, v123, v208, v207
	v_fma_f32 v108, v108, v208, v216
	v_fma_f32 v109, v109, v208, v217
	v_fma_f32 v110, v110, v208, v218
	v_fma_f32 v111, v111, v208, v219
	v_fma_f32 v104, v104, v208, v220
	v_fma_f32 v105, v105, v208, v221
	v_fma_f32 v106, v106, v208, v222
	v_fma_f32 v107, v107, v208, v223
	v_fma_f32 v116, v116, v209, v200
	v_fma_f32 v117, v117, v209, v201
	v_fma_f32 v118, v118, v209, v202
	v_fma_f32 v119, v119, v209, v203
	v_fma_f32 v112, v112, v209, v204
	v_fma_f32 v113, v113, v209, v205
	v_fma_f32 v114, v114, v209, v206
	v_fma_f32 v115, v115, v209, v207
	v_fma_f32 v100, v100, v209, v216
	v_fma_f32 v101, v101, v209, v217
	v_fma_f32 v102, v102, v209, v218
	v_fma_f32 v103, v103, v209, v219
	v_fma_f32 v92, v92, v209, v220
	v_fma_f32 v93, v93, v209, v221
	v_fma_f32 v94, v94, v209, v222
	v_fma_f32 v95, v95, v209, v223
	v_fma_f32 v96, v96, v210, v200
	v_fma_f32 v97, v97, v210, v201
	v_fma_f32 v98, v98, v210, v202
	v_fma_f32 v99, v99, v210, v203
	v_fma_f32 v88, v88, v210, v204
	v_fma_f32 v89, v89, v210, v205
	v_fma_f32 v90, v90, v210, v206
	v_fma_f32 v91, v91, v210, v207
	v_fma_f32 v84, v84, v210, v216
	v_fma_f32 v85, v85, v210, v217
	v_fma_f32 v86, v86, v210, v218
	v_fma_f32 v87, v87, v210, v219
	v_fma_f32 v76, v76, v210, v220
	v_fma_f32 v77, v77, v210, v221
	v_fma_f32 v78, v78, v210, v222
	v_fma_f32 v79, v79, v210, v223
	v_fma_f32 v80, v80, v211, v200
	v_fma_f32 v81, v81, v211, v201
	v_fma_f32 v82, v82, v211, v202
	v_fma_f32 v83, v83, v211, v203
	v_fma_f32 v72, v72, v211, v204
	v_fma_f32 v73, v73, v211, v205
	v_fma_f32 v74, v74, v211, v206
	v_fma_f32 v75, v75, v211, v207
	v_fma_f32 v68, v68, v211, v216
	v_fma_f32 v69, v69, v211, v217
	v_fma_f32 v70, v70, v211, v218
	v_fma_f32 v71, v71, v211, v219
	v_fma_f32 v64, v64, v211, v220
	v_fma_f32 v65, v65, v211, v221
	v_fma_f32 v66, v66, v211, v222
	v_fma_f32 v67, v67, v211, v223
	v_fma_f32 v60, v60, v212, v200
	v_fma_f32 v61, v61, v212, v201
	v_fma_f32 v62, v62, v212, v202
	v_fma_f32 v63, v63, v212, v203
	v_fma_f32 v56, v56, v212, v204
	v_fma_f32 v57, v57, v212, v205
	v_fma_f32 v58, v58, v212, v206
	v_fma_f32 v59, v59, v212, v207
	v_fma_f32 v52, v52, v212, v216
	v_fma_f32 v53, v53, v212, v217
	v_fma_f32 v54, v54, v212, v218
	v_fma_f32 v55, v55, v212, v219
	v_fma_f32 v44, v44, v212, v220
	v_fma_f32 v45, v45, v212, v221
	v_fma_f32 v46, v46, v212, v222
	v_fma_f32 v47, v47, v212, v223
	v_fma_f32 v48, v48, v213, v200
	v_fma_f32 v49, v49, v213, v201
	v_fma_f32 v50, v50, v213, v202
	v_fma_f32 v51, v51, v213, v203
	v_fma_f32 v40, v40, v213, v204
	v_fma_f32 v41, v41, v213, v205
	v_fma_f32 v42, v42, v213, v206
	v_fma_f32 v43, v43, v213, v207
	v_fma_f32 v36, v36, v213, v216
	v_fma_f32 v37, v37, v213, v217
	v_fma_f32 v38, v38, v213, v218
	v_fma_f32 v39, v39, v213, v219
	v_fma_f32 v28, v28, v213, v220
	v_fma_f32 v29, v29, v213, v221
	v_fma_f32 v30, v30, v213, v222
	v_fma_f32 v31, v31, v213, v223
	v_fma_f32 v32, v32, v214, v200
	v_fma_f32 v33, v33, v214, v201
	v_fma_f32 v34, v34, v214, v202
	v_fma_f32 v35, v35, v214, v203
	v_fma_f32 v24, v24, v214, v204
	v_fma_f32 v25, v25, v214, v205
	v_fma_f32 v26, v26, v214, v206
	v_fma_f32 v27, v27, v214, v207
	v_fma_f32 v20, v20, v214, v216
	v_fma_f32 v21, v21, v214, v217
	v_fma_f32 v22, v22, v214, v218
	v_fma_f32 v23, v23, v214, v219
	v_fma_f32 v12, v12, v214, v220
	v_fma_f32 v13, v13, v214, v221
	v_fma_f32 v14, v14, v214, v222
	v_fma_f32 v15, v15, v214, v223
	v_fma_f32 v16, v16, v215, v200
	v_fma_f32 v17, v17, v215, v201
	v_fma_f32 v18, v18, v215, v202
	v_fma_f32 v19, v19, v215, v203
	v_fma_f32 v8, v8, v215, v204
	v_fma_f32 v9, v9, v215, v205
	v_fma_f32 v10, v10, v215, v206
	v_fma_f32 v11, v11, v215, v207
	v_fma_f32 v4, v4, v215, v216
	v_fma_f32 v5, v5, v215, v217
	v_fma_f32 v6, v6, v215, v218
	v_fma_f32 v7, v7, v215, v219
	v_fma_f32 v0, v0, v215, v220
	v_fma_f32 v1, v1, v215, v221
	v_fma_f32 v2, v2, v215, v222
	v_fma_f32 v3, v3, v215, v223
	global_load_dwordx4 v[128:131], v229, s[36:37]
	v_add_u32_e32 v211, 0x5800, v229
	global_load_dwordx4 v[132:135], v211, s[36:37]
	v_add_u32_e32 v210, 0xb000, v229
	global_load_dwordx4 v[136:139], v210, s[36:37]
	global_load_dwordx4 v[140:143], v229, s[38:39]
	v_add_u32_e32 v210, 0x2c00, v229
	global_load_dwordx4 v[160:163], v210, s[36:37]
	v_add_u32_e32 v211, 0x8400, v229
	global_load_dwordx4 v[172:175], v211, s[36:37]
	v_add_u32_e32 v210, 0xdc00, v229
	global_load_dwordx4 v[176:179], v210, s[36:37]
	v_add_u32_e32 v211, 0x2c00, v229
	global_load_dwordx4 v[180:183], v211, s[38:39]
	v_mov_b32_e32 v212, 0
	v_mov_b32_e32 v213, 0
	v_mov_b32_e32 v214, 0
	v_mov_b32_e32 v215, 0
	s_lshl_b32 s96, s27, 12
	s_sub_i32 s96, 0x2000, s96
	s_mul_i32 s94, s27, 0x1400
	s_add_i32 s94, s94, 0xc00
	s_lshl_b32 s79, s27, 10
	s_add_i32 s95, s79, 5120
	s_add_i32 s92, s79, 1024
	s_mov_b64 s[58:59], exec
	s_mov_b64 exec, s[54:55]
	v_add_u32_e32 v250, s96, v228
	ds_write_b128 v250, v[124:127] offset:0
	ds_write_b128 v250, v[120:123] offset:16
	ds_write_b128 v250, v[108:111] offset:512
	ds_write_b128 v250, v[104:107] offset:528
	v_add_u32_e32 v250, s95, v228
	ds_write_b128 v250, v[60:63] offset:0
	ds_write_b128 v250, v[56:59] offset:16
	ds_write_b128 v250, v[52:55] offset:512
	ds_write_b128 v250, v[44:47] offset:528
	ds_write_b128 v228, v[212:215] offset:0
	ds_write_b128 v228, v[212:215] offset:16
	ds_write_b128 v228, v[212:215] offset:512
	ds_write_b128 v228, v[212:215] offset:528
	s_mov_b64 exec, s[56:57]
	v_add_u32_e32 v251, s92, v228
	ds_write_b128 v251, v[80:83] offset:0
	ds_write_b128 v251, v[72:75] offset:16
	ds_write_b128 v251, v[68:71] offset:512
	ds_write_b128 v251, v[64:67] offset:528
	v_add_u32_e32 v251, s94, v228
	ds_write_b128 v251, v[16:19] offset:0
	ds_write_b128 v251, v[8:11] offset:16
	ds_write_b128 v251, v[4:7] offset:512
	ds_write_b128 v251, v[0:3] offset:528
	ds_write_b128 v228, v[212:215] offset:7168
	ds_write_b128 v228, v[212:215] offset:7184
	ds_write_b128 v228, v[212:215] offset:7680
	ds_write_b128 v228, v[212:215] offset:7696
	s_mov_b64 exec, s[58:59]
	s_waitcnt lgkmcnt(0)
	s_barrier
	ds_read_b128 v[184:187], v231 offset:0
	ds_read_b128 v[188:191], v231 offset:512
	ds_read_b128 v[192:195], v231 offset:2048
	ds_read_b128 v[196:199], v231 offset:2560
	s_waitcnt vmcnt(0)
	v_cndmask_b32_e64 v216, 0, v128, s[54:55]
	v_cndmask_b32_e64 v220, 0, v136, s[56:57]
	v_cndmask_b32_e64 v217, 0, v129, s[54:55]
	v_cndmask_b32_e64 v221, 0, v137, s[56:57]
	v_cndmask_b32_e64 v218, 0, v130, s[54:55]
	v_cndmask_b32_e64 v222, 0, v138, s[56:57]
	v_cndmask_b32_e64 v219, 0, v131, s[54:55]
	v_cndmask_b32_e64 v223, 0, v139, s[56:57]
	v_cndmask_b32_e64 v224, 0, v160, s[54:55]
	v_cndmask_b32_e64 v232, 0, v176, s[56:57]
	v_cndmask_b32_e64 v225, 0, v161, s[54:55]
	v_cndmask_b32_e64 v233, 0, v177, s[56:57]
	v_cndmask_b32_e64 v226, 0, v162, s[54:55]
	v_cndmask_b32_e64 v234, 0, v178, s[56:57]
	v_cndmask_b32_e64 v227, 0, v163, s[54:55]
	v_cndmask_b32_e64 v235, 0, v179, s[56:57]
	s_waitcnt lgkmcnt(0)
	s_nop 1
	v_fma_f32 v200, v132, v124, v140
	v_fma_f32 v201, v133, v125, v141
	v_fma_f32 v202, v134, v126, v142
	v_fma_f32 v203, v135, v127, v143
	v_fmac_f32_dpp v200, v124, v128 row_shr:1 row_mask:0xf bank_mask:0xf
	v_fmac_f32_dpp v201, v125, v129 row_shr:1 row_mask:0xf bank_mask:0xf
	v_fmac_f32_dpp v202, v126, v130 row_shr:1 row_mask:0xf bank_mask:0xf
	v_fmac_f32_dpp v203, v127, v131 row_shr:1 row_mask:0xf bank_mask:0xf
	v_fmac_f32_e32 v200, v184, v216
	v_fmac_f32_e32 v201, v185, v217
	v_fmac_f32_e32 v202, v186, v218
	v_fmac_f32_e32 v203, v187, v219
	v_fmac_f32_dpp v200, v124, v136 row_shl:1 row_mask:0xf bank_mask:0xf
	v_fmac_f32_dpp v201, v125, v137 row_shl:1 row_mask:0xf bank_mask:0xf
	v_fmac_f32_dpp v202, v126, v138 row_shl:1 row_mask:0xf bank_mask:0xf
	v_fmac_f32_dpp v203, v127, v139 row_shl:1 row_mask:0xf bank_mask:0xf
	v_fmac_f32_dpp v200, v116, v220 row_ror:15 row_mask:0xf bank_mask:0xf
	v_fmac_f32_dpp v201, v117, v221 row_ror:15 row_mask:0xf bank_mask:0xf
	v_fmac_f32_dpp v202, v118, v222 row_ror:15 row_mask:0xf bank_mask:0xf
	v_fmac_f32_dpp v203, v119, v223 row_ror:15 row_mask:0xf bank_mask:0xf
	v_fma_f32 v204, v172, v108, v180
	v_fma_f32 v205, v173, v109, v181
	v_fma_f32 v206, v174, v110, v182
	v_fma_f32 v207, v175, v111, v183
	v_fmac_f32_dpp v204, v108, v160 row_shr:1 row_mask:0xf bank_mask:0xf
	v_fmac_f32_dpp v205, v109, v161 row_shr:1 row_mask:0xf bank_mask:0xf
	v_fmac_f32_dpp v206, v110, v162 row_shr:1 row_mask:0xf bank_mask:0xf
	v_fmac_f32_dpp v207, v111, v163 row_shr:1 row_mask:0xf bank_mask:0xf
	v_fmac_f32_e32 v204, v188, v224
	v_fmac_f32_e32 v205, v189, v225
	v_fmac_f32_e32 v206, v190, v226
	v_fmac_f32_e32 v207, v191, v227
	v_fmac_f32_dpp v204, v108, v176 row_shl:1 row_mask:0xf bank_mask:0xf
	v_fmac_f32_dpp v205, v109, v177 row_shl:1 row_mask:0xf bank_mask:0xf
	v_fmac_f32_dpp v206, v110, v178 row_shl:1 row_mask:0xf bank_mask:0xf
	v_fmac_f32_dpp v207, v111, v179 row_shl:1 row_mask:0xf bank_mask:0xf
	v_fmac_f32_dpp v204, v100, v232 row_ror:15 row_mask:0xf bank_mask:0xf
	v_fmac_f32_dpp v205, v101, v233 row_ror:15 row_mask:0xf bank_mask:0xf
	v_fmac_f32_dpp v206, v102, v234 row_ror:15 row_mask:0xf bank_mask:0xf
	v_fmac_f32_dpp v207, v103, v235 row_ror:15 row_mask:0xf bank_mask:0xf
	v_mul_f32_e32 v208, 0xbfb8aa3b, v200
	v_mul_f32_e32 v209, 0xbfb8aa3b, v201
	v_mul_f32_e32 v210, 0xbfb8aa3b, v202
	v_mul_f32_e32 v211, 0xbfb8aa3b, v203
	v_exp_f32_e32 v208, v208
	v_exp_f32_e32 v209, v209
	v_exp_f32_e32 v210, v210
	v_exp_f32_e32 v211, v211
	v_add_f32_e32 v208, 1.0, v208
	v_add_f32_e32 v209, 1.0, v209
	v_add_f32_e32 v210, 1.0, v210
	v_add_f32_e32 v211, 1.0, v211
	v_rcp_f32_e32 v208, v208
	v_rcp_f32_e32 v209, v209
	v_rcp_f32_e32 v210, v210
	v_rcp_f32_e32 v211, v211
	v_mul_f32_e32 v200, v200, v208
	v_mul_f32_e32 v201, v201, v209
	v_mul_f32_e32 v202, v202, v210
	v_mul_f32_e32 v203, v203, v211
	v_mul_f32_e32 v200, v200, v204
	v_mul_f32_e32 v201, v201, v205
	v_mul_f32_e32 v202, v202, v206
	v_mul_f32_e32 v203, v203, v207
	v_cvt_pk_bf16_f32 v236, v200, v201
	v_cvt_pk_bf16_f32 v237, v202, v203
	v_fma_f32 v200, v132, v116, v140
	v_fma_f32 v201, v133, v117, v141
	v_fma_f32 v202, v134, v118, v142
	v_fma_f32 v203, v135, v119, v143
	v_fmac_f32_dpp v200, v116, v128 row_shr:1 row_mask:0xf bank_mask:0xf
	v_fmac_f32_dpp v201, v117, v129 row_shr:1 row_mask:0xf bank_mask:0xf
	v_fmac_f32_dpp v202, v118, v130 row_shr:1 row_mask:0xf bank_mask:0xf
	v_fmac_f32_dpp v203, v119, v131 row_shr:1 row_mask:0xf bank_mask:0xf
	v_fmac_f32_dpp v200, v124, v216 row_ror:1 row_mask:0xf bank_mask:0xf
	v_fmac_f32_dpp v201, v125, v217 row_ror:1 row_mask:0xf bank_mask:0xf
	v_fmac_f32_dpp v202, v126, v218 row_ror:1 row_mask:0xf bank_mask:0xf
	v_fmac_f32_dpp v203, v127, v219 row_ror:1 row_mask:0xf bank_mask:0xf
	v_fmac_f32_dpp v200, v116, v136 row_shl:1 row_mask:0xf bank_mask:0xf
	v_fmac_f32_dpp v201, v117, v137 row_shl:1 row_mask:0xf bank_mask:0xf
	v_fmac_f32_dpp v202, v118, v138 row_shl:1 row_mask:0xf bank_mask:0xf
	v_fmac_f32_dpp v203, v119, v139 row_shl:1 row_mask:0xf bank_mask:0xf
	v_fmac_f32_dpp v200, v96, v220 row_ror:15 row_mask:0xf bank_mask:0xf
	v_fmac_f32_dpp v201, v97, v221 row_ror:15 row_mask:0xf bank_mask:0xf
	v_fmac_f32_dpp v202, v98, v222 row_ror:15 row_mask:0xf bank_mask:0xf
	v_fmac_f32_dpp v203, v99, v223 row_ror:15 row_mask:0xf bank_mask:0xf
	v_fma_f32 v204, v172, v100, v180
	v_fma_f32 v205, v173, v101, v181
	v_fma_f32 v206, v174, v102, v182
	v_fma_f32 v207, v175, v103, v183
	v_fmac_f32_dpp v204, v100, v160 row_shr:1 row_mask:0xf bank_mask:0xf
	v_fmac_f32_dpp v205, v101, v161 row_shr:1 row_mask:0xf bank_mask:0xf
	v_fmac_f32_dpp v206, v102, v162 row_shr:1 row_mask:0xf bank_mask:0xf
	v_fmac_f32_dpp v207, v103, v163 row_shr:1 row_mask:0xf bank_mask:0xf
	v_fmac_f32_dpp v204, v108, v224 row_ror:1 row_mask:0xf bank_mask:0xf
	v_fmac_f32_dpp v205, v109, v225 row_ror:1 row_mask:0xf bank_mask:0xf
	v_fmac_f32_dpp v206, v110, v226 row_ror:1 row_mask:0xf bank_mask:0xf
	v_fmac_f32_dpp v207, v111, v227 row_ror:1 row_mask:0xf bank_mask:0xf
	v_fmac_f32_dpp v204, v100, v176 row_shl:1 row_mask:0xf bank_mask:0xf
	v_fmac_f32_dpp v205, v101, v177 row_shl:1 row_mask:0xf bank_mask:0xf
	v_fmac_f32_dpp v206, v102, v178 row_shl:1 row_mask:0xf bank_mask:0xf
	v_fmac_f32_dpp v207, v103, v179 row_shl:1 row_mask:0xf bank_mask:0xf
	v_fmac_f32_dpp v204, v84, v232 row_ror:15 row_mask:0xf bank_mask:0xf
	v_fmac_f32_dpp v205, v85, v233 row_ror:15 row_mask:0xf bank_mask:0xf
	v_fmac_f32_dpp v206, v86, v234 row_ror:15 row_mask:0xf bank_mask:0xf
	v_fmac_f32_dpp v207, v87, v235 row_ror:15 row_mask:0xf bank_mask:0xf
	v_mul_f32_e32 v208, 0xbfb8aa3b, v200
	v_mul_f32_e32 v209, 0xbfb8aa3b, v201
	v_mul_f32_e32 v210, 0xbfb8aa3b, v202
	v_mul_f32_e32 v211, 0xbfb8aa3b, v203
	v_exp_f32_e32 v208, v208
	v_exp_f32_e32 v209, v209
	v_exp_f32_e32 v210, v210
	v_exp_f32_e32 v211, v211
	v_add_f32_e32 v208, 1.0, v208
	v_add_f32_e32 v209, 1.0, v209
	v_add_f32_e32 v210, 1.0, v210
	v_add_f32_e32 v211, 1.0, v211
	v_rcp_f32_e32 v208, v208
	v_rcp_f32_e32 v209, v209
	v_rcp_f32_e32 v210, v210
	v_rcp_f32_e32 v211, v211
	v_mul_f32_e32 v200, v200, v208
	v_mul_f32_e32 v201, v201, v209
	v_mul_f32_e32 v202, v202, v210
	v_mul_f32_e32 v203, v203, v211
	v_mul_f32_e32 v200, v200, v204
	v_mul_f32_e32 v201, v201, v205
	v_mul_f32_e32 v202, v202, v206
	v_mul_f32_e32 v203, v203, v207
	v_cvt_pk_bf16_f32 v238, v200, v201
	v_cvt_pk_bf16_f32 v239, v202, v203
	v_fma_f32 v200, v132, v96, v140
	v_fma_f32 v201, v133, v97, v141
	v_fma_f32 v202, v134, v98, v142
	v_fma_f32 v203, v135, v99, v143
	v_fmac_f32_dpp v200, v96, v128 row_shr:1 row_mask:0xf bank_mask:0xf
	v_fmac_f32_dpp v201, v97, v129 row_shr:1 row_mask:0xf bank_mask:0xf
	v_fmac_f32_dpp v202, v98, v130 row_shr:1 row_mask:0xf bank_mask:0xf
	v_fmac_f32_dpp v203, v99, v131 row_shr:1 row_mask:0xf bank_mask:0xf
	v_fmac_f32_dpp v200, v116, v216 row_ror:1 row_mask:0xf bank_mask:0xf
	v_fmac_f32_dpp v201, v117, v217 row_ror:1 row_mask:0xf bank_mask:0xf
	v_fmac_f32_dpp v202, v118, v218 row_ror:1 row_mask:0xf bank_mask:0xf
	v_fmac_f32_dpp v203, v119, v219 row_ror:1 row_mask:0xf bank_mask:0xf
	v_fmac_f32_dpp v200, v96, v136 row_shl:1 row_mask:0xf bank_mask:0xf
	v_fmac_f32_dpp v201, v97, v137 row_shl:1 row_mask:0xf bank_mask:0xf
	v_fmac_f32_dpp v202, v98, v138 row_shl:1 row_mask:0xf bank_mask:0xf
	v_fmac_f32_dpp v203, v99, v139 row_shl:1 row_mask:0xf bank_mask:0xf
	v_fmac_f32_dpp v200, v80, v220 row_ror:15 row_mask:0xf bank_mask:0xf
	v_fmac_f32_dpp v201, v81, v221 row_ror:15 row_mask:0xf bank_mask:0xf
	v_fmac_f32_dpp v202, v82, v222 row_ror:15 row_mask:0xf bank_mask:0xf
	v_fmac_f32_dpp v203, v83, v223 row_ror:15 row_mask:0xf bank_mask:0xf
	v_fma_f32 v204, v172, v84, v180
	v_fma_f32 v205, v173, v85, v181
	v_fma_f32 v206, v174, v86, v182
	v_fma_f32 v207, v175, v87, v183
	v_fmac_f32_dpp v204, v84, v160 row_shr:1 row_mask:0xf bank_mask:0xf
	v_fmac_f32_dpp v205, v85, v161 row_shr:1 row_mask:0xf bank_mask:0xf
	v_fmac_f32_dpp v206, v86, v162 row_shr:1 row_mask:0xf bank_mask:0xf
	v_fmac_f32_dpp v207, v87, v163 row_shr:1 row_mask:0xf bank_mask:0xf
	v_fmac_f32_dpp v204, v100, v224 row_ror:1 row_mask:0xf bank_mask:0xf
	v_fmac_f32_dpp v205, v101, v225 row_ror:1 row_mask:0xf bank_mask:0xf
	v_fmac_f32_dpp v206, v102, v226 row_ror:1 row_mask:0xf bank_mask:0xf
	v_fmac_f32_dpp v207, v103, v227 row_ror:1 row_mask:0xf bank_mask:0xf
	v_fmac_f32_dpp v204, v84, v176 row_shl:1 row_mask:0xf bank_mask:0xf
	v_fmac_f32_dpp v205, v85, v177 row_shl:1 row_mask:0xf bank_mask:0xf
	v_fmac_f32_dpp v206, v86, v178 row_shl:1 row_mask:0xf bank_mask:0xf
	v_fmac_f32_dpp v207, v87, v179 row_shl:1 row_mask:0xf bank_mask:0xf
	v_fmac_f32_dpp v204, v68, v232 row_ror:15 row_mask:0xf bank_mask:0xf
	v_fmac_f32_dpp v205, v69, v233 row_ror:15 row_mask:0xf bank_mask:0xf
	v_fmac_f32_dpp v206, v70, v234 row_ror:15 row_mask:0xf bank_mask:0xf
	v_fmac_f32_dpp v207, v71, v235 row_ror:15 row_mask:0xf bank_mask:0xf
	v_mul_f32_e32 v208, 0xbfb8aa3b, v200
	v_mul_f32_e32 v209, 0xbfb8aa3b, v201
	v_mul_f32_e32 v210, 0xbfb8aa3b, v202
	v_mul_f32_e32 v211, 0xbfb8aa3b, v203
	v_exp_f32_e32 v208, v208
	v_exp_f32_e32 v209, v209
	v_exp_f32_e32 v210, v210
	v_exp_f32_e32 v211, v211
	v_add_f32_e32 v208, 1.0, v208
	v_add_f32_e32 v209, 1.0, v209
	v_add_f32_e32 v210, 1.0, v210
	v_add_f32_e32 v211, 1.0, v211
	v_rcp_f32_e32 v208, v208
	v_rcp_f32_e32 v209, v209
	v_rcp_f32_e32 v210, v210
	v_rcp_f32_e32 v211, v211
	v_mul_f32_e32 v200, v200, v208
	v_mul_f32_e32 v201, v201, v209
	v_mul_f32_e32 v202, v202, v210
	v_mul_f32_e32 v203, v203, v211
	v_mul_f32_e32 v200, v200, v204
	v_mul_f32_e32 v201, v201, v205
	v_mul_f32_e32 v202, v202, v206
	v_mul_f32_e32 v203, v203, v207
	v_cvt_pk_bf16_f32 v240, v200, v201
	v_cvt_pk_bf16_f32 v241, v202, v203
	v_fma_f32 v200, v132, v80, v140
	v_fma_f32 v201, v133, v81, v141
	v_fma_f32 v202, v134, v82, v142
	v_fma_f32 v203, v135, v83, v143
	v_fmac_f32_dpp v200, v80, v128 row_shr:1 row_mask:0xf bank_mask:0xf
	v_fmac_f32_dpp v201, v81, v129 row_shr:1 row_mask:0xf bank_mask:0xf
	v_fmac_f32_dpp v202, v82, v130 row_shr:1 row_mask:0xf bank_mask:0xf
	v_fmac_f32_dpp v203, v83, v131 row_shr:1 row_mask:0xf bank_mask:0xf
	v_fmac_f32_dpp v200, v96, v216 row_ror:1 row_mask:0xf bank_mask:0xf
	v_fmac_f32_dpp v201, v97, v217 row_ror:1 row_mask:0xf bank_mask:0xf
	v_fmac_f32_dpp v202, v98, v218 row_ror:1 row_mask:0xf bank_mask:0xf
	v_fmac_f32_dpp v203, v99, v219 row_ror:1 row_mask:0xf bank_mask:0xf
	v_fmac_f32_dpp v200, v80, v136 row_shl:1 row_mask:0xf bank_mask:0xf
	v_fmac_f32_dpp v201, v81, v137 row_shl:1 row_mask:0xf bank_mask:0xf
	v_fmac_f32_dpp v202, v82, v138 row_shl:1 row_mask:0xf bank_mask:0xf
	v_fmac_f32_dpp v203, v83, v139 row_shl:1 row_mask:0xf bank_mask:0xf
	v_fmac_f32_e32 v200, v184, v220
	v_fmac_f32_e32 v201, v185, v221
	v_fmac_f32_e32 v202, v186, v222
	v_fmac_f32_e32 v203, v187, v223
	v_fma_f32 v204, v172, v68, v180
	v_fma_f32 v205, v173, v69, v181
	v_fma_f32 v206, v174, v70, v182
	v_fma_f32 v207, v175, v71, v183
	v_fmac_f32_dpp v204, v68, v160 row_shr:1 row_mask:0xf bank_mask:0xf
	v_fmac_f32_dpp v205, v69, v161 row_shr:1 row_mask:0xf bank_mask:0xf
	v_fmac_f32_dpp v206, v70, v162 row_shr:1 row_mask:0xf bank_mask:0xf
	v_fmac_f32_dpp v207, v71, v163 row_shr:1 row_mask:0xf bank_mask:0xf
	v_fmac_f32_dpp v204, v84, v224 row_ror:1 row_mask:0xf bank_mask:0xf
	v_fmac_f32_dpp v205, v85, v225 row_ror:1 row_mask:0xf bank_mask:0xf
	v_fmac_f32_dpp v206, v86, v226 row_ror:1 row_mask:0xf bank_mask:0xf
	v_fmac_f32_dpp v207, v87, v227 row_ror:1 row_mask:0xf bank_mask:0xf
	v_fmac_f32_dpp v204, v68, v176 row_shl:1 row_mask:0xf bank_mask:0xf
	v_fmac_f32_dpp v205, v69, v177 row_shl:1 row_mask:0xf bank_mask:0xf
	v_fmac_f32_dpp v206, v70, v178 row_shl:1 row_mask:0xf bank_mask:0xf
	v_fmac_f32_dpp v207, v71, v179 row_shl:1 row_mask:0xf bank_mask:0xf
	v_fmac_f32_e32 v204, v188, v232
	v_fmac_f32_e32 v205, v189, v233
	v_fmac_f32_e32 v206, v190, v234
	v_fmac_f32_e32 v207, v191, v235
	v_mul_f32_e32 v208, 0xbfb8aa3b, v200
	v_mul_f32_e32 v209, 0xbfb8aa3b, v201
	v_mul_f32_e32 v210, 0xbfb8aa3b, v202
	v_mul_f32_e32 v211, 0xbfb8aa3b, v203
	v_exp_f32_e32 v208, v208
	v_exp_f32_e32 v209, v209
	v_exp_f32_e32 v210, v210
	v_exp_f32_e32 v211, v211
	v_add_f32_e32 v208, 1.0, v208
	v_add_f32_e32 v209, 1.0, v209
	v_add_f32_e32 v210, 1.0, v210
	v_add_f32_e32 v211, 1.0, v211
	v_rcp_f32_e32 v208, v208
	v_rcp_f32_e32 v209, v209
	v_rcp_f32_e32 v210, v210
	v_rcp_f32_e32 v211, v211
	v_mul_f32_e32 v200, v200, v208
	v_mul_f32_e32 v201, v201, v209
	v_mul_f32_e32 v202, v202, v210
	v_mul_f32_e32 v203, v203, v211
	v_mul_f32_e32 v200, v200, v204
	v_mul_f32_e32 v201, v201, v205
	v_mul_f32_e32 v202, v202, v206
	v_mul_f32_e32 v203, v203, v207
	v_cvt_pk_bf16_f32 v242, v200, v201
	v_cvt_pk_bf16_f32 v243, v202, v203
	v_fma_f32 v200, v132, v60, v140
	v_fma_f32 v201, v133, v61, v141
	v_fma_f32 v202, v134, v62, v142
	v_fma_f32 v203, v135, v63, v143
	v_fmac_f32_dpp v200, v60, v128 row_shr:1 row_mask:0xf bank_mask:0xf
	v_fmac_f32_dpp v201, v61, v129 row_shr:1 row_mask:0xf bank_mask:0xf
	v_fmac_f32_dpp v202, v62, v130 row_shr:1 row_mask:0xf bank_mask:0xf
	v_fmac_f32_dpp v203, v63, v131 row_shr:1 row_mask:0xf bank_mask:0xf
	v_fmac_f32_e32 v200, v192, v216
	v_fmac_f32_e32 v201, v193, v217
	v_fmac_f32_e32 v202, v194, v218
	v_fmac_f32_e32 v203, v195, v219
	v_fmac_f32_dpp v200, v60, v136 row_shl:1 row_mask:0xf bank_mask:0xf
	v_fmac_f32_dpp v201, v61, v137 row_shl:1 row_mask:0xf bank_mask:0xf
	v_fmac_f32_dpp v202, v62, v138 row_shl:1 row_mask:0xf bank_mask:0xf
	v_fmac_f32_dpp v203, v63, v139 row_shl:1 row_mask:0xf bank_mask:0xf
	v_fmac_f32_dpp v200, v48, v220 row_ror:15 row_mask:0xf bank_mask:0xf
	v_fmac_f32_dpp v201, v49, v221 row_ror:15 row_mask:0xf bank_mask:0xf
	v_fmac_f32_dpp v202, v50, v222 row_ror:15 row_mask:0xf bank_mask:0xf
	v_fmac_f32_dpp v203, v51, v223 row_ror:15 row_mask:0xf bank_mask:0xf
	v_fma_f32 v204, v172, v52, v180
	v_fma_f32 v205, v173, v53, v181
	v_fma_f32 v206, v174, v54, v182
	v_fma_f32 v207, v175, v55, v183
	v_fmac_f32_dpp v204, v52, v160 row_shr:1 row_mask:0xf bank_mask:0xf
	v_fmac_f32_dpp v205, v53, v161 row_shr:1 row_mask:0xf bank_mask:0xf
	v_fmac_f32_dpp v206, v54, v162 row_shr:1 row_mask:0xf bank_mask:0xf
	v_fmac_f32_dpp v207, v55, v163 row_shr:1 row_mask:0xf bank_mask:0xf
	v_fmac_f32_e32 v204, v196, v224
	v_fmac_f32_e32 v205, v197, v225
	v_fmac_f32_e32 v206, v198, v226
	v_fmac_f32_e32 v207, v199, v227
	v_fmac_f32_dpp v204, v52, v176 row_shl:1 row_mask:0xf bank_mask:0xf
	v_fmac_f32_dpp v205, v53, v177 row_shl:1 row_mask:0xf bank_mask:0xf
	v_fmac_f32_dpp v206, v54, v178 row_shl:1 row_mask:0xf bank_mask:0xf
	v_fmac_f32_dpp v207, v55, v179 row_shl:1 row_mask:0xf bank_mask:0xf
	v_fmac_f32_dpp v204, v36, v232 row_ror:15 row_mask:0xf bank_mask:0xf
	v_fmac_f32_dpp v205, v37, v233 row_ror:15 row_mask:0xf bank_mask:0xf
	v_fmac_f32_dpp v206, v38, v234 row_ror:15 row_mask:0xf bank_mask:0xf
	v_fmac_f32_dpp v207, v39, v235 row_ror:15 row_mask:0xf bank_mask:0xf
	v_mul_f32_e32 v208, 0xbfb8aa3b, v200
	v_mul_f32_e32 v209, 0xbfb8aa3b, v201
	v_mul_f32_e32 v210, 0xbfb8aa3b, v202
	v_mul_f32_e32 v211, 0xbfb8aa3b, v203
	v_exp_f32_e32 v208, v208
	v_exp_f32_e32 v209, v209
	v_exp_f32_e32 v210, v210
	v_exp_f32_e32 v211, v211
	v_add_f32_e32 v208, 1.0, v208
	v_add_f32_e32 v209, 1.0, v209
	v_add_f32_e32 v210, 1.0, v210
	v_add_f32_e32 v211, 1.0, v211
	v_rcp_f32_e32 v208, v208
	v_rcp_f32_e32 v209, v209
	v_rcp_f32_e32 v210, v210
	v_rcp_f32_e32 v211, v211
	v_mul_f32_e32 v200, v200, v208
	v_mul_f32_e32 v201, v201, v209
	v_mul_f32_e32 v202, v202, v210
	v_mul_f32_e32 v203, v203, v211
	v_mul_f32_e32 v200, v200, v204
	v_mul_f32_e32 v201, v201, v205
	v_mul_f32_e32 v202, v202, v206
	v_mul_f32_e32 v203, v203, v207
	v_cvt_pk_bf16_f32 v244, v200, v201
	v_cvt_pk_bf16_f32 v245, v202, v203
	v_fma_f32 v200, v132, v48, v140
	v_fma_f32 v201, v133, v49, v141
	v_fma_f32 v202, v134, v50, v142
	v_fma_f32 v203, v135, v51, v143
	v_fmac_f32_dpp v200, v48, v128 row_shr:1 row_mask:0xf bank_mask:0xf
	v_fmac_f32_dpp v201, v49, v129 row_shr:1 row_mask:0xf bank_mask:0xf
	v_fmac_f32_dpp v202, v50, v130 row_shr:1 row_mask:0xf bank_mask:0xf
	v_fmac_f32_dpp v203, v51, v131 row_shr:1 row_mask:0xf bank_mask:0xf
	v_fmac_f32_dpp v200, v60, v216 row_ror:1 row_mask:0xf bank_mask:0xf
	v_fmac_f32_dpp v201, v61, v217 row_ror:1 row_mask:0xf bank_mask:0xf
	v_fmac_f32_dpp v202, v62, v218 row_ror:1 row_mask:0xf bank_mask:0xf
	v_fmac_f32_dpp v203, v63, v219 row_ror:1 row_mask:0xf bank_mask:0xf
	v_fmac_f32_dpp v200, v48, v136 row_shl:1 row_mask:0xf bank_mask:0xf
	v_fmac_f32_dpp v201, v49, v137 row_shl:1 row_mask:0xf bank_mask:0xf
	v_fmac_f32_dpp v202, v50, v138 row_shl:1 row_mask:0xf bank_mask:0xf
	v_fmac_f32_dpp v203, v51, v139 row_shl:1 row_mask:0xf bank_mask:0xf
	v_fmac_f32_dpp v200, v32, v220 row_ror:15 row_mask:0xf bank_mask:0xf
	v_fmac_f32_dpp v201, v33, v221 row_ror:15 row_mask:0xf bank_mask:0xf
	v_fmac_f32_dpp v202, v34, v222 row_ror:15 row_mask:0xf bank_mask:0xf
	v_fmac_f32_dpp v203, v35, v223 row_ror:15 row_mask:0xf bank_mask:0xf
	v_fma_f32 v204, v172, v36, v180
	v_fma_f32 v205, v173, v37, v181
	v_fma_f32 v206, v174, v38, v182
	v_fma_f32 v207, v175, v39, v183
	v_fmac_f32_dpp v204, v36, v160 row_shr:1 row_mask:0xf bank_mask:0xf
	v_fmac_f32_dpp v205, v37, v161 row_shr:1 row_mask:0xf bank_mask:0xf
	v_fmac_f32_dpp v206, v38, v162 row_shr:1 row_mask:0xf bank_mask:0xf
	v_fmac_f32_dpp v207, v39, v163 row_shr:1 row_mask:0xf bank_mask:0xf
	v_fmac_f32_dpp v204, v52, v224 row_ror:1 row_mask:0xf bank_mask:0xf
	v_fmac_f32_dpp v205, v53, v225 row_ror:1 row_mask:0xf bank_mask:0xf
	v_fmac_f32_dpp v206, v54, v226 row_ror:1 row_mask:0xf bank_mask:0xf
	v_fmac_f32_dpp v207, v55, v227 row_ror:1 row_mask:0xf bank_mask:0xf
	v_fmac_f32_dpp v204, v36, v176 row_shl:1 row_mask:0xf bank_mask:0xf
	v_fmac_f32_dpp v205, v37, v177 row_shl:1 row_mask:0xf bank_mask:0xf
	v_fmac_f32_dpp v206, v38, v178 row_shl:1 row_mask:0xf bank_mask:0xf
	v_fmac_f32_dpp v207, v39, v179 row_shl:1 row_mask:0xf bank_mask:0xf
	v_fmac_f32_dpp v204, v20, v232 row_ror:15 row_mask:0xf bank_mask:0xf
	v_fmac_f32_dpp v205, v21, v233 row_ror:15 row_mask:0xf bank_mask:0xf
	v_fmac_f32_dpp v206, v22, v234 row_ror:15 row_mask:0xf bank_mask:0xf
	v_fmac_f32_dpp v207, v23, v235 row_ror:15 row_mask:0xf bank_mask:0xf
	v_mul_f32_e32 v208, 0xbfb8aa3b, v200
	v_mul_f32_e32 v209, 0xbfb8aa3b, v201
	v_mul_f32_e32 v210, 0xbfb8aa3b, v202
	v_mul_f32_e32 v211, 0xbfb8aa3b, v203
	v_exp_f32_e32 v208, v208
	v_exp_f32_e32 v209, v209
	v_exp_f32_e32 v210, v210
	v_exp_f32_e32 v211, v211
	v_add_f32_e32 v208, 1.0, v208
	v_add_f32_e32 v209, 1.0, v209
	v_add_f32_e32 v210, 1.0, v210
	v_add_f32_e32 v211, 1.0, v211
	v_rcp_f32_e32 v208, v208
	v_rcp_f32_e32 v209, v209
	v_rcp_f32_e32 v210, v210
	v_rcp_f32_e32 v211, v211
	v_mul_f32_e32 v200, v200, v208
	v_mul_f32_e32 v201, v201, v209
	v_mul_f32_e32 v202, v202, v210
	v_mul_f32_e32 v203, v203, v211
	v_mul_f32_e32 v200, v200, v204
	v_mul_f32_e32 v201, v201, v205
	v_mul_f32_e32 v202, v202, v206
	v_mul_f32_e32 v203, v203, v207
	v_cvt_pk_bf16_f32 v246, v200, v201
	v_cvt_pk_bf16_f32 v247, v202, v203
	v_fma_f32 v200, v132, v32, v140
	v_fma_f32 v201, v133, v33, v141
	v_fma_f32 v202, v134, v34, v142
	v_fma_f32 v203, v135, v35, v143
	v_fmac_f32_dpp v200, v32, v128 row_shr:1 row_mask:0xf bank_mask:0xf
	v_fmac_f32_dpp v201, v33, v129 row_shr:1 row_mask:0xf bank_mask:0xf
	v_fmac_f32_dpp v202, v34, v130 row_shr:1 row_mask:0xf bank_mask:0xf
	v_fmac_f32_dpp v203, v35, v131 row_shr:1 row_mask:0xf bank_mask:0xf
	v_fmac_f32_dpp v200, v48, v216 row_ror:1 row_mask:0xf bank_mask:0xf
	v_fmac_f32_dpp v201, v49, v217 row_ror:1 row_mask:0xf bank_mask:0xf
	v_fmac_f32_dpp v202, v50, v218 row_ror:1 row_mask:0xf bank_mask:0xf
	v_fmac_f32_dpp v203, v51, v219 row_ror:1 row_mask:0xf bank_mask:0xf
	v_fmac_f32_dpp v200, v32, v136 row_shl:1 row_mask:0xf bank_mask:0xf
	v_fmac_f32_dpp v201, v33, v137 row_shl:1 row_mask:0xf bank_mask:0xf
	v_fmac_f32_dpp v202, v34, v138 row_shl:1 row_mask:0xf bank_mask:0xf
	v_fmac_f32_dpp v203, v35, v139 row_shl:1 row_mask:0xf bank_mask:0xf
	v_fmac_f32_dpp v200, v16, v220 row_ror:15 row_mask:0xf bank_mask:0xf
	v_fmac_f32_dpp v201, v17, v221 row_ror:15 row_mask:0xf bank_mask:0xf
	v_fmac_f32_dpp v202, v18, v222 row_ror:15 row_mask:0xf bank_mask:0xf
	v_fmac_f32_dpp v203, v19, v223 row_ror:15 row_mask:0xf bank_mask:0xf
	v_fma_f32 v204, v172, v20, v180
	v_fma_f32 v205, v173, v21, v181
	v_fma_f32 v206, v174, v22, v182
	v_fma_f32 v207, v175, v23, v183
	v_fmac_f32_dpp v204, v20, v160 row_shr:1 row_mask:0xf bank_mask:0xf
	v_fmac_f32_dpp v205, v21, v161 row_shr:1 row_mask:0xf bank_mask:0xf
	v_fmac_f32_dpp v206, v22, v162 row_shr:1 row_mask:0xf bank_mask:0xf
	v_fmac_f32_dpp v207, v23, v163 row_shr:1 row_mask:0xf bank_mask:0xf
	v_fmac_f32_dpp v204, v36, v224 row_ror:1 row_mask:0xf bank_mask:0xf
	v_fmac_f32_dpp v205, v37, v225 row_ror:1 row_mask:0xf bank_mask:0xf
	v_fmac_f32_dpp v206, v38, v226 row_ror:1 row_mask:0xf bank_mask:0xf
	v_fmac_f32_dpp v207, v39, v227 row_ror:1 row_mask:0xf bank_mask:0xf
	v_fmac_f32_dpp v204, v20, v176 row_shl:1 row_mask:0xf bank_mask:0xf
	v_fmac_f32_dpp v205, v21, v177 row_shl:1 row_mask:0xf bank_mask:0xf
	v_fmac_f32_dpp v206, v22, v178 row_shl:1 row_mask:0xf bank_mask:0xf
	v_fmac_f32_dpp v207, v23, v179 row_shl:1 row_mask:0xf bank_mask:0xf
	v_fmac_f32_dpp v204, v4, v232 row_ror:15 row_mask:0xf bank_mask:0xf
	v_fmac_f32_dpp v205, v5, v233 row_ror:15 row_mask:0xf bank_mask:0xf
	v_fmac_f32_dpp v206, v6, v234 row_ror:15 row_mask:0xf bank_mask:0xf
	v_fmac_f32_dpp v207, v7, v235 row_ror:15 row_mask:0xf bank_mask:0xf
	v_mul_f32_e32 v208, 0xbfb8aa3b, v200
	v_mul_f32_e32 v209, 0xbfb8aa3b, v201
	v_mul_f32_e32 v210, 0xbfb8aa3b, v202
	v_mul_f32_e32 v211, 0xbfb8aa3b, v203
	v_exp_f32_e32 v208, v208
	v_exp_f32_e32 v209, v209
	v_exp_f32_e32 v210, v210
	v_exp_f32_e32 v211, v211
	v_add_f32_e32 v208, 1.0, v208
	v_add_f32_e32 v209, 1.0, v209
	v_add_f32_e32 v210, 1.0, v210
	v_add_f32_e32 v211, 1.0, v211
	v_rcp_f32_e32 v208, v208
	v_rcp_f32_e32 v209, v209
	v_rcp_f32_e32 v210, v210
	v_rcp_f32_e32 v211, v211
	v_mul_f32_e32 v200, v200, v208
	v_mul_f32_e32 v201, v201, v209
	v_mul_f32_e32 v202, v202, v210
	v_mul_f32_e32 v203, v203, v211
	v_mul_f32_e32 v200, v200, v204
	v_mul_f32_e32 v201, v201, v205
	v_mul_f32_e32 v202, v202, v206
	v_mul_f32_e32 v203, v203, v207
	v_cvt_pk_bf16_f32 v248, v200, v201
	v_cvt_pk_bf16_f32 v249, v202, v203
	v_fma_f32 v200, v132, v16, v140
	v_fma_f32 v201, v133, v17, v141
	v_fma_f32 v202, v134, v18, v142
	v_fma_f32 v203, v135, v19, v143
	v_fmac_f32_dpp v200, v16, v128 row_shr:1 row_mask:0xf bank_mask:0xf
	v_fmac_f32_dpp v201, v17, v129 row_shr:1 row_mask:0xf bank_mask:0xf
	v_fmac_f32_dpp v202, v18, v130 row_shr:1 row_mask:0xf bank_mask:0xf
	v_fmac_f32_dpp v203, v19, v131 row_shr:1 row_mask:0xf bank_mask:0xf
	v_fmac_f32_dpp v200, v32, v216 row_ror:1 row_mask:0xf bank_mask:0xf
	v_fmac_f32_dpp v201, v33, v217 row_ror:1 row_mask:0xf bank_mask:0xf
	v_fmac_f32_dpp v202, v34, v218 row_ror:1 row_mask:0xf bank_mask:0xf
	v_fmac_f32_dpp v203, v35, v219 row_ror:1 row_mask:0xf bank_mask:0xf
	v_fmac_f32_dpp v200, v16, v136 row_shl:1 row_mask:0xf bank_mask:0xf
	v_fmac_f32_dpp v201, v17, v137 row_shl:1 row_mask:0xf bank_mask:0xf
	v_fmac_f32_dpp v202, v18, v138 row_shl:1 row_mask:0xf bank_mask:0xf
	v_fmac_f32_dpp v203, v19, v139 row_shl:1 row_mask:0xf bank_mask:0xf
	v_fmac_f32_e32 v200, v192, v220
	v_fmac_f32_e32 v201, v193, v221
	v_fmac_f32_e32 v202, v194, v222
	v_fmac_f32_e32 v203, v195, v223
	v_fma_f32 v204, v172, v4, v180
	v_fma_f32 v205, v173, v5, v181
	v_fma_f32 v206, v174, v6, v182
	v_fma_f32 v207, v175, v7, v183
	v_fmac_f32_dpp v204, v4, v160 row_shr:1 row_mask:0xf bank_mask:0xf
	v_fmac_f32_dpp v205, v5, v161 row_shr:1 row_mask:0xf bank_mask:0xf
	v_fmac_f32_dpp v206, v6, v162 row_shr:1 row_mask:0xf bank_mask:0xf
	v_fmac_f32_dpp v207, v7, v163 row_shr:1 row_mask:0xf bank_mask:0xf
	v_fmac_f32_dpp v204, v20, v224 row_ror:1 row_mask:0xf bank_mask:0xf
	v_fmac_f32_dpp v205, v21, v225 row_ror:1 row_mask:0xf bank_mask:0xf
	v_fmac_f32_dpp v206, v22, v226 row_ror:1 row_mask:0xf bank_mask:0xf
	v_fmac_f32_dpp v207, v23, v227 row_ror:1 row_mask:0xf bank_mask:0xf
	v_fmac_f32_dpp v204, v4, v176 row_shl:1 row_mask:0xf bank_mask:0xf
	v_fmac_f32_dpp v205, v5, v177 row_shl:1 row_mask:0xf bank_mask:0xf
	v_fmac_f32_dpp v206, v6, v178 row_shl:1 row_mask:0xf bank_mask:0xf
	v_fmac_f32_dpp v207, v7, v179 row_shl:1 row_mask:0xf bank_mask:0xf
	v_fmac_f32_e32 v204, v196, v232
	v_fmac_f32_e32 v205, v197, v233
	v_fmac_f32_e32 v206, v198, v234
	v_fmac_f32_e32 v207, v199, v235
	v_mul_f32_e32 v208, 0xbfb8aa3b, v200
	v_mul_f32_e32 v209, 0xbfb8aa3b, v201
	v_mul_f32_e32 v210, 0xbfb8aa3b, v202
	v_mul_f32_e32 v211, 0xbfb8aa3b, v203
	v_exp_f32_e32 v208, v208
	v_exp_f32_e32 v209, v209
	v_exp_f32_e32 v210, v210
	v_exp_f32_e32 v211, v211
	v_add_f32_e32 v208, 1.0, v208
	v_add_f32_e32 v209, 1.0, v209
	v_add_f32_e32 v210, 1.0, v210
	v_add_f32_e32 v211, 1.0, v211
	v_rcp_f32_e32 v208, v208
	v_rcp_f32_e32 v209, v209
	v_rcp_f32_e32 v210, v210
	v_rcp_f32_e32 v211, v211
	v_mul_f32_e32 v200, v200, v208
	v_mul_f32_e32 v201, v201, v209
	v_mul_f32_e32 v202, v202, v210
	v_mul_f32_e32 v203, v203, v211
	v_mul_f32_e32 v200, v200, v204
	v_mul_f32_e32 v201, v201, v205
	v_mul_f32_e32 v202, v202, v206
	v_mul_f32_e32 v203, v203, v207
	v_cvt_pk_bf16_f32 v250, v200, v201
	v_cvt_pk_bf16_f32 v251, v202, v203
	global_load_dwordx4 v[128:131], v229, s[36:37] offset:16
	v_add_u32_e32 v211, 0x5800, v229
	global_load_dwordx4 v[132:135], v211, s[36:37] offset:16
	v_add_u32_e32 v210, 0xb000, v229
	global_load_dwordx4 v[136:139], v210, s[36:37] offset:16
	global_load_dwordx4 v[140:143], v229, s[38:39] offset:16
	v_add_u32_e32 v210, 0x2c00, v229
	global_load_dwordx4 v[160:163], v210, s[36:37] offset:16
	v_add_u32_e32 v211, 0x8400, v229
	global_load_dwordx4 v[172:175], v211, s[36:37] offset:16
	v_add_u32_e32 v210, 0xdc00, v229
	global_load_dwordx4 v[176:179], v210, s[36:37] offset:16
	v_add_u32_e32 v211, 0x2c00, v229
	global_load_dwordx4 v[180:183], v211, s[38:39] offset:16
	v_mov_b32_e32 v124, v236
	v_mov_b32_e32 v125, v237
	v_mov_b32_e32 v116, v238
	v_mov_b32_e32 v117, v239
	v_mov_b32_e32 v96, v240
	v_mov_b32_e32 v97, v241
	v_mov_b32_e32 v80, v242
	v_mov_b32_e32 v81, v243
	v_mov_b32_e32 v60, v244
	v_mov_b32_e32 v61, v245
	v_mov_b32_e32 v48, v246
	v_mov_b32_e32 v49, v247
	v_mov_b32_e32 v32, v248
	v_mov_b32_e32 v33, v249
	v_mov_b32_e32 v16, v250
	v_mov_b32_e32 v17, v251
	ds_read_b128 v[184:187], v231 offset:16
	ds_read_b128 v[188:191], v231 offset:528
	ds_read_b128 v[192:195], v231 offset:2064
	ds_read_b128 v[196:199], v231 offset:2576
	s_waitcnt vmcnt(0)
	v_cndmask_b32_e64 v216, 0, v128, s[54:55]
	v_cndmask_b32_e64 v220, 0, v136, s[56:57]
	v_cndmask_b32_e64 v217, 0, v129, s[54:55]
	v_cndmask_b32_e64 v221, 0, v137, s[56:57]
	v_cndmask_b32_e64 v218, 0, v130, s[54:55]
	v_cndmask_b32_e64 v222, 0, v138, s[56:57]
	v_cndmask_b32_e64 v219, 0, v131, s[54:55]
	v_cndmask_b32_e64 v223, 0, v139, s[56:57]
	v_cndmask_b32_e64 v224, 0, v160, s[54:55]
	v_cndmask_b32_e64 v232, 0, v176, s[56:57]
	v_cndmask_b32_e64 v225, 0, v161, s[54:55]
	v_cndmask_b32_e64 v233, 0, v177, s[56:57]
	v_cndmask_b32_e64 v226, 0, v162, s[54:55]
	v_cndmask_b32_e64 v234, 0, v178, s[56:57]
	v_cndmask_b32_e64 v227, 0, v163, s[54:55]
	v_cndmask_b32_e64 v235, 0, v179, s[56:57]
	s_waitcnt lgkmcnt(0)
	s_nop 1
	v_fma_f32 v200, v132, v120, v140
	v_fma_f32 v201, v133, v121, v141
	v_fma_f32 v202, v134, v122, v142
	v_fma_f32 v203, v135, v123, v143
	v_fmac_f32_dpp v200, v120, v128 row_shr:1 row_mask:0xf bank_mask:0xf
	v_fmac_f32_dpp v201, v121, v129 row_shr:1 row_mask:0xf bank_mask:0xf
	v_fmac_f32_dpp v202, v122, v130 row_shr:1 row_mask:0xf bank_mask:0xf
	v_fmac_f32_dpp v203, v123, v131 row_shr:1 row_mask:0xf bank_mask:0xf
	v_fmac_f32_e32 v200, v184, v216
	v_fmac_f32_e32 v201, v185, v217
	v_fmac_f32_e32 v202, v186, v218
	v_fmac_f32_e32 v203, v187, v219
	v_fmac_f32_dpp v200, v120, v136 row_shl:1 row_mask:0xf bank_mask:0xf
	v_fmac_f32_dpp v201, v121, v137 row_shl:1 row_mask:0xf bank_mask:0xf
	v_fmac_f32_dpp v202, v122, v138 row_shl:1 row_mask:0xf bank_mask:0xf
	v_fmac_f32_dpp v203, v123, v139 row_shl:1 row_mask:0xf bank_mask:0xf
	v_fmac_f32_dpp v200, v112, v220 row_ror:15 row_mask:0xf bank_mask:0xf
	v_fmac_f32_dpp v201, v113, v221 row_ror:15 row_mask:0xf bank_mask:0xf
	v_fmac_f32_dpp v202, v114, v222 row_ror:15 row_mask:0xf bank_mask:0xf
	v_fmac_f32_dpp v203, v115, v223 row_ror:15 row_mask:0xf bank_mask:0xf
	v_fma_f32 v204, v172, v104, v180
	v_fma_f32 v205, v173, v105, v181
	v_fma_f32 v206, v174, v106, v182
	v_fma_f32 v207, v175, v107, v183
	v_fmac_f32_dpp v204, v104, v160 row_shr:1 row_mask:0xf bank_mask:0xf
	v_fmac_f32_dpp v205, v105, v161 row_shr:1 row_mask:0xf bank_mask:0xf
	v_fmac_f32_dpp v206, v106, v162 row_shr:1 row_mask:0xf bank_mask:0xf
	v_fmac_f32_dpp v207, v107, v163 row_shr:1 row_mask:0xf bank_mask:0xf
	v_fmac_f32_e32 v204, v188, v224
	v_fmac_f32_e32 v205, v189, v225
	v_fmac_f32_e32 v206, v190, v226
	v_fmac_f32_e32 v207, v191, v227
	v_fmac_f32_dpp v204, v104, v176 row_shl:1 row_mask:0xf bank_mask:0xf
	v_fmac_f32_dpp v205, v105, v177 row_shl:1 row_mask:0xf bank_mask:0xf
	v_fmac_f32_dpp v206, v106, v178 row_shl:1 row_mask:0xf bank_mask:0xf
	v_fmac_f32_dpp v207, v107, v179 row_shl:1 row_mask:0xf bank_mask:0xf
	v_fmac_f32_dpp v204, v92, v232 row_ror:15 row_mask:0xf bank_mask:0xf
	v_fmac_f32_dpp v205, v93, v233 row_ror:15 row_mask:0xf bank_mask:0xf
	v_fmac_f32_dpp v206, v94, v234 row_ror:15 row_mask:0xf bank_mask:0xf
	v_fmac_f32_dpp v207, v95, v235 row_ror:15 row_mask:0xf bank_mask:0xf
	v_mul_f32_e32 v208, 0xbfb8aa3b, v200
	v_mul_f32_e32 v209, 0xbfb8aa3b, v201
	v_mul_f32_e32 v210, 0xbfb8aa3b, v202
	v_mul_f32_e32 v211, 0xbfb8aa3b, v203
	v_exp_f32_e32 v208, v208
	v_exp_f32_e32 v209, v209
	v_exp_f32_e32 v210, v210
	v_exp_f32_e32 v211, v211
	v_add_f32_e32 v208, 1.0, v208
	v_add_f32_e32 v209, 1.0, v209
	v_add_f32_e32 v210, 1.0, v210
	v_add_f32_e32 v211, 1.0, v211
	v_rcp_f32_e32 v208, v208
	v_rcp_f32_e32 v209, v209
	v_rcp_f32_e32 v210, v210
	v_rcp_f32_e32 v211, v211
	v_mul_f32_e32 v200, v200, v208
	v_mul_f32_e32 v201, v201, v209
	v_mul_f32_e32 v202, v202, v210
	v_mul_f32_e32 v203, v203, v211
	v_mul_f32_e32 v200, v200, v204
	v_mul_f32_e32 v201, v201, v205
	v_mul_f32_e32 v202, v202, v206
	v_mul_f32_e32 v203, v203, v207
	v_cvt_pk_bf16_f32 v126, v200, v201
	v_cvt_pk_bf16_f32 v127, v202, v203
	v_fma_f32 v200, v132, v112, v140
	v_fma_f32 v201, v133, v113, v141
	v_fma_f32 v202, v134, v114, v142
	v_fma_f32 v203, v135, v115, v143
	v_fmac_f32_dpp v200, v112, v128 row_shr:1 row_mask:0xf bank_mask:0xf
	v_fmac_f32_dpp v201, v113, v129 row_shr:1 row_mask:0xf bank_mask:0xf
	v_fmac_f32_dpp v202, v114, v130 row_shr:1 row_mask:0xf bank_mask:0xf
	v_fmac_f32_dpp v203, v115, v131 row_shr:1 row_mask:0xf bank_mask:0xf
	v_fmac_f32_dpp v200, v120, v216 row_ror:1 row_mask:0xf bank_mask:0xf
	v_fmac_f32_dpp v201, v121, v217 row_ror:1 row_mask:0xf bank_mask:0xf
	v_fmac_f32_dpp v202, v122, v218 row_ror:1 row_mask:0xf bank_mask:0xf
	v_fmac_f32_dpp v203, v123, v219 row_ror:1 row_mask:0xf bank_mask:0xf
	v_fmac_f32_dpp v200, v112, v136 row_shl:1 row_mask:0xf bank_mask:0xf
	v_fmac_f32_dpp v201, v113, v137 row_shl:1 row_mask:0xf bank_mask:0xf
	v_fmac_f32_dpp v202, v114, v138 row_shl:1 row_mask:0xf bank_mask:0xf
	v_fmac_f32_dpp v203, v115, v139 row_shl:1 row_mask:0xf bank_mask:0xf
	v_fmac_f32_dpp v200, v88, v220 row_ror:15 row_mask:0xf bank_mask:0xf
	v_fmac_f32_dpp v201, v89, v221 row_ror:15 row_mask:0xf bank_mask:0xf
	v_fmac_f32_dpp v202, v90, v222 row_ror:15 row_mask:0xf bank_mask:0xf
	v_fmac_f32_dpp v203, v91, v223 row_ror:15 row_mask:0xf bank_mask:0xf
	v_fma_f32 v204, v172, v92, v180
	v_fma_f32 v205, v173, v93, v181
	v_fma_f32 v206, v174, v94, v182
	v_fma_f32 v207, v175, v95, v183
	v_fmac_f32_dpp v204, v92, v160 row_shr:1 row_mask:0xf bank_mask:0xf
	v_fmac_f32_dpp v205, v93, v161 row_shr:1 row_mask:0xf bank_mask:0xf
	v_fmac_f32_dpp v206, v94, v162 row_shr:1 row_mask:0xf bank_mask:0xf
	v_fmac_f32_dpp v207, v95, v163 row_shr:1 row_mask:0xf bank_mask:0xf
	v_fmac_f32_dpp v204, v104, v224 row_ror:1 row_mask:0xf bank_mask:0xf
	v_fmac_f32_dpp v205, v105, v225 row_ror:1 row_mask:0xf bank_mask:0xf
	v_fmac_f32_dpp v206, v106, v226 row_ror:1 row_mask:0xf bank_mask:0xf
	v_fmac_f32_dpp v207, v107, v227 row_ror:1 row_mask:0xf bank_mask:0xf
	v_fmac_f32_dpp v204, v92, v176 row_shl:1 row_mask:0xf bank_mask:0xf
	v_fmac_f32_dpp v205, v93, v177 row_shl:1 row_mask:0xf bank_mask:0xf
	v_fmac_f32_dpp v206, v94, v178 row_shl:1 row_mask:0xf bank_mask:0xf
	v_fmac_f32_dpp v207, v95, v179 row_shl:1 row_mask:0xf bank_mask:0xf
	v_fmac_f32_dpp v204, v76, v232 row_ror:15 row_mask:0xf bank_mask:0xf
	v_fmac_f32_dpp v205, v77, v233 row_ror:15 row_mask:0xf bank_mask:0xf
	v_fmac_f32_dpp v206, v78, v234 row_ror:15 row_mask:0xf bank_mask:0xf
	v_fmac_f32_dpp v207, v79, v235 row_ror:15 row_mask:0xf bank_mask:0xf
	v_mul_f32_e32 v208, 0xbfb8aa3b, v200
	v_mul_f32_e32 v209, 0xbfb8aa3b, v201
	v_mul_f32_e32 v210, 0xbfb8aa3b, v202
	v_mul_f32_e32 v211, 0xbfb8aa3b, v203
	v_exp_f32_e32 v208, v208
	v_exp_f32_e32 v209, v209
	v_exp_f32_e32 v210, v210
	v_exp_f32_e32 v211, v211
	v_add_f32_e32 v208, 1.0, v208
	v_add_f32_e32 v209, 1.0, v209
	v_add_f32_e32 v210, 1.0, v210
	v_add_f32_e32 v211, 1.0, v211
	v_rcp_f32_e32 v208, v208
	v_rcp_f32_e32 v209, v209
	v_rcp_f32_e32 v210, v210
	v_rcp_f32_e32 v211, v211
	v_mul_f32_e32 v200, v200, v208
	v_mul_f32_e32 v201, v201, v209
	v_mul_f32_e32 v202, v202, v210
	v_mul_f32_e32 v203, v203, v211
	v_mul_f32_e32 v200, v200, v204
	v_mul_f32_e32 v201, v201, v205
	v_mul_f32_e32 v202, v202, v206
	v_mul_f32_e32 v203, v203, v207
	v_cvt_pk_bf16_f32 v118, v200, v201
	v_cvt_pk_bf16_f32 v119, v202, v203
	v_fma_f32 v200, v132, v88, v140
	v_fma_f32 v201, v133, v89, v141
	v_fma_f32 v202, v134, v90, v142
	v_fma_f32 v203, v135, v91, v143
	v_fmac_f32_dpp v200, v88, v128 row_shr:1 row_mask:0xf bank_mask:0xf
	v_fmac_f32_dpp v201, v89, v129 row_shr:1 row_mask:0xf bank_mask:0xf
	v_fmac_f32_dpp v202, v90, v130 row_shr:1 row_mask:0xf bank_mask:0xf
	v_fmac_f32_dpp v203, v91, v131 row_shr:1 row_mask:0xf bank_mask:0xf
	v_fmac_f32_dpp v200, v112, v216 row_ror:1 row_mask:0xf bank_mask:0xf
	v_fmac_f32_dpp v201, v113, v217 row_ror:1 row_mask:0xf bank_mask:0xf
	v_fmac_f32_dpp v202, v114, v218 row_ror:1 row_mask:0xf bank_mask:0xf
	v_fmac_f32_dpp v203, v115, v219 row_ror:1 row_mask:0xf bank_mask:0xf
	v_fmac_f32_dpp v200, v88, v136 row_shl:1 row_mask:0xf bank_mask:0xf
	v_fmac_f32_dpp v201, v89, v137 row_shl:1 row_mask:0xf bank_mask:0xf
	v_fmac_f32_dpp v202, v90, v138 row_shl:1 row_mask:0xf bank_mask:0xf
	v_fmac_f32_dpp v203, v91, v139 row_shl:1 row_mask:0xf bank_mask:0xf
	v_fmac_f32_dpp v200, v72, v220 row_ror:15 row_mask:0xf bank_mask:0xf
	v_fmac_f32_dpp v201, v73, v221 row_ror:15 row_mask:0xf bank_mask:0xf
	v_fmac_f32_dpp v202, v74, v222 row_ror:15 row_mask:0xf bank_mask:0xf
	v_fmac_f32_dpp v203, v75, v223 row_ror:15 row_mask:0xf bank_mask:0xf
	v_fma_f32 v204, v172, v76, v180
	v_fma_f32 v205, v173, v77, v181
	v_fma_f32 v206, v174, v78, v182
	v_fma_f32 v207, v175, v79, v183
	v_fmac_f32_dpp v204, v76, v160 row_shr:1 row_mask:0xf bank_mask:0xf
	v_fmac_f32_dpp v205, v77, v161 row_shr:1 row_mask:0xf bank_mask:0xf
	v_fmac_f32_dpp v206, v78, v162 row_shr:1 row_mask:0xf bank_mask:0xf
	v_fmac_f32_dpp v207, v79, v163 row_shr:1 row_mask:0xf bank_mask:0xf
	v_fmac_f32_dpp v204, v92, v224 row_ror:1 row_mask:0xf bank_mask:0xf
	v_fmac_f32_dpp v205, v93, v225 row_ror:1 row_mask:0xf bank_mask:0xf
	v_fmac_f32_dpp v206, v94, v226 row_ror:1 row_mask:0xf bank_mask:0xf
	v_fmac_f32_dpp v207, v95, v227 row_ror:1 row_mask:0xf bank_mask:0xf
	v_fmac_f32_dpp v204, v76, v176 row_shl:1 row_mask:0xf bank_mask:0xf
	v_fmac_f32_dpp v205, v77, v177 row_shl:1 row_mask:0xf bank_mask:0xf
	v_fmac_f32_dpp v206, v78, v178 row_shl:1 row_mask:0xf bank_mask:0xf
	v_fmac_f32_dpp v207, v79, v179 row_shl:1 row_mask:0xf bank_mask:0xf
	v_fmac_f32_dpp v204, v64, v232 row_ror:15 row_mask:0xf bank_mask:0xf
	v_fmac_f32_dpp v205, v65, v233 row_ror:15 row_mask:0xf bank_mask:0xf
	v_fmac_f32_dpp v206, v66, v234 row_ror:15 row_mask:0xf bank_mask:0xf
	v_fmac_f32_dpp v207, v67, v235 row_ror:15 row_mask:0xf bank_mask:0xf
	v_mul_f32_e32 v208, 0xbfb8aa3b, v200
	v_mul_f32_e32 v209, 0xbfb8aa3b, v201
	v_mul_f32_e32 v210, 0xbfb8aa3b, v202
	v_mul_f32_e32 v211, 0xbfb8aa3b, v203
	v_exp_f32_e32 v208, v208
	v_exp_f32_e32 v209, v209
	v_exp_f32_e32 v210, v210
	v_exp_f32_e32 v211, v211
	v_add_f32_e32 v208, 1.0, v208
	v_add_f32_e32 v209, 1.0, v209
	v_add_f32_e32 v210, 1.0, v210
	v_add_f32_e32 v211, 1.0, v211
	v_rcp_f32_e32 v208, v208
	v_rcp_f32_e32 v209, v209
	v_rcp_f32_e32 v210, v210
	v_rcp_f32_e32 v211, v211
	v_mul_f32_e32 v200, v200, v208
	v_mul_f32_e32 v201, v201, v209
	v_mul_f32_e32 v202, v202, v210
	v_mul_f32_e32 v203, v203, v211
	v_mul_f32_e32 v200, v200, v204
	v_mul_f32_e32 v201, v201, v205
	v_mul_f32_e32 v202, v202, v206
	v_mul_f32_e32 v203, v203, v207
	v_cvt_pk_bf16_f32 v98, v200, v201
	v_cvt_pk_bf16_f32 v99, v202, v203
	v_fma_f32 v200, v132, v72, v140
	v_fma_f32 v201, v133, v73, v141
	v_fma_f32 v202, v134, v74, v142
	v_fma_f32 v203, v135, v75, v143
	v_fmac_f32_dpp v200, v72, v128 row_shr:1 row_mask:0xf bank_mask:0xf
	v_fmac_f32_dpp v201, v73, v129 row_shr:1 row_mask:0xf bank_mask:0xf
	v_fmac_f32_dpp v202, v74, v130 row_shr:1 row_mask:0xf bank_mask:0xf
	v_fmac_f32_dpp v203, v75, v131 row_shr:1 row_mask:0xf bank_mask:0xf
	v_fmac_f32_dpp v200, v88, v216 row_ror:1 row_mask:0xf bank_mask:0xf
	v_fmac_f32_dpp v201, v89, v217 row_ror:1 row_mask:0xf bank_mask:0xf
	v_fmac_f32_dpp v202, v90, v218 row_ror:1 row_mask:0xf bank_mask:0xf
	v_fmac_f32_dpp v203, v91, v219 row_ror:1 row_mask:0xf bank_mask:0xf
	v_fmac_f32_dpp v200, v72, v136 row_shl:1 row_mask:0xf bank_mask:0xf
	v_fmac_f32_dpp v201, v73, v137 row_shl:1 row_mask:0xf bank_mask:0xf
	v_fmac_f32_dpp v202, v74, v138 row_shl:1 row_mask:0xf bank_mask:0xf
	v_fmac_f32_dpp v203, v75, v139 row_shl:1 row_mask:0xf bank_mask:0xf
	v_fmac_f32_e32 v200, v184, v220
	v_fmac_f32_e32 v201, v185, v221
	v_fmac_f32_e32 v202, v186, v222
	v_fmac_f32_e32 v203, v187, v223
	v_fma_f32 v204, v172, v64, v180
	v_fma_f32 v205, v173, v65, v181
	v_fma_f32 v206, v174, v66, v182
	v_fma_f32 v207, v175, v67, v183
	v_fmac_f32_dpp v204, v64, v160 row_shr:1 row_mask:0xf bank_mask:0xf
	v_fmac_f32_dpp v205, v65, v161 row_shr:1 row_mask:0xf bank_mask:0xf
	v_fmac_f32_dpp v206, v66, v162 row_shr:1 row_mask:0xf bank_mask:0xf
	v_fmac_f32_dpp v207, v67, v163 row_shr:1 row_mask:0xf bank_mask:0xf
	v_fmac_f32_dpp v204, v76, v224 row_ror:1 row_mask:0xf bank_mask:0xf
	v_fmac_f32_dpp v205, v77, v225 row_ror:1 row_mask:0xf bank_mask:0xf
	v_fmac_f32_dpp v206, v78, v226 row_ror:1 row_mask:0xf bank_mask:0xf
	v_fmac_f32_dpp v207, v79, v227 row_ror:1 row_mask:0xf bank_mask:0xf
	v_fmac_f32_dpp v204, v64, v176 row_shl:1 row_mask:0xf bank_mask:0xf
	v_fmac_f32_dpp v205, v65, v177 row_shl:1 row_mask:0xf bank_mask:0xf
	v_fmac_f32_dpp v206, v66, v178 row_shl:1 row_mask:0xf bank_mask:0xf
	v_fmac_f32_dpp v207, v67, v179 row_shl:1 row_mask:0xf bank_mask:0xf
	v_fmac_f32_e32 v204, v188, v232
	v_fmac_f32_e32 v205, v189, v233
	v_fmac_f32_e32 v206, v190, v234
	v_fmac_f32_e32 v207, v191, v235
	v_mul_f32_e32 v208, 0xbfb8aa3b, v200
	v_mul_f32_e32 v209, 0xbfb8aa3b, v201
	v_mul_f32_e32 v210, 0xbfb8aa3b, v202
	v_mul_f32_e32 v211, 0xbfb8aa3b, v203
	v_exp_f32_e32 v208, v208
	v_exp_f32_e32 v209, v209
	v_exp_f32_e32 v210, v210
	v_exp_f32_e32 v211, v211
	v_add_f32_e32 v208, 1.0, v208
	v_add_f32_e32 v209, 1.0, v209
	v_add_f32_e32 v210, 1.0, v210
	v_add_f32_e32 v211, 1.0, v211
	v_rcp_f32_e32 v208, v208
	v_rcp_f32_e32 v209, v209
	v_rcp_f32_e32 v210, v210
	v_rcp_f32_e32 v211, v211
	v_mul_f32_e32 v200, v200, v208
	v_mul_f32_e32 v201, v201, v209
	v_mul_f32_e32 v202, v202, v210
	v_mul_f32_e32 v203, v203, v211
	v_mul_f32_e32 v200, v200, v204
	v_mul_f32_e32 v201, v201, v205
	v_mul_f32_e32 v202, v202, v206
	v_mul_f32_e32 v203, v203, v207
	v_cvt_pk_bf16_f32 v82, v200, v201
	v_cvt_pk_bf16_f32 v83, v202, v203
	v_fma_f32 v200, v132, v56, v140
	v_fma_f32 v201, v133, v57, v141
	v_fma_f32 v202, v134, v58, v142
	v_fma_f32 v203, v135, v59, v143
	v_fmac_f32_dpp v200, v56, v128 row_shr:1 row_mask:0xf bank_mask:0xf
	v_fmac_f32_dpp v201, v57, v129 row_shr:1 row_mask:0xf bank_mask:0xf
	v_fmac_f32_dpp v202, v58, v130 row_shr:1 row_mask:0xf bank_mask:0xf
	v_fmac_f32_dpp v203, v59, v131 row_shr:1 row_mask:0xf bank_mask:0xf
	v_fmac_f32_e32 v200, v192, v216
	v_fmac_f32_e32 v201, v193, v217
	v_fmac_f32_e32 v202, v194, v218
	v_fmac_f32_e32 v203, v195, v219
	v_fmac_f32_dpp v200, v56, v136 row_shl:1 row_mask:0xf bank_mask:0xf
	v_fmac_f32_dpp v201, v57, v137 row_shl:1 row_mask:0xf bank_mask:0xf
	v_fmac_f32_dpp v202, v58, v138 row_shl:1 row_mask:0xf bank_mask:0xf
	v_fmac_f32_dpp v203, v59, v139 row_shl:1 row_mask:0xf bank_mask:0xf
	v_fmac_f32_dpp v200, v40, v220 row_ror:15 row_mask:0xf bank_mask:0xf
	v_fmac_f32_dpp v201, v41, v221 row_ror:15 row_mask:0xf bank_mask:0xf
	v_fmac_f32_dpp v202, v42, v222 row_ror:15 row_mask:0xf bank_mask:0xf
	v_fmac_f32_dpp v203, v43, v223 row_ror:15 row_mask:0xf bank_mask:0xf
	v_fma_f32 v204, v172, v44, v180
	v_fma_f32 v205, v173, v45, v181
	v_fma_f32 v206, v174, v46, v182
	v_fma_f32 v207, v175, v47, v183
	v_fmac_f32_dpp v204, v44, v160 row_shr:1 row_mask:0xf bank_mask:0xf
	v_fmac_f32_dpp v205, v45, v161 row_shr:1 row_mask:0xf bank_mask:0xf
	v_fmac_f32_dpp v206, v46, v162 row_shr:1 row_mask:0xf bank_mask:0xf
	v_fmac_f32_dpp v207, v47, v163 row_shr:1 row_mask:0xf bank_mask:0xf
	v_fmac_f32_e32 v204, v196, v224
	v_fmac_f32_e32 v205, v197, v225
	v_fmac_f32_e32 v206, v198, v226
	v_fmac_f32_e32 v207, v199, v227
	v_fmac_f32_dpp v204, v44, v176 row_shl:1 row_mask:0xf bank_mask:0xf
	v_fmac_f32_dpp v205, v45, v177 row_shl:1 row_mask:0xf bank_mask:0xf
	v_fmac_f32_dpp v206, v46, v178 row_shl:1 row_mask:0xf bank_mask:0xf
	v_fmac_f32_dpp v207, v47, v179 row_shl:1 row_mask:0xf bank_mask:0xf
	v_fmac_f32_dpp v204, v28, v232 row_ror:15 row_mask:0xf bank_mask:0xf
	v_fmac_f32_dpp v205, v29, v233 row_ror:15 row_mask:0xf bank_mask:0xf
	v_fmac_f32_dpp v206, v30, v234 row_ror:15 row_mask:0xf bank_mask:0xf
	v_fmac_f32_dpp v207, v31, v235 row_ror:15 row_mask:0xf bank_mask:0xf
	v_mul_f32_e32 v208, 0xbfb8aa3b, v200
	v_mul_f32_e32 v209, 0xbfb8aa3b, v201
	v_mul_f32_e32 v210, 0xbfb8aa3b, v202
	v_mul_f32_e32 v211, 0xbfb8aa3b, v203
	v_exp_f32_e32 v208, v208
	v_exp_f32_e32 v209, v209
	v_exp_f32_e32 v210, v210
	v_exp_f32_e32 v211, v211
	v_add_f32_e32 v208, 1.0, v208
	v_add_f32_e32 v209, 1.0, v209
	v_add_f32_e32 v210, 1.0, v210
	v_add_f32_e32 v211, 1.0, v211
	v_rcp_f32_e32 v208, v208
	v_rcp_f32_e32 v209, v209
	v_rcp_f32_e32 v210, v210
	v_rcp_f32_e32 v211, v211
	v_mul_f32_e32 v200, v200, v208
	v_mul_f32_e32 v201, v201, v209
	v_mul_f32_e32 v202, v202, v210
	v_mul_f32_e32 v203, v203, v211
	v_mul_f32_e32 v200, v200, v204
	v_mul_f32_e32 v201, v201, v205
	v_mul_f32_e32 v202, v202, v206
	v_mul_f32_e32 v203, v203, v207
	v_cvt_pk_bf16_f32 v62, v200, v201
	v_cvt_pk_bf16_f32 v63, v202, v203
	v_fma_f32 v200, v132, v40, v140
	v_fma_f32 v201, v133, v41, v141
	v_fma_f32 v202, v134, v42, v142
	v_fma_f32 v203, v135, v43, v143
	v_fmac_f32_dpp v200, v40, v128 row_shr:1 row_mask:0xf bank_mask:0xf
	v_fmac_f32_dpp v201, v41, v129 row_shr:1 row_mask:0xf bank_mask:0xf
	v_fmac_f32_dpp v202, v42, v130 row_shr:1 row_mask:0xf bank_mask:0xf
	v_fmac_f32_dpp v203, v43, v131 row_shr:1 row_mask:0xf bank_mask:0xf
	v_fmac_f32_dpp v200, v56, v216 row_ror:1 row_mask:0xf bank_mask:0xf
	v_fmac_f32_dpp v201, v57, v217 row_ror:1 row_mask:0xf bank_mask:0xf
	v_fmac_f32_dpp v202, v58, v218 row_ror:1 row_mask:0xf bank_mask:0xf
	v_fmac_f32_dpp v203, v59, v219 row_ror:1 row_mask:0xf bank_mask:0xf
	v_fmac_f32_dpp v200, v40, v136 row_shl:1 row_mask:0xf bank_mask:0xf
	v_fmac_f32_dpp v201, v41, v137 row_shl:1 row_mask:0xf bank_mask:0xf
	v_fmac_f32_dpp v202, v42, v138 row_shl:1 row_mask:0xf bank_mask:0xf
	v_fmac_f32_dpp v203, v43, v139 row_shl:1 row_mask:0xf bank_mask:0xf
	v_fmac_f32_dpp v200, v24, v220 row_ror:15 row_mask:0xf bank_mask:0xf
	v_fmac_f32_dpp v201, v25, v221 row_ror:15 row_mask:0xf bank_mask:0xf
	v_fmac_f32_dpp v202, v26, v222 row_ror:15 row_mask:0xf bank_mask:0xf
	v_fmac_f32_dpp v203, v27, v223 row_ror:15 row_mask:0xf bank_mask:0xf
	v_fma_f32 v204, v172, v28, v180
	v_fma_f32 v205, v173, v29, v181
	v_fma_f32 v206, v174, v30, v182
	v_fma_f32 v207, v175, v31, v183
	v_fmac_f32_dpp v204, v28, v160 row_shr:1 row_mask:0xf bank_mask:0xf
	v_fmac_f32_dpp v205, v29, v161 row_shr:1 row_mask:0xf bank_mask:0xf
	v_fmac_f32_dpp v206, v30, v162 row_shr:1 row_mask:0xf bank_mask:0xf
	v_fmac_f32_dpp v207, v31, v163 row_shr:1 row_mask:0xf bank_mask:0xf
	v_fmac_f32_dpp v204, v44, v224 row_ror:1 row_mask:0xf bank_mask:0xf
	v_fmac_f32_dpp v205, v45, v225 row_ror:1 row_mask:0xf bank_mask:0xf
	v_fmac_f32_dpp v206, v46, v226 row_ror:1 row_mask:0xf bank_mask:0xf
	v_fmac_f32_dpp v207, v47, v227 row_ror:1 row_mask:0xf bank_mask:0xf
	v_fmac_f32_dpp v204, v28, v176 row_shl:1 row_mask:0xf bank_mask:0xf
	v_fmac_f32_dpp v205, v29, v177 row_shl:1 row_mask:0xf bank_mask:0xf
	v_fmac_f32_dpp v206, v30, v178 row_shl:1 row_mask:0xf bank_mask:0xf
	v_fmac_f32_dpp v207, v31, v179 row_shl:1 row_mask:0xf bank_mask:0xf
	v_fmac_f32_dpp v204, v12, v232 row_ror:15 row_mask:0xf bank_mask:0xf
	v_fmac_f32_dpp v205, v13, v233 row_ror:15 row_mask:0xf bank_mask:0xf
	v_fmac_f32_dpp v206, v14, v234 row_ror:15 row_mask:0xf bank_mask:0xf
	v_fmac_f32_dpp v207, v15, v235 row_ror:15 row_mask:0xf bank_mask:0xf
	v_mul_f32_e32 v208, 0xbfb8aa3b, v200
	v_mul_f32_e32 v209, 0xbfb8aa3b, v201
	v_mul_f32_e32 v210, 0xbfb8aa3b, v202
	v_mul_f32_e32 v211, 0xbfb8aa3b, v203
	v_exp_f32_e32 v208, v208
	v_exp_f32_e32 v209, v209
	v_exp_f32_e32 v210, v210
	v_exp_f32_e32 v211, v211
	v_add_f32_e32 v208, 1.0, v208
	v_add_f32_e32 v209, 1.0, v209
	v_add_f32_e32 v210, 1.0, v210
	v_add_f32_e32 v211, 1.0, v211
	v_rcp_f32_e32 v208, v208
	v_rcp_f32_e32 v209, v209
	v_rcp_f32_e32 v210, v210
	v_rcp_f32_e32 v211, v211
	v_mul_f32_e32 v200, v200, v208
	v_mul_f32_e32 v201, v201, v209
	v_mul_f32_e32 v202, v202, v210
	v_mul_f32_e32 v203, v203, v211
	v_mul_f32_e32 v200, v200, v204
	v_mul_f32_e32 v201, v201, v205
	v_mul_f32_e32 v202, v202, v206
	v_mul_f32_e32 v203, v203, v207
	v_cvt_pk_bf16_f32 v50, v200, v201
	v_cvt_pk_bf16_f32 v51, v202, v203
	v_fma_f32 v200, v132, v24, v140
	v_fma_f32 v201, v133, v25, v141
	v_fma_f32 v202, v134, v26, v142
	v_fma_f32 v203, v135, v27, v143
	v_fmac_f32_dpp v200, v24, v128 row_shr:1 row_mask:0xf bank_mask:0xf
	v_fmac_f32_dpp v201, v25, v129 row_shr:1 row_mask:0xf bank_mask:0xf
	v_fmac_f32_dpp v202, v26, v130 row_shr:1 row_mask:0xf bank_mask:0xf
	v_fmac_f32_dpp v203, v27, v131 row_shr:1 row_mask:0xf bank_mask:0xf
	v_fmac_f32_dpp v200, v40, v216 row_ror:1 row_mask:0xf bank_mask:0xf
	v_fmac_f32_dpp v201, v41, v217 row_ror:1 row_mask:0xf bank_mask:0xf
	v_fmac_f32_dpp v202, v42, v218 row_ror:1 row_mask:0xf bank_mask:0xf
	v_fmac_f32_dpp v203, v43, v219 row_ror:1 row_mask:0xf bank_mask:0xf
	v_fmac_f32_dpp v200, v24, v136 row_shl:1 row_mask:0xf bank_mask:0xf
	v_fmac_f32_dpp v201, v25, v137 row_shl:1 row_mask:0xf bank_mask:0xf
	v_fmac_f32_dpp v202, v26, v138 row_shl:1 row_mask:0xf bank_mask:0xf
	v_fmac_f32_dpp v203, v27, v139 row_shl:1 row_mask:0xf bank_mask:0xf
	v_fmac_f32_dpp v200, v8, v220 row_ror:15 row_mask:0xf bank_mask:0xf
	v_fmac_f32_dpp v201, v9, v221 row_ror:15 row_mask:0xf bank_mask:0xf
	v_fmac_f32_dpp v202, v10, v222 row_ror:15 row_mask:0xf bank_mask:0xf
	v_fmac_f32_dpp v203, v11, v223 row_ror:15 row_mask:0xf bank_mask:0xf
	v_fma_f32 v204, v172, v12, v180
	v_fma_f32 v205, v173, v13, v181
	v_fma_f32 v206, v174, v14, v182
	v_fma_f32 v207, v175, v15, v183
	v_fmac_f32_dpp v204, v12, v160 row_shr:1 row_mask:0xf bank_mask:0xf
	v_fmac_f32_dpp v205, v13, v161 row_shr:1 row_mask:0xf bank_mask:0xf
	v_fmac_f32_dpp v206, v14, v162 row_shr:1 row_mask:0xf bank_mask:0xf
	v_fmac_f32_dpp v207, v15, v163 row_shr:1 row_mask:0xf bank_mask:0xf
	v_fmac_f32_dpp v204, v28, v224 row_ror:1 row_mask:0xf bank_mask:0xf
	v_fmac_f32_dpp v205, v29, v225 row_ror:1 row_mask:0xf bank_mask:0xf
	v_fmac_f32_dpp v206, v30, v226 row_ror:1 row_mask:0xf bank_mask:0xf
	v_fmac_f32_dpp v207, v31, v227 row_ror:1 row_mask:0xf bank_mask:0xf
	v_fmac_f32_dpp v204, v12, v176 row_shl:1 row_mask:0xf bank_mask:0xf
	v_fmac_f32_dpp v205, v13, v177 row_shl:1 row_mask:0xf bank_mask:0xf
	v_fmac_f32_dpp v206, v14, v178 row_shl:1 row_mask:0xf bank_mask:0xf
	v_fmac_f32_dpp v207, v15, v179 row_shl:1 row_mask:0xf bank_mask:0xf
	v_fmac_f32_dpp v204, v0, v232 row_ror:15 row_mask:0xf bank_mask:0xf
	v_fmac_f32_dpp v205, v1, v233 row_ror:15 row_mask:0xf bank_mask:0xf
	v_fmac_f32_dpp v206, v2, v234 row_ror:15 row_mask:0xf bank_mask:0xf
	v_fmac_f32_dpp v207, v3, v235 row_ror:15 row_mask:0xf bank_mask:0xf
	v_mul_f32_e32 v208, 0xbfb8aa3b, v200
	v_mul_f32_e32 v209, 0xbfb8aa3b, v201
	v_mul_f32_e32 v210, 0xbfb8aa3b, v202
	v_mul_f32_e32 v211, 0xbfb8aa3b, v203
	v_exp_f32_e32 v208, v208
	v_exp_f32_e32 v209, v209
	v_exp_f32_e32 v210, v210
	v_exp_f32_e32 v211, v211
	v_add_f32_e32 v208, 1.0, v208
	v_add_f32_e32 v209, 1.0, v209
	v_add_f32_e32 v210, 1.0, v210
	v_add_f32_e32 v211, 1.0, v211
	v_rcp_f32_e32 v208, v208
	v_rcp_f32_e32 v209, v209
	v_rcp_f32_e32 v210, v210
	v_rcp_f32_e32 v211, v211
	v_mul_f32_e32 v200, v200, v208
	v_mul_f32_e32 v201, v201, v209
	v_mul_f32_e32 v202, v202, v210
	v_mul_f32_e32 v203, v203, v211
	v_mul_f32_e32 v200, v200, v204
	v_mul_f32_e32 v201, v201, v205
	v_mul_f32_e32 v202, v202, v206
	v_mul_f32_e32 v203, v203, v207
	v_cvt_pk_bf16_f32 v34, v200, v201
	v_cvt_pk_bf16_f32 v35, v202, v203
	v_fma_f32 v200, v132, v8, v140
	v_fma_f32 v201, v133, v9, v141
	v_fma_f32 v202, v134, v10, v142
	v_fma_f32 v203, v135, v11, v143
	v_fmac_f32_dpp v200, v8, v128 row_shr:1 row_mask:0xf bank_mask:0xf
	v_fmac_f32_dpp v201, v9, v129 row_shr:1 row_mask:0xf bank_mask:0xf
	v_fmac_f32_dpp v202, v10, v130 row_shr:1 row_mask:0xf bank_mask:0xf
	v_fmac_f32_dpp v203, v11, v131 row_shr:1 row_mask:0xf bank_mask:0xf
	v_fmac_f32_dpp v200, v24, v216 row_ror:1 row_mask:0xf bank_mask:0xf
	v_fmac_f32_dpp v201, v25, v217 row_ror:1 row_mask:0xf bank_mask:0xf
	v_fmac_f32_dpp v202, v26, v218 row_ror:1 row_mask:0xf bank_mask:0xf
	v_fmac_f32_dpp v203, v27, v219 row_ror:1 row_mask:0xf bank_mask:0xf
	v_fmac_f32_dpp v200, v8, v136 row_shl:1 row_mask:0xf bank_mask:0xf
	v_fmac_f32_dpp v201, v9, v137 row_shl:1 row_mask:0xf bank_mask:0xf
	v_fmac_f32_dpp v202, v10, v138 row_shl:1 row_mask:0xf bank_mask:0xf
	v_fmac_f32_dpp v203, v11, v139 row_shl:1 row_mask:0xf bank_mask:0xf
	v_fmac_f32_e32 v200, v192, v220
	v_fmac_f32_e32 v201, v193, v221
	v_fmac_f32_e32 v202, v194, v222
	v_fmac_f32_e32 v203, v195, v223
	v_fma_f32 v204, v172, v0, v180
	v_fma_f32 v205, v173, v1, v181
	v_fma_f32 v206, v174, v2, v182
	v_fma_f32 v207, v175, v3, v183
	v_fmac_f32_dpp v204, v0, v160 row_shr:1 row_mask:0xf bank_mask:0xf
	v_fmac_f32_dpp v205, v1, v161 row_shr:1 row_mask:0xf bank_mask:0xf
	v_fmac_f32_dpp v206, v2, v162 row_shr:1 row_mask:0xf bank_mask:0xf
	v_fmac_f32_dpp v207, v3, v163 row_shr:1 row_mask:0xf bank_mask:0xf
	v_fmac_f32_dpp v204, v12, v224 row_ror:1 row_mask:0xf bank_mask:0xf
	v_fmac_f32_dpp v205, v13, v225 row_ror:1 row_mask:0xf bank_mask:0xf
	v_fmac_f32_dpp v206, v14, v226 row_ror:1 row_mask:0xf bank_mask:0xf
	v_fmac_f32_dpp v207, v15, v227 row_ror:1 row_mask:0xf bank_mask:0xf
	v_fmac_f32_dpp v204, v0, v176 row_shl:1 row_mask:0xf bank_mask:0xf
	v_fmac_f32_dpp v205, v1, v177 row_shl:1 row_mask:0xf bank_mask:0xf
	v_fmac_f32_dpp v206, v2, v178 row_shl:1 row_mask:0xf bank_mask:0xf
	v_fmac_f32_dpp v207, v3, v179 row_shl:1 row_mask:0xf bank_mask:0xf
	v_fmac_f32_e32 v204, v196, v232
	v_fmac_f32_e32 v205, v197, v233
	v_fmac_f32_e32 v206, v198, v234
	v_fmac_f32_e32 v207, v199, v235
	v_mul_f32_e32 v208, 0xbfb8aa3b, v200
	v_mul_f32_e32 v209, 0xbfb8aa3b, v201
	v_mul_f32_e32 v210, 0xbfb8aa3b, v202
	v_mul_f32_e32 v211, 0xbfb8aa3b, v203
	v_exp_f32_e32 v208, v208
	v_exp_f32_e32 v209, v209
	v_exp_f32_e32 v210, v210
	v_exp_f32_e32 v211, v211
	v_add_f32_e32 v208, 1.0, v208
	v_add_f32_e32 v209, 1.0, v209
	v_add_f32_e32 v210, 1.0, v210
	v_add_f32_e32 v211, 1.0, v211
	v_rcp_f32_e32 v208, v208
	v_rcp_f32_e32 v209, v209
	v_rcp_f32_e32 v210, v210
	v_rcp_f32_e32 v211, v211
	v_mul_f32_e32 v200, v200, v208
	v_mul_f32_e32 v201, v201, v209
	v_mul_f32_e32 v202, v202, v210
	v_mul_f32_e32 v203, v203, v211
	v_mul_f32_e32 v200, v200, v204
	v_mul_f32_e32 v201, v201, v205
	v_mul_f32_e32 v202, v202, v206
	v_mul_f32_e32 v203, v203, v207
	v_cvt_pk_bf16_f32 v18, v200, v201
	v_cvt_pk_bf16_f32 v19, v202, v203
	global_store_dwordx4 v171, v[124:127], s[40:41]
	v_add_u32_e32 v250, 0x16000, v171
	global_store_dwordx4 v250, v[116:119], s[40:41]
	s_nop 0
	v_add_u32_e32 v250, 0x2c000, v171
	global_store_dwordx4 v250, v[96:99], s[40:41]
	s_nop 0
	v_add_u32_e32 v250, 0x42000, v171
	global_store_dwordx4 v250, v[80:83], s[40:41]
	s_nop 0
	v_add_u32_e32 v250, 0xb0000, v171
	global_store_dwordx4 v250, v[60:63], s[40:41]
	s_nop 0
	v_add_u32_e32 v250, 0xc6000, v171
	global_store_dwordx4 v250, v[48:51], s[40:41]
	s_nop 0
	v_add_u32_e32 v250, 0xdc000, v171
	global_store_dwordx4 v250, v[32:35], s[40:41]
	s_nop 0
	v_add_u32_e32 v250, 0xf2000, v171
	global_store_dwordx4 v250, v[16:19], s[40:41]
	s_nop 0
	s_andn2_b64 vcc, exec, s[6:7]
	s_mov_b64 s[4:5], -1
	s_cbranch_vccnz .LBB0_1748
	s_andn2_b64 vcc, exec, s[12:13]
	s_cbranch_vccnz .LBB0_1747
	s_barrier
	s_branch .LBB0_1747

.LBB0_1867:
	s_cmp_gt_i32 s72, 20
	s_cselect_b64 s[4:5], -1, 0
	s_cmp_lt_i32 s73, 21
	s_cselect_b64 s[6:7], -1, 0
	s_or_b64 s[4:5], s[4:5], s[6:7]
	s_and_b64 vcc, exec, s[4:5]
	s_cbranch_vccnz .LBB0_1934
	v_readlane_b32 s4, v255, 2
	v_mov_b32_e32 v9, v230
	v_readlane_b32 s5, v255, 3
	s_and_b64 vcc, exec, s[4:5]
	v_readfirstlane_b32 s5, v9
	s_cbranch_vccnz .LBB0_1884
	v_lshlrev_b32_e32 v0, 4, v9
	s_waitcnt lgkmcnt(0)
	v_add_u32_e32 v1, 0x2000, v0
	v_ashrrev_i32_e32 v2, 31, v1
	v_lshrrev_b32_e32 v2, 22, v2
	v_add_u32_e32 v2, v1, v2
	v_ashrrev_i32_e32 v8, 10, v2
	v_mul_i32_i24_e32 v2, 0x400, v8
	v_sub_u32_e32 v1, v1, v2
	v_lshrrev_b32_e32 v2, 4, v1
	v_bitop3_b32 v1, v2, v1, 32 bitop3:0x6c
	v_ashrrev_i32_e32 v2, 31, v1
	v_lshrrev_b32_e32 v2, 26, v2
	v_add_u32_e32 v2, v1, v2
	v_lshlrev_b32_e32 v3, 3, v8
	v_ashrrev_i32_e32 v10, 6, v2
	v_and_b32_e32 v3, -16, v3
	v_add_u32_e32 v3, v10, v3
	v_and_b32_e32 v4, 3, v10
	s_mov_b32 s4, 0x1fffe0
	v_lshrrev_b32_e32 v5, 2, v3
	v_lshlrev_b32_e32 v6, 1, v3
	v_and_b32_e32 v2, 0xc0, v2
	v_and_or_b32 v4, v3, s4, v4
	v_and_b32_e32 v5, 4, v5
	v_and_b32_e32 v6, 24, v6
	v_sub_u32_e32 v1, v1, v2
	v_mov_b32_e32 v2, 1
	v_or3_b32 v4, v4, v5, v6
	v_lshlrev_b32_e32 v5, 5, v8
	v_ashrrev_i16_sdwa v1, v2, sext(v1) dst_sel:DWORD dst_unused:UNUSED_PAD src0_sel:DWORD src1_sel:BYTE_0
	v_and_b32_e32 v5, 32, v5
	v_bfe_i32 v11, v1, 0, 16
	v_add_lshl_u32 v1, v5, v11, 1
	v_lshl_add_u32 v144, v4, 11, v1
	v_lshl_add_u32 v146, v3, 11, v1
	v_bfe_i32 v1, v9, 27, 1
	v_lshrrev_b32_e32 v1, 22, v1
	v_add_u32_e32 v1, v0, v1
	v_and_b32_e32 v1, 0xfffffc00, v1
	v_sub_u32_e32 v0, v0, v1
	v_lshrrev_b32_e32 v1, 4, v0
	v_ashrrev_i32_e32 v3, 31, v9
	v_bitop3_b32 v0, v1, v0, 32 bitop3:0x6c
	v_lshrrev_b32_e32 v3, 26, v3
	v_ashrrev_i32_e32 v1, 31, v0
	v_add_u32_e32 v3, v9, v3
	s_add_u32 s20, s70, 0x4b00000
	v_lshrrev_b32_e32 v1, 26, v1
	v_ashrrev_i32_e32 v13, 6, v3
	s_addc_u32 s21, s71, 0
	s_ashr_i32 s14, s5, 6
	v_add_u32_e32 v1, v0, v1
	v_lshlrev_b32_e32 v3, 3, v13
	v_readlane_b32 s6, v254, 62
	s_ashr_i32 s16, s5, 8
	s_lshl_b32 s38, s14, 10
	v_ashrrev_i32_e32 v12, 6, v1
	v_and_b32_e32 v3, -16, v3
	v_readlane_b32 s7, v254, 63
	v_add_u32_e32 v3, v12, v3
	v_and_b32_e32 v4, 3, v12
	s_movk_i32 s39, 0x59
	s_and_b64 s[6:7], s[6:7], exec
	v_and_or_b32 v4, v3, s4, v4
	s_cselect_b32 s4, s39, 0x58
	v_readlane_b32 s6, v254, 51
	s_mul_i32 s4, s4, s6
	v_readlane_b32 s6, v254, 61
	s_add_i32 s4, s4, s6
	s_mul_hi_i32 s6, s4, 0x2e8ba2e9
	s_lshr_b32 s7, s6, 31
	s_ashr_i32 s6, s6, 5
	s_add_i32 s6, s6, s7
	s_lshl_b32 s7, s6, 3
	s_mulk_i32 s6, 0xb0
	s_sub_i32 s6, s4, s6
	s_bfe_u32 s4, s6, 0x3001c
	s_add_i32 s8, s6, s4
	s_sext_i32_i16 s4, s8
	s_and_b32 s8, s8, 0xfff8
	s_sub_i32 s6, s6, s8
	s_sext_i32_i16 s6, s6
	v_lshrrev_b32_e32 v5, 2, v3
	v_lshlrev_b32_e32 v6, 1, v3
	v_and_b32_e32 v1, 0xc0, v1
	s_lshr_b32 s4, s4, 3
	s_add_i32 s6, s7, s6
	v_and_b32_e32 v5, 4, v5
	v_and_b32_e32 v6, 24, v6
	v_sub_u32_e32 v0, v0, v1
	s_ashr_i32 s7, s6, 31
	s_bfe_i64 s[10:11], s[4:5], 0x100000
	v_or3_b32 v4, v4, v5, v6
	v_lshlrev_b32_e32 v5, 5, v13
	v_ashrrev_i16_sdwa v0, v2, sext(v0) dst_sel:DWORD dst_unused:UNUSED_PAD src0_sel:DWORD src1_sel:BYTE_0
	s_lshl_b64 s[8:9], s[6:7], 19
	s_lshl_b64 s[10:11], s[10:11], 18
	v_and_b32_e32 v5, 32, v5
	v_bfe_i32 v14, v0, 0, 16
	s_add_u32 s34, s0, s10
	v_add_lshl_u32 v0, v5, v14, 1
	s_addc_u32 s35, s1, s11
	s_add_i32 s40, s38, 0
	v_lshl_add_u32 v148, v4, 11, v0
	s_add_i32 m0, s40, 0x10000
	v_lshl_add_u32 v150, v3, 11, v0
	global_load_lds_dwordx4 v148, s[34:35]
	s_add_i32 m0, s40, 0x12000
	s_add_u32 s10, s34, 0x580000
	global_load_lds_dwordx4 v144, s[34:35]
	s_addc_u32 s11, s35, 0
	s_add_i32 m0, s40, 0x14000
	v_mov_b32_e32 v149, 0
	global_load_lds_dwordx4 v148, s[10:11]
	s_add_i32 m0, s40, 0x16000
	s_add_u32 s30, s20, s8
	s_addc_u32 s31, s21, s9
	s_add_i32 s41, s40, 0x2000
	global_load_lds_dwordx4 v144, s[10:11]
	s_mov_b32 m0, s40
	s_add_u32 s8, s30, 0x40000
	global_load_lds_dwordx4 v150, s[30:31]
	s_mov_b32 m0, s41
	s_addc_u32 s9, s31, 0
	s_add_i32 s42, s40, 0x4000
	global_load_lds_dwordx4 v146, s[30:31]
	s_mov_b32 m0, s42
	s_add_i32 s43, s40, 0x6000
	global_load_lds_dwordx4 v150, s[8:9]
	s_mov_b32 m0, s43
	v_mov_b32_e32 v145, v149
	global_load_lds_dwordx4 v146, s[8:9]
	v_mov_b32_e32 v151, v149
	v_mov_b32_e32 v147, v149
	s_cmp_eq_u32 s16, 1
	s_mov_b32 s44, 0
	v_lshl_add_u64 v[6:7], s[34:35], 0, v[148:149]
	v_lshl_add_u64 v[4:5], s[34:35], 0, v[144:145]
	v_lshl_add_u64 v[0:1], s[30:31], 0, v[150:151]
	s_cselect_b64 s[8:9], -1, 0
	s_cmp_lg_u32 s16, 1
	v_lshl_add_u64 v[2:3], s[30:31], 0, v[146:147]
	s_cbranch_scc1 .LBB0_1871
	s_barrier
.LBB0_1871:
	s_add_u32 s10, s70, 0x128000
	s_addc_u32 s11, s71, 0
	s_add_u32 s12, s70, 0x3b00000
	s_addc_u32 s13, s71, 0
	s_lshl_b32 s7, s14, 5
	s_mov_b64 s[14:15], 0x80
	s_and_b32 s24, s7, 0x60
	s_add_i32 m0, s40, 0x18000
	v_lshl_add_u64 v[6:7], v[6:7], 0, s[14:15]
	s_lshl_b32 s17, s16, 13
	s_lshl_b32 s25, s24, 7
	s_waitcnt vmcnt(2)
	s_barrier
	global_load_lds_dwordx4 v[6:7], off
	v_lshl_add_u64 v[4:5], v[4:5], 0, s[14:15]
	s_add_i32 m0, s40, 0x1a000
	s_add_i32 s45, s40, 0x8000
	s_add_i32 s46, s40, 0xa000
	global_load_lds_dwordx4 v[4:5], off
	v_lshl_add_u64 v[0:1], v[0:1], 0, s[14:15]
	s_mov_b32 m0, s45
	s_add_u32 s22, s34, 0x580080
	global_load_lds_dwordx4 v[0:1], off
	v_lshl_add_u64 v[0:1], v[2:3], 0, s[14:15]
	s_mov_b32 m0, s46
	s_addc_u32 s23, s35, 0
	global_load_lds_dwordx4 v[0:1], off
	s_add_i32 m0, s40, 0x1c000
	v_lshl_add_u64 v[0:1], s[22:23], 0, v[148:149]
	global_load_lds_dwordx4 v[0:1], off
	v_lshl_add_u64 v[0:1], s[22:23], 0, v[144:145]
	s_add_i32 m0, s40, 0x1e000
	s_cmpk_lt_u32 s5, 0x100
	global_load_lds_dwordx4 v[0:1], off
	v_lshrrev_b32_e32 v1, 1, v9
	v_and_b32_e32 v1, 24, v1
	v_and_b32_e32 v0, 15, v9
	v_lshlrev_b32_e32 v2, 1, v1
	v_lshl_or_b32 v164, s16, 6, v0
	v_lshl_or_b32 v0, v0, 6, v2
	v_lshlrev_b32_e32 v2, 2, v9
	v_and_b32_e32 v2, 32, v2
	v_bitop3_b32 v3, v0, s17, v2 bitop3:0xde
	v_bitop3_b32 v165, v0, s25, v2 bitop3:0xde
	v_lshlrev_b32_e32 v0, 14, v13
	v_and_b32_e32 v0, 0xffff8000, v0
	v_or_b32_e32 v166, s24, v1
	v_lshl_add_u32 v0, v12, 11, v0
	v_and_b32_e32 v1, 1, v13
	v_lshl_or_b32 v0, v1, 6, v0
	v_lshl_add_u32 v152, v14, 1, v0
	v_lshlrev_b32_e32 v0, 14, v8
	v_and_b32_e32 v0, 0xffff8000, v0
	s_waitcnt vmcnt(6)
	v_lshl_add_u32 v0, v10, 11, v0
	v_and_b32_e32 v1, 1, v8
	s_cselect_b64 s[16:17], -1, 0
	v_lshl_or_b32 v0, v1, 6, v0
	s_add_i32 s47, 0, 0x10000
	s_add_i32 s48, 0, 0x14000
	s_sext_i32_i16 s7, s4
	v_mov_b32_e32 v153, v149
	v_lshl_add_u32 v154, v11, 1, v0
	v_mov_b32_e32 v155, v149
	v_mov_b64_e32 v[156:157], 0x2c0
	v_mov_b64_e32 v[158:159], 0x2bf
	v_add_u32_e32 v167, s47, v165
	v_add_u32_e32 v168, s48, v165
	v_add_u32_e32 v169, 0, v3
	v_mov_b32_e32 v170, 0x358637bd
	s_mov_b32 s49, 0x800000
	s_movk_i32 s51, 0x2c00
	s_barrier
	s_branch .LBB0_1874

.LBB0_1876:
	s_ashr_i32 s25, s24, 31
	s_lshl_b64 s[26:27], s[24:25], 19
	s_add_u32 s26, s20, s26
	v_cmp_lt_i64_e64 s[4:5], s[4:5], v[156:157]
	s_addc_u32 s27, s21, s27
	s_and_b64 s[28:29], s[4:5], exec
	s_cselect_b32 s25, s27, s31
	s_cselect_b32 s52, s26, s30
	s_ashr_i32 s23, s22, 31
	s_lshl_b64 s[28:29], s[22:23], 18
	s_add_u32 s28, s0, s28
	s_addc_u32 s29, s1, s29
	s_and_b64 s[36:37], s[4:5], exec
	s_cselect_b32 s23, s29, s35
	s_cselect_b32 s53, s28, s34
	s_add_u32 s30, s30, 0x40080
	s_addc_u32 s31, s31, 0
	s_add_u32 s54, s34, 0x100
	v_mov_b32_e32 v0, 0
	s_addc_u32 s55, s35, 0
	s_mov_b32 s56, -2
	v_mov_b32_e32 v1, v0
	v_mov_b32_e32 v2, v0
	v_mov_b32_e32 v3, v0
	v_mov_b32_e32 v4, v0
	v_mov_b32_e32 v5, v0
	v_mov_b32_e32 v6, v0
	v_mov_b32_e32 v7, v0
	v_mov_b32_e32 v12, v0
	v_mov_b32_e32 v13, v0
	v_mov_b32_e32 v14, v0
	v_mov_b32_e32 v15, v0
	v_mov_b32_e32 v20, v0
	v_mov_b32_e32 v21, v0
	v_mov_b32_e32 v22, v0
	v_mov_b32_e32 v23, v0
	v_mov_b32_e32 v28, v0
	v_mov_b32_e32 v29, v0
	v_mov_b32_e32 v30, v0
	v_mov_b32_e32 v31, v0
	v_mov_b32_e32 v36, v0
	v_mov_b32_e32 v37, v0
	v_mov_b32_e32 v38, v0
	v_mov_b32_e32 v39, v0
	v_mov_b32_e32 v44, v0
	v_mov_b32_e32 v45, v0
	v_mov_b32_e32 v46, v0
	v_mov_b32_e32 v47, v0
	v_mov_b32_e32 v52, v0
	v_mov_b32_e32 v53, v0
	v_mov_b32_e32 v54, v0
	v_mov_b32_e32 v55, v0
	v_mov_b32_e32 v8, v0
	v_mov_b32_e32 v9, v0
	v_mov_b32_e32 v10, v0
	v_mov_b32_e32 v11, v0
	v_mov_b32_e32 v16, v0
	v_mov_b32_e32 v17, v0
	v_mov_b32_e32 v18, v0
	v_mov_b32_e32 v19, v0
	v_mov_b32_e32 v24, v0
	v_mov_b32_e32 v25, v0
	v_mov_b32_e32 v26, v0
	v_mov_b32_e32 v27, v0
	v_mov_b32_e32 v32, v0
	v_mov_b32_e32 v33, v0
	v_mov_b32_e32 v34, v0
	v_mov_b32_e32 v35, v0
	v_mov_b32_e32 v40, v0
	v_mov_b32_e32 v41, v0
	v_mov_b32_e32 v42, v0
	v_mov_b32_e32 v43, v0
	v_mov_b32_e32 v48, v0
	v_mov_b32_e32 v49, v0
	v_mov_b32_e32 v50, v0
	v_mov_b32_e32 v51, v0
	v_mov_b32_e32 v56, v0
	v_mov_b32_e32 v57, v0
	v_mov_b32_e32 v58, v0
	v_mov_b32_e32 v59, v0
	v_mov_b32_e32 v60, v0
	v_mov_b32_e32 v61, v0
	v_mov_b32_e32 v62, v0
	v_mov_b32_e32 v63, v0
	v_mov_b32_e32 v64, v0
	v_mov_b32_e32 v65, v0
	v_mov_b32_e32 v66, v0
	v_mov_b32_e32 v67, v0
	v_mov_b32_e32 v68, v0
	v_mov_b32_e32 v69, v0
	v_mov_b32_e32 v70, v0
	v_mov_b32_e32 v71, v0
	v_mov_b32_e32 v76, v0
	v_mov_b32_e32 v77, v0
	v_mov_b32_e32 v78, v0
	v_mov_b32_e32 v79, v0
	v_mov_b32_e32 v84, v0
	v_mov_b32_e32 v85, v0
	v_mov_b32_e32 v86, v0
	v_mov_b32_e32 v87, v0
	v_mov_b32_e32 v92, v0
	v_mov_b32_e32 v93, v0
	v_mov_b32_e32 v94, v0
	v_mov_b32_e32 v95, v0
	v_mov_b32_e32 v100, v0
	v_mov_b32_e32 v101, v0
	v_mov_b32_e32 v102, v0
	v_mov_b32_e32 v103, v0
	v_mov_b32_e32 v104, v0
	v_mov_b32_e32 v105, v0
	v_mov_b32_e32 v106, v0
	v_mov_b32_e32 v107, v0
	v_mov_b32_e32 v108, v0
	v_mov_b32_e32 v109, v0
	v_mov_b32_e32 v110, v0
	v_mov_b32_e32 v111, v0
	v_mov_b32_e32 v72, v0
	v_mov_b32_e32 v73, v0
	v_mov_b32_e32 v74, v0
	v_mov_b32_e32 v75, v0
	v_mov_b32_e32 v80, v0
	v_mov_b32_e32 v81, v0
	v_mov_b32_e32 v82, v0
	v_mov_b32_e32 v83, v0
	v_mov_b32_e32 v88, v0
	v_mov_b32_e32 v89, v0
	v_mov_b32_e32 v90, v0
	v_mov_b32_e32 v91, v0
	v_mov_b32_e32 v96, v0
	v_mov_b32_e32 v97, v0
	v_mov_b32_e32 v98, v0
	v_mov_b32_e32 v99, v0
	v_mov_b32_e32 v112, v0
	v_mov_b32_e32 v113, v0
	v_mov_b32_e32 v114, v0
	v_mov_b32_e32 v115, v0
	v_mov_b32_e32 v116, v0
	v_mov_b32_e32 v117, v0
	v_mov_b32_e32 v118, v0
	v_mov_b32_e32 v119, v0
	v_mov_b32_e32 v120, v0
	v_mov_b32_e32 v121, v0
	v_mov_b32_e32 v122, v0
	v_mov_b32_e32 v123, v0
	v_mov_b32_e32 v124, v0
	v_mov_b32_e32 v125, v0
	v_mov_b32_e32 v126, v0
	v_mov_b32_e32 v127, v0
.LBB0_1877:
	ds_read_b128 v[128:131], v167
	ds_read_b128 v[132:135], v167 offset:1024
	ds_read_b128 v[136:139], v167 offset:2048
	ds_read_b128 v[140:143], v167 offset:3072
	ds_read_b128 v[160:163], v168
	ds_read_b128 v[172:175], v168 offset:1024
	ds_read_b128 v[176:179], v168 offset:2048
	ds_read_b128 v[180:183], v168 offset:3072
	s_add_u32 s34, s30, 0xfffc0080
	s_addc_u32 s35, s31, -1
	s_cmp_eq_u32 s56, 12
	s_cselect_b32 s37, s25, s35
	s_cselect_b32 s36, s52, s34
	s_cselect_b32 s35, s23, s55
	s_cselect_b32 s34, s53, s54
	v_lshl_add_u64 v[216:217], s[30:31], 0, v[152:153]
	s_add_i32 m0, s40, 0xc000
	ds_read_b128 v[184:187], v169
	ds_read_b128 v[188:191], v169 offset:1024
	ds_read_b128 v[192:195], v169 offset:2048
	ds_read_b128 v[196:199], v169 offset:3072
	ds_read_b128 v[200:203], v169 offset:4096
	ds_read_b128 v[204:207], v169 offset:5120
	ds_read_b128 v[208:211], v169 offset:6144
	ds_read_b128 v[212:215], v169 offset:7168
	global_load_lds_dwordx4 v[216:217], off
	v_lshl_add_u64 v[216:217], s[30:31], 0, v[154:155]
	s_add_i32 m0, s40, 0xe000
	s_nop 0
	global_load_lds_dwordx4 v[216:217], off
	s_waitcnt vmcnt(8)
	s_waitcnt lgkmcnt(0)
	s_barrier
	s_setprio 1
	s_waitcnt lgkmcnt(0)
	v_mfma_f32_16x16x32_bf16 v[124:127], v[128:131], v[184:187], v[124:127]
	v_mfma_f32_16x16x32_bf16 v[120:123], v[136:139], v[184:187], v[120:123]
	v_mfma_f32_16x16x32_bf16 v[116:119], v[128:131], v[192:195], v[116:119]
	v_mfma_f32_16x16x32_bf16 v[112:115], v[136:139], v[192:195], v[112:115]
	v_mfma_f32_16x16x32_bf16 v[96:99], v[128:131], v[200:203], v[96:99]
	v_mfma_f32_16x16x32_bf16 v[88:91], v[136:139], v[200:203], v[88:91]
	v_mfma_f32_16x16x32_bf16 v[80:83], v[128:131], v[208:211], v[80:83]
	v_mfma_f32_16x16x32_bf16 v[72:75], v[136:139], v[208:211], v[72:75]
	v_mfma_f32_16x16x32_bf16 v[124:127], v[132:135], v[188:191], v[124:127]
	v_mfma_f32_16x16x32_bf16 v[120:123], v[140:143], v[188:191], v[120:123]
	v_mfma_f32_16x16x32_bf16 v[116:119], v[132:135], v[196:199], v[116:119]
	v_mfma_f32_16x16x32_bf16 v[112:115], v[140:143], v[196:199], v[112:115]
	v_mfma_f32_16x16x32_bf16 v[96:99], v[132:135], v[204:207], v[96:99]
	v_mfma_f32_16x16x32_bf16 v[88:91], v[140:143], v[204:207], v[88:91]
	v_mfma_f32_16x16x32_bf16 v[80:83], v[132:135], v[212:215], v[80:83]
	v_mfma_f32_16x16x32_bf16 v[72:75], v[140:143], v[212:215], v[72:75]
	s_setprio 0
	s_setprio 1
	v_mfma_f32_16x16x32_bf16 v[108:111], v[160:163], v[184:187], v[108:111]
	v_mfma_f32_16x16x32_bf16 v[104:107], v[176:179], v[184:187], v[104:107]
	v_mfma_f32_16x16x32_bf16 v[100:103], v[160:163], v[192:195], v[100:103]
	v_mfma_f32_16x16x32_bf16 v[92:95], v[176:179], v[192:195], v[92:95]
	v_mfma_f32_16x16x32_bf16 v[84:87], v[160:163], v[200:203], v[84:87]
	v_mfma_f32_16x16x32_bf16 v[76:79], v[176:179], v[200:203], v[76:79]
	v_mfma_f32_16x16x32_bf16 v[68:71], v[160:163], v[208:211], v[68:71]
	v_mfma_f32_16x16x32_bf16 v[64:67], v[176:179], v[208:211], v[64:67]
	v_mfma_f32_16x16x32_bf16 v[108:111], v[172:175], v[188:191], v[108:111]
	v_mfma_f32_16x16x32_bf16 v[104:107], v[180:183], v[188:191], v[104:107]
	v_mfma_f32_16x16x32_bf16 v[100:103], v[172:175], v[196:199], v[100:103]
	v_mfma_f32_16x16x32_bf16 v[92:95], v[180:183], v[196:199], v[92:95]
	v_mfma_f32_16x16x32_bf16 v[84:87], v[172:175], v[204:207], v[84:87]
	v_mfma_f32_16x16x32_bf16 v[76:79], v[180:183], v[204:207], v[76:79]
	v_mfma_f32_16x16x32_bf16 v[68:71], v[172:175], v[212:215], v[68:71]
	v_mfma_f32_16x16x32_bf16 v[64:67], v[180:183], v[212:215], v[64:67]
	s_setprio 0
	s_barrier
	s_add_i32 s57, s47, s38
	v_lshl_add_u64 v[216:217], s[34:35], 0, v[148:149]
	s_mov_b32 m0, s57
	ds_read_b128 v[184:187], v169 offset:16384
	ds_read_b128 v[188:191], v169 offset:17408
	ds_read_b128 v[192:195], v169 offset:18432
	ds_read_b128 v[196:199], v169 offset:19456
	ds_read_b128 v[200:203], v169 offset:20480
	ds_read_b128 v[204:207], v169 offset:21504
	ds_read_b128 v[208:211], v169 offset:22528
	ds_read_b128 v[212:215], v169 offset:23552
	global_load_lds_dwordx4 v[216:217], off
	s_add_i32 m0, s57, 0x2000
	s_add_u32 s58, s34, 0x580000
	v_lshl_add_u64 v[218:219], s[34:35], 0, v[144:145]
	s_addc_u32 s59, s35, 0
	s_add_i32 s57, s48, s38
	global_load_lds_dwordx4 v[218:219], off
	v_lshl_add_u64 v[220:221], s[58:59], 0, v[148:149]
	s_mov_b32 m0, s57
	v_lshl_add_u64 v[222:223], s[36:37], 0, v[146:147]
	global_load_lds_dwordx4 v[220:221], off
	v_lshl_add_u64 v[220:221], s[58:59], 0, v[144:145]
	s_add_i32 m0, s57, 0x2000
	s_nop 0
	global_load_lds_dwordx4 v[220:221], off
	v_lshl_add_u64 v[220:221], s[36:37], 0, v[150:151]
	s_mov_b32 m0, s40
	s_nop 0
	global_load_lds_dwordx4 v[220:221], off
	s_mov_b32 m0, s41
	s_nop 0
	global_load_lds_dwordx4 v[222:223], off
	s_waitcnt vmcnt(8)
	s_waitcnt lgkmcnt(0)
	s_barrier
	s_setprio 1
	s_waitcnt lgkmcnt(0)
	v_mfma_f32_16x16x32_bf16 v[60:63], v[128:131], v[184:187], v[60:63]
	v_mfma_f32_16x16x32_bf16 v[56:59], v[136:139], v[184:187], v[56:59]
	v_mfma_f32_16x16x32_bf16 v[48:51], v[128:131], v[192:195], v[48:51]
	v_mfma_f32_16x16x32_bf16 v[40:43], v[136:139], v[192:195], v[40:43]
	v_mfma_f32_16x16x32_bf16 v[32:35], v[128:131], v[200:203], v[32:35]
	v_mfma_f32_16x16x32_bf16 v[24:27], v[136:139], v[200:203], v[24:27]
	v_mfma_f32_16x16x32_bf16 v[16:19], v[128:131], v[208:211], v[16:19]
	v_mfma_f32_16x16x32_bf16 v[8:11], v[136:139], v[208:211], v[8:11]
	v_mfma_f32_16x16x32_bf16 v[60:63], v[132:135], v[188:191], v[60:63]
	v_mfma_f32_16x16x32_bf16 v[56:59], v[140:143], v[188:191], v[56:59]
	v_mfma_f32_16x16x32_bf16 v[48:51], v[132:135], v[196:199], v[48:51]
	v_mfma_f32_16x16x32_bf16 v[40:43], v[140:143], v[196:199], v[40:43]
	v_mfma_f32_16x16x32_bf16 v[32:35], v[132:135], v[204:207], v[32:35]
	v_mfma_f32_16x16x32_bf16 v[24:27], v[140:143], v[204:207], v[24:27]
	v_mfma_f32_16x16x32_bf16 v[16:19], v[132:135], v[212:215], v[16:19]
	v_mfma_f32_16x16x32_bf16 v[8:11], v[140:143], v[212:215], v[8:11]
	s_setprio 0
	s_setprio 1
	v_mfma_f32_16x16x32_bf16 v[52:55], v[160:163], v[184:187], v[52:55]
	v_mfma_f32_16x16x32_bf16 v[44:47], v[176:179], v[184:187], v[44:47]
	v_mfma_f32_16x16x32_bf16 v[36:39], v[160:163], v[192:195], v[36:39]
	v_mfma_f32_16x16x32_bf16 v[28:31], v[176:179], v[192:195], v[28:31]
	v_mfma_f32_16x16x32_bf16 v[20:23], v[160:163], v[200:203], v[20:23]
	v_mfma_f32_16x16x32_bf16 v[12:15], v[176:179], v[200:203], v[12:15]
	v_mfma_f32_16x16x32_bf16 v[4:7], v[160:163], v[208:211], v[4:7]
	v_mfma_f32_16x16x32_bf16 v[0:3], v[176:179], v[208:211], v[0:3]
	v_mfma_f32_16x16x32_bf16 v[52:55], v[172:175], v[188:191], v[52:55]
	v_mfma_f32_16x16x32_bf16 v[44:47], v[180:183], v[188:191], v[44:47]
	v_mfma_f32_16x16x32_bf16 v[36:39], v[172:175], v[196:199], v[36:39]
	v_mfma_f32_16x16x32_bf16 v[28:31], v[180:183], v[196:199], v[28:31]
	v_mfma_f32_16x16x32_bf16 v[20:23], v[172:175], v[204:207], v[20:23]
	v_mfma_f32_16x16x32_bf16 v[12:15], v[180:183], v[204:207], v[12:15]
	v_mfma_f32_16x16x32_bf16 v[4:7], v[172:175], v[212:215], v[4:7]
	v_mfma_f32_16x16x32_bf16 v[0:3], v[180:183], v[212:215], v[0:3]
	s_setprio 0
	s_barrier
	s_add_i32 s57, 0, 0x18000
	s_add_i32 s58, 0, 0x1c000
	v_add_u32_e32 v140, s57, v165
	v_add_u32_e32 v171, s58, v165
	ds_read_b128 v[128:131], v140
	ds_read_b128 v[132:135], v140 offset:1024
	ds_read_b128 v[136:139], v140 offset:2048
	ds_read_b128 v[140:143], v140 offset:3072
	ds_read_b128 v[160:163], v171
	ds_read_b128 v[172:175], v171 offset:1024
	ds_read_b128 v[176:179], v171 offset:2048
	ds_read_b128 v[180:183], v171 offset:3072
	s_add_u32 s36, s36, 0x40000
	s_addc_u32 s37, s37, 0
	s_mov_b32 m0, s42
	v_lshl_add_u64 v[224:225], s[36:37], 0, v[150:151]
	ds_read_b128 v[184:187], v169 offset:32768
	ds_read_b128 v[188:191], v169 offset:33792
	ds_read_b128 v[192:195], v169 offset:34816
	ds_read_b128 v[196:199], v169 offset:35840
	ds_read_b128 v[200:203], v169 offset:36864
	ds_read_b128 v[204:207], v169 offset:37888
	ds_read_b128 v[208:211], v169 offset:38912
	ds_read_b128 v[212:215], v169 offset:39936
	global_load_lds_dwordx4 v[224:225], off
	v_lshl_add_u64 v[224:225], s[36:37], 0, v[146:147]
	s_mov_b32 m0, s43
	s_nop 0
	global_load_lds_dwordx4 v[224:225], off
	s_waitcnt vmcnt(8)
	s_waitcnt lgkmcnt(0)
	s_barrier
	s_setprio 1
	s_waitcnt lgkmcnt(0)
	v_mfma_f32_16x16x32_bf16 v[124:127], v[128:131], v[184:187], v[124:127]
	v_mfma_f32_16x16x32_bf16 v[120:123], v[136:139], v[184:187], v[120:123]
	v_mfma_f32_16x16x32_bf16 v[116:119], v[128:131], v[192:195], v[116:119]
	v_mfma_f32_16x16x32_bf16 v[112:115], v[136:139], v[192:195], v[112:115]
	v_mfma_f32_16x16x32_bf16 v[96:99], v[128:131], v[200:203], v[96:99]
	v_mfma_f32_16x16x32_bf16 v[88:91], v[136:139], v[200:203], v[88:91]
	v_mfma_f32_16x16x32_bf16 v[80:83], v[128:131], v[208:211], v[80:83]
	v_mfma_f32_16x16x32_bf16 v[72:75], v[136:139], v[208:211], v[72:75]
	v_mfma_f32_16x16x32_bf16 v[124:127], v[132:135], v[188:191], v[124:127]
	v_mfma_f32_16x16x32_bf16 v[120:123], v[140:143], v[188:191], v[120:123]
	v_mfma_f32_16x16x32_bf16 v[116:119], v[132:135], v[196:199], v[116:119]
	v_mfma_f32_16x16x32_bf16 v[112:115], v[140:143], v[196:199], v[112:115]
	v_mfma_f32_16x16x32_bf16 v[96:99], v[132:135], v[204:207], v[96:99]
	v_mfma_f32_16x16x32_bf16 v[88:91], v[140:143], v[204:207], v[88:91]
	v_mfma_f32_16x16x32_bf16 v[80:83], v[132:135], v[212:215], v[80:83]
	v_mfma_f32_16x16x32_bf16 v[72:75], v[140:143], v[212:215], v[72:75]
	s_setprio 0
	s_setprio 1
	v_mfma_f32_16x16x32_bf16 v[108:111], v[160:163], v[184:187], v[108:111]
	v_mfma_f32_16x16x32_bf16 v[104:107], v[176:179], v[184:187], v[104:107]
	v_mfma_f32_16x16x32_bf16 v[100:103], v[160:163], v[192:195], v[100:103]
	v_mfma_f32_16x16x32_bf16 v[92:95], v[176:179], v[192:195], v[92:95]
	v_mfma_f32_16x16x32_bf16 v[84:87], v[160:163], v[200:203], v[84:87]
	v_mfma_f32_16x16x32_bf16 v[76:79], v[176:179], v[200:203], v[76:79]
	v_mfma_f32_16x16x32_bf16 v[68:71], v[160:163], v[208:211], v[68:71]
	v_mfma_f32_16x16x32_bf16 v[64:67], v[176:179], v[208:211], v[64:67]
	v_mfma_f32_16x16x32_bf16 v[108:111], v[172:175], v[188:191], v[108:111]
	v_mfma_f32_16x16x32_bf16 v[104:107], v[180:183], v[188:191], v[104:107]
	v_mfma_f32_16x16x32_bf16 v[100:103], v[172:175], v[196:199], v[100:103]
	v_mfma_f32_16x16x32_bf16 v[92:95], v[180:183], v[196:199], v[92:95]
	v_mfma_f32_16x16x32_bf16 v[84:87], v[172:175], v[204:207], v[84:87]
	v_mfma_f32_16x16x32_bf16 v[76:79], v[180:183], v[204:207], v[76:79]
	v_mfma_f32_16x16x32_bf16 v[68:71], v[172:175], v[212:215], v[68:71]
	v_mfma_f32_16x16x32_bf16 v[64:67], v[180:183], v[212:215], v[64:67]
	s_setprio 0
	s_barrier
	s_add_i32 s36, s57, s38
	v_lshl_add_u64 v[216:217], v[216:217], 0, s[14:15]
	s_mov_b32 m0, s36
	ds_read_b128 v[184:187], v169 offset:49152
	ds_read_b128 v[188:191], v169 offset:50176
	ds_read_b128 v[192:195], v169 offset:51200
	ds_read_b128 v[196:199], v169 offset:52224
	ds_read_b128 v[200:203], v169 offset:53248
	ds_read_b128 v[204:207], v169 offset:54272
	ds_read_b128 v[208:211], v169 offset:55296
	ds_read_b128 v[212:215], v169 offset:56320
	global_load_lds_dwordx4 v[216:217], off
	s_add_i32 m0, s36, 0x2000
	s_add_u32 s34, s34, 0x580080
	v_lshl_add_u64 v[216:217], v[218:219], 0, s[14:15]
	s_addc_u32 s35, s35, 0
	s_add_i32 s36, s58, s38
	global_load_lds_dwordx4 v[216:217], off
	v_lshl_add_u64 v[216:217], s[34:35], 0, v[148:149]
	s_mov_b32 m0, s36
	s_nop 0
	global_load_lds_dwordx4 v[216:217], off
	v_lshl_add_u64 v[216:217], s[34:35], 0, v[144:145]
	s_add_i32 m0, s36, 0x2000
	s_nop 0
	global_load_lds_dwordx4 v[216:217], off
	v_lshl_add_u64 v[216:217], v[220:221], 0, s[14:15]
	s_mov_b32 m0, s45
	s_nop 0
	global_load_lds_dwordx4 v[216:217], off
	v_lshl_add_u64 v[216:217], v[222:223], 0, s[14:15]
	s_mov_b32 m0, s46
	s_nop 0
	global_load_lds_dwordx4 v[216:217], off
	s_waitcnt vmcnt(8)
	s_waitcnt lgkmcnt(0)
	s_barrier
	s_setprio 1
	s_waitcnt lgkmcnt(0)
	v_mfma_f32_16x16x32_bf16 v[60:63], v[128:131], v[184:187], v[60:63]
	v_mfma_f32_16x16x32_bf16 v[56:59], v[136:139], v[184:187], v[56:59]
	v_mfma_f32_16x16x32_bf16 v[48:51], v[128:131], v[192:195], v[48:51]
	v_mfma_f32_16x16x32_bf16 v[40:43], v[136:139], v[192:195], v[40:43]
	v_mfma_f32_16x16x32_bf16 v[32:35], v[128:131], v[200:203], v[32:35]
	v_mfma_f32_16x16x32_bf16 v[24:27], v[136:139], v[200:203], v[24:27]
	v_mfma_f32_16x16x32_bf16 v[16:19], v[128:131], v[208:211], v[16:19]
	v_mfma_f32_16x16x32_bf16 v[8:11], v[136:139], v[208:211], v[8:11]
	v_mfma_f32_16x16x32_bf16 v[60:63], v[132:135], v[188:191], v[60:63]
	v_mfma_f32_16x16x32_bf16 v[56:59], v[140:143], v[188:191], v[56:59]
	v_mfma_f32_16x16x32_bf16 v[48:51], v[132:135], v[196:199], v[48:51]
	v_mfma_f32_16x16x32_bf16 v[40:43], v[140:143], v[196:199], v[40:43]
	v_mfma_f32_16x16x32_bf16 v[32:35], v[132:135], v[204:207], v[32:35]
	v_mfma_f32_16x16x32_bf16 v[24:27], v[140:143], v[204:207], v[24:27]
	v_mfma_f32_16x16x32_bf16 v[16:19], v[132:135], v[212:215], v[16:19]
	v_mfma_f32_16x16x32_bf16 v[8:11], v[140:143], v[212:215], v[8:11]
	s_setprio 0
	s_setprio 1
	v_mfma_f32_16x16x32_bf16 v[52:55], v[160:163], v[184:187], v[52:55]
	v_mfma_f32_16x16x32_bf16 v[44:47], v[176:179], v[184:187], v[44:47]
	v_mfma_f32_16x16x32_bf16 v[36:39], v[160:163], v[192:195], v[36:39]
	v_mfma_f32_16x16x32_bf16 v[28:31], v[176:179], v[192:195], v[28:31]
	v_mfma_f32_16x16x32_bf16 v[20:23], v[160:163], v[200:203], v[20:23]
	v_mfma_f32_16x16x32_bf16 v[12:15], v[176:179], v[200:203], v[12:15]
	v_mfma_f32_16x16x32_bf16 v[4:7], v[160:163], v[208:211], v[4:7]
	v_mfma_f32_16x16x32_bf16 v[0:3], v[176:179], v[208:211], v[0:3]
	v_mfma_f32_16x16x32_bf16 v[52:55], v[172:175], v[188:191], v[52:55]
	v_mfma_f32_16x16x32_bf16 v[44:47], v[180:183], v[188:191], v[44:47]
	v_mfma_f32_16x16x32_bf16 v[36:39], v[172:175], v[196:199], v[36:39]
	v_mfma_f32_16x16x32_bf16 v[28:31], v[180:183], v[196:199], v[28:31]
	v_mfma_f32_16x16x32_bf16 v[20:23], v[172:175], v[204:207], v[20:23]
	v_mfma_f32_16x16x32_bf16 v[12:15], v[180:183], v[204:207], v[12:15]
	v_mfma_f32_16x16x32_bf16 v[4:7], v[172:175], v[212:215], v[4:7]
	v_mfma_f32_16x16x32_bf16 v[0:3], v[180:183], v[212:215], v[0:3]
	s_setprio 0
	s_barrier
	s_add_i32 s56, s56, 2
	s_add_u32 s30, s30, 0x100
	s_addc_u32 s31, s31, 0
	s_add_u32 s54, s54, 0x100
	s_addc_u32 s55, s55, 0
	s_cmp_lt_u32 s56, 14
	s_cbranch_scc1 .LBB0_1877
	s_andn2_b64 vcc, exec, s[16:17]
	s_cbranch_vccnz .LBB0_1880
	s_barrier
.LBB0_1880:
	s_and_b32 s23, s8, 1
	s_add_i32 s30, s6, 0
	s_ashr_i32 s30, s30, 2
	s_add_i32 s30, s30, 1
	s_cmp_gt_i32 s6, -1
	s_cselect_b32 s30, s30, 0
	s_mul_hi_i32 s31, s30, 0x5800
	s_mulk_i32 s30, 0x5800
	s_add_u32 s30, s33, s30
	s_addc_u32 s31, s50, s31
	v_lshl_add_u32 v236, s6, 8, v164
	v_lshlrev_b32_e32 v236, 2, v236
	v_lshl_or_b32 v229, s7, 7, v166
	v_lshlrev_b32_e32 v229, 2, v229
	global_load_dword v208, v236, s[10:11] offset:0
	global_load_dword v209, v236, s[10:11] offset:64
	global_load_dword v210, v236, s[10:11] offset:128
	global_load_dword v211, v236, s[10:11] offset:192
	global_load_dword v212, v236, s[10:11] offset:512
	global_load_dword v213, v236, s[10:11] offset:576
	global_load_dword v214, v236, s[10:11] offset:640
	global_load_dword v215, v236, s[10:11] offset:704
	global_load_dwordx4 v[200:203], v229, s[30:31]
	global_load_dwordx4 v[204:207], v229, s[30:31] offset:16
	v_add_u32_e32 v224, 0x2c00, v229
	global_load_dwordx4 v[216:219], v224, s[30:31]
	global_load_dwordx4 v[220:223], v224, s[30:31] offset:16
	v_readlane_b32 s34, v254, 5
	v_readlane_b32 s35, v254, 6
	v_readlane_b32 s36, v254, 7
	v_readlane_b32 s37, v254, 8
	s_add_u32 s34, s34, 0x10800
	s_addc_u32 s35, s35, 0
	s_add_u32 s36, s36, 0x5800
	s_addc_u32 s37, s37, 0
	s_mul_i32 s52, s6, 0x160000
	s_lshl_b32 s79, s7, 8
	s_add_i32 s52, s52, s79
	s_add_i32 s52, s52, 0xbf00000
	s_add_u32 s52, s52, s70
	s_addc_u32 s53, s71, 0
	v_mul_u32_u24_e32 v171, 0x1600, v164
	v_lshl_add_u32 v171, v166, 1, v171
	s_mov_b32 s32, 0x20800
	v_lshl_add_u32 v228, v166, 2, s32
	v_and_b32_e32 v237, 15, v164
	v_cmp_eq_u32_e64 s[54:55], 0, v237
	v_cmp_eq_u32_e64 s[56:57], 15, v237
	v_and_b32_e32 v231, 8, v237
	v_lshlrev_b32_e32 v231, 9, v231
	s_lshl_b32 s79, s23, 10
	v_add3_u32 v231, v231, v228, s79
	s_waitcnt vmcnt(4)
	v_fmamk_f32 v208, v208, 0x3a800000, v170
	v_fmamk_f32 v209, v209, 0x3a800000, v170
	v_fmamk_f32 v210, v210, 0x3a800000, v170
	v_fmamk_f32 v211, v211, 0x3a800000, v170
	v_fmamk_f32 v212, v212, 0x3a800000, v170
	v_fmamk_f32 v213, v213, 0x3a800000, v170
	v_fmamk_f32 v214, v214, 0x3a800000, v170
	v_fmamk_f32 v215, v215, 0x3a800000, v170
	s_mov_b32 s79, 0x800000
	v_mul_f32_e32 v224, 0x4b800000, v208
	v_mul_f32_e32 v225, 0x4b800000, v209
	v_mul_f32_e32 v226, 0x4b800000, v210
	v_mul_f32_e32 v227, 0x4b800000, v211
	v_mul_f32_e32 v232, 0x4b800000, v212
	v_mul_f32_e32 v233, 0x4b800000, v213
	v_mul_f32_e32 v234, 0x4b800000, v214
	v_mul_f32_e32 v235, 0x4b800000, v215
	v_cmp_gt_f32_e32 vcc, s79, v208
	s_nop 1
	v_cndmask_b32_e32 v208, v208, v224, vcc
	v_rsq_f32_e32 v208, v208
	s_nop 0
	v_mul_f32_e32 v224, 0x45800000, v208
	v_cndmask_b32_e32 v208, v208, v224, vcc
	v_cmp_gt_f32_e32 vcc, s79, v209
	s_nop 1
	v_cndmask_b32_e32 v209, v209, v225, vcc
	v_rsq_f32_e32 v209, v209
	s_nop 0
	v_mul_f32_e32 v225, 0x45800000, v209
	v_cndmask_b32_e32 v209, v209, v225, vcc
	v_cmp_gt_f32_e32 vcc, s79, v210
	s_nop 1
	v_cndmask_b32_e32 v210, v210, v226, vcc
	v_rsq_f32_e32 v210, v210
	s_nop 0
	v_mul_f32_e32 v226, 0x45800000, v210
	v_cndmask_b32_e32 v210, v210, v226, vcc
	v_cmp_gt_f32_e32 vcc, s79, v211
	s_nop 1
	v_cndmask_b32_e32 v211, v211, v227, vcc
	v_rsq_f32_e32 v211, v211
	s_nop 0
	v_mul_f32_e32 v227, 0x45800000, v211
	v_cndmask_b32_e32 v211, v211, v227, vcc
	v_cmp_gt_f32_e32 vcc, s79, v212
	s_nop 1
	v_cndmask_b32_e32 v212, v212, v232, vcc
	v_rsq_f32_e32 v212, v212
	s_nop 0
	v_mul_f32_e32 v232, 0x45800000, v212
	v_cndmask_b32_e32 v212, v212, v232, vcc
	v_cmp_gt_f32_e32 vcc, s79, v213
	s_nop 1
	v_cndmask_b32_e32 v213, v213, v233, vcc
	v_rsq_f32_e32 v213, v213
	s_nop 0
	v_mul_f32_e32 v233, 0x45800000, v213
	v_cndmask_b32_e32 v213, v213, v233, vcc
	v_cmp_gt_f32_e32 vcc, s79, v214
	s_nop 1
	v_cndmask_b32_e32 v214, v214, v234, vcc
	v_rsq_f32_e32 v214, v214
	s_nop 0
	v_mul_f32_e32 v234, 0x45800000, v214
	v_cndmask_b32_e32 v214, v214, v234, vcc
	v_cmp_gt_f32_e32 vcc, s79, v215
	s_nop 1
	v_cndmask_b32_e32 v215, v215, v235, vcc
	v_rsq_f32_e32 v215, v215
	s_nop 0
	v_mul_f32_e32 v235, 0x45800000, v215
	v_cndmask_b32_e32 v215, v215, v235, vcc
	s_waitcnt vmcnt(0)
	v_fma_f32 v124, v124, v208, v200
	v_fma_f32 v125, v125, v208, v201
	v_fma_f32 v126, v126, v208, v202
	v_fma_f32 v127, v127, v208, v203
	v_fma_f32 v120, v120, v208, v204
	v_fma_f32 v121, v121, v208, v205
	v_fma_f32 v122, v122, v208, v206
	v_fma_f32 v123, v123, v208, v207
	v_fma_f32 v108, v108, v208, v216
	v_fma_f32 v109, v109, v208, v217
	v_fma_f32 v110, v110, v208, v218
	v_fma_f32 v111, v111, v208, v219
	v_fma_f32 v104, v104, v208, v220
	v_fma_f32 v105, v105, v208, v221
	v_fma_f32 v106, v106, v208, v222
	v_fma_f32 v107, v107, v208, v223
	v_fma_f32 v116, v116, v209, v200
	v_fma_f32 v117, v117, v209, v201
	v_fma_f32 v118, v118, v209, v202
	v_fma_f32 v119, v119, v209, v203
	v_fma_f32 v112, v112, v209, v204
	v_fma_f32 v113, v113, v209, v205
	v_fma_f32 v114, v114, v209, v206
	v_fma_f32 v115, v115, v209, v207
	v_fma_f32 v100, v100, v209, v216
	v_fma_f32 v101, v101, v209, v217
	v_fma_f32 v102, v102, v209, v218
	v_fma_f32 v103, v103, v209, v219
	v_fma_f32 v92, v92, v209, v220
	v_fma_f32 v93, v93, v209, v221
	v_fma_f32 v94, v94, v209, v222
	v_fma_f32 v95, v95, v209, v223
	v_fma_f32 v96, v96, v210, v200
	v_fma_f32 v97, v97, v210, v201
	v_fma_f32 v98, v98, v210, v202
	v_fma_f32 v99, v99, v210, v203
	v_fma_f32 v88, v88, v210, v204
	v_fma_f32 v89, v89, v210, v205
	v_fma_f32 v90, v90, v210, v206
	v_fma_f32 v91, v91, v210, v207
	v_fma_f32 v84, v84, v210, v216
	v_fma_f32 v85, v85, v210, v217
	v_fma_f32 v86, v86, v210, v218
	v_fma_f32 v87, v87, v210, v219
	v_fma_f32 v76, v76, v210, v220
	v_fma_f32 v77, v77, v210, v221
	v_fma_f32 v78, v78, v210, v222
	v_fma_f32 v79, v79, v210, v223
	v_fma_f32 v80, v80, v211, v200
	v_fma_f32 v81, v81, v211, v201
	v_fma_f32 v82, v82, v211, v202
	v_fma_f32 v83, v83, v211, v203
	v_fma_f32 v72, v72, v211, v204
	v_fma_f32 v73, v73, v211, v205
	v_fma_f32 v74, v74, v211, v206
	v_fma_f32 v75, v75, v211, v207
	v_fma_f32 v68, v68, v211, v216
	v_fma_f32 v69, v69, v211, v217
	v_fma_f32 v70, v70, v211, v218
	v_fma_f32 v71, v71, v211, v219
	v_fma_f32 v64, v64, v211, v220
	v_fma_f32 v65, v65, v211, v221
	v_fma_f32 v66, v66, v211, v222
	v_fma_f32 v67, v67, v211, v223
	v_fma_f32 v60, v60, v212, v200
	v_fma_f32 v61, v61, v212, v201
	v_fma_f32 v62, v62, v212, v202
	v_fma_f32 v63, v63, v212, v203
	v_fma_f32 v56, v56, v212, v204
	v_fma_f32 v57, v57, v212, v205
	v_fma_f32 v58, v58, v212, v206
	v_fma_f32 v59, v59, v212, v207
	v_fma_f32 v52, v52, v212, v216
	v_fma_f32 v53, v53, v212, v217
	v_fma_f32 v54, v54, v212, v218
	v_fma_f32 v55, v55, v212, v219
	v_fma_f32 v44, v44, v212, v220
	v_fma_f32 v45, v45, v212, v221
	v_fma_f32 v46, v46, v212, v222
	v_fma_f32 v47, v47, v212, v223
	v_fma_f32 v48, v48, v213, v200
	v_fma_f32 v49, v49, v213, v201
	v_fma_f32 v50, v50, v213, v202
	v_fma_f32 v51, v51, v213, v203
	v_fma_f32 v40, v40, v213, v204
	v_fma_f32 v41, v41, v213, v205
	v_fma_f32 v42, v42, v213, v206
	v_fma_f32 v43, v43, v213, v207
	v_fma_f32 v36, v36, v213, v216
	v_fma_f32 v37, v37, v213, v217
	v_fma_f32 v38, v38, v213, v218
	v_fma_f32 v39, v39, v213, v219
	v_fma_f32 v28, v28, v213, v220
	v_fma_f32 v29, v29, v213, v221
	v_fma_f32 v30, v30, v213, v222
	v_fma_f32 v31, v31, v213, v223
	v_fma_f32 v32, v32, v214, v200
	v_fma_f32 v33, v33, v214, v201
	v_fma_f32 v34, v34, v214, v202
	v_fma_f32 v35, v35, v214, v203
	v_fma_f32 v24, v24, v214, v204
	v_fma_f32 v25, v25, v214, v205
	v_fma_f32 v26, v26, v214, v206
	v_fma_f32 v27, v27, v214, v207
	v_fma_f32 v20, v20, v214, v216
	v_fma_f32 v21, v21, v214, v217
	v_fma_f32 v22, v22, v214, v218
	v_fma_f32 v23, v23, v214, v219
	v_fma_f32 v12, v12, v214, v220
	v_fma_f32 v13, v13, v214, v221
	v_fma_f32 v14, v14, v214, v222
	v_fma_f32 v15, v15, v214, v223
	v_fma_f32 v16, v16, v215, v200
	v_fma_f32 v17, v17, v215, v201
	v_fma_f32 v18, v18, v215, v202
	v_fma_f32 v19, v19, v215, v203
	v_fma_f32 v8, v8, v215, v204
	v_fma_f32 v9, v9, v215, v205
	v_fma_f32 v10, v10, v215, v206
	v_fma_f32 v11, v11, v215, v207
	v_fma_f32 v4, v4, v215, v216
	v_fma_f32 v5, v5, v215, v217
	v_fma_f32 v6, v6, v215, v218
	v_fma_f32 v7, v7, v215, v219
	v_fma_f32 v0, v0, v215, v220
	v_fma_f32 v1, v1, v215, v221
	v_fma_f32 v2, v2, v215, v222
	v_fma_f32 v3, v3, v215, v223
	global_load_dwordx4 v[128:131], v229, s[34:35]
	v_add_u32_e32 v211, 0x5800, v229
	global_load_dwordx4 v[132:135], v211, s[34:35]
	v_add_u32_e32 v210, 0xb000, v229
	global_load_dwordx4 v[136:139], v210, s[34:35]
	global_load_dwordx4 v[140:143], v229, s[36:37]
	v_add_u32_e32 v210, 0x2c00, v229
	global_load_dwordx4 v[160:163], v210, s[34:35]
	v_add_u32_e32 v211, 0x8400, v229
	global_load_dwordx4 v[172:175], v211, s[34:35]
	v_add_u32_e32 v210, 0xdc00, v229
	global_load_dwordx4 v[176:179], v210, s[34:35]
	v_add_u32_e32 v211, 0x2c00, v229
	global_load_dwordx4 v[180:183], v211, s[36:37]
	v_mov_b32_e32 v212, 0
	v_mov_b32_e32 v213, 0
	v_mov_b32_e32 v214, 0
	v_mov_b32_e32 v215, 0
	s_lshl_b32 s96, s23, 12
	s_sub_i32 s96, 0x2000, s96
	s_mul_i32 s94, s23, 0x1400
	s_add_i32 s94, s94, 0xc00
	s_lshl_b32 s79, s23, 10
	s_add_i32 s95, s79, 5120
	s_add_i32 s92, s79, 1024
	s_mov_b64 s[58:59], exec
	s_mov_b64 exec, s[54:55]
	v_add_u32_e32 v250, s96, v228
	ds_write_b128 v250, v[124:127] offset:0
	ds_write_b128 v250, v[120:123] offset:16
	ds_write_b128 v250, v[108:111] offset:512
	ds_write_b128 v250, v[104:107] offset:528
	v_add_u32_e32 v250, s95, v228
	ds_write_b128 v250, v[60:63] offset:0
	ds_write_b128 v250, v[56:59] offset:16
	ds_write_b128 v250, v[52:55] offset:512
	ds_write_b128 v250, v[44:47] offset:528
	ds_write_b128 v228, v[212:215] offset:0
	ds_write_b128 v228, v[212:215] offset:16
	ds_write_b128 v228, v[212:215] offset:512
	ds_write_b128 v228, v[212:215] offset:528
	s_mov_b64 exec, s[56:57]
	v_add_u32_e32 v251, s92, v228
	ds_write_b128 v251, v[80:83] offset:0
	ds_write_b128 v251, v[72:75] offset:16
	ds_write_b128 v251, v[68:71] offset:512
	ds_write_b128 v251, v[64:67] offset:528
	v_add_u32_e32 v251, s94, v228
	ds_write_b128 v251, v[16:19] offset:0
	ds_write_b128 v251, v[8:11] offset:16
	ds_write_b128 v251, v[4:7] offset:512
	ds_write_b128 v251, v[0:3] offset:528
	ds_write_b128 v228, v[212:215] offset:7168
	ds_write_b128 v228, v[212:215] offset:7184
	ds_write_b128 v228, v[212:215] offset:7680
	ds_write_b128 v228, v[212:215] offset:7696
	s_mov_b64 exec, s[58:59]
	s_cmp_eq_u32 s23, 0
	s_cselect_b64 s[60:61], s[54:55], 0
	s_cselect_b64 s[62:63], 0, s[56:57]
	s_mul_i32 s64, s6, 0x16000
	s_add_u32 s64, s64, 0x5b00000
	s_add_u32 s64, s64, s70
	s_addc_u32 s65, s71, 0
	s_mov_b64 exec, s[60:61]
	global_store_dwordx4 v229, v[124:127], s[64:65]
	global_store_dwordx4 v229, v[120:123], s[64:65] offset:16
	v_add_u32_e32 v250, 0x2c00, v229
	global_store_dwordx4 v250, v[108:111], s[64:65]
	global_store_dwordx4 v250, v[104:107], s[64:65] offset:16
	s_mov_b64 exec, s[62:63]
	v_add_u32_e32 v250, 0xb000, v229
	global_store_dwordx4 v250, v[16:19], s[64:65]
	global_store_dwordx4 v250, v[8:11], s[64:65] offset:16
	v_add_u32_e32 v250, 0xdc00, v229
	global_store_dwordx4 v250, v[4:7], s[64:65]
	global_store_dwordx4 v250, v[0:3], s[64:65] offset:16
	s_mov_b64 exec, s[58:59]
	s_waitcnt lgkmcnt(0)
	s_barrier
	ds_read_b128 v[184:187], v231 offset:0
	ds_read_b128 v[188:191], v231 offset:512
	ds_read_b128 v[192:195], v231 offset:2048
	ds_read_b128 v[196:199], v231 offset:2560
	s_waitcnt vmcnt(0)
	v_cndmask_b32_e64 v216, 0, v128, s[54:55]
	v_cndmask_b32_e64 v220, 0, v136, s[56:57]
	v_cndmask_b32_e64 v217, 0, v129, s[54:55]
	v_cndmask_b32_e64 v221, 0, v137, s[56:57]
	v_cndmask_b32_e64 v218, 0, v130, s[54:55]
	v_cndmask_b32_e64 v222, 0, v138, s[56:57]
	v_cndmask_b32_e64 v219, 0, v131, s[54:55]
	v_cndmask_b32_e64 v223, 0, v139, s[56:57]
	v_cndmask_b32_e64 v224, 0, v160, s[54:55]
	v_cndmask_b32_e64 v232, 0, v176, s[56:57]
	v_cndmask_b32_e64 v225, 0, v161, s[54:55]
	v_cndmask_b32_e64 v233, 0, v177, s[56:57]
	v_cndmask_b32_e64 v226, 0, v162, s[54:55]
	v_cndmask_b32_e64 v234, 0, v178, s[56:57]
	v_cndmask_b32_e64 v227, 0, v163, s[54:55]
	v_cndmask_b32_e64 v235, 0, v179, s[56:57]
	s_waitcnt lgkmcnt(0)
	s_nop 1
	v_fma_f32 v200, v132, v124, v140
	v_fma_f32 v201, v133, v125, v141
	v_fma_f32 v202, v134, v126, v142
	v_fma_f32 v203, v135, v127, v143
	v_fmac_f32_dpp v200, v124, v128 row_shr:1 row_mask:0xf bank_mask:0xf
	v_fmac_f32_dpp v201, v125, v129 row_shr:1 row_mask:0xf bank_mask:0xf
	v_fmac_f32_dpp v202, v126, v130 row_shr:1 row_mask:0xf bank_mask:0xf
	v_fmac_f32_dpp v203, v127, v131 row_shr:1 row_mask:0xf bank_mask:0xf
	v_fmac_f32_e32 v200, v184, v216
	v_fmac_f32_e32 v201, v185, v217
	v_fmac_f32_e32 v202, v186, v218
	v_fmac_f32_e32 v203, v187, v219
	v_fmac_f32_dpp v200, v124, v136 row_shl:1 row_mask:0xf bank_mask:0xf
	v_fmac_f32_dpp v201, v125, v137 row_shl:1 row_mask:0xf bank_mask:0xf
	v_fmac_f32_dpp v202, v126, v138 row_shl:1 row_mask:0xf bank_mask:0xf
	v_fmac_f32_dpp v203, v127, v139 row_shl:1 row_mask:0xf bank_mask:0xf
	v_fmac_f32_dpp v200, v116, v220 row_ror:15 row_mask:0xf bank_mask:0xf
	v_fmac_f32_dpp v201, v117, v221 row_ror:15 row_mask:0xf bank_mask:0xf
	v_fmac_f32_dpp v202, v118, v222 row_ror:15 row_mask:0xf bank_mask:0xf
	v_fmac_f32_dpp v203, v119, v223 row_ror:15 row_mask:0xf bank_mask:0xf
	v_fma_f32 v204, v172, v108, v180
	v_fma_f32 v205, v173, v109, v181
	v_fma_f32 v206, v174, v110, v182
	v_fma_f32 v207, v175, v111, v183
	v_fmac_f32_dpp v204, v108, v160 row_shr:1 row_mask:0xf bank_mask:0xf
	v_fmac_f32_dpp v205, v109, v161 row_shr:1 row_mask:0xf bank_mask:0xf
	v_fmac_f32_dpp v206, v110, v162 row_shr:1 row_mask:0xf bank_mask:0xf
	v_fmac_f32_dpp v207, v111, v163 row_shr:1 row_mask:0xf bank_mask:0xf
	v_fmac_f32_e32 v204, v188, v224
	v_fmac_f32_e32 v205, v189, v225
	v_fmac_f32_e32 v206, v190, v226
	v_fmac_f32_e32 v207, v191, v227
	v_fmac_f32_dpp v204, v108, v176 row_shl:1 row_mask:0xf bank_mask:0xf
	v_fmac_f32_dpp v205, v109, v177 row_shl:1 row_mask:0xf bank_mask:0xf
	v_fmac_f32_dpp v206, v110, v178 row_shl:1 row_mask:0xf bank_mask:0xf
	v_fmac_f32_dpp v207, v111, v179 row_shl:1 row_mask:0xf bank_mask:0xf
	v_fmac_f32_dpp v204, v100, v232 row_ror:15 row_mask:0xf bank_mask:0xf
	v_fmac_f32_dpp v205, v101, v233 row_ror:15 row_mask:0xf bank_mask:0xf
	v_fmac_f32_dpp v206, v102, v234 row_ror:15 row_mask:0xf bank_mask:0xf
	v_fmac_f32_dpp v207, v103, v235 row_ror:15 row_mask:0xf bank_mask:0xf
	s_mov_b64 exec, s[60:61]
	v_add_u32_e32 v250, 0x5800, v229
	global_store_dwordx4 v250, v[200:203], s[64:65]
	v_add_u32_e32 v250, 0x8400, v229
	global_store_dwordx4 v250, v[204:207], s[64:65]
	s_mov_b64 exec, s[58:59]
	s_nop 4
	v_mul_f32_e32 v208, 0xbfb8aa3b, v200
	v_mul_f32_e32 v209, 0xbfb8aa3b, v201
	v_mul_f32_e32 v210, 0xbfb8aa3b, v202
	v_mul_f32_e32 v211, 0xbfb8aa3b, v203
	v_exp_f32_e32 v208, v208
	v_exp_f32_e32 v209, v209
	v_exp_f32_e32 v210, v210
	v_exp_f32_e32 v211, v211
	v_add_f32_e32 v208, 1.0, v208
	v_add_f32_e32 v209, 1.0, v209
	v_add_f32_e32 v210, 1.0, v210
	v_add_f32_e32 v211, 1.0, v211
	v_rcp_f32_e32 v208, v208
	v_rcp_f32_e32 v209, v209
	v_rcp_f32_e32 v210, v210
	v_rcp_f32_e32 v211, v211
	v_mul_f32_e32 v200, v200, v208
	v_mul_f32_e32 v201, v201, v209
	v_mul_f32_e32 v202, v202, v210
	v_mul_f32_e32 v203, v203, v211
	v_mul_f32_e32 v200, v200, v204
	v_mul_f32_e32 v201, v201, v205
	v_mul_f32_e32 v202, v202, v206
	v_mul_f32_e32 v203, v203, v207
	v_cvt_pk_bf16_f32 v236, v200, v201
	v_cvt_pk_bf16_f32 v237, v202, v203
	v_fma_f32 v200, v132, v116, v140
	v_fma_f32 v201, v133, v117, v141
	v_fma_f32 v202, v134, v118, v142
	v_fma_f32 v203, v135, v119, v143
	v_fmac_f32_dpp v200, v116, v128 row_shr:1 row_mask:0xf bank_mask:0xf
	v_fmac_f32_dpp v201, v117, v129 row_shr:1 row_mask:0xf bank_mask:0xf
	v_fmac_f32_dpp v202, v118, v130 row_shr:1 row_mask:0xf bank_mask:0xf
	v_fmac_f32_dpp v203, v119, v131 row_shr:1 row_mask:0xf bank_mask:0xf
	v_fmac_f32_dpp v200, v124, v216 row_ror:1 row_mask:0xf bank_mask:0xf
	v_fmac_f32_dpp v201, v125, v217 row_ror:1 row_mask:0xf bank_mask:0xf
	v_fmac_f32_dpp v202, v126, v218 row_ror:1 row_mask:0xf bank_mask:0xf
	v_fmac_f32_dpp v203, v127, v219 row_ror:1 row_mask:0xf bank_mask:0xf
	v_fmac_f32_dpp v200, v116, v136 row_shl:1 row_mask:0xf bank_mask:0xf
	v_fmac_f32_dpp v201, v117, v137 row_shl:1 row_mask:0xf bank_mask:0xf
	v_fmac_f32_dpp v202, v118, v138 row_shl:1 row_mask:0xf bank_mask:0xf
	v_fmac_f32_dpp v203, v119, v139 row_shl:1 row_mask:0xf bank_mask:0xf
	v_fmac_f32_dpp v200, v96, v220 row_ror:15 row_mask:0xf bank_mask:0xf
	v_fmac_f32_dpp v201, v97, v221 row_ror:15 row_mask:0xf bank_mask:0xf
	v_fmac_f32_dpp v202, v98, v222 row_ror:15 row_mask:0xf bank_mask:0xf
	v_fmac_f32_dpp v203, v99, v223 row_ror:15 row_mask:0xf bank_mask:0xf
	v_fma_f32 v204, v172, v100, v180
	v_fma_f32 v205, v173, v101, v181
	v_fma_f32 v206, v174, v102, v182
	v_fma_f32 v207, v175, v103, v183
	v_fmac_f32_dpp v204, v100, v160 row_shr:1 row_mask:0xf bank_mask:0xf
	v_fmac_f32_dpp v205, v101, v161 row_shr:1 row_mask:0xf bank_mask:0xf
	v_fmac_f32_dpp v206, v102, v162 row_shr:1 row_mask:0xf bank_mask:0xf
	v_fmac_f32_dpp v207, v103, v163 row_shr:1 row_mask:0xf bank_mask:0xf
	v_fmac_f32_dpp v204, v108, v224 row_ror:1 row_mask:0xf bank_mask:0xf
	v_fmac_f32_dpp v205, v109, v225 row_ror:1 row_mask:0xf bank_mask:0xf
	v_fmac_f32_dpp v206, v110, v226 row_ror:1 row_mask:0xf bank_mask:0xf
	v_fmac_f32_dpp v207, v111, v227 row_ror:1 row_mask:0xf bank_mask:0xf
	v_fmac_f32_dpp v204, v100, v176 row_shl:1 row_mask:0xf bank_mask:0xf
	v_fmac_f32_dpp v205, v101, v177 row_shl:1 row_mask:0xf bank_mask:0xf
	v_fmac_f32_dpp v206, v102, v178 row_shl:1 row_mask:0xf bank_mask:0xf
	v_fmac_f32_dpp v207, v103, v179 row_shl:1 row_mask:0xf bank_mask:0xf
	v_fmac_f32_dpp v204, v84, v232 row_ror:15 row_mask:0xf bank_mask:0xf
	v_fmac_f32_dpp v205, v85, v233 row_ror:15 row_mask:0xf bank_mask:0xf
	v_fmac_f32_dpp v206, v86, v234 row_ror:15 row_mask:0xf bank_mask:0xf
	v_fmac_f32_dpp v207, v87, v235 row_ror:15 row_mask:0xf bank_mask:0xf
	v_mul_f32_e32 v208, 0xbfb8aa3b, v200
	v_mul_f32_e32 v209, 0xbfb8aa3b, v201
	v_mul_f32_e32 v210, 0xbfb8aa3b, v202
	v_mul_f32_e32 v211, 0xbfb8aa3b, v203
	v_exp_f32_e32 v208, v208
	v_exp_f32_e32 v209, v209
	v_exp_f32_e32 v210, v210
	v_exp_f32_e32 v211, v211
	v_add_f32_e32 v208, 1.0, v208
	v_add_f32_e32 v209, 1.0, v209
	v_add_f32_e32 v210, 1.0, v210
	v_add_f32_e32 v211, 1.0, v211
	v_rcp_f32_e32 v208, v208
	v_rcp_f32_e32 v209, v209
	v_rcp_f32_e32 v210, v210
	v_rcp_f32_e32 v211, v211
	v_mul_f32_e32 v200, v200, v208
	v_mul_f32_e32 v201, v201, v209
	v_mul_f32_e32 v202, v202, v210
	v_mul_f32_e32 v203, v203, v211
	v_mul_f32_e32 v200, v200, v204
	v_mul_f32_e32 v201, v201, v205
	v_mul_f32_e32 v202, v202, v206
	v_mul_f32_e32 v203, v203, v207
	v_cvt_pk_bf16_f32 v238, v200, v201
	v_cvt_pk_bf16_f32 v239, v202, v203
	v_fma_f32 v200, v132, v96, v140
	v_fma_f32 v201, v133, v97, v141
	v_fma_f32 v202, v134, v98, v142
	v_fma_f32 v203, v135, v99, v143
	v_fmac_f32_dpp v200, v96, v128 row_shr:1 row_mask:0xf bank_mask:0xf
	v_fmac_f32_dpp v201, v97, v129 row_shr:1 row_mask:0xf bank_mask:0xf
	v_fmac_f32_dpp v202, v98, v130 row_shr:1 row_mask:0xf bank_mask:0xf
	v_fmac_f32_dpp v203, v99, v131 row_shr:1 row_mask:0xf bank_mask:0xf
	v_fmac_f32_dpp v200, v116, v216 row_ror:1 row_mask:0xf bank_mask:0xf
	v_fmac_f32_dpp v201, v117, v217 row_ror:1 row_mask:0xf bank_mask:0xf
	v_fmac_f32_dpp v202, v118, v218 row_ror:1 row_mask:0xf bank_mask:0xf
	v_fmac_f32_dpp v203, v119, v219 row_ror:1 row_mask:0xf bank_mask:0xf
	v_fmac_f32_dpp v200, v96, v136 row_shl:1 row_mask:0xf bank_mask:0xf
	v_fmac_f32_dpp v201, v97, v137 row_shl:1 row_mask:0xf bank_mask:0xf
	v_fmac_f32_dpp v202, v98, v138 row_shl:1 row_mask:0xf bank_mask:0xf
	v_fmac_f32_dpp v203, v99, v139 row_shl:1 row_mask:0xf bank_mask:0xf
	v_fmac_f32_dpp v200, v80, v220 row_ror:15 row_mask:0xf bank_mask:0xf
	v_fmac_f32_dpp v201, v81, v221 row_ror:15 row_mask:0xf bank_mask:0xf
	v_fmac_f32_dpp v202, v82, v222 row_ror:15 row_mask:0xf bank_mask:0xf
	v_fmac_f32_dpp v203, v83, v223 row_ror:15 row_mask:0xf bank_mask:0xf
	v_fma_f32 v204, v172, v84, v180
	v_fma_f32 v205, v173, v85, v181
	v_fma_f32 v206, v174, v86, v182
	v_fma_f32 v207, v175, v87, v183
	v_fmac_f32_dpp v204, v84, v160 row_shr:1 row_mask:0xf bank_mask:0xf
	v_fmac_f32_dpp v205, v85, v161 row_shr:1 row_mask:0xf bank_mask:0xf
	v_fmac_f32_dpp v206, v86, v162 row_shr:1 row_mask:0xf bank_mask:0xf
	v_fmac_f32_dpp v207, v87, v163 row_shr:1 row_mask:0xf bank_mask:0xf
	v_fmac_f32_dpp v204, v100, v224 row_ror:1 row_mask:0xf bank_mask:0xf
	v_fmac_f32_dpp v205, v101, v225 row_ror:1 row_mask:0xf bank_mask:0xf
	v_fmac_f32_dpp v206, v102, v226 row_ror:1 row_mask:0xf bank_mask:0xf
	v_fmac_f32_dpp v207, v103, v227 row_ror:1 row_mask:0xf bank_mask:0xf
	v_fmac_f32_dpp v204, v84, v176 row_shl:1 row_mask:0xf bank_mask:0xf
	v_fmac_f32_dpp v205, v85, v177 row_shl:1 row_mask:0xf bank_mask:0xf
	v_fmac_f32_dpp v206, v86, v178 row_shl:1 row_mask:0xf bank_mask:0xf
	v_fmac_f32_dpp v207, v87, v179 row_shl:1 row_mask:0xf bank_mask:0xf
	v_fmac_f32_dpp v204, v68, v232 row_ror:15 row_mask:0xf bank_mask:0xf
	v_fmac_f32_dpp v205, v69, v233 row_ror:15 row_mask:0xf bank_mask:0xf
	v_fmac_f32_dpp v206, v70, v234 row_ror:15 row_mask:0xf bank_mask:0xf
	v_fmac_f32_dpp v207, v71, v235 row_ror:15 row_mask:0xf bank_mask:0xf
	v_mul_f32_e32 v208, 0xbfb8aa3b, v200
	v_mul_f32_e32 v209, 0xbfb8aa3b, v201
	v_mul_f32_e32 v210, 0xbfb8aa3b, v202
	v_mul_f32_e32 v211, 0xbfb8aa3b, v203
	v_exp_f32_e32 v208, v208
	v_exp_f32_e32 v209, v209
	v_exp_f32_e32 v210, v210
	v_exp_f32_e32 v211, v211
	v_add_f32_e32 v208, 1.0, v208
	v_add_f32_e32 v209, 1.0, v209
	v_add_f32_e32 v210, 1.0, v210
	v_add_f32_e32 v211, 1.0, v211
	v_rcp_f32_e32 v208, v208
	v_rcp_f32_e32 v209, v209
	v_rcp_f32_e32 v210, v210
	v_rcp_f32_e32 v211, v211
	v_mul_f32_e32 v200, v200, v208
	v_mul_f32_e32 v201, v201, v209
	v_mul_f32_e32 v202, v202, v210
	v_mul_f32_e32 v203, v203, v211
	v_mul_f32_e32 v200, v200, v204
	v_mul_f32_e32 v201, v201, v205
	v_mul_f32_e32 v202, v202, v206
	v_mul_f32_e32 v203, v203, v207
	v_cvt_pk_bf16_f32 v240, v200, v201
	v_cvt_pk_bf16_f32 v241, v202, v203
	v_fma_f32 v200, v132, v80, v140
	v_fma_f32 v201, v133, v81, v141
	v_fma_f32 v202, v134, v82, v142
	v_fma_f32 v203, v135, v83, v143
	v_fmac_f32_dpp v200, v80, v128 row_shr:1 row_mask:0xf bank_mask:0xf
	v_fmac_f32_dpp v201, v81, v129 row_shr:1 row_mask:0xf bank_mask:0xf
	v_fmac_f32_dpp v202, v82, v130 row_shr:1 row_mask:0xf bank_mask:0xf
	v_fmac_f32_dpp v203, v83, v131 row_shr:1 row_mask:0xf bank_mask:0xf
	v_fmac_f32_dpp v200, v96, v216 row_ror:1 row_mask:0xf bank_mask:0xf
	v_fmac_f32_dpp v201, v97, v217 row_ror:1 row_mask:0xf bank_mask:0xf
	v_fmac_f32_dpp v202, v98, v218 row_ror:1 row_mask:0xf bank_mask:0xf
	v_fmac_f32_dpp v203, v99, v219 row_ror:1 row_mask:0xf bank_mask:0xf
	v_fmac_f32_dpp v200, v80, v136 row_shl:1 row_mask:0xf bank_mask:0xf
	v_fmac_f32_dpp v201, v81, v137 row_shl:1 row_mask:0xf bank_mask:0xf
	v_fmac_f32_dpp v202, v82, v138 row_shl:1 row_mask:0xf bank_mask:0xf
	v_fmac_f32_dpp v203, v83, v139 row_shl:1 row_mask:0xf bank_mask:0xf
	v_fmac_f32_e32 v200, v184, v220
	v_fmac_f32_e32 v201, v185, v221
	v_fmac_f32_e32 v202, v186, v222
	v_fmac_f32_e32 v203, v187, v223
	v_fma_f32 v204, v172, v68, v180
	v_fma_f32 v205, v173, v69, v181
	v_fma_f32 v206, v174, v70, v182
	v_fma_f32 v207, v175, v71, v183
	v_fmac_f32_dpp v204, v68, v160 row_shr:1 row_mask:0xf bank_mask:0xf
	v_fmac_f32_dpp v205, v69, v161 row_shr:1 row_mask:0xf bank_mask:0xf
	v_fmac_f32_dpp v206, v70, v162 row_shr:1 row_mask:0xf bank_mask:0xf
	v_fmac_f32_dpp v207, v71, v163 row_shr:1 row_mask:0xf bank_mask:0xf
	v_fmac_f32_dpp v204, v84, v224 row_ror:1 row_mask:0xf bank_mask:0xf
	v_fmac_f32_dpp v205, v85, v225 row_ror:1 row_mask:0xf bank_mask:0xf
	v_fmac_f32_dpp v206, v86, v226 row_ror:1 row_mask:0xf bank_mask:0xf
	v_fmac_f32_dpp v207, v87, v227 row_ror:1 row_mask:0xf bank_mask:0xf
	v_fmac_f32_dpp v204, v68, v176 row_shl:1 row_mask:0xf bank_mask:0xf
	v_fmac_f32_dpp v205, v69, v177 row_shl:1 row_mask:0xf bank_mask:0xf
	v_fmac_f32_dpp v206, v70, v178 row_shl:1 row_mask:0xf bank_mask:0xf
	v_fmac_f32_dpp v207, v71, v179 row_shl:1 row_mask:0xf bank_mask:0xf
	v_fmac_f32_e32 v204, v188, v232
	v_fmac_f32_e32 v205, v189, v233
	v_fmac_f32_e32 v206, v190, v234
	v_fmac_f32_e32 v207, v191, v235
	v_mul_f32_e32 v208, 0xbfb8aa3b, v200
	v_mul_f32_e32 v209, 0xbfb8aa3b, v201
	v_mul_f32_e32 v210, 0xbfb8aa3b, v202
	v_mul_f32_e32 v211, 0xbfb8aa3b, v203
	v_exp_f32_e32 v208, v208
	v_exp_f32_e32 v209, v209
	v_exp_f32_e32 v210, v210
	v_exp_f32_e32 v211, v211
	v_add_f32_e32 v208, 1.0, v208
	v_add_f32_e32 v209, 1.0, v209
	v_add_f32_e32 v210, 1.0, v210
	v_add_f32_e32 v211, 1.0, v211
	v_rcp_f32_e32 v208, v208
	v_rcp_f32_e32 v209, v209
	v_rcp_f32_e32 v210, v210
	v_rcp_f32_e32 v211, v211
	v_mul_f32_e32 v200, v200, v208
	v_mul_f32_e32 v201, v201, v209
	v_mul_f32_e32 v202, v202, v210
	v_mul_f32_e32 v203, v203, v211
	v_mul_f32_e32 v200, v200, v204
	v_mul_f32_e32 v201, v201, v205
	v_mul_f32_e32 v202, v202, v206
	v_mul_f32_e32 v203, v203, v207
	v_cvt_pk_bf16_f32 v242, v200, v201
	v_cvt_pk_bf16_f32 v243, v202, v203
	v_fma_f32 v200, v132, v60, v140
	v_fma_f32 v201, v133, v61, v141
	v_fma_f32 v202, v134, v62, v142
	v_fma_f32 v203, v135, v63, v143
	v_fmac_f32_dpp v200, v60, v128 row_shr:1 row_mask:0xf bank_mask:0xf
	v_fmac_f32_dpp v201, v61, v129 row_shr:1 row_mask:0xf bank_mask:0xf
	v_fmac_f32_dpp v202, v62, v130 row_shr:1 row_mask:0xf bank_mask:0xf
	v_fmac_f32_dpp v203, v63, v131 row_shr:1 row_mask:0xf bank_mask:0xf
	v_fmac_f32_e32 v200, v192, v216
	v_fmac_f32_e32 v201, v193, v217
	v_fmac_f32_e32 v202, v194, v218
	v_fmac_f32_e32 v203, v195, v219
	v_fmac_f32_dpp v200, v60, v136 row_shl:1 row_mask:0xf bank_mask:0xf
	v_fmac_f32_dpp v201, v61, v137 row_shl:1 row_mask:0xf bank_mask:0xf
	v_fmac_f32_dpp v202, v62, v138 row_shl:1 row_mask:0xf bank_mask:0xf
	v_fmac_f32_dpp v203, v63, v139 row_shl:1 row_mask:0xf bank_mask:0xf
	v_fmac_f32_dpp v200, v48, v220 row_ror:15 row_mask:0xf bank_mask:0xf
	v_fmac_f32_dpp v201, v49, v221 row_ror:15 row_mask:0xf bank_mask:0xf
	v_fmac_f32_dpp v202, v50, v222 row_ror:15 row_mask:0xf bank_mask:0xf
	v_fmac_f32_dpp v203, v51, v223 row_ror:15 row_mask:0xf bank_mask:0xf
	v_fma_f32 v204, v172, v52, v180
	v_fma_f32 v205, v173, v53, v181
	v_fma_f32 v206, v174, v54, v182
	v_fma_f32 v207, v175, v55, v183
	v_fmac_f32_dpp v204, v52, v160 row_shr:1 row_mask:0xf bank_mask:0xf
	v_fmac_f32_dpp v205, v53, v161 row_shr:1 row_mask:0xf bank_mask:0xf
	v_fmac_f32_dpp v206, v54, v162 row_shr:1 row_mask:0xf bank_mask:0xf
	v_fmac_f32_dpp v207, v55, v163 row_shr:1 row_mask:0xf bank_mask:0xf
	v_fmac_f32_e32 v204, v196, v224
	v_fmac_f32_e32 v205, v197, v225
	v_fmac_f32_e32 v206, v198, v226
	v_fmac_f32_e32 v207, v199, v227
	v_fmac_f32_dpp v204, v52, v176 row_shl:1 row_mask:0xf bank_mask:0xf
	v_fmac_f32_dpp v205, v53, v177 row_shl:1 row_mask:0xf bank_mask:0xf
	v_fmac_f32_dpp v206, v54, v178 row_shl:1 row_mask:0xf bank_mask:0xf
	v_fmac_f32_dpp v207, v55, v179 row_shl:1 row_mask:0xf bank_mask:0xf
	v_fmac_f32_dpp v204, v36, v232 row_ror:15 row_mask:0xf bank_mask:0xf
	v_fmac_f32_dpp v205, v37, v233 row_ror:15 row_mask:0xf bank_mask:0xf
	v_fmac_f32_dpp v206, v38, v234 row_ror:15 row_mask:0xf bank_mask:0xf
	v_fmac_f32_dpp v207, v39, v235 row_ror:15 row_mask:0xf bank_mask:0xf
	v_mul_f32_e32 v208, 0xbfb8aa3b, v200
	v_mul_f32_e32 v209, 0xbfb8aa3b, v201
	v_mul_f32_e32 v210, 0xbfb8aa3b, v202
	v_mul_f32_e32 v211, 0xbfb8aa3b, v203
	v_exp_f32_e32 v208, v208
	v_exp_f32_e32 v209, v209
	v_exp_f32_e32 v210, v210
	v_exp_f32_e32 v211, v211
	v_add_f32_e32 v208, 1.0, v208
	v_add_f32_e32 v209, 1.0, v209
	v_add_f32_e32 v210, 1.0, v210
	v_add_f32_e32 v211, 1.0, v211
	v_rcp_f32_e32 v208, v208
	v_rcp_f32_e32 v209, v209
	v_rcp_f32_e32 v210, v210
	v_rcp_f32_e32 v211, v211
	v_mul_f32_e32 v200, v200, v208
	v_mul_f32_e32 v201, v201, v209
	v_mul_f32_e32 v202, v202, v210
	v_mul_f32_e32 v203, v203, v211
	v_mul_f32_e32 v200, v200, v204
	v_mul_f32_e32 v201, v201, v205
	v_mul_f32_e32 v202, v202, v206
	v_mul_f32_e32 v203, v203, v207
	v_cvt_pk_bf16_f32 v244, v200, v201
	v_cvt_pk_bf16_f32 v245, v202, v203
	v_fma_f32 v200, v132, v48, v140
	v_fma_f32 v201, v133, v49, v141
	v_fma_f32 v202, v134, v50, v142
	v_fma_f32 v203, v135, v51, v143
	v_fmac_f32_dpp v200, v48, v128 row_shr:1 row_mask:0xf bank_mask:0xf
	v_fmac_f32_dpp v201, v49, v129 row_shr:1 row_mask:0xf bank_mask:0xf
	v_fmac_f32_dpp v202, v50, v130 row_shr:1 row_mask:0xf bank_mask:0xf
	v_fmac_f32_dpp v203, v51, v131 row_shr:1 row_mask:0xf bank_mask:0xf
	v_fmac_f32_dpp v200, v60, v216 row_ror:1 row_mask:0xf bank_mask:0xf
	v_fmac_f32_dpp v201, v61, v217 row_ror:1 row_mask:0xf bank_mask:0xf
	v_fmac_f32_dpp v202, v62, v218 row_ror:1 row_mask:0xf bank_mask:0xf
	v_fmac_f32_dpp v203, v63, v219 row_ror:1 row_mask:0xf bank_mask:0xf
	v_fmac_f32_dpp v200, v48, v136 row_shl:1 row_mask:0xf bank_mask:0xf
	v_fmac_f32_dpp v201, v49, v137 row_shl:1 row_mask:0xf bank_mask:0xf
	v_fmac_f32_dpp v202, v50, v138 row_shl:1 row_mask:0xf bank_mask:0xf
	v_fmac_f32_dpp v203, v51, v139 row_shl:1 row_mask:0xf bank_mask:0xf
	v_fmac_f32_dpp v200, v32, v220 row_ror:15 row_mask:0xf bank_mask:0xf
	v_fmac_f32_dpp v201, v33, v221 row_ror:15 row_mask:0xf bank_mask:0xf
	v_fmac_f32_dpp v202, v34, v222 row_ror:15 row_mask:0xf bank_mask:0xf
	v_fmac_f32_dpp v203, v35, v223 row_ror:15 row_mask:0xf bank_mask:0xf
	v_fma_f32 v204, v172, v36, v180
	v_fma_f32 v205, v173, v37, v181
	v_fma_f32 v206, v174, v38, v182
	v_fma_f32 v207, v175, v39, v183
	v_fmac_f32_dpp v204, v36, v160 row_shr:1 row_mask:0xf bank_mask:0xf
	v_fmac_f32_dpp v205, v37, v161 row_shr:1 row_mask:0xf bank_mask:0xf
	v_fmac_f32_dpp v206, v38, v162 row_shr:1 row_mask:0xf bank_mask:0xf
	v_fmac_f32_dpp v207, v39, v163 row_shr:1 row_mask:0xf bank_mask:0xf
	v_fmac_f32_dpp v204, v52, v224 row_ror:1 row_mask:0xf bank_mask:0xf
	v_fmac_f32_dpp v205, v53, v225 row_ror:1 row_mask:0xf bank_mask:0xf
	v_fmac_f32_dpp v206, v54, v226 row_ror:1 row_mask:0xf bank_mask:0xf
	v_fmac_f32_dpp v207, v55, v227 row_ror:1 row_mask:0xf bank_mask:0xf
	v_fmac_f32_dpp v204, v36, v176 row_shl:1 row_mask:0xf bank_mask:0xf
	v_fmac_f32_dpp v205, v37, v177 row_shl:1 row_mask:0xf bank_mask:0xf
	v_fmac_f32_dpp v206, v38, v178 row_shl:1 row_mask:0xf bank_mask:0xf
	v_fmac_f32_dpp v207, v39, v179 row_shl:1 row_mask:0xf bank_mask:0xf
	v_fmac_f32_dpp v204, v20, v232 row_ror:15 row_mask:0xf bank_mask:0xf
	v_fmac_f32_dpp v205, v21, v233 row_ror:15 row_mask:0xf bank_mask:0xf
	v_fmac_f32_dpp v206, v22, v234 row_ror:15 row_mask:0xf bank_mask:0xf
	v_fmac_f32_dpp v207, v23, v235 row_ror:15 row_mask:0xf bank_mask:0xf
	v_mul_f32_e32 v208, 0xbfb8aa3b, v200
	v_mul_f32_e32 v209, 0xbfb8aa3b, v201
	v_mul_f32_e32 v210, 0xbfb8aa3b, v202
	v_mul_f32_e32 v211, 0xbfb8aa3b, v203
	v_exp_f32_e32 v208, v208
	v_exp_f32_e32 v209, v209
	v_exp_f32_e32 v210, v210
	v_exp_f32_e32 v211, v211
	v_add_f32_e32 v208, 1.0, v208
	v_add_f32_e32 v209, 1.0, v209
	v_add_f32_e32 v210, 1.0, v210
	v_add_f32_e32 v211, 1.0, v211
	v_rcp_f32_e32 v208, v208
	v_rcp_f32_e32 v209, v209
	v_rcp_f32_e32 v210, v210
	v_rcp_f32_e32 v211, v211
	v_mul_f32_e32 v200, v200, v208
	v_mul_f32_e32 v201, v201, v209
	v_mul_f32_e32 v202, v202, v210
	v_mul_f32_e32 v203, v203, v211
	v_mul_f32_e32 v200, v200, v204
	v_mul_f32_e32 v201, v201, v205
	v_mul_f32_e32 v202, v202, v206
	v_mul_f32_e32 v203, v203, v207
	v_cvt_pk_bf16_f32 v246, v200, v201
	v_cvt_pk_bf16_f32 v247, v202, v203
	v_fma_f32 v200, v132, v32, v140
	v_fma_f32 v201, v133, v33, v141
	v_fma_f32 v202, v134, v34, v142
	v_fma_f32 v203, v135, v35, v143
	v_fmac_f32_dpp v200, v32, v128 row_shr:1 row_mask:0xf bank_mask:0xf
	v_fmac_f32_dpp v201, v33, v129 row_shr:1 row_mask:0xf bank_mask:0xf
	v_fmac_f32_dpp v202, v34, v130 row_shr:1 row_mask:0xf bank_mask:0xf
	v_fmac_f32_dpp v203, v35, v131 row_shr:1 row_mask:0xf bank_mask:0xf
	v_fmac_f32_dpp v200, v48, v216 row_ror:1 row_mask:0xf bank_mask:0xf
	v_fmac_f32_dpp v201, v49, v217 row_ror:1 row_mask:0xf bank_mask:0xf
	v_fmac_f32_dpp v202, v50, v218 row_ror:1 row_mask:0xf bank_mask:0xf
	v_fmac_f32_dpp v203, v51, v219 row_ror:1 row_mask:0xf bank_mask:0xf
	v_fmac_f32_dpp v200, v32, v136 row_shl:1 row_mask:0xf bank_mask:0xf
	v_fmac_f32_dpp v201, v33, v137 row_shl:1 row_mask:0xf bank_mask:0xf
	v_fmac_f32_dpp v202, v34, v138 row_shl:1 row_mask:0xf bank_mask:0xf
	v_fmac_f32_dpp v203, v35, v139 row_shl:1 row_mask:0xf bank_mask:0xf
	v_fmac_f32_dpp v200, v16, v220 row_ror:15 row_mask:0xf bank_mask:0xf
	v_fmac_f32_dpp v201, v17, v221 row_ror:15 row_mask:0xf bank_mask:0xf
	v_fmac_f32_dpp v202, v18, v222 row_ror:15 row_mask:0xf bank_mask:0xf
	v_fmac_f32_dpp v203, v19, v223 row_ror:15 row_mask:0xf bank_mask:0xf
	v_fma_f32 v204, v172, v20, v180
	v_fma_f32 v205, v173, v21, v181
	v_fma_f32 v206, v174, v22, v182
	v_fma_f32 v207, v175, v23, v183
	v_fmac_f32_dpp v204, v20, v160 row_shr:1 row_mask:0xf bank_mask:0xf
	v_fmac_f32_dpp v205, v21, v161 row_shr:1 row_mask:0xf bank_mask:0xf
	v_fmac_f32_dpp v206, v22, v162 row_shr:1 row_mask:0xf bank_mask:0xf
	v_fmac_f32_dpp v207, v23, v163 row_shr:1 row_mask:0xf bank_mask:0xf
	v_fmac_f32_dpp v204, v36, v224 row_ror:1 row_mask:0xf bank_mask:0xf
	v_fmac_f32_dpp v205, v37, v225 row_ror:1 row_mask:0xf bank_mask:0xf
	v_fmac_f32_dpp v206, v38, v226 row_ror:1 row_mask:0xf bank_mask:0xf
	v_fmac_f32_dpp v207, v39, v227 row_ror:1 row_mask:0xf bank_mask:0xf
	v_fmac_f32_dpp v204, v20, v176 row_shl:1 row_mask:0xf bank_mask:0xf
	v_fmac_f32_dpp v205, v21, v177 row_shl:1 row_mask:0xf bank_mask:0xf
	v_fmac_f32_dpp v206, v22, v178 row_shl:1 row_mask:0xf bank_mask:0xf
	v_fmac_f32_dpp v207, v23, v179 row_shl:1 row_mask:0xf bank_mask:0xf
	v_fmac_f32_dpp v204, v4, v232 row_ror:15 row_mask:0xf bank_mask:0xf
	v_fmac_f32_dpp v205, v5, v233 row_ror:15 row_mask:0xf bank_mask:0xf
	v_fmac_f32_dpp v206, v6, v234 row_ror:15 row_mask:0xf bank_mask:0xf
	v_fmac_f32_dpp v207, v7, v235 row_ror:15 row_mask:0xf bank_mask:0xf
	v_mul_f32_e32 v208, 0xbfb8aa3b, v200
	v_mul_f32_e32 v209, 0xbfb8aa3b, v201
	v_mul_f32_e32 v210, 0xbfb8aa3b, v202
	v_mul_f32_e32 v211, 0xbfb8aa3b, v203
	v_exp_f32_e32 v208, v208
	v_exp_f32_e32 v209, v209
	v_exp_f32_e32 v210, v210
	v_exp_f32_e32 v211, v211
	v_add_f32_e32 v208, 1.0, v208
	v_add_f32_e32 v209, 1.0, v209
	v_add_f32_e32 v210, 1.0, v210
	v_add_f32_e32 v211, 1.0, v211
	v_rcp_f32_e32 v208, v208
	v_rcp_f32_e32 v209, v209
	v_rcp_f32_e32 v210, v210
	v_rcp_f32_e32 v211, v211
	v_mul_f32_e32 v200, v200, v208
	v_mul_f32_e32 v201, v201, v209
	v_mul_f32_e32 v202, v202, v210
	v_mul_f32_e32 v203, v203, v211
	v_mul_f32_e32 v200, v200, v204
	v_mul_f32_e32 v201, v201, v205
	v_mul_f32_e32 v202, v202, v206
	v_mul_f32_e32 v203, v203, v207
	v_cvt_pk_bf16_f32 v248, v200, v201
	v_cvt_pk_bf16_f32 v249, v202, v203
	v_fma_f32 v200, v132, v16, v140
	v_fma_f32 v201, v133, v17, v141
	v_fma_f32 v202, v134, v18, v142
	v_fma_f32 v203, v135, v19, v143
	v_fmac_f32_dpp v200, v16, v128 row_shr:1 row_mask:0xf bank_mask:0xf
	v_fmac_f32_dpp v201, v17, v129 row_shr:1 row_mask:0xf bank_mask:0xf
	v_fmac_f32_dpp v202, v18, v130 row_shr:1 row_mask:0xf bank_mask:0xf
	v_fmac_f32_dpp v203, v19, v131 row_shr:1 row_mask:0xf bank_mask:0xf
	v_fmac_f32_dpp v200, v32, v216 row_ror:1 row_mask:0xf bank_mask:0xf
	v_fmac_f32_dpp v201, v33, v217 row_ror:1 row_mask:0xf bank_mask:0xf
	v_fmac_f32_dpp v202, v34, v218 row_ror:1 row_mask:0xf bank_mask:0xf
	v_fmac_f32_dpp v203, v35, v219 row_ror:1 row_mask:0xf bank_mask:0xf
	v_fmac_f32_dpp v200, v16, v136 row_shl:1 row_mask:0xf bank_mask:0xf
	v_fmac_f32_dpp v201, v17, v137 row_shl:1 row_mask:0xf bank_mask:0xf
	v_fmac_f32_dpp v202, v18, v138 row_shl:1 row_mask:0xf bank_mask:0xf
	v_fmac_f32_dpp v203, v19, v139 row_shl:1 row_mask:0xf bank_mask:0xf
	v_fmac_f32_e32 v200, v192, v220
	v_fmac_f32_e32 v201, v193, v221
	v_fmac_f32_e32 v202, v194, v222
	v_fmac_f32_e32 v203, v195, v223
	v_fma_f32 v204, v172, v4, v180
	v_fma_f32 v205, v173, v5, v181
	v_fma_f32 v206, v174, v6, v182
	v_fma_f32 v207, v175, v7, v183
	v_fmac_f32_dpp v204, v4, v160 row_shr:1 row_mask:0xf bank_mask:0xf
	v_fmac_f32_dpp v205, v5, v161 row_shr:1 row_mask:0xf bank_mask:0xf
	v_fmac_f32_dpp v206, v6, v162 row_shr:1 row_mask:0xf bank_mask:0xf
	v_fmac_f32_dpp v207, v7, v163 row_shr:1 row_mask:0xf bank_mask:0xf
	v_fmac_f32_dpp v204, v20, v224 row_ror:1 row_mask:0xf bank_mask:0xf
	v_fmac_f32_dpp v205, v21, v225 row_ror:1 row_mask:0xf bank_mask:0xf
	v_fmac_f32_dpp v206, v22, v226 row_ror:1 row_mask:0xf bank_mask:0xf
	v_fmac_f32_dpp v207, v23, v227 row_ror:1 row_mask:0xf bank_mask:0xf
	v_fmac_f32_dpp v204, v4, v176 row_shl:1 row_mask:0xf bank_mask:0xf
	v_fmac_f32_dpp v205, v5, v177 row_shl:1 row_mask:0xf bank_mask:0xf
	v_fmac_f32_dpp v206, v6, v178 row_shl:1 row_mask:0xf bank_mask:0xf
	v_fmac_f32_dpp v207, v7, v179 row_shl:1 row_mask:0xf bank_mask:0xf
	v_fmac_f32_e32 v204, v196, v232
	v_fmac_f32_e32 v205, v197, v233
	v_fmac_f32_e32 v206, v198, v234
	v_fmac_f32_e32 v207, v199, v235
	s_mov_b64 exec, s[62:63]
	v_add_u32_e32 v250, 0x10800, v229
	global_store_dwordx4 v250, v[200:203], s[64:65]
	v_add_u32_e32 v250, 0x13400, v229
	global_store_dwordx4 v250, v[204:207], s[64:65]
	s_mov_b64 exec, s[58:59]
	s_nop 4
	v_mul_f32_e32 v208, 0xbfb8aa3b, v200
	v_mul_f32_e32 v209, 0xbfb8aa3b, v201
	v_mul_f32_e32 v210, 0xbfb8aa3b, v202
	v_mul_f32_e32 v211, 0xbfb8aa3b, v203
	v_exp_f32_e32 v208, v208
	v_exp_f32_e32 v209, v209
	v_exp_f32_e32 v210, v210
	v_exp_f32_e32 v211, v211
	v_add_f32_e32 v208, 1.0, v208
	v_add_f32_e32 v209, 1.0, v209
	v_add_f32_e32 v210, 1.0, v210
	v_add_f32_e32 v211, 1.0, v211
	v_rcp_f32_e32 v208, v208
	v_rcp_f32_e32 v209, v209
	v_rcp_f32_e32 v210, v210
	v_rcp_f32_e32 v211, v211
	v_mul_f32_e32 v200, v200, v208
	v_mul_f32_e32 v201, v201, v209
	v_mul_f32_e32 v202, v202, v210
	v_mul_f32_e32 v203, v203, v211
	v_mul_f32_e32 v200, v200, v204
	v_mul_f32_e32 v201, v201, v205
	v_mul_f32_e32 v202, v202, v206
	v_mul_f32_e32 v203, v203, v207
	v_cvt_pk_bf16_f32 v250, v200, v201
	v_cvt_pk_bf16_f32 v251, v202, v203
	global_load_dwordx4 v[128:131], v229, s[34:35] offset:16
	v_add_u32_e32 v211, 0x5800, v229
	global_load_dwordx4 v[132:135], v211, s[34:35] offset:16
	v_add_u32_e32 v210, 0xb000, v229
	global_load_dwordx4 v[136:139], v210, s[34:35] offset:16
	global_load_dwordx4 v[140:143], v229, s[36:37] offset:16
	v_add_u32_e32 v210, 0x2c00, v229
	global_load_dwordx4 v[160:163], v210, s[34:35] offset:16
	v_add_u32_e32 v211, 0x8400, v229
	global_load_dwordx4 v[172:175], v211, s[34:35] offset:16
	v_add_u32_e32 v210, 0xdc00, v229
	global_load_dwordx4 v[176:179], v210, s[34:35] offset:16
	v_add_u32_e32 v211, 0x2c00, v229
	global_load_dwordx4 v[180:183], v211, s[36:37] offset:16
	v_mov_b32_e32 v124, v236
	v_mov_b32_e32 v125, v237
	v_mov_b32_e32 v116, v238
	v_mov_b32_e32 v117, v239
	v_mov_b32_e32 v96, v240
	v_mov_b32_e32 v97, v241
	v_mov_b32_e32 v80, v242
	v_mov_b32_e32 v81, v243
	v_mov_b32_e32 v60, v244
	v_mov_b32_e32 v61, v245
	v_mov_b32_e32 v48, v246
	v_mov_b32_e32 v49, v247
	v_mov_b32_e32 v32, v248
	v_mov_b32_e32 v33, v249
	v_mov_b32_e32 v16, v250
	v_mov_b32_e32 v17, v251
	ds_read_b128 v[184:187], v231 offset:16
	ds_read_b128 v[188:191], v231 offset:528
	ds_read_b128 v[192:195], v231 offset:2064
	ds_read_b128 v[196:199], v231 offset:2576
	s_waitcnt vmcnt(0)
	v_cndmask_b32_e64 v216, 0, v128, s[54:55]
	v_cndmask_b32_e64 v220, 0, v136, s[56:57]
	v_cndmask_b32_e64 v217, 0, v129, s[54:55]
	v_cndmask_b32_e64 v221, 0, v137, s[56:57]
	v_cndmask_b32_e64 v218, 0, v130, s[54:55]
	v_cndmask_b32_e64 v222, 0, v138, s[56:57]
	v_cndmask_b32_e64 v219, 0, v131, s[54:55]
	v_cndmask_b32_e64 v223, 0, v139, s[56:57]
	v_cndmask_b32_e64 v224, 0, v160, s[54:55]
	v_cndmask_b32_e64 v232, 0, v176, s[56:57]
	v_cndmask_b32_e64 v225, 0, v161, s[54:55]
	v_cndmask_b32_e64 v233, 0, v177, s[56:57]
	v_cndmask_b32_e64 v226, 0, v162, s[54:55]
	v_cndmask_b32_e64 v234, 0, v178, s[56:57]
	v_cndmask_b32_e64 v227, 0, v163, s[54:55]
	v_cndmask_b32_e64 v235, 0, v179, s[56:57]
	s_waitcnt lgkmcnt(0)
	s_nop 1
	v_fma_f32 v200, v132, v120, v140
	v_fma_f32 v201, v133, v121, v141
	v_fma_f32 v202, v134, v122, v142
	v_fma_f32 v203, v135, v123, v143
	v_fmac_f32_dpp v200, v120, v128 row_shr:1 row_mask:0xf bank_mask:0xf
	v_fmac_f32_dpp v201, v121, v129 row_shr:1 row_mask:0xf bank_mask:0xf
	v_fmac_f32_dpp v202, v122, v130 row_shr:1 row_mask:0xf bank_mask:0xf
	v_fmac_f32_dpp v203, v123, v131 row_shr:1 row_mask:0xf bank_mask:0xf
	v_fmac_f32_e32 v200, v184, v216
	v_fmac_f32_e32 v201, v185, v217
	v_fmac_f32_e32 v202, v186, v218
	v_fmac_f32_e32 v203, v187, v219
	v_fmac_f32_dpp v200, v120, v136 row_shl:1 row_mask:0xf bank_mask:0xf
	v_fmac_f32_dpp v201, v121, v137 row_shl:1 row_mask:0xf bank_mask:0xf
	v_fmac_f32_dpp v202, v122, v138 row_shl:1 row_mask:0xf bank_mask:0xf
	v_fmac_f32_dpp v203, v123, v139 row_shl:1 row_mask:0xf bank_mask:0xf
	v_fmac_f32_dpp v200, v112, v220 row_ror:15 row_mask:0xf bank_mask:0xf
	v_fmac_f32_dpp v201, v113, v221 row_ror:15 row_mask:0xf bank_mask:0xf
	v_fmac_f32_dpp v202, v114, v222 row_ror:15 row_mask:0xf bank_mask:0xf
	v_fmac_f32_dpp v203, v115, v223 row_ror:15 row_mask:0xf bank_mask:0xf
	v_fma_f32 v204, v172, v104, v180
	v_fma_f32 v205, v173, v105, v181
	v_fma_f32 v206, v174, v106, v182
	v_fma_f32 v207, v175, v107, v183
	v_fmac_f32_dpp v204, v104, v160 row_shr:1 row_mask:0xf bank_mask:0xf
	v_fmac_f32_dpp v205, v105, v161 row_shr:1 row_mask:0xf bank_mask:0xf
	v_fmac_f32_dpp v206, v106, v162 row_shr:1 row_mask:0xf bank_mask:0xf
	v_fmac_f32_dpp v207, v107, v163 row_shr:1 row_mask:0xf bank_mask:0xf
	v_fmac_f32_e32 v204, v188, v224
	v_fmac_f32_e32 v205, v189, v225
	v_fmac_f32_e32 v206, v190, v226
	v_fmac_f32_e32 v207, v191, v227
	v_fmac_f32_dpp v204, v104, v176 row_shl:1 row_mask:0xf bank_mask:0xf
	v_fmac_f32_dpp v205, v105, v177 row_shl:1 row_mask:0xf bank_mask:0xf
	v_fmac_f32_dpp v206, v106, v178 row_shl:1 row_mask:0xf bank_mask:0xf
	v_fmac_f32_dpp v207, v107, v179 row_shl:1 row_mask:0xf bank_mask:0xf
	v_fmac_f32_dpp v204, v92, v232 row_ror:15 row_mask:0xf bank_mask:0xf
	v_fmac_f32_dpp v205, v93, v233 row_ror:15 row_mask:0xf bank_mask:0xf
	v_fmac_f32_dpp v206, v94, v234 row_ror:15 row_mask:0xf bank_mask:0xf
	v_fmac_f32_dpp v207, v95, v235 row_ror:15 row_mask:0xf bank_mask:0xf
	s_mov_b64 exec, s[60:61]
	v_add_u32_e32 v250, 0x5800, v229
	global_store_dwordx4 v250, v[200:203], s[64:65] offset:16
	v_add_u32_e32 v250, 0x8400, v229
	global_store_dwordx4 v250, v[204:207], s[64:65] offset:16
	s_mov_b64 exec, s[58:59]
	s_nop 4
	v_mul_f32_e32 v208, 0xbfb8aa3b, v200
	v_mul_f32_e32 v209, 0xbfb8aa3b, v201
	v_mul_f32_e32 v210, 0xbfb8aa3b, v202
	v_mul_f32_e32 v211, 0xbfb8aa3b, v203
	v_exp_f32_e32 v208, v208
	v_exp_f32_e32 v209, v209
	v_exp_f32_e32 v210, v210
	v_exp_f32_e32 v211, v211
	v_add_f32_e32 v208, 1.0, v208
	v_add_f32_e32 v209, 1.0, v209
	v_add_f32_e32 v210, 1.0, v210
	v_add_f32_e32 v211, 1.0, v211
	v_rcp_f32_e32 v208, v208
	v_rcp_f32_e32 v209, v209
	v_rcp_f32_e32 v210, v210
	v_rcp_f32_e32 v211, v211
	v_mul_f32_e32 v200, v200, v208
	v_mul_f32_e32 v201, v201, v209
	v_mul_f32_e32 v202, v202, v210
	v_mul_f32_e32 v203, v203, v211
	v_mul_f32_e32 v200, v200, v204
	v_mul_f32_e32 v201, v201, v205
	v_mul_f32_e32 v202, v202, v206
	v_mul_f32_e32 v203, v203, v207
	v_cvt_pk_bf16_f32 v126, v200, v201
	v_cvt_pk_bf16_f32 v127, v202, v203
	v_fma_f32 v200, v132, v112, v140
	v_fma_f32 v201, v133, v113, v141
	v_fma_f32 v202, v134, v114, v142
	v_fma_f32 v203, v135, v115, v143
	v_fmac_f32_dpp v200, v112, v128 row_shr:1 row_mask:0xf bank_mask:0xf
	v_fmac_f32_dpp v201, v113, v129 row_shr:1 row_mask:0xf bank_mask:0xf
	v_fmac_f32_dpp v202, v114, v130 row_shr:1 row_mask:0xf bank_mask:0xf
	v_fmac_f32_dpp v203, v115, v131 row_shr:1 row_mask:0xf bank_mask:0xf
	v_fmac_f32_dpp v200, v120, v216 row_ror:1 row_mask:0xf bank_mask:0xf
	v_fmac_f32_dpp v201, v121, v217 row_ror:1 row_mask:0xf bank_mask:0xf
	v_fmac_f32_dpp v202, v122, v218 row_ror:1 row_mask:0xf bank_mask:0xf
	v_fmac_f32_dpp v203, v123, v219 row_ror:1 row_mask:0xf bank_mask:0xf
	v_fmac_f32_dpp v200, v112, v136 row_shl:1 row_mask:0xf bank_mask:0xf
	v_fmac_f32_dpp v201, v113, v137 row_shl:1 row_mask:0xf bank_mask:0xf
	v_fmac_f32_dpp v202, v114, v138 row_shl:1 row_mask:0xf bank_mask:0xf
	v_fmac_f32_dpp v203, v115, v139 row_shl:1 row_mask:0xf bank_mask:0xf
	v_fmac_f32_dpp v200, v88, v220 row_ror:15 row_mask:0xf bank_mask:0xf
	v_fmac_f32_dpp v201, v89, v221 row_ror:15 row_mask:0xf bank_mask:0xf
	v_fmac_f32_dpp v202, v90, v222 row_ror:15 row_mask:0xf bank_mask:0xf
	v_fmac_f32_dpp v203, v91, v223 row_ror:15 row_mask:0xf bank_mask:0xf
	v_fma_f32 v204, v172, v92, v180
	v_fma_f32 v205, v173, v93, v181
	v_fma_f32 v206, v174, v94, v182
	v_fma_f32 v207, v175, v95, v183
	v_fmac_f32_dpp v204, v92, v160 row_shr:1 row_mask:0xf bank_mask:0xf
	v_fmac_f32_dpp v205, v93, v161 row_shr:1 row_mask:0xf bank_mask:0xf
	v_fmac_f32_dpp v206, v94, v162 row_shr:1 row_mask:0xf bank_mask:0xf
	v_fmac_f32_dpp v207, v95, v163 row_shr:1 row_mask:0xf bank_mask:0xf
	v_fmac_f32_dpp v204, v104, v224 row_ror:1 row_mask:0xf bank_mask:0xf
	v_fmac_f32_dpp v205, v105, v225 row_ror:1 row_mask:0xf bank_mask:0xf
	v_fmac_f32_dpp v206, v106, v226 row_ror:1 row_mask:0xf bank_mask:0xf
	v_fmac_f32_dpp v207, v107, v227 row_ror:1 row_mask:0xf bank_mask:0xf
	v_fmac_f32_dpp v204, v92, v176 row_shl:1 row_mask:0xf bank_mask:0xf
	v_fmac_f32_dpp v205, v93, v177 row_shl:1 row_mask:0xf bank_mask:0xf
	v_fmac_f32_dpp v206, v94, v178 row_shl:1 row_mask:0xf bank_mask:0xf
	v_fmac_f32_dpp v207, v95, v179 row_shl:1 row_mask:0xf bank_mask:0xf
	v_fmac_f32_dpp v204, v76, v232 row_ror:15 row_mask:0xf bank_mask:0xf
	v_fmac_f32_dpp v205, v77, v233 row_ror:15 row_mask:0xf bank_mask:0xf
	v_fmac_f32_dpp v206, v78, v234 row_ror:15 row_mask:0xf bank_mask:0xf
	v_fmac_f32_dpp v207, v79, v235 row_ror:15 row_mask:0xf bank_mask:0xf
	v_mul_f32_e32 v208, 0xbfb8aa3b, v200
	v_mul_f32_e32 v209, 0xbfb8aa3b, v201
	v_mul_f32_e32 v210, 0xbfb8aa3b, v202
	v_mul_f32_e32 v211, 0xbfb8aa3b, v203
	v_exp_f32_e32 v208, v208
	v_exp_f32_e32 v209, v209
	v_exp_f32_e32 v210, v210
	v_exp_f32_e32 v211, v211
	v_add_f32_e32 v208, 1.0, v208
	v_add_f32_e32 v209, 1.0, v209
	v_add_f32_e32 v210, 1.0, v210
	v_add_f32_e32 v211, 1.0, v211
	v_rcp_f32_e32 v208, v208
	v_rcp_f32_e32 v209, v209
	v_rcp_f32_e32 v210, v210
	v_rcp_f32_e32 v211, v211
	v_mul_f32_e32 v200, v200, v208
	v_mul_f32_e32 v201, v201, v209
	v_mul_f32_e32 v202, v202, v210
	v_mul_f32_e32 v203, v203, v211
	v_mul_f32_e32 v200, v200, v204
	v_mul_f32_e32 v201, v201, v205
	v_mul_f32_e32 v202, v202, v206
	v_mul_f32_e32 v203, v203, v207
	v_cvt_pk_bf16_f32 v118, v200, v201
	v_cvt_pk_bf16_f32 v119, v202, v203
	v_fma_f32 v200, v132, v88, v140
	v_fma_f32 v201, v133, v89, v141
	v_fma_f32 v202, v134, v90, v142
	v_fma_f32 v203, v135, v91, v143
	v_fmac_f32_dpp v200, v88, v128 row_shr:1 row_mask:0xf bank_mask:0xf
	v_fmac_f32_dpp v201, v89, v129 row_shr:1 row_mask:0xf bank_mask:0xf
	v_fmac_f32_dpp v202, v90, v130 row_shr:1 row_mask:0xf bank_mask:0xf
	v_fmac_f32_dpp v203, v91, v131 row_shr:1 row_mask:0xf bank_mask:0xf
	v_fmac_f32_dpp v200, v112, v216 row_ror:1 row_mask:0xf bank_mask:0xf
	v_fmac_f32_dpp v201, v113, v217 row_ror:1 row_mask:0xf bank_mask:0xf
	v_fmac_f32_dpp v202, v114, v218 row_ror:1 row_mask:0xf bank_mask:0xf
	v_fmac_f32_dpp v203, v115, v219 row_ror:1 row_mask:0xf bank_mask:0xf
	v_fmac_f32_dpp v200, v88, v136 row_shl:1 row_mask:0xf bank_mask:0xf
	v_fmac_f32_dpp v201, v89, v137 row_shl:1 row_mask:0xf bank_mask:0xf
	v_fmac_f32_dpp v202, v90, v138 row_shl:1 row_mask:0xf bank_mask:0xf
	v_fmac_f32_dpp v203, v91, v139 row_shl:1 row_mask:0xf bank_mask:0xf
	v_fmac_f32_dpp v200, v72, v220 row_ror:15 row_mask:0xf bank_mask:0xf
	v_fmac_f32_dpp v201, v73, v221 row_ror:15 row_mask:0xf bank_mask:0xf
	v_fmac_f32_dpp v202, v74, v222 row_ror:15 row_mask:0xf bank_mask:0xf
	v_fmac_f32_dpp v203, v75, v223 row_ror:15 row_mask:0xf bank_mask:0xf
	v_fma_f32 v204, v172, v76, v180
	v_fma_f32 v205, v173, v77, v181
	v_fma_f32 v206, v174, v78, v182
	v_fma_f32 v207, v175, v79, v183
	v_fmac_f32_dpp v204, v76, v160 row_shr:1 row_mask:0xf bank_mask:0xf
	v_fmac_f32_dpp v205, v77, v161 row_shr:1 row_mask:0xf bank_mask:0xf
	v_fmac_f32_dpp v206, v78, v162 row_shr:1 row_mask:0xf bank_mask:0xf
	v_fmac_f32_dpp v207, v79, v163 row_shr:1 row_mask:0xf bank_mask:0xf
	v_fmac_f32_dpp v204, v92, v224 row_ror:1 row_mask:0xf bank_mask:0xf
	v_fmac_f32_dpp v205, v93, v225 row_ror:1 row_mask:0xf bank_mask:0xf
	v_fmac_f32_dpp v206, v94, v226 row_ror:1 row_mask:0xf bank_mask:0xf
	v_fmac_f32_dpp v207, v95, v227 row_ror:1 row_mask:0xf bank_mask:0xf
	v_fmac_f32_dpp v204, v76, v176 row_shl:1 row_mask:0xf bank_mask:0xf
	v_fmac_f32_dpp v205, v77, v177 row_shl:1 row_mask:0xf bank_mask:0xf
	v_fmac_f32_dpp v206, v78, v178 row_shl:1 row_mask:0xf bank_mask:0xf
	v_fmac_f32_dpp v207, v79, v179 row_shl:1 row_mask:0xf bank_mask:0xf
	v_fmac_f32_dpp v204, v64, v232 row_ror:15 row_mask:0xf bank_mask:0xf
	v_fmac_f32_dpp v205, v65, v233 row_ror:15 row_mask:0xf bank_mask:0xf
	v_fmac_f32_dpp v206, v66, v234 row_ror:15 row_mask:0xf bank_mask:0xf
	v_fmac_f32_dpp v207, v67, v235 row_ror:15 row_mask:0xf bank_mask:0xf
	v_mul_f32_e32 v208, 0xbfb8aa3b, v200
	v_mul_f32_e32 v209, 0xbfb8aa3b, v201
	v_mul_f32_e32 v210, 0xbfb8aa3b, v202
	v_mul_f32_e32 v211, 0xbfb8aa3b, v203
	v_exp_f32_e32 v208, v208
	v_exp_f32_e32 v209, v209
	v_exp_f32_e32 v210, v210
	v_exp_f32_e32 v211, v211
	v_add_f32_e32 v208, 1.0, v208
	v_add_f32_e32 v209, 1.0, v209
	v_add_f32_e32 v210, 1.0, v210
	v_add_f32_e32 v211, 1.0, v211
	v_rcp_f32_e32 v208, v208
	v_rcp_f32_e32 v209, v209
	v_rcp_f32_e32 v210, v210
	v_rcp_f32_e32 v211, v211
	v_mul_f32_e32 v200, v200, v208
	v_mul_f32_e32 v201, v201, v209
	v_mul_f32_e32 v202, v202, v210
	v_mul_f32_e32 v203, v203, v211
	v_mul_f32_e32 v200, v200, v204
	v_mul_f32_e32 v201, v201, v205
	v_mul_f32_e32 v202, v202, v206
	v_mul_f32_e32 v203, v203, v207
	v_cvt_pk_bf16_f32 v98, v200, v201
	v_cvt_pk_bf16_f32 v99, v202, v203
	v_fma_f32 v200, v132, v72, v140
	v_fma_f32 v201, v133, v73, v141
	v_fma_f32 v202, v134, v74, v142
	v_fma_f32 v203, v135, v75, v143
	v_fmac_f32_dpp v200, v72, v128 row_shr:1 row_mask:0xf bank_mask:0xf
	v_fmac_f32_dpp v201, v73, v129 row_shr:1 row_mask:0xf bank_mask:0xf
	v_fmac_f32_dpp v202, v74, v130 row_shr:1 row_mask:0xf bank_mask:0xf
	v_fmac_f32_dpp v203, v75, v131 row_shr:1 row_mask:0xf bank_mask:0xf
	v_fmac_f32_dpp v200, v88, v216 row_ror:1 row_mask:0xf bank_mask:0xf
	v_fmac_f32_dpp v201, v89, v217 row_ror:1 row_mask:0xf bank_mask:0xf
	v_fmac_f32_dpp v202, v90, v218 row_ror:1 row_mask:0xf bank_mask:0xf
	v_fmac_f32_dpp v203, v91, v219 row_ror:1 row_mask:0xf bank_mask:0xf
	v_fmac_f32_dpp v200, v72, v136 row_shl:1 row_mask:0xf bank_mask:0xf
	v_fmac_f32_dpp v201, v73, v137 row_shl:1 row_mask:0xf bank_mask:0xf
	v_fmac_f32_dpp v202, v74, v138 row_shl:1 row_mask:0xf bank_mask:0xf
	v_fmac_f32_dpp v203, v75, v139 row_shl:1 row_mask:0xf bank_mask:0xf
	v_fmac_f32_e32 v200, v184, v220
	v_fmac_f32_e32 v201, v185, v221
	v_fmac_f32_e32 v202, v186, v222
	v_fmac_f32_e32 v203, v187, v223
	v_fma_f32 v204, v172, v64, v180
	v_fma_f32 v205, v173, v65, v181
	v_fma_f32 v206, v174, v66, v182
	v_fma_f32 v207, v175, v67, v183
	v_fmac_f32_dpp v204, v64, v160 row_shr:1 row_mask:0xf bank_mask:0xf
	v_fmac_f32_dpp v205, v65, v161 row_shr:1 row_mask:0xf bank_mask:0xf
	v_fmac_f32_dpp v206, v66, v162 row_shr:1 row_mask:0xf bank_mask:0xf
	v_fmac_f32_dpp v207, v67, v163 row_shr:1 row_mask:0xf bank_mask:0xf
	v_fmac_f32_dpp v204, v76, v224 row_ror:1 row_mask:0xf bank_mask:0xf
	v_fmac_f32_dpp v205, v77, v225 row_ror:1 row_mask:0xf bank_mask:0xf
	v_fmac_f32_dpp v206, v78, v226 row_ror:1 row_mask:0xf bank_mask:0xf
	v_fmac_f32_dpp v207, v79, v227 row_ror:1 row_mask:0xf bank_mask:0xf
	v_fmac_f32_dpp v204, v64, v176 row_shl:1 row_mask:0xf bank_mask:0xf
	v_fmac_f32_dpp v205, v65, v177 row_shl:1 row_mask:0xf bank_mask:0xf
	v_fmac_f32_dpp v206, v66, v178 row_shl:1 row_mask:0xf bank_mask:0xf
	v_fmac_f32_dpp v207, v67, v179 row_shl:1 row_mask:0xf bank_mask:0xf
	v_fmac_f32_e32 v204, v188, v232
	v_fmac_f32_e32 v205, v189, v233
	v_fmac_f32_e32 v206, v190, v234
	v_fmac_f32_e32 v207, v191, v235
	v_mul_f32_e32 v208, 0xbfb8aa3b, v200
	v_mul_f32_e32 v209, 0xbfb8aa3b, v201
	v_mul_f32_e32 v210, 0xbfb8aa3b, v202
	v_mul_f32_e32 v211, 0xbfb8aa3b, v203
	v_exp_f32_e32 v208, v208
	v_exp_f32_e32 v209, v209
	v_exp_f32_e32 v210, v210
	v_exp_f32_e32 v211, v211
	v_add_f32_e32 v208, 1.0, v208
	v_add_f32_e32 v209, 1.0, v209
	v_add_f32_e32 v210, 1.0, v210
	v_add_f32_e32 v211, 1.0, v211
	v_rcp_f32_e32 v208, v208
	v_rcp_f32_e32 v209, v209
	v_rcp_f32_e32 v210, v210
	v_rcp_f32_e32 v211, v211
	v_mul_f32_e32 v200, v200, v208
	v_mul_f32_e32 v201, v201, v209
	v_mul_f32_e32 v202, v202, v210
	v_mul_f32_e32 v203, v203, v211
	v_mul_f32_e32 v200, v200, v204
	v_mul_f32_e32 v201, v201, v205
	v_mul_f32_e32 v202, v202, v206
	v_mul_f32_e32 v203, v203, v207
	v_cvt_pk_bf16_f32 v82, v200, v201
	v_cvt_pk_bf16_f32 v83, v202, v203
	v_fma_f32 v200, v132, v56, v140
	v_fma_f32 v201, v133, v57, v141
	v_fma_f32 v202, v134, v58, v142
	v_fma_f32 v203, v135, v59, v143
	v_fmac_f32_dpp v200, v56, v128 row_shr:1 row_mask:0xf bank_mask:0xf
	v_fmac_f32_dpp v201, v57, v129 row_shr:1 row_mask:0xf bank_mask:0xf
	v_fmac_f32_dpp v202, v58, v130 row_shr:1 row_mask:0xf bank_mask:0xf
	v_fmac_f32_dpp v203, v59, v131 row_shr:1 row_mask:0xf bank_mask:0xf
	v_fmac_f32_e32 v200, v192, v216
	v_fmac_f32_e32 v201, v193, v217
	v_fmac_f32_e32 v202, v194, v218
	v_fmac_f32_e32 v203, v195, v219
	v_fmac_f32_dpp v200, v56, v136 row_shl:1 row_mask:0xf bank_mask:0xf
	v_fmac_f32_dpp v201, v57, v137 row_shl:1 row_mask:0xf bank_mask:0xf
	v_fmac_f32_dpp v202, v58, v138 row_shl:1 row_mask:0xf bank_mask:0xf
	v_fmac_f32_dpp v203, v59, v139 row_shl:1 row_mask:0xf bank_mask:0xf
	v_fmac_f32_dpp v200, v40, v220 row_ror:15 row_mask:0xf bank_mask:0xf
	v_fmac_f32_dpp v201, v41, v221 row_ror:15 row_mask:0xf bank_mask:0xf
	v_fmac_f32_dpp v202, v42, v222 row_ror:15 row_mask:0xf bank_mask:0xf
	v_fmac_f32_dpp v203, v43, v223 row_ror:15 row_mask:0xf bank_mask:0xf
	v_fma_f32 v204, v172, v44, v180
	v_fma_f32 v205, v173, v45, v181
	v_fma_f32 v206, v174, v46, v182
	v_fma_f32 v207, v175, v47, v183
	v_fmac_f32_dpp v204, v44, v160 row_shr:1 row_mask:0xf bank_mask:0xf
	v_fmac_f32_dpp v205, v45, v161 row_shr:1 row_mask:0xf bank_mask:0xf
	v_fmac_f32_dpp v206, v46, v162 row_shr:1 row_mask:0xf bank_mask:0xf
	v_fmac_f32_dpp v207, v47, v163 row_shr:1 row_mask:0xf bank_mask:0xf
	v_fmac_f32_e32 v204, v196, v224
	v_fmac_f32_e32 v205, v197, v225
	v_fmac_f32_e32 v206, v198, v226
	v_fmac_f32_e32 v207, v199, v227
	v_fmac_f32_dpp v204, v44, v176 row_shl:1 row_mask:0xf bank_mask:0xf
	v_fmac_f32_dpp v205, v45, v177 row_shl:1 row_mask:0xf bank_mask:0xf
	v_fmac_f32_dpp v206, v46, v178 row_shl:1 row_mask:0xf bank_mask:0xf
	v_fmac_f32_dpp v207, v47, v179 row_shl:1 row_mask:0xf bank_mask:0xf
	v_fmac_f32_dpp v204, v28, v232 row_ror:15 row_mask:0xf bank_mask:0xf
	v_fmac_f32_dpp v205, v29, v233 row_ror:15 row_mask:0xf bank_mask:0xf
	v_fmac_f32_dpp v206, v30, v234 row_ror:15 row_mask:0xf bank_mask:0xf
	v_fmac_f32_dpp v207, v31, v235 row_ror:15 row_mask:0xf bank_mask:0xf
	v_mul_f32_e32 v208, 0xbfb8aa3b, v200
	v_mul_f32_e32 v209, 0xbfb8aa3b, v201
	v_mul_f32_e32 v210, 0xbfb8aa3b, v202
	v_mul_f32_e32 v211, 0xbfb8aa3b, v203
	v_exp_f32_e32 v208, v208
	v_exp_f32_e32 v209, v209
	v_exp_f32_e32 v210, v210
	v_exp_f32_e32 v211, v211
	v_add_f32_e32 v208, 1.0, v208
	v_add_f32_e32 v209, 1.0, v209
	v_add_f32_e32 v210, 1.0, v210
	v_add_f32_e32 v211, 1.0, v211
	v_rcp_f32_e32 v208, v208
	v_rcp_f32_e32 v209, v209
	v_rcp_f32_e32 v210, v210
	v_rcp_f32_e32 v211, v211
	v_mul_f32_e32 v200, v200, v208
	v_mul_f32_e32 v201, v201, v209
	v_mul_f32_e32 v202, v202, v210
	v_mul_f32_e32 v203, v203, v211
	v_mul_f32_e32 v200, v200, v204
	v_mul_f32_e32 v201, v201, v205
	v_mul_f32_e32 v202, v202, v206
	v_mul_f32_e32 v203, v203, v207
	v_cvt_pk_bf16_f32 v62, v200, v201
	v_cvt_pk_bf16_f32 v63, v202, v203
	v_fma_f32 v200, v132, v40, v140
	v_fma_f32 v201, v133, v41, v141
	v_fma_f32 v202, v134, v42, v142
	v_fma_f32 v203, v135, v43, v143
	v_fmac_f32_dpp v200, v40, v128 row_shr:1 row_mask:0xf bank_mask:0xf
	v_fmac_f32_dpp v201, v41, v129 row_shr:1 row_mask:0xf bank_mask:0xf
	v_fmac_f32_dpp v202, v42, v130 row_shr:1 row_mask:0xf bank_mask:0xf
	v_fmac_f32_dpp v203, v43, v131 row_shr:1 row_mask:0xf bank_mask:0xf
	v_fmac_f32_dpp v200, v56, v216 row_ror:1 row_mask:0xf bank_mask:0xf
	v_fmac_f32_dpp v201, v57, v217 row_ror:1 row_mask:0xf bank_mask:0xf
	v_fmac_f32_dpp v202, v58, v218 row_ror:1 row_mask:0xf bank_mask:0xf
	v_fmac_f32_dpp v203, v59, v219 row_ror:1 row_mask:0xf bank_mask:0xf
	v_fmac_f32_dpp v200, v40, v136 row_shl:1 row_mask:0xf bank_mask:0xf
	v_fmac_f32_dpp v201, v41, v137 row_shl:1 row_mask:0xf bank_mask:0xf
	v_fmac_f32_dpp v202, v42, v138 row_shl:1 row_mask:0xf bank_mask:0xf
	v_fmac_f32_dpp v203, v43, v139 row_shl:1 row_mask:0xf bank_mask:0xf
	v_fmac_f32_dpp v200, v24, v220 row_ror:15 row_mask:0xf bank_mask:0xf
	v_fmac_f32_dpp v201, v25, v221 row_ror:15 row_mask:0xf bank_mask:0xf
	v_fmac_f32_dpp v202, v26, v222 row_ror:15 row_mask:0xf bank_mask:0xf
	v_fmac_f32_dpp v203, v27, v223 row_ror:15 row_mask:0xf bank_mask:0xf
	v_fma_f32 v204, v172, v28, v180
	v_fma_f32 v205, v173, v29, v181
	v_fma_f32 v206, v174, v30, v182
	v_fma_f32 v207, v175, v31, v183
	v_fmac_f32_dpp v204, v28, v160 row_shr:1 row_mask:0xf bank_mask:0xf
	v_fmac_f32_dpp v205, v29, v161 row_shr:1 row_mask:0xf bank_mask:0xf
	v_fmac_f32_dpp v206, v30, v162 row_shr:1 row_mask:0xf bank_mask:0xf
	v_fmac_f32_dpp v207, v31, v163 row_shr:1 row_mask:0xf bank_mask:0xf
	v_fmac_f32_dpp v204, v44, v224 row_ror:1 row_mask:0xf bank_mask:0xf
	v_fmac_f32_dpp v205, v45, v225 row_ror:1 row_mask:0xf bank_mask:0xf
	v_fmac_f32_dpp v206, v46, v226 row_ror:1 row_mask:0xf bank_mask:0xf
	v_fmac_f32_dpp v207, v47, v227 row_ror:1 row_mask:0xf bank_mask:0xf
	v_fmac_f32_dpp v204, v28, v176 row_shl:1 row_mask:0xf bank_mask:0xf
	v_fmac_f32_dpp v205, v29, v177 row_shl:1 row_mask:0xf bank_mask:0xf
	v_fmac_f32_dpp v206, v30, v178 row_shl:1 row_mask:0xf bank_mask:0xf
	v_fmac_f32_dpp v207, v31, v179 row_shl:1 row_mask:0xf bank_mask:0xf
	v_fmac_f32_dpp v204, v12, v232 row_ror:15 row_mask:0xf bank_mask:0xf
	v_fmac_f32_dpp v205, v13, v233 row_ror:15 row_mask:0xf bank_mask:0xf
	v_fmac_f32_dpp v206, v14, v234 row_ror:15 row_mask:0xf bank_mask:0xf
	v_fmac_f32_dpp v207, v15, v235 row_ror:15 row_mask:0xf bank_mask:0xf
	v_mul_f32_e32 v208, 0xbfb8aa3b, v200
	v_mul_f32_e32 v209, 0xbfb8aa3b, v201
	v_mul_f32_e32 v210, 0xbfb8aa3b, v202
	v_mul_f32_e32 v211, 0xbfb8aa3b, v203
	v_exp_f32_e32 v208, v208
	v_exp_f32_e32 v209, v209
	v_exp_f32_e32 v210, v210
	v_exp_f32_e32 v211, v211
	v_add_f32_e32 v208, 1.0, v208
	v_add_f32_e32 v209, 1.0, v209
	v_add_f32_e32 v210, 1.0, v210
	v_add_f32_e32 v211, 1.0, v211
	v_rcp_f32_e32 v208, v208
	v_rcp_f32_e32 v209, v209
	v_rcp_f32_e32 v210, v210
	v_rcp_f32_e32 v211, v211
	v_mul_f32_e32 v200, v200, v208
	v_mul_f32_e32 v201, v201, v209
	v_mul_f32_e32 v202, v202, v210
	v_mul_f32_e32 v203, v203, v211
	v_mul_f32_e32 v200, v200, v204
	v_mul_f32_e32 v201, v201, v205
	v_mul_f32_e32 v202, v202, v206
	v_mul_f32_e32 v203, v203, v207
	v_cvt_pk_bf16_f32 v50, v200, v201
	v_cvt_pk_bf16_f32 v51, v202, v203
	v_fma_f32 v200, v132, v24, v140
	v_fma_f32 v201, v133, v25, v141
	v_fma_f32 v202, v134, v26, v142
	v_fma_f32 v203, v135, v27, v143
	v_fmac_f32_dpp v200, v24, v128 row_shr:1 row_mask:0xf bank_mask:0xf
	v_fmac_f32_dpp v201, v25, v129 row_shr:1 row_mask:0xf bank_mask:0xf
	v_fmac_f32_dpp v202, v26, v130 row_shr:1 row_mask:0xf bank_mask:0xf
	v_fmac_f32_dpp v203, v27, v131 row_shr:1 row_mask:0xf bank_mask:0xf
	v_fmac_f32_dpp v200, v40, v216 row_ror:1 row_mask:0xf bank_mask:0xf
	v_fmac_f32_dpp v201, v41, v217 row_ror:1 row_mask:0xf bank_mask:0xf
	v_fmac_f32_dpp v202, v42, v218 row_ror:1 row_mask:0xf bank_mask:0xf
	v_fmac_f32_dpp v203, v43, v219 row_ror:1 row_mask:0xf bank_mask:0xf
	v_fmac_f32_dpp v200, v24, v136 row_shl:1 row_mask:0xf bank_mask:0xf
	v_fmac_f32_dpp v201, v25, v137 row_shl:1 row_mask:0xf bank_mask:0xf
	v_fmac_f32_dpp v202, v26, v138 row_shl:1 row_mask:0xf bank_mask:0xf
	v_fmac_f32_dpp v203, v27, v139 row_shl:1 row_mask:0xf bank_mask:0xf
	v_fmac_f32_dpp v200, v8, v220 row_ror:15 row_mask:0xf bank_mask:0xf
	v_fmac_f32_dpp v201, v9, v221 row_ror:15 row_mask:0xf bank_mask:0xf
	v_fmac_f32_dpp v202, v10, v222 row_ror:15 row_mask:0xf bank_mask:0xf
	v_fmac_f32_dpp v203, v11, v223 row_ror:15 row_mask:0xf bank_mask:0xf
	v_fma_f32 v204, v172, v12, v180
	v_fma_f32 v205, v173, v13, v181
	v_fma_f32 v206, v174, v14, v182
	v_fma_f32 v207, v175, v15, v183
	v_fmac_f32_dpp v204, v12, v160 row_shr:1 row_mask:0xf bank_mask:0xf
	v_fmac_f32_dpp v205, v13, v161 row_shr:1 row_mask:0xf bank_mask:0xf
	v_fmac_f32_dpp v206, v14, v162 row_shr:1 row_mask:0xf bank_mask:0xf
	v_fmac_f32_dpp v207, v15, v163 row_shr:1 row_mask:0xf bank_mask:0xf
	v_fmac_f32_dpp v204, v28, v224 row_ror:1 row_mask:0xf bank_mask:0xf
	v_fmac_f32_dpp v205, v29, v225 row_ror:1 row_mask:0xf bank_mask:0xf
	v_fmac_f32_dpp v206, v30, v226 row_ror:1 row_mask:0xf bank_mask:0xf
	v_fmac_f32_dpp v207, v31, v227 row_ror:1 row_mask:0xf bank_mask:0xf
	v_fmac_f32_dpp v204, v12, v176 row_shl:1 row_mask:0xf bank_mask:0xf
	v_fmac_f32_dpp v205, v13, v177 row_shl:1 row_mask:0xf bank_mask:0xf
	v_fmac_f32_dpp v206, v14, v178 row_shl:1 row_mask:0xf bank_mask:0xf
	v_fmac_f32_dpp v207, v15, v179 row_shl:1 row_mask:0xf bank_mask:0xf
	v_fmac_f32_dpp v204, v0, v232 row_ror:15 row_mask:0xf bank_mask:0xf
	v_fmac_f32_dpp v205, v1, v233 row_ror:15 row_mask:0xf bank_mask:0xf
	v_fmac_f32_dpp v206, v2, v234 row_ror:15 row_mask:0xf bank_mask:0xf
	v_fmac_f32_dpp v207, v3, v235 row_ror:15 row_mask:0xf bank_mask:0xf
	v_mul_f32_e32 v208, 0xbfb8aa3b, v200
	v_mul_f32_e32 v209, 0xbfb8aa3b, v201
	v_mul_f32_e32 v210, 0xbfb8aa3b, v202
	v_mul_f32_e32 v211, 0xbfb8aa3b, v203
	v_exp_f32_e32 v208, v208
	v_exp_f32_e32 v209, v209
	v_exp_f32_e32 v210, v210
	v_exp_f32_e32 v211, v211
	v_add_f32_e32 v208, 1.0, v208
	v_add_f32_e32 v209, 1.0, v209
	v_add_f32_e32 v210, 1.0, v210
	v_add_f32_e32 v211, 1.0, v211
	v_rcp_f32_e32 v208, v208
	v_rcp_f32_e32 v209, v209
	v_rcp_f32_e32 v210, v210
	v_rcp_f32_e32 v211, v211
	v_mul_f32_e32 v200, v200, v208
	v_mul_f32_e32 v201, v201, v209
	v_mul_f32_e32 v202, v202, v210
	v_mul_f32_e32 v203, v203, v211
	v_mul_f32_e32 v200, v200, v204
	v_mul_f32_e32 v201, v201, v205
	v_mul_f32_e32 v202, v202, v206
	v_mul_f32_e32 v203, v203, v207
	v_cvt_pk_bf16_f32 v34, v200, v201
	v_cvt_pk_bf16_f32 v35, v202, v203
	v_fma_f32 v200, v132, v8, v140
	v_fma_f32 v201, v133, v9, v141
	v_fma_f32 v202, v134, v10, v142
	v_fma_f32 v203, v135, v11, v143
	v_fmac_f32_dpp v200, v8, v128 row_shr:1 row_mask:0xf bank_mask:0xf
	v_fmac_f32_dpp v201, v9, v129 row_shr:1 row_mask:0xf bank_mask:0xf
	v_fmac_f32_dpp v202, v10, v130 row_shr:1 row_mask:0xf bank_mask:0xf
	v_fmac_f32_dpp v203, v11, v131 row_shr:1 row_mask:0xf bank_mask:0xf
	v_fmac_f32_dpp v200, v24, v216 row_ror:1 row_mask:0xf bank_mask:0xf
	v_fmac_f32_dpp v201, v25, v217 row_ror:1 row_mask:0xf bank_mask:0xf
	v_fmac_f32_dpp v202, v26, v218 row_ror:1 row_mask:0xf bank_mask:0xf
	v_fmac_f32_dpp v203, v27, v219 row_ror:1 row_mask:0xf bank_mask:0xf
	v_fmac_f32_dpp v200, v8, v136 row_shl:1 row_mask:0xf bank_mask:0xf
	v_fmac_f32_dpp v201, v9, v137 row_shl:1 row_mask:0xf bank_mask:0xf
	v_fmac_f32_dpp v202, v10, v138 row_shl:1 row_mask:0xf bank_mask:0xf
	v_fmac_f32_dpp v203, v11, v139 row_shl:1 row_mask:0xf bank_mask:0xf
	v_fmac_f32_e32 v200, v192, v220
	v_fmac_f32_e32 v201, v193, v221
	v_fmac_f32_e32 v202, v194, v222
	v_fmac_f32_e32 v203, v195, v223
	v_fma_f32 v204, v172, v0, v180
	v_fma_f32 v205, v173, v1, v181
	v_fma_f32 v206, v174, v2, v182
	v_fma_f32 v207, v175, v3, v183
	v_fmac_f32_dpp v204, v0, v160 row_shr:1 row_mask:0xf bank_mask:0xf
	v_fmac_f32_dpp v205, v1, v161 row_shr:1 row_mask:0xf bank_mask:0xf
	v_fmac_f32_dpp v206, v2, v162 row_shr:1 row_mask:0xf bank_mask:0xf
	v_fmac_f32_dpp v207, v3, v163 row_shr:1 row_mask:0xf bank_mask:0xf
	v_fmac_f32_dpp v204, v12, v224 row_ror:1 row_mask:0xf bank_mask:0xf
	v_fmac_f32_dpp v205, v13, v225 row_ror:1 row_mask:0xf bank_mask:0xf
	v_fmac_f32_dpp v206, v14, v226 row_ror:1 row_mask:0xf bank_mask:0xf
	v_fmac_f32_dpp v207, v15, v227 row_ror:1 row_mask:0xf bank_mask:0xf
	v_fmac_f32_dpp v204, v0, v176 row_shl:1 row_mask:0xf bank_mask:0xf
	v_fmac_f32_dpp v205, v1, v177 row_shl:1 row_mask:0xf bank_mask:0xf
	v_fmac_f32_dpp v206, v2, v178 row_shl:1 row_mask:0xf bank_mask:0xf
	v_fmac_f32_dpp v207, v3, v179 row_shl:1 row_mask:0xf bank_mask:0xf
	v_fmac_f32_e32 v204, v196, v232
	v_fmac_f32_e32 v205, v197, v233
	v_fmac_f32_e32 v206, v198, v234
	v_fmac_f32_e32 v207, v199, v235
	s_mov_b64 exec, s[62:63]
	v_add_u32_e32 v250, 0x10800, v229
	global_store_dwordx4 v250, v[200:203], s[64:65] offset:16
	v_add_u32_e32 v250, 0x13400, v229
	global_store_dwordx4 v250, v[204:207], s[64:65] offset:16
	s_mov_b64 exec, s[58:59]
	s_nop 4
	v_mul_f32_e32 v208, 0xbfb8aa3b, v200
	v_mul_f32_e32 v209, 0xbfb8aa3b, v201
	v_mul_f32_e32 v210, 0xbfb8aa3b, v202
	v_mul_f32_e32 v211, 0xbfb8aa3b, v203
	v_exp_f32_e32 v208, v208
	v_exp_f32_e32 v209, v209
	v_exp_f32_e32 v210, v210
	v_exp_f32_e32 v211, v211
	v_add_f32_e32 v208, 1.0, v208
	v_add_f32_e32 v209, 1.0, v209
	v_add_f32_e32 v210, 1.0, v210
	v_add_f32_e32 v211, 1.0, v211
	v_rcp_f32_e32 v208, v208
	v_rcp_f32_e32 v209, v209
	v_rcp_f32_e32 v210, v210
	v_rcp_f32_e32 v211, v211
	v_mul_f32_e32 v200, v200, v208
	v_mul_f32_e32 v201, v201, v209
	v_mul_f32_e32 v202, v202, v210
	v_mul_f32_e32 v203, v203, v211
	v_mul_f32_e32 v200, v200, v204
	v_mul_f32_e32 v201, v201, v205
	v_mul_f32_e32 v202, v202, v206
	v_mul_f32_e32 v203, v203, v207
	v_cvt_pk_bf16_f32 v18, v200, v201
	v_cvt_pk_bf16_f32 v19, v202, v203
	global_store_dwordx4 v171, v[124:127], s[52:53]
	v_add_u32_e32 v250, 0x16000, v171
	global_store_dwordx4 v250, v[116:119], s[52:53]
	s_nop 0
	v_add_u32_e32 v250, 0x2c000, v171
	global_store_dwordx4 v250, v[96:99], s[52:53]
	s_nop 0
	v_add_u32_e32 v250, 0x42000, v171
	global_store_dwordx4 v250, v[80:83], s[52:53]
	s_nop 0
	v_add_u32_e32 v250, 0xb0000, v171
	global_store_dwordx4 v250, v[60:63], s[52:53]
	s_nop 0
	v_add_u32_e32 v250, 0xc6000, v171
	global_store_dwordx4 v250, v[48:51], s[52:53]
	s_nop 0
	v_add_u32_e32 v250, 0xdc000, v171
	global_store_dwordx4 v250, v[32:35], s[52:53]
	s_nop 0
	v_add_u32_e32 v250, 0xf2000, v171
	global_store_dwordx4 v250, v[16:19], s[52:53]
	s_nop 0
	s_mov_b64 s[6:7], -1
	s_and_b64 vcc, exec, s[4:5]
	s_cbranch_vccz .LBB0_1873
	s_andn2_b64 vcc, exec, s[8:9]
	s_cbranch_vccnz .LBB0_1872
	s_barrier
	s_branch .LBB0_1872

.LBB0_1934:
	s_cmp_gt_i32 s72, 21
	s_cselect_b64 s[0:1], -1, 0
	s_cmp_lt_i32 s73, 22
	s_cselect_b64 s[4:5], -1, 0
	s_or_b64 s[0:1], s[0:1], s[4:5]
	s_and_b64 vcc, exec, s[0:1]
	s_cbranch_vccnz .LBB0_1992
	s_mov_b64 s[4:5], exec
	s_cmpk_gt_i32 s84, 63
	s_cbranch_scc1 .LfixB_done
	s_lshr_b32 s8, s84, 1
	s_and_b32 s9, s84, 1
	s_and_b32 s10, s8, 3
	s_mul_i32 s11, s9, 3
	s_cmp_eq_u32 s10, s11
	s_cbranch_scc1 .LfixB_done
	s_add_u32 s12, s70, 0x5b00000
	s_addc_u32 s13, s71, 0
	s_mul_i32 s14, s8, 0x16000
	s_mul_i32 s15, s9, 0xb000
	s_add_i32 s14, s14, s15
	s_add_i32 s14, s14, 0x5800
	s_add_u32 s60, s12, s14
	s_addc_u32 s61, s13, 0
	s_lshl_b32 s14, s9, 1
	s_add_i32 s14, s14, s8
	s_add_i32 s14, s14, -1
	s_mul_i32 s14, s14, 0x16000
	s_sub_i32 s15, 1, s9
	s_mul_i32 s15, s15, 0xb000
	s_add_i32 s14, s14, s15
	s_add_u32 s62, s12, s14
	s_addc_u32 s63, s13, 0
	v_readlane_b32 s64, v254, 5
	v_readlane_b32 s65, v254, 6
	s_mul_i32 s15, s9, 0xb000
	s_add_i32 s15, s15, 0x10800
	s_add_u32 s64, s64, s15
	s_addc_u32 s65, s65, 0
	s_lshl_b32 s14, s8, 8
	s_mul_i32 s15, s9, 255
	s_add_i32 s14, s14, s15
	s_mul_i32 s14, s14, 0x1600
	s_add_u32 s14, s14, 0xbf00000
	s_add_u32 s66, s70, s14
	s_addc_u32 s67, s71, 0
	s_nop 4
	v_mov_b32_e32 v0, v230
	v_cmp_gt_u32_e32 vcc, 0x580, v0
	s_and_saveexec_b64 s[74:75], vcc
	v_lshlrev_b32_e32 v1, 3, v0
	v_add_u32_e32 v2, 0x2c00, v1
	global_load_dwordx2 v[4:5], v1, s[60:61]
	global_load_dwordx2 v[6:7], v2, s[60:61]
	global_load_dwordx2 v[8:9], v1, s[62:63]
	global_load_dwordx2 v[10:11], v2, s[62:63]
	global_load_dwordx2 v[12:13], v1, s[64:65]
	global_load_dwordx2 v[14:15], v2, s[64:65]
	v_lshlrev_b32_e32 v3, 2, v0
	s_waitcnt vmcnt(0)
	v_fmac_f32_e32 v4, v12, v8
	v_fmac_f32_e32 v5, v13, v9
	v_fmac_f32_e32 v6, v14, v10
	v_fmac_f32_e32 v7, v15, v11
	v_mul_f32_e32 v16, 0xbfb8aa3b, v4
	v_mul_f32_e32 v17, 0xbfb8aa3b, v5
	v_exp_f32_e32 v16, v16
	v_exp_f32_e32 v17, v17
	s_nop 0
	v_add_f32_e32 v16, 1.0, v16
	v_add_f32_e32 v17, 1.0, v17
	v_rcp_f32_e32 v16, v16
	v_rcp_f32_e32 v17, v17
	s_nop 0
	v_mul_f32_e32 v4, v4, v16
	v_mul_f32_e32 v5, v5, v17
	v_mul_f32_e32 v4, v4, v6
	v_mul_f32_e32 v5, v5, v7
	v_cvt_pk_bf16_f32 v4, v4, v5
	global_store_dword v3, v4, s[66:67]
	s_or_b64 exec, exec, s[74:75]
	v_add_u32_e32 v0, 512, v230
	v_cmp_gt_u32_e32 vcc, 0x580, v0
	s_and_saveexec_b64 s[74:75], vcc
	v_lshlrev_b32_e32 v1, 3, v0
	v_add_u32_e32 v2, 0x2c00, v1
	global_load_dwordx2 v[4:5], v1, s[60:61]
	global_load_dwordx2 v[6:7], v2, s[60:61]
	global_load_dwordx2 v[8:9], v1, s[62:63]
	global_load_dwordx2 v[10:11], v2, s[62:63]
	global_load_dwordx2 v[12:13], v1, s[64:65]
	global_load_dwordx2 v[14:15], v2, s[64:65]
	v_lshlrev_b32_e32 v3, 2, v0
	s_waitcnt vmcnt(0)
	v_fmac_f32_e32 v4, v12, v8
	v_fmac_f32_e32 v5, v13, v9
	v_fmac_f32_e32 v6, v14, v10
	v_fmac_f32_e32 v7, v15, v11
	v_mul_f32_e32 v16, 0xbfb8aa3b, v4
	v_mul_f32_e32 v17, 0xbfb8aa3b, v5
	v_exp_f32_e32 v16, v16
	v_exp_f32_e32 v17, v17
	s_nop 0
	v_add_f32_e32 v16, 1.0, v16
	v_add_f32_e32 v17, 1.0, v17
	v_rcp_f32_e32 v16, v16
	v_rcp_f32_e32 v17, v17
	s_nop 0
	v_mul_f32_e32 v4, v4, v16
	v_mul_f32_e32 v5, v5, v17
	v_mul_f32_e32 v4, v4, v6
	v_mul_f32_e32 v5, v5, v7
	v_cvt_pk_bf16_f32 v4, v4, v5
	global_store_dword v3, v4, s[66:67]
	s_or_b64 exec, exec, s[74:75]
	v_add_u32_e32 v0, 1024, v230
	v_cmp_gt_u32_e32 vcc, 0x580, v0
	s_and_saveexec_b64 s[74:75], vcc
	v_lshlrev_b32_e32 v1, 3, v0
	v_add_u32_e32 v2, 0x2c00, v1
	global_load_dwordx2 v[4:5], v1, s[60:61]
	global_load_dwordx2 v[6:7], v2, s[60:61]
	global_load_dwordx2 v[8:9], v1, s[62:63]
	global_load_dwordx2 v[10:11], v2, s[62:63]
	global_load_dwordx2 v[12:13], v1, s[64:65]
	global_load_dwordx2 v[14:15], v2, s[64:65]
	v_lshlrev_b32_e32 v3, 2, v0
	s_waitcnt vmcnt(0)
	v_fmac_f32_e32 v4, v12, v8
	v_fmac_f32_e32 v5, v13, v9
	v_fmac_f32_e32 v6, v14, v10
	v_fmac_f32_e32 v7, v15, v11
	v_mul_f32_e32 v16, 0xbfb8aa3b, v4
	v_mul_f32_e32 v17, 0xbfb8aa3b, v5
	v_exp_f32_e32 v16, v16
	v_exp_f32_e32 v17, v17
	s_nop 0
	v_add_f32_e32 v16, 1.0, v16
	v_add_f32_e32 v17, 1.0, v17
	v_rcp_f32_e32 v16, v16
	v_rcp_f32_e32 v17, v17
	s_nop 0
	v_mul_f32_e32 v4, v4, v16
	v_mul_f32_e32 v5, v5, v17
	v_mul_f32_e32 v4, v4, v6
	v_mul_f32_e32 v5, v5, v7
	v_cvt_pk_bf16_f32 v4, v4, v5
	global_store_dword v3, v4, s[66:67]
	s_or_b64 exec, exec, s[74:75]
.LfixB_done:
	s_waitcnt vmcnt(0)
	s_branch .LBB0_1942
	v_mov_b32_e32 v0, v230
	v_readlane_b32 s0, v254, 55
	s_nop 1
	v_add_u32_e32 v160, s0, v0
	s_mov_b32 s0, 0x58000
	v_cmp_gt_i32_e32 vcc, s0, v160
	s_and_saveexec_b64 s[4:5], vcc
	s_cbranch_execz .LBB0_1942
	s_add_u32 s6, s70, 0x3b00000
	s_addc_u32 s7, s71, 0
	v_readlane_b32 s20, v254, 3
	s_add_u32 s8, s70, 0xbf00000
	v_readlane_b32 s22, v254, 5
	v_readlane_b32 s23, v254, 6
	s_addc_u32 s9, s71, 0
	s_mov_b64 s[38:39], s[22:23]
	v_readlane_b32 s24, v254, 7
	v_readlane_b32 s25, v254, 8
	s_add_u32 s10, s38, 0x10800
	s_mov_b64 s[40:41], s[24:25]
	s_addc_u32 s11, s39, 0
	s_add_u32 s12, s40, 0x5800
	s_addc_u32 s13, s41, 0
	s_add_u32 s14, s40, 0x8400
	s_addc_u32 s15, s41, 0
	s_add_u32 s16, s38, 0x13400
	s_addc_u32 s17, s39, 0
	s_add_u32 s22, s38, 0x16000
	s_addc_u32 s23, s39, 0
	s_add_u32 s24, s38, 0x18c00
	v_readlane_b32 s26, v254, 9
	s_addc_u32 s25, s39, 0
	v_readlane_b32 s27, v254, 10
	s_add_u32 s26, s38, 0x1b800
	s_addc_u32 s27, s39, 0
	s_add_u32 s28, s38, 0x1e400
	v_lshlrev_b32_e32 v0, 3, v0
	s_addc_u32 s29, s39, 0
	v_lshl_add_u32 v161, s84, 12, v0
	s_lshl_b32 s0, s97, 3
	s_mov_b64 s[30:31], 0
	s_mov_b32 s1, 0x2e8ba2e9
	s_movk_i32 s33, 0x2c00
	s_movk_i32 s35, 0x3f8
	v_mov_b64_e32 v[144:145], s[6:7]
	s_mov_b32 s34, 0xbfb8aa3b
	s_movk_i32 s36, 0x1600
	s_mov_b32 s37, 0x57fff
	v_readlane_b32 s21, v254, 4
	s_branch .LBB0_1938
